# v104 + k-loop segment closing waits merged into one s_waitcnt vmcnt(N) lgkmcnt(0) and the redundant post-barrier lgkmcnt(0) wait removed (68 segments)
# speedup vs baseline: 1.0079x; 1.0023x over previous
; __device__ __forceinline__ unsigned xb_ld(unsigned* p)              { return __hip_atomic_load(p, __ATOMIC_RELAXED, __HIP_MEMORY_SCOPE_AGENT); }
; __device__ __forceinline__ void xcd_barrier_complete(unsigned* bar, unsigned x, unsigned& nloc, unsigned& nx) {
;     const unsigned G = gridDim.x * gridDim.y * gridDim.z;
;     unsigned sum, cnt, mine, sp = 0u;
;     for (;;) {
;         sum = 0u; cnt = 0u; mine = 0u;
; #pragma unroll
;         for (unsigned j = 0; j < 16; ++j) { const unsigned c = xb_ld(&bar[XB_XCNT(j)]); sum += c; cnt += (c > 0u) ? 1u : 0u; mine = (j == x) ? c : mine; }
;         if (sum == G) break;
;         __builtin_amdgcn_s_sleep(1);
;         if ((++sp & 255u) == 0u) { if (xb_ld(&bar[XB_TMO])) break; if (sp > XB_SPIN_CAP) { atomicAdd(&bar[XB_TMO], 1u); break; } }
;     }
;     nloc = mine > 0u ? mine : 1u; nx = cnt > 0u ? cnt : 1u;
; }
; __device__ __forceinline__ void xcd_barrier(const XcdBarrier& b) {
;     asm volatile("s_waitcnt vmcnt(0)" ::: "memory");
;     __syncthreads();
;     if (threadIdx.x == 0) {
;         unsigned* bar = b.bar;
;         __builtin_amdgcn_s_waitcnt(0);
;         unsigned nloc = b.st[0], nx = b.st[1];
;         if (nloc == 0u) { xcd_barrier_complete(bar, b.x, nloc, nx); b.st[0] = nloc; b.st[1] = nx; }
.LBB0_44:
	s_waitcnt vmcnt(0) lgkmcnt(0)
	s_barrier
	s_and_saveexec_b64 s[4:5], s[24:25]
	s_xor_b64 s[46:47], exec, s[4:5]
	s_cbranch_execz .LBB0_89
	s_add_i32 s3, 0, 0x22000
	v_mov_b32_e32 v0, s3
	s_waitcnt vmcnt(0) expcnt(0) lgkmcnt(0)
	ds_read_b32 v2, v0
	s_add_i32 s3, 0, 0x22004
	v_mov_b32_e32 v0, s3
	ds_read_b32 v0, v0
	s_waitcnt lgkmcnt(1)
	v_cmp_ne_u32_e32 vcc, 0, v2
	s_cbranch_vccnz .LBB0_59
	s_add_u32 s4, s44, 0x3e00200
	s_addc_u32 s5, s45, 0
	s_add_u32 s8, s44, 0x3e00400
	s_addc_u32 s9, s45, 0
	s_add_u32 s10, s44, 0x3e00500
	s_addc_u32 s11, s45, 0
	s_add_u32 s12, s44, 0x3e00600
	s_addc_u32 s13, s45, 0
	s_add_u32 s14, s44, 0x3e00700
	s_addc_u32 s15, s45, 0
	s_add_u32 s16, s44, 0x3e00800
	s_addc_u32 s17, s45, 0
	s_add_u32 s18, s44, 0x3e00900
	s_addc_u32 s19, s45, 0
	s_add_u32 s20, s44, 0x3e00a00
	s_addc_u32 s21, s45, 0
	s_add_u32 s22, s44, 0x3e00b00
	s_addc_u32 s23, s45, 0
	s_add_u32 s28, s44, 0x3e00c00
	s_addc_u32 s29, s45, 0
	s_add_u32 s30, s44, 0x3e00d00
	s_addc_u32 s31, s45, 0
	s_add_u32 s34, s44, 0x3e00e00
	s_addc_u32 s35, s45, 0
	s_add_u32 s36, s44, 0x3e00f00
	s_addc_u32 s37, s45, 0
	s_add_u32 s42, s44, 0x3e01000
	s_addc_u32 s43, s45, 0
	s_load_dword s3, s[0:1], 0xb0
	s_add_u32 s48, s44, 0x3e01100
	s_addc_u32 s49, s45, 0
	s_add_u32 s50, s44, 0x3e01200
	s_addc_u32 s51, s45, 0
	s_add_u32 s52, s44, 0x3e01300
	s_waitcnt lgkmcnt(0)
	s_mul_i32 s3, s41, s3
	s_addc_u32 s53, s45, 0
	s_mul_i32 s3, s3, s40
	s_mov_b32 s26, 1
	s_mov_b64 s[6:7], 0
	v_mov_b64_e32 v[0:1], s[8:9]
	v_mov_b64_e32 v[2:3], s[10:11]
	v_mov_b64_e32 v[4:5], s[12:13]
	v_mov_b64_e32 v[6:7], s[14:15]
	v_mov_b64_e32 v[8:9], s[16:17]
	v_mov_b64_e32 v[10:11], s[18:19]
	v_mov_b64_e32 v[12:13], s[20:21]
	v_mov_b64_e32 v[14:15], s[22:23]
	v_mov_b64_e32 v[16:17], s[28:29]
	v_mov_b64_e32 v[18:19], s[30:31]
	v_mov_b64_e32 v[20:21], s[34:35]
	v_mov_b64_e32 v[22:23], s[36:37]
	v_mov_b64_e32 v[24:25], s[42:43]
	v_mov_b64_e32 v[26:27], s[48:49]
	v_mov_b64_e32 v[28:29], s[50:51]
	v_mov_b64_e32 v[30:31], s[52:53]
	s_branch .LBB0_49

; #define PG8_STAGE(bufoff, gbase, voff) do { _Pragma("unroll") for (int _i = 0; _i < 2; ++_i) \
;         __builtin_amdgcn_global_load_lds((const unsigned*)((const char*)(gbase) + (voff)[_i]), (PG8_LAS unsigned*)(lds + (bufoff) + ldsw + _i * 8192), 16, 0, 0); } while (0)
; #define PG8_LDA(dst, b, h) do { _Pragma("unroll") for (int m = 0; m < 4; ++m) _Pragma("unroll") for (int k = 0; k < 2; ++k) dst[m][k] = *(const PG8_LAS bf16x8*)(lds + PG8_SA(b, h) + aoff + m * 2048 + k * 1024); } while (0)
; #define PG8_LDB(dst, b, h) do { _Pragma("unroll") for (int n = 0; n < 2; ++n) _Pragma("unroll") for (int k = 0; k < 2; ++k) dst[n][k] = *(const PG8_LAS bf16x8*)(lds + PG8_SB(b, h) + boff + n * 2048 + k * 1024); } while (0)
; #define PG8_MMA(ai, bj, At, Bt) do { __builtin_amdgcn_s_setprio(1); _Pragma("unroll") for (int m = 0; m < 4; ++m) _Pragma("unroll") for (int n = 0; n < 2; ++n) _Pragma("unroll") for (int k = 0; k < 2; ++k) \
;         acc[ai][bj][m][n] = __builtin_amdgcn_mfma_f32_16x16x32_bf16(Bt[n][k], At[m][k], acc[ai][bj][m][n], 0, 0, 0); __builtin_amdgcn_s_setprio(0); } while (0)
; #define PG8_WAIT_V(n) asm volatile("s_waitcnt vmcnt(" #n ")" ::: "memory")
; #define PG8_BAR __builtin_amdgcn_s_barrier()
; template <class Epi, class Sched>
; __device__ __forceinline__ void gemm_phase(PG8_LAS unsigned char* lds, PG8_LAS unsigned char* xl, const Gemm g, const Sched& S, const Epi& E) {
;     ...
;     for (;;) {
;         const bool has_next = S.next(ui + 1, nxt);
;         const char* nA = has_next ? (const char*)g.A + nxt.aoff : cA; const char* nB = has_next ? (const char*)g.Bt + nxt.boff : cB;
; #pragma unroll 1
;         for (int t = 0; t < nt; t += 2) {
;             const bool last = (t == nt - 2);
;             const char* a1 = cA + (size_t)(t + 1) * kstep;
;             const char* a2 = last ? nA : cA + (size_t)(t + 2) * kstep; const char* b2 = last ? nB : cB + (size_t)(t + 2) * kstep;
;             const char* a3 = a2 + kstep; const char* b3 = b2 + kstep;
;             PG8_LDB(B0, 0, 0); PG8_LDB(B1, 0, 1); PG8_SCHED; PG8_LDA(At, 0, 0); PG8_STAGE(PG8_SA(1, 1), a1 + hsA, voffA);
;             PG8_WAIT_V(8); PG8_WAIT_L(0); PG8_BAR; PG8_MMA(0, 0, At, B0); PG8_MMA(0, 1, At, B1); PG8_BAR; PG8_SCHED;
;             PG8_LDA(At, 0, 1); PG8_STAGE(PG8_SB(0, 0), b2, voffB); PG8_STAGE(PG8_SB(0, 1), b2 + hsB, voffB); PG8_STAGE(PG8_SA(0, 0), a2, voffA);
.LBB0_101:
	s_add_u32 s20, s35, s16
	s_addc_u32 s21, s36, s17
	s_and_b64 s[22:23], s[4:5], exec
	s_cselect_b32 s73, s21, s29
	s_cselect_b32 s74, s20, s28
	s_add_u32 s22, s2, s18
	s_addc_u32 s23, s3, s19
	s_and_b64 s[30:31], s[4:5], exec
	s_cselect_b32 s75, s23, s27
	s_cselect_b32 s76, s22, s26
	s_add_u32 s77, s26, 0x100
	s_addc_u32 s78, s27, 0
	s_add_u32 s26, s28, 0x40080
	v_mov_b32_e32 v0, 0
	s_addc_u32 s27, s29, 0
	s_mov_b32 s79, -2
	ds_read_b128 v[148:151], v153
	ds_read_b128 v[158:161], v153 offset:1024
	ds_read_b128 v[162:165], v153 offset:2048
	ds_read_b128 v[166:169], v153 offset:3072
	ds_read_b128 v[170:173], v154
	ds_read_b128 v[174:177], v154 offset:1024
	ds_read_b128 v[178:181], v154 offset:2048
	ds_read_b128 v[182:185], v154 offset:3072
	s_add_u32 s28, s26, 0xfffc0080
	s_addc_u32 s29, s27, -1
	s_cmp_eq_u32 s79, 12
	s_cselect_b32 s31, s73, s29
	s_cselect_b32 s30, s74, s28
	s_cselect_b32 s29, s75, s78
	s_cselect_b32 s28, s76, s77
	v_lshl_add_u64 v[218:219], s[26:27], 0, v[142:143]
	s_add_i32 m0, s52, 0xc000
	ds_read_b128 v[186:189], v155
	ds_read_b128 v[190:193], v155 offset:1024
	ds_read_b128 v[194:197], v155 offset:2048
	ds_read_b128 v[198:201], v155 offset:3072
	ds_read_b128 v[202:205], v155 offset:4096
	ds_read_b128 v[206:209], v155 offset:5120
	ds_read_b128 v[210:213], v155 offset:6144
	ds_read_b128 v[214:217], v155 offset:7168
	global_load_lds_dwordx4 v[218:219], off
	v_lshl_add_u64 v[218:219], s[26:27], 0, v[140:141]
	s_add_i32 m0, s52, 0xe000
	s_nop 0
	global_load_lds_dwordx4 v[218:219], off
	s_waitcnt vmcnt(8) lgkmcnt(0)
	s_barrier
	s_setprio 1
	v_mfma_f32_16x16x32_bf16 v[124:127], v[148:151], v[186:189], 0
	v_mfma_f32_16x16x32_bf16 v[116:119], v[162:165], v[186:189], 0
	v_mfma_f32_16x16x32_bf16 v[108:111], v[148:151], v[194:197], 0
	v_mfma_f32_16x16x32_bf16 v[100:103], v[162:165], v[194:197], 0
	v_mfma_f32_16x16x32_bf16 v[92:95], v[148:151], v[202:205], 0
	v_mfma_f32_16x16x32_bf16 v[84:87], v[162:165], v[202:205], 0
	v_mfma_f32_16x16x32_bf16 v[76:79], v[148:151], v[210:213], 0
	v_mfma_f32_16x16x32_bf16 v[68:71], v[162:165], v[210:213], 0
	v_mfma_f32_16x16x32_bf16 v[124:127], v[158:161], v[190:193], v[124:127]
	v_mfma_f32_16x16x32_bf16 v[116:119], v[166:169], v[190:193], v[116:119]
	v_mfma_f32_16x16x32_bf16 v[108:111], v[158:161], v[198:201], v[108:111]
	v_mfma_f32_16x16x32_bf16 v[100:103], v[166:169], v[198:201], v[100:103]
	v_mfma_f32_16x16x32_bf16 v[92:95], v[158:161], v[206:209], v[92:95]
	v_mfma_f32_16x16x32_bf16 v[84:87], v[166:169], v[206:209], v[84:87]
	v_mfma_f32_16x16x32_bf16 v[76:79], v[158:161], v[214:217], v[76:79]
	v_mfma_f32_16x16x32_bf16 v[68:71], v[166:169], v[214:217], v[68:71]
	s_setprio 0
	s_setprio 1
	v_mfma_f32_16x16x32_bf16 v[120:123], v[170:173], v[186:189], 0
	v_mfma_f32_16x16x32_bf16 v[112:115], v[178:181], v[186:189], 0
	v_mfma_f32_16x16x32_bf16 v[104:107], v[170:173], v[194:197], 0
	v_mfma_f32_16x16x32_bf16 v[96:99], v[178:181], v[194:197], 0
	v_mfma_f32_16x16x32_bf16 v[88:91], v[170:173], v[202:205], 0
	v_mfma_f32_16x16x32_bf16 v[80:83], v[178:181], v[202:205], 0
	v_mfma_f32_16x16x32_bf16 v[72:75], v[170:173], v[210:213], 0
	v_mfma_f32_16x16x32_bf16 v[64:67], v[178:181], v[210:213], 0
	v_mfma_f32_16x16x32_bf16 v[120:123], v[174:177], v[190:193], v[120:123]
	v_mfma_f32_16x16x32_bf16 v[112:115], v[182:185], v[190:193], v[112:115]
	v_mfma_f32_16x16x32_bf16 v[104:107], v[174:177], v[198:201], v[104:107]
	v_mfma_f32_16x16x32_bf16 v[96:99], v[182:185], v[198:201], v[96:99]
	v_mfma_f32_16x16x32_bf16 v[88:91], v[174:177], v[206:209], v[88:91]
	v_mfma_f32_16x16x32_bf16 v[80:83], v[182:185], v[206:209], v[80:83]
	v_mfma_f32_16x16x32_bf16 v[72:75], v[174:177], v[214:217], v[72:75]
	v_mfma_f32_16x16x32_bf16 v[64:67], v[182:185], v[214:217], v[64:67]
	s_setprio 0
	s_barrier
	s_add_i32 s68, s60, s42
	v_lshl_add_u64 v[218:219], s[28:29], 0, v[132:133]
	s_mov_b32 m0, s68
	ds_read_b128 v[186:189], v155 offset:16384
	ds_read_b128 v[190:193], v155 offset:17408
	ds_read_b128 v[194:197], v155 offset:18432
	ds_read_b128 v[198:201], v155 offset:19456
	ds_read_b128 v[202:205], v155 offset:20480
	ds_read_b128 v[206:209], v155 offset:21504
	ds_read_b128 v[210:213], v155 offset:22528
	ds_read_b128 v[214:217], v155 offset:23552
	global_load_lds_dwordx4 v[218:219], off
	s_add_i32 m0, s68, 0x2000
	s_add_u32 s80, s28, 0x40000
	v_lshl_add_u64 v[222:223], s[28:29], 0, v[128:129]
	s_addc_u32 s81, s29, 0
	s_add_i32 s68, s61, s42
	global_load_lds_dwordx4 v[222:223], off
	v_lshl_add_u64 v[224:225], s[80:81], 0, v[132:133]
	s_mov_b32 m0, s68
	v_lshl_add_u64 v[226:227], s[30:31], 0, v[130:131]
	global_load_lds_dwordx4 v[224:225], off
	v_lshl_add_u64 v[224:225], s[80:81], 0, v[128:129]
	s_add_i32 m0, s68, 0x2000
	s_nop 0
	global_load_lds_dwordx4 v[224:225], off
	v_lshl_add_u64 v[224:225], s[30:31], 0, v[134:135]
	s_mov_b32 m0, s52
	s_nop 0
	global_load_lds_dwordx4 v[224:225], off
	s_mov_b32 m0, s53
	s_nop 0
	global_load_lds_dwordx4 v[226:227], off
	s_waitcnt vmcnt(8) lgkmcnt(0)
	s_barrier
; #define PG8_STAGE(bufoff, gbase, voff) do { _Pragma("unroll") for (int _i = 0; _i < 2; ++_i) \
;         __builtin_amdgcn_global_load_lds((const unsigned*)((const char*)(gbase) + (voff)[_i]), (PG8_LAS unsigned*)(lds + (bufoff) + ldsw + _i * 8192), 16, 0, 0); } while (0)
; #define PG8_LDA(dst, b, h) do { _Pragma("unroll") for (int m = 0; m < 4; ++m) _Pragma("unroll") for (int k = 0; k < 2; ++k) dst[m][k] = *(const PG8_LAS bf16x8*)(lds + PG8_SA(b, h) + aoff + m * 2048 + k * 1024); } while (0)
; #define PG8_LDB(dst, b, h) do { _Pragma("unroll") for (int n = 0; n < 2; ++n) _Pragma("unroll") for (int k = 0; k < 2; ++k) dst[n][k] = *(const PG8_LAS bf16x8*)(lds + PG8_SB(b, h) + boff + n * 2048 + k * 1024); } while (0)
; #define PG8_MMA(ai, bj, At, Bt) do { __builtin_amdgcn_s_setprio(1); _Pragma("unroll") for (int m = 0; m < 4; ++m) _Pragma("unroll") for (int n = 0; n < 2; ++n) _Pragma("unroll") for (int k = 0; k < 2; ++k) \
;         acc[ai][bj][m][n] = __builtin_amdgcn_mfma_f32_16x16x32_bf16(Bt[n][k], At[m][k], acc[ai][bj][m][n], 0, 0, 0); __builtin_amdgcn_s_setprio(0); } while (0)
; #define PG8_WAIT_V(n) asm volatile("s_waitcnt vmcnt(" #n ")" ::: "memory")
; #define PG8_WAIT_L(n) asm volatile("s_waitcnt lgkmcnt(" #n ")" ::: "memory")
; #define PG8_BAR __builtin_amdgcn_s_barrier()
; #define PG8_SCHED __builtin_amdgcn_sched_barrier(0)
; template <class Epi, class Sched>
; __device__ __forceinline__ void gemm_phase(PG8_LAS unsigned char* lds, PG8_LAS unsigned char* xl, const Gemm g, const Sched& S, const Epi& E) {
;     ...
;             PG8_WAIT_V(8); PG8_WAIT_L(0); PG8_BAR; PG8_MMA(1, 0, At, B0); PG8_MMA(1, 1, At, B1); PG8_BAR; PG8_SCHED;
;             PG8_LDB(B0, 1, 0); PG8_LDB(B1, 1, 1); PG8_SCHED; PG8_LDA(At, 1, 0); PG8_STAGE(PG8_SA(0, 1), a2 + hsA, voffA);
;             PG8_WAIT_V(8); PG8_WAIT_L(0); PG8_BAR; PG8_MMA(0, 0, At, B0); PG8_MMA(0, 1, At, B1); PG8_BAR; PG8_SCHED;
	s_setprio 1
	v_mfma_f32_16x16x32_bf16 v[60:63], v[148:151], v[186:189], 0
	v_mfma_f32_16x16x32_bf16 v[52:55], v[162:165], v[186:189], 0
	v_mfma_f32_16x16x32_bf16 v[44:47], v[148:151], v[194:197], 0
	v_mfma_f32_16x16x32_bf16 v[36:39], v[162:165], v[194:197], 0
	v_mfma_f32_16x16x32_bf16 v[28:31], v[148:151], v[202:205], 0
	v_mfma_f32_16x16x32_bf16 v[20:23], v[162:165], v[202:205], 0
	v_mfma_f32_16x16x32_bf16 v[12:15], v[148:151], v[210:213], 0
	v_mfma_f32_16x16x32_bf16 v[4:7], v[162:165], v[210:213], 0
	v_mfma_f32_16x16x32_bf16 v[60:63], v[158:161], v[190:193], v[60:63]
	v_mfma_f32_16x16x32_bf16 v[52:55], v[166:169], v[190:193], v[52:55]
	v_mfma_f32_16x16x32_bf16 v[44:47], v[158:161], v[198:201], v[44:47]
	v_mfma_f32_16x16x32_bf16 v[36:39], v[166:169], v[198:201], v[36:39]
	v_mfma_f32_16x16x32_bf16 v[28:31], v[158:161], v[206:209], v[28:31]
	v_mfma_f32_16x16x32_bf16 v[20:23], v[166:169], v[206:209], v[20:23]
	v_mfma_f32_16x16x32_bf16 v[12:15], v[158:161], v[214:217], v[12:15]
	v_mfma_f32_16x16x32_bf16 v[4:7], v[166:169], v[214:217], v[4:7]
	s_setprio 0
	s_setprio 1
	v_mfma_f32_16x16x32_bf16 v[56:59], v[170:173], v[186:189], 0
	v_mfma_f32_16x16x32_bf16 v[48:51], v[178:181], v[186:189], 0
	v_mfma_f32_16x16x32_bf16 v[40:43], v[170:173], v[194:197], 0
	v_mfma_f32_16x16x32_bf16 v[32:35], v[178:181], v[194:197], 0
	v_mfma_f32_16x16x32_bf16 v[24:27], v[170:173], v[202:205], 0
	v_mfma_f32_16x16x32_bf16 v[16:19], v[178:181], v[202:205], 0
	v_mfma_f32_16x16x32_bf16 v[8:11], v[170:173], v[210:213], 0
	v_mfma_f32_16x16x32_bf16 v[0:3], v[178:181], v[210:213], 0
	v_mfma_f32_16x16x32_bf16 v[56:59], v[174:177], v[190:193], v[56:59]
	v_mfma_f32_16x16x32_bf16 v[48:51], v[182:185], v[190:193], v[48:51]
	v_mfma_f32_16x16x32_bf16 v[40:43], v[174:177], v[198:201], v[40:43]
	v_mfma_f32_16x16x32_bf16 v[32:35], v[182:185], v[198:201], v[32:35]
	v_mfma_f32_16x16x32_bf16 v[24:27], v[174:177], v[206:209], v[24:27]
	v_mfma_f32_16x16x32_bf16 v[16:19], v[182:185], v[206:209], v[16:19]
	v_mfma_f32_16x16x32_bf16 v[8:11], v[174:177], v[214:217], v[8:11]
	v_mfma_f32_16x16x32_bf16 v[0:3], v[182:185], v[214:217], v[0:3]
	s_setprio 0
	s_barrier
	s_add_i32 s68, 0, 0x18000
	v_add_u32_e32 v136, s68, v152
	s_add_i32 s80, 0, 0x1c000
	ds_read_b128 v[148:151], v136
	ds_read_b128 v[158:161], v136 offset:1024
	ds_read_b128 v[162:165], v136 offset:2048
	ds_read_b128 v[166:169], v136 offset:3072
	v_add_u32_e32 v136, s80, v152
	ds_read_b128 v[170:173], v136
	ds_read_b128 v[174:177], v136 offset:1024
	ds_read_b128 v[178:181], v136 offset:2048
	ds_read_b128 v[182:185], v136 offset:3072
	s_add_u32 s30, s30, 0x40000
	s_addc_u32 s31, s31, 0
	s_mov_b32 m0, s54
	v_lshl_add_u64 v[228:229], s[30:31], 0, v[134:135]
	ds_read_b128 v[186:189], v155 offset:32768
	ds_read_b128 v[190:193], v155 offset:33792
	ds_read_b128 v[194:197], v155 offset:34816
	ds_read_b128 v[198:201], v155 offset:35840
	ds_read_b128 v[202:205], v155 offset:36864
	ds_read_b128 v[206:209], v155 offset:37888
	ds_read_b128 v[210:213], v155 offset:38912
	ds_read_b128 v[214:217], v155 offset:39936
	global_load_lds_dwordx4 v[228:229], off
	v_lshl_add_u64 v[228:229], s[30:31], 0, v[130:131]
	s_mov_b32 m0, s55
	s_nop 0
	global_load_lds_dwordx4 v[228:229], off
	s_waitcnt vmcnt(8) lgkmcnt(0)
	s_barrier
	s_setprio 1
	v_mfma_f32_16x16x32_bf16 v[124:127], v[148:151], v[186:189], v[124:127]
	v_mfma_f32_16x16x32_bf16 v[116:119], v[162:165], v[186:189], v[116:119]
	v_mfma_f32_16x16x32_bf16 v[108:111], v[148:151], v[194:197], v[108:111]
	v_mfma_f32_16x16x32_bf16 v[100:103], v[162:165], v[194:197], v[100:103]
	v_mfma_f32_16x16x32_bf16 v[92:95], v[148:151], v[202:205], v[92:95]
	v_mfma_f32_16x16x32_bf16 v[84:87], v[162:165], v[202:205], v[84:87]
	v_mfma_f32_16x16x32_bf16 v[76:79], v[148:151], v[210:213], v[76:79]
	v_mfma_f32_16x16x32_bf16 v[68:71], v[162:165], v[210:213], v[68:71]
	v_mfma_f32_16x16x32_bf16 v[124:127], v[158:161], v[190:193], v[124:127]
	v_mfma_f32_16x16x32_bf16 v[116:119], v[166:169], v[190:193], v[116:119]
	v_mfma_f32_16x16x32_bf16 v[108:111], v[158:161], v[198:201], v[108:111]
	v_mfma_f32_16x16x32_bf16 v[100:103], v[166:169], v[198:201], v[100:103]
	v_mfma_f32_16x16x32_bf16 v[92:95], v[158:161], v[206:209], v[92:95]
	v_mfma_f32_16x16x32_bf16 v[84:87], v[166:169], v[206:209], v[84:87]
	v_mfma_f32_16x16x32_bf16 v[76:79], v[158:161], v[214:217], v[76:79]
	v_mfma_f32_16x16x32_bf16 v[68:71], v[166:169], v[214:217], v[68:71]
	s_setprio 0
	s_setprio 1
	v_mfma_f32_16x16x32_bf16 v[120:123], v[170:173], v[186:189], v[120:123]
	v_mfma_f32_16x16x32_bf16 v[112:115], v[178:181], v[186:189], v[112:115]
	v_mfma_f32_16x16x32_bf16 v[104:107], v[170:173], v[194:197], v[104:107]
	v_mfma_f32_16x16x32_bf16 v[96:99], v[178:181], v[194:197], v[96:99]
	v_mfma_f32_16x16x32_bf16 v[88:91], v[170:173], v[202:205], v[88:91]
	v_mfma_f32_16x16x32_bf16 v[80:83], v[178:181], v[202:205], v[80:83]
	v_mfma_f32_16x16x32_bf16 v[72:75], v[170:173], v[210:213], v[72:75]
	v_mfma_f32_16x16x32_bf16 v[64:67], v[178:181], v[210:213], v[64:67]
	v_mfma_f32_16x16x32_bf16 v[120:123], v[174:177], v[190:193], v[120:123]
	v_mfma_f32_16x16x32_bf16 v[112:115], v[182:185], v[190:193], v[112:115]
	v_mfma_f32_16x16x32_bf16 v[104:107], v[174:177], v[198:201], v[104:107]
	v_mfma_f32_16x16x32_bf16 v[96:99], v[182:185], v[198:201], v[96:99]
	v_mfma_f32_16x16x32_bf16 v[88:91], v[174:177], v[206:209], v[88:91]
	v_mfma_f32_16x16x32_bf16 v[80:83], v[182:185], v[206:209], v[80:83]
	v_mfma_f32_16x16x32_bf16 v[72:75], v[174:177], v[214:217], v[72:75]
	v_mfma_f32_16x16x32_bf16 v[64:67], v[182:185], v[214:217], v[64:67]
	s_setprio 0
	s_barrier
; #define PG8_STAGE(bufoff, gbase, voff) do { _Pragma("unroll") for (int _i = 0; _i < 2; ++_i) \
;         __builtin_amdgcn_global_load_lds((const unsigned*)((const char*)(gbase) + (voff)[_i]), (PG8_LAS unsigned*)(lds + (bufoff) + ldsw + _i * 8192), 16, 0, 0); } while (0)
; #define PG8_LDA(dst, b, h) do { _Pragma("unroll") for (int m = 0; m < 4; ++m) _Pragma("unroll") for (int k = 0; k < 2; ++k) dst[m][k] = *(const PG8_LAS bf16x8*)(lds + PG8_SA(b, h) + aoff + m * 2048 + k * 1024); } while (0)
; #define PG8_LDB(dst, b, h) do { _Pragma("unroll") for (int n = 0; n < 2; ++n) _Pragma("unroll") for (int k = 0; k < 2; ++k) dst[n][k] = *(const PG8_LAS bf16x8*)(lds + PG8_SB(b, h) + boff + n * 2048 + k * 1024); } while (0)
; #define PG8_MMA(ai, bj, At, Bt) do { __builtin_amdgcn_s_setprio(1); _Pragma("unroll") for (int m = 0; m < 4; ++m) _Pragma("unroll") for (int n = 0; n < 2; ++n) _Pragma("unroll") for (int k = 0; k < 2; ++k) \
;         acc[ai][bj][m][n] = __builtin_amdgcn_mfma_f32_16x16x32_bf16(Bt[n][k], At[m][k], acc[ai][bj][m][n], 0, 0, 0); __builtin_amdgcn_s_setprio(0); } while (0)
; #define PG8_WAIT_V(n) asm volatile("s_waitcnt vmcnt(" #n ")" ::: "memory")
; #define PG8_WAIT_L(n) asm volatile("s_waitcnt lgkmcnt(" #n ")" ::: "memory")
; #define PG8_BAR __builtin_amdgcn_s_barrier()
; #define PG8_SCHED __builtin_amdgcn_sched_barrier(0)
; template <class Epi, class Sched>
; __device__ __forceinline__ void gemm_phase(PG8_LAS unsigned char* lds, PG8_LAS unsigned char* xl, const Gemm g, const Sched& S, const Epi& E) {
;     ...
;             PG8_LDB(B0, 0, 0); PG8_LDB(B1, 0, 1); PG8_SCHED; PG8_LDA(At, 0, 0); PG8_STAGE(PG8_SA(1, 1), a1 + hsA, voffA);
;             PG8_WAIT_V(8); PG8_WAIT_L(0); PG8_BAR; PG8_MMA(0, 0, At, B0); PG8_MMA(0, 1, At, B1); PG8_BAR; PG8_SCHED;
;     ...
;             PG8_LDA(At, 1, 1); PG8_STAGE(PG8_SB(1, 0), b3, voffB); PG8_STAGE(PG8_SB(1, 1), b3 + hsB, voffB); PG8_STAGE(PG8_SA(1, 0), a3, voffA);
;             PG8_WAIT_V(8); PG8_WAIT_L(0); PG8_BAR; PG8_MMA(1, 0, At, B0); PG8_MMA(1, 1, At, B1); PG8_BAR; PG8_SCHED;
;         }
	s_add_i32 s30, s68, s42
	v_lshl_add_u64 v[218:219], v[218:219], 0, s[12:13]
	s_mov_b32 m0, s30
	ds_read_b128 v[186:189], v155 offset:49152
	ds_read_b128 v[190:193], v155 offset:50176
	ds_read_b128 v[194:197], v155 offset:51200
	ds_read_b128 v[198:201], v155 offset:52224
	ds_read_b128 v[202:205], v155 offset:53248
	ds_read_b128 v[206:209], v155 offset:54272
	ds_read_b128 v[210:213], v155 offset:55296
	ds_read_b128 v[214:217], v155 offset:56320
	global_load_lds_dwordx4 v[218:219], off
	s_add_i32 m0, s30, 0x2000
	s_add_u32 s28, s28, 0x40080
	v_lshl_add_u64 v[218:219], v[222:223], 0, s[12:13]
	s_addc_u32 s29, s29, 0
	s_add_i32 s30, s80, s42
	global_load_lds_dwordx4 v[218:219], off
	v_lshl_add_u64 v[218:219], s[28:29], 0, v[132:133]
	s_mov_b32 m0, s30
	s_nop 0
	global_load_lds_dwordx4 v[218:219], off
	v_lshl_add_u64 v[218:219], s[28:29], 0, v[128:129]
	s_add_i32 m0, s30, 0x2000
	s_nop 0
	global_load_lds_dwordx4 v[218:219], off
	v_lshl_add_u64 v[218:219], v[224:225], 0, s[12:13]
	s_mov_b32 m0, s58
	s_nop 0
	global_load_lds_dwordx4 v[218:219], off
	v_lshl_add_u64 v[218:219], v[226:227], 0, s[12:13]
	s_mov_b32 m0, s59
	s_nop 0
	global_load_lds_dwordx4 v[218:219], off
	s_waitcnt vmcnt(8) lgkmcnt(0)
	s_barrier
	s_setprio 1
	v_mfma_f32_16x16x32_bf16 v[60:63], v[148:151], v[186:189], v[60:63]
	v_mfma_f32_16x16x32_bf16 v[52:55], v[162:165], v[186:189], v[52:55]
	v_mfma_f32_16x16x32_bf16 v[44:47], v[148:151], v[194:197], v[44:47]
	v_mfma_f32_16x16x32_bf16 v[36:39], v[162:165], v[194:197], v[36:39]
	v_mfma_f32_16x16x32_bf16 v[28:31], v[148:151], v[202:205], v[28:31]
	v_mfma_f32_16x16x32_bf16 v[20:23], v[162:165], v[202:205], v[20:23]
	v_mfma_f32_16x16x32_bf16 v[12:15], v[148:151], v[210:213], v[12:15]
	v_mfma_f32_16x16x32_bf16 v[4:7], v[162:165], v[210:213], v[4:7]
	v_mfma_f32_16x16x32_bf16 v[60:63], v[158:161], v[190:193], v[60:63]
	v_mfma_f32_16x16x32_bf16 v[52:55], v[166:169], v[190:193], v[52:55]
	v_mfma_f32_16x16x32_bf16 v[44:47], v[158:161], v[198:201], v[44:47]
	v_mfma_f32_16x16x32_bf16 v[36:39], v[166:169], v[198:201], v[36:39]
	v_mfma_f32_16x16x32_bf16 v[28:31], v[158:161], v[206:209], v[28:31]
	v_mfma_f32_16x16x32_bf16 v[20:23], v[166:169], v[206:209], v[20:23]
	v_mfma_f32_16x16x32_bf16 v[12:15], v[158:161], v[214:217], v[12:15]
	v_mfma_f32_16x16x32_bf16 v[4:7], v[166:169], v[214:217], v[4:7]
	s_setprio 0
	s_setprio 1
	v_mfma_f32_16x16x32_bf16 v[56:59], v[170:173], v[186:189], v[56:59]
	s_add_i32 s79, s79, 2
	v_mfma_f32_16x16x32_bf16 v[48:51], v[178:181], v[186:189], v[48:51]
	s_add_u32 s77, s77, 0x100
	v_mfma_f32_16x16x32_bf16 v[40:43], v[170:173], v[194:197], v[40:43]
	s_addc_u32 s78, s78, 0
	v_mfma_f32_16x16x32_bf16 v[32:35], v[178:181], v[194:197], v[32:35]
	s_add_u32 s26, s26, 0x100
	v_mfma_f32_16x16x32_bf16 v[24:27], v[170:173], v[202:205], v[24:27]
	s_addc_u32 s27, s27, 0
	v_mfma_f32_16x16x32_bf16 v[16:19], v[178:181], v[202:205], v[16:19]
	s_cmp_gt_u32 s79, 13
	v_mfma_f32_16x16x32_bf16 v[8:11], v[170:173], v[210:213], v[8:11]
	v_mfma_f32_16x16x32_bf16 v[0:3], v[178:181], v[210:213], v[0:3]
	v_mfma_f32_16x16x32_bf16 v[56:59], v[174:177], v[190:193], v[56:59]
	v_mfma_f32_16x16x32_bf16 v[48:51], v[182:185], v[190:193], v[48:51]
	v_mfma_f32_16x16x32_bf16 v[40:43], v[174:177], v[198:201], v[40:43]
	v_mfma_f32_16x16x32_bf16 v[32:35], v[182:185], v[198:201], v[32:35]
	v_mfma_f32_16x16x32_bf16 v[24:27], v[174:177], v[206:209], v[24:27]
	v_mfma_f32_16x16x32_bf16 v[16:19], v[182:185], v[206:209], v[16:19]
	v_mfma_f32_16x16x32_bf16 v[8:11], v[174:177], v[214:217], v[8:11]
	v_mfma_f32_16x16x32_bf16 v[0:3], v[182:185], v[214:217], v[0:3]
	s_setprio 0
	s_barrier
	s_cbranch_scc1 .Lpeel_after_P1
.LBB0_102:
	ds_read_b128 v[148:151], v153
	ds_read_b128 v[158:161], v153 offset:1024
	ds_read_b128 v[162:165], v153 offset:2048
	ds_read_b128 v[166:169], v153 offset:3072
	ds_read_b128 v[170:173], v154
	ds_read_b128 v[174:177], v154 offset:1024
	ds_read_b128 v[178:181], v154 offset:2048
	ds_read_b128 v[182:185], v154 offset:3072
	s_add_u32 s28, s26, 0xfffc0080
	s_addc_u32 s29, s27, -1
	s_cmp_eq_u32 s79, 12
	s_cselect_b32 s31, s73, s29
	s_cselect_b32 s30, s74, s28
	s_cselect_b32 s29, s75, s78
	s_cselect_b32 s28, s76, s77
	v_lshl_add_u64 v[218:219], s[26:27], 0, v[142:143]
	s_add_i32 m0, s52, 0xc000
	ds_read_b128 v[186:189], v155
	ds_read_b128 v[190:193], v155 offset:1024
	ds_read_b128 v[194:197], v155 offset:2048
	ds_read_b128 v[198:201], v155 offset:3072
	ds_read_b128 v[202:205], v155 offset:4096
	ds_read_b128 v[206:209], v155 offset:5120
	ds_read_b128 v[210:213], v155 offset:6144
	ds_read_b128 v[214:217], v155 offset:7168
	global_load_lds_dwordx4 v[218:219], off
	v_lshl_add_u64 v[218:219], s[26:27], 0, v[140:141]
	s_add_i32 m0, s52, 0xe000
	s_nop 0
	global_load_lds_dwordx4 v[218:219], off
	s_waitcnt vmcnt(8) lgkmcnt(0)
	s_barrier
; #define PG8_STAGE(bufoff, gbase, voff) do { _Pragma("unroll") for (int _i = 0; _i < 2; ++_i) \
;         __builtin_amdgcn_global_load_lds((const unsigned*)((const char*)(gbase) + (voff)[_i]), (PG8_LAS unsigned*)(lds + (bufoff) + ldsw + _i * 8192), 16, 0, 0); } while (0)
; #define PG8_LDA(dst, b, h) do { _Pragma("unroll") for (int m = 0; m < 4; ++m) _Pragma("unroll") for (int k = 0; k < 2; ++k) dst[m][k] = *(const PG8_LAS bf16x8*)(lds + PG8_SA(b, h) + aoff + m * 2048 + k * 1024); } while (0)
; #define PG8_MMA(ai, bj, At, Bt) do { __builtin_amdgcn_s_setprio(1); _Pragma("unroll") for (int m = 0; m < 4; ++m) _Pragma("unroll") for (int n = 0; n < 2; ++n) _Pragma("unroll") for (int k = 0; k < 2; ++k) \
;         acc[ai][bj][m][n] = __builtin_amdgcn_mfma_f32_16x16x32_bf16(Bt[n][k], At[m][k], acc[ai][bj][m][n], 0, 0, 0); __builtin_amdgcn_s_setprio(0); } while (0)
; #define PG8_WAIT_V(n) asm volatile("s_waitcnt vmcnt(" #n ")" ::: "memory")
; #define PG8_WAIT_L(n) asm volatile("s_waitcnt lgkmcnt(" #n ")" ::: "memory")
; #define PG8_BAR __builtin_amdgcn_s_barrier()
; #define PG8_SCHED __builtin_amdgcn_sched_barrier(0)
; template <class Epi, class Sched>
; __device__ __forceinline__ void gemm_phase(PG8_LAS unsigned char* lds, PG8_LAS unsigned char* xl, const Gemm g, const Sched& S, const Epi& E) {
;     ...
;             PG8_WAIT_V(8); PG8_WAIT_L(0); PG8_BAR; PG8_MMA(0, 0, At, B0); PG8_MMA(0, 1, At, B1); PG8_BAR; PG8_SCHED;
;             PG8_LDA(At, 0, 1); PG8_STAGE(PG8_SB(0, 0), b2, voffB); PG8_STAGE(PG8_SB(0, 1), b2 + hsB, voffB); PG8_STAGE(PG8_SA(0, 0), a2, voffA);
;             PG8_WAIT_V(8); PG8_WAIT_L(0); PG8_BAR; PG8_MMA(1, 0, At, B0); PG8_MMA(1, 1, At, B1); PG8_BAR; PG8_SCHED;
	s_setprio 1
	v_mfma_f32_16x16x32_bf16 v[124:127], v[148:151], v[186:189], v[124:127]
	v_mfma_f32_16x16x32_bf16 v[116:119], v[162:165], v[186:189], v[116:119]
	v_mfma_f32_16x16x32_bf16 v[108:111], v[148:151], v[194:197], v[108:111]
	v_mfma_f32_16x16x32_bf16 v[100:103], v[162:165], v[194:197], v[100:103]
	v_mfma_f32_16x16x32_bf16 v[92:95], v[148:151], v[202:205], v[92:95]
	v_mfma_f32_16x16x32_bf16 v[84:87], v[162:165], v[202:205], v[84:87]
	v_mfma_f32_16x16x32_bf16 v[76:79], v[148:151], v[210:213], v[76:79]
	v_mfma_f32_16x16x32_bf16 v[68:71], v[162:165], v[210:213], v[68:71]
	v_mfma_f32_16x16x32_bf16 v[124:127], v[158:161], v[190:193], v[124:127]
	v_mfma_f32_16x16x32_bf16 v[116:119], v[166:169], v[190:193], v[116:119]
	v_mfma_f32_16x16x32_bf16 v[108:111], v[158:161], v[198:201], v[108:111]
	v_mfma_f32_16x16x32_bf16 v[100:103], v[166:169], v[198:201], v[100:103]
	v_mfma_f32_16x16x32_bf16 v[92:95], v[158:161], v[206:209], v[92:95]
	v_mfma_f32_16x16x32_bf16 v[84:87], v[166:169], v[206:209], v[84:87]
	v_mfma_f32_16x16x32_bf16 v[76:79], v[158:161], v[214:217], v[76:79]
	v_mfma_f32_16x16x32_bf16 v[68:71], v[166:169], v[214:217], v[68:71]
	s_setprio 0
	s_setprio 1
	v_mfma_f32_16x16x32_bf16 v[120:123], v[170:173], v[186:189], v[120:123]
	v_mfma_f32_16x16x32_bf16 v[112:115], v[178:181], v[186:189], v[112:115]
	v_mfma_f32_16x16x32_bf16 v[104:107], v[170:173], v[194:197], v[104:107]
	v_mfma_f32_16x16x32_bf16 v[96:99], v[178:181], v[194:197], v[96:99]
	v_mfma_f32_16x16x32_bf16 v[88:91], v[170:173], v[202:205], v[88:91]
	v_mfma_f32_16x16x32_bf16 v[80:83], v[178:181], v[202:205], v[80:83]
	v_mfma_f32_16x16x32_bf16 v[72:75], v[170:173], v[210:213], v[72:75]
	v_mfma_f32_16x16x32_bf16 v[64:67], v[178:181], v[210:213], v[64:67]
	v_mfma_f32_16x16x32_bf16 v[120:123], v[174:177], v[190:193], v[120:123]
	v_mfma_f32_16x16x32_bf16 v[112:115], v[182:185], v[190:193], v[112:115]
	v_mfma_f32_16x16x32_bf16 v[104:107], v[174:177], v[198:201], v[104:107]
	v_mfma_f32_16x16x32_bf16 v[96:99], v[182:185], v[198:201], v[96:99]
	v_mfma_f32_16x16x32_bf16 v[88:91], v[174:177], v[206:209], v[88:91]
	v_mfma_f32_16x16x32_bf16 v[80:83], v[182:185], v[206:209], v[80:83]
	v_mfma_f32_16x16x32_bf16 v[72:75], v[174:177], v[214:217], v[72:75]
	v_mfma_f32_16x16x32_bf16 v[64:67], v[182:185], v[214:217], v[64:67]
	s_setprio 0
	s_barrier
	s_add_i32 s68, s60, s42
	v_lshl_add_u64 v[218:219], s[28:29], 0, v[132:133]
	s_mov_b32 m0, s68
	ds_read_b128 v[186:189], v155 offset:16384
	ds_read_b128 v[190:193], v155 offset:17408
	ds_read_b128 v[194:197], v155 offset:18432
	ds_read_b128 v[198:201], v155 offset:19456
	ds_read_b128 v[202:205], v155 offset:20480
	ds_read_b128 v[206:209], v155 offset:21504
	ds_read_b128 v[210:213], v155 offset:22528
	ds_read_b128 v[214:217], v155 offset:23552
	global_load_lds_dwordx4 v[218:219], off
	s_add_i32 m0, s68, 0x2000
	s_add_u32 s80, s28, 0x40000
	v_lshl_add_u64 v[222:223], s[28:29], 0, v[128:129]
	s_addc_u32 s81, s29, 0
	s_add_i32 s68, s61, s42
	global_load_lds_dwordx4 v[222:223], off
	v_lshl_add_u64 v[224:225], s[80:81], 0, v[132:133]
	s_mov_b32 m0, s68
	v_lshl_add_u64 v[226:227], s[30:31], 0, v[130:131]
	global_load_lds_dwordx4 v[224:225], off
	v_lshl_add_u64 v[224:225], s[80:81], 0, v[128:129]
	s_add_i32 m0, s68, 0x2000
	s_nop 0
	global_load_lds_dwordx4 v[224:225], off
	v_lshl_add_u64 v[224:225], s[30:31], 0, v[134:135]
	s_mov_b32 m0, s52
	s_nop 0
	global_load_lds_dwordx4 v[224:225], off
	s_mov_b32 m0, s53
	s_nop 0
	global_load_lds_dwordx4 v[226:227], off
	s_waitcnt vmcnt(8) lgkmcnt(0)
	s_barrier
	s_setprio 1
	v_mfma_f32_16x16x32_bf16 v[60:63], v[148:151], v[186:189], v[60:63]
	v_mfma_f32_16x16x32_bf16 v[52:55], v[162:165], v[186:189], v[52:55]
	v_mfma_f32_16x16x32_bf16 v[44:47], v[148:151], v[194:197], v[44:47]
	v_mfma_f32_16x16x32_bf16 v[36:39], v[162:165], v[194:197], v[36:39]
	v_mfma_f32_16x16x32_bf16 v[28:31], v[148:151], v[202:205], v[28:31]
	v_mfma_f32_16x16x32_bf16 v[20:23], v[162:165], v[202:205], v[20:23]
	v_mfma_f32_16x16x32_bf16 v[12:15], v[148:151], v[210:213], v[12:15]
	v_mfma_f32_16x16x32_bf16 v[4:7], v[162:165], v[210:213], v[4:7]
	v_mfma_f32_16x16x32_bf16 v[60:63], v[158:161], v[190:193], v[60:63]
	v_mfma_f32_16x16x32_bf16 v[52:55], v[166:169], v[190:193], v[52:55]
	v_mfma_f32_16x16x32_bf16 v[44:47], v[158:161], v[198:201], v[44:47]
	v_mfma_f32_16x16x32_bf16 v[36:39], v[166:169], v[198:201], v[36:39]
	v_mfma_f32_16x16x32_bf16 v[28:31], v[158:161], v[206:209], v[28:31]
	v_mfma_f32_16x16x32_bf16 v[20:23], v[166:169], v[206:209], v[20:23]
	v_mfma_f32_16x16x32_bf16 v[12:15], v[158:161], v[214:217], v[12:15]
	v_mfma_f32_16x16x32_bf16 v[4:7], v[166:169], v[214:217], v[4:7]
	s_setprio 0
	s_setprio 1
	v_mfma_f32_16x16x32_bf16 v[56:59], v[170:173], v[186:189], v[56:59]
	v_mfma_f32_16x16x32_bf16 v[48:51], v[178:181], v[186:189], v[48:51]
	v_mfma_f32_16x16x32_bf16 v[40:43], v[170:173], v[194:197], v[40:43]
	v_mfma_f32_16x16x32_bf16 v[32:35], v[178:181], v[194:197], v[32:35]
	v_mfma_f32_16x16x32_bf16 v[24:27], v[170:173], v[202:205], v[24:27]
	v_mfma_f32_16x16x32_bf16 v[16:19], v[178:181], v[202:205], v[16:19]
	v_mfma_f32_16x16x32_bf16 v[8:11], v[170:173], v[210:213], v[8:11]
	v_mfma_f32_16x16x32_bf16 v[0:3], v[178:181], v[210:213], v[0:3]
	v_mfma_f32_16x16x32_bf16 v[56:59], v[174:177], v[190:193], v[56:59]
	v_mfma_f32_16x16x32_bf16 v[48:51], v[182:185], v[190:193], v[48:51]
	v_mfma_f32_16x16x32_bf16 v[40:43], v[174:177], v[198:201], v[40:43]
	v_mfma_f32_16x16x32_bf16 v[32:35], v[182:185], v[198:201], v[32:35]
	v_mfma_f32_16x16x32_bf16 v[24:27], v[174:177], v[206:209], v[24:27]
	v_mfma_f32_16x16x32_bf16 v[16:19], v[182:185], v[206:209], v[16:19]
	v_mfma_f32_16x16x32_bf16 v[8:11], v[174:177], v[214:217], v[8:11]
	v_mfma_f32_16x16x32_bf16 v[0:3], v[182:185], v[214:217], v[0:3]
	s_setprio 0
	s_barrier
; #define PG8_STAGE(bufoff, gbase, voff) do { _Pragma("unroll") for (int _i = 0; _i < 2; ++_i) \
;         __builtin_amdgcn_global_load_lds((const unsigned*)((const char*)(gbase) + (voff)[_i]), (PG8_LAS unsigned*)(lds + (bufoff) + ldsw + _i * 8192), 16, 0, 0); } while (0)
; #define PG8_LDA(dst, b, h) do { _Pragma("unroll") for (int m = 0; m < 4; ++m) _Pragma("unroll") for (int k = 0; k < 2; ++k) dst[m][k] = *(const PG8_LAS bf16x8*)(lds + PG8_SA(b, h) + aoff + m * 2048 + k * 1024); } while (0)
; #define PG8_LDB(dst, b, h) do { _Pragma("unroll") for (int n = 0; n < 2; ++n) _Pragma("unroll") for (int k = 0; k < 2; ++k) dst[n][k] = *(const PG8_LAS bf16x8*)(lds + PG8_SB(b, h) + boff + n * 2048 + k * 1024); } while (0)
; #define PG8_MMA(ai, bj, At, Bt) do { __builtin_amdgcn_s_setprio(1); _Pragma("unroll") for (int m = 0; m < 4; ++m) _Pragma("unroll") for (int n = 0; n < 2; ++n) _Pragma("unroll") for (int k = 0; k < 2; ++k) \
;         acc[ai][bj][m][n] = __builtin_amdgcn_mfma_f32_16x16x32_bf16(Bt[n][k], At[m][k], acc[ai][bj][m][n], 0, 0, 0); __builtin_amdgcn_s_setprio(0); } while (0)
; #define PG8_WAIT_V(n) asm volatile("s_waitcnt vmcnt(" #n ")" ::: "memory")
; #define PG8_WAIT_L(n) asm volatile("s_waitcnt lgkmcnt(" #n ")" ::: "memory")
; #define PG8_BAR __builtin_amdgcn_s_barrier()
; #define PG8_SCHED __builtin_amdgcn_sched_barrier(0)
; template <class Epi, class Sched>
; __device__ __forceinline__ void gemm_phase(PG8_LAS unsigned char* lds, PG8_LAS unsigned char* xl, const Gemm g, const Sched& S, const Epi& E) {
;     ...
;             PG8_LDB(B0, 1, 0); PG8_LDB(B1, 1, 1); PG8_SCHED; PG8_LDA(At, 1, 0); PG8_STAGE(PG8_SA(0, 1), a2 + hsA, voffA);
;             PG8_WAIT_V(8); PG8_WAIT_L(0); PG8_BAR; PG8_MMA(0, 0, At, B0); PG8_MMA(0, 1, At, B1); PG8_BAR; PG8_SCHED;
	s_add_i32 s68, 0, 0x18000
	v_add_u32_e32 v136, s68, v152
	s_add_i32 s80, 0, 0x1c000
	ds_read_b128 v[148:151], v136
	ds_read_b128 v[158:161], v136 offset:1024
	ds_read_b128 v[162:165], v136 offset:2048
	ds_read_b128 v[166:169], v136 offset:3072
	v_add_u32_e32 v136, s80, v152
	ds_read_b128 v[170:173], v136
	ds_read_b128 v[174:177], v136 offset:1024
	ds_read_b128 v[178:181], v136 offset:2048
	ds_read_b128 v[182:185], v136 offset:3072
	s_add_u32 s30, s30, 0x40000
	s_addc_u32 s31, s31, 0
	s_mov_b32 m0, s54
	v_lshl_add_u64 v[228:229], s[30:31], 0, v[134:135]
	ds_read_b128 v[186:189], v155 offset:32768
	ds_read_b128 v[190:193], v155 offset:33792
	ds_read_b128 v[194:197], v155 offset:34816
	ds_read_b128 v[198:201], v155 offset:35840
	ds_read_b128 v[202:205], v155 offset:36864
	ds_read_b128 v[206:209], v155 offset:37888
	ds_read_b128 v[210:213], v155 offset:38912
	ds_read_b128 v[214:217], v155 offset:39936
	global_load_lds_dwordx4 v[228:229], off
	v_lshl_add_u64 v[228:229], s[30:31], 0, v[130:131]
	s_mov_b32 m0, s55
	s_nop 0
	global_load_lds_dwordx4 v[228:229], off
	s_waitcnt vmcnt(8) lgkmcnt(0)
	s_barrier
	s_setprio 1
	v_mfma_f32_16x16x32_bf16 v[124:127], v[148:151], v[186:189], v[124:127]
	v_mfma_f32_16x16x32_bf16 v[116:119], v[162:165], v[186:189], v[116:119]
	v_mfma_f32_16x16x32_bf16 v[108:111], v[148:151], v[194:197], v[108:111]
	v_mfma_f32_16x16x32_bf16 v[100:103], v[162:165], v[194:197], v[100:103]
	v_mfma_f32_16x16x32_bf16 v[92:95], v[148:151], v[202:205], v[92:95]
	v_mfma_f32_16x16x32_bf16 v[84:87], v[162:165], v[202:205], v[84:87]
	v_mfma_f32_16x16x32_bf16 v[76:79], v[148:151], v[210:213], v[76:79]
	v_mfma_f32_16x16x32_bf16 v[68:71], v[162:165], v[210:213], v[68:71]
	v_mfma_f32_16x16x32_bf16 v[124:127], v[158:161], v[190:193], v[124:127]
	v_mfma_f32_16x16x32_bf16 v[116:119], v[166:169], v[190:193], v[116:119]
	v_mfma_f32_16x16x32_bf16 v[108:111], v[158:161], v[198:201], v[108:111]
	v_mfma_f32_16x16x32_bf16 v[100:103], v[166:169], v[198:201], v[100:103]
	v_mfma_f32_16x16x32_bf16 v[92:95], v[158:161], v[206:209], v[92:95]
	v_mfma_f32_16x16x32_bf16 v[84:87], v[166:169], v[206:209], v[84:87]
	v_mfma_f32_16x16x32_bf16 v[76:79], v[158:161], v[214:217], v[76:79]
	v_mfma_f32_16x16x32_bf16 v[68:71], v[166:169], v[214:217], v[68:71]
	s_setprio 0
	s_setprio 1
	v_mfma_f32_16x16x32_bf16 v[120:123], v[170:173], v[186:189], v[120:123]
	v_mfma_f32_16x16x32_bf16 v[112:115], v[178:181], v[186:189], v[112:115]
	v_mfma_f32_16x16x32_bf16 v[104:107], v[170:173], v[194:197], v[104:107]
	v_mfma_f32_16x16x32_bf16 v[96:99], v[178:181], v[194:197], v[96:99]
	v_mfma_f32_16x16x32_bf16 v[88:91], v[170:173], v[202:205], v[88:91]
	v_mfma_f32_16x16x32_bf16 v[80:83], v[178:181], v[202:205], v[80:83]
	v_mfma_f32_16x16x32_bf16 v[72:75], v[170:173], v[210:213], v[72:75]
	v_mfma_f32_16x16x32_bf16 v[64:67], v[178:181], v[210:213], v[64:67]
	v_mfma_f32_16x16x32_bf16 v[120:123], v[174:177], v[190:193], v[120:123]
	v_mfma_f32_16x16x32_bf16 v[112:115], v[182:185], v[190:193], v[112:115]
	v_mfma_f32_16x16x32_bf16 v[104:107], v[174:177], v[198:201], v[104:107]
	v_mfma_f32_16x16x32_bf16 v[96:99], v[182:185], v[198:201], v[96:99]
	v_mfma_f32_16x16x32_bf16 v[88:91], v[174:177], v[206:209], v[88:91]
	v_mfma_f32_16x16x32_bf16 v[80:83], v[182:185], v[206:209], v[80:83]
	v_mfma_f32_16x16x32_bf16 v[72:75], v[174:177], v[214:217], v[72:75]
	v_mfma_f32_16x16x32_bf16 v[64:67], v[182:185], v[214:217], v[64:67]
	s_setprio 0
	s_barrier
; #define PG8_STAGE(bufoff, gbase, voff) do { _Pragma("unroll") for (int _i = 0; _i < 2; ++_i) \
;         __builtin_amdgcn_global_load_lds((const unsigned*)((const char*)(gbase) + (voff)[_i]), (PG8_LAS unsigned*)(lds + (bufoff) + ldsw + _i * 8192), 16, 0, 0); } while (0)
; #define PG8_LDA(dst, b, h) do { _Pragma("unroll") for (int m = 0; m < 4; ++m) _Pragma("unroll") for (int k = 0; k < 2; ++k) dst[m][k] = *(const PG8_LAS bf16x8*)(lds + PG8_SA(b, h) + aoff + m * 2048 + k * 1024); } while (0)
; #define PG8_MMA(ai, bj, At, Bt) do { __builtin_amdgcn_s_setprio(1); _Pragma("unroll") for (int m = 0; m < 4; ++m) _Pragma("unroll") for (int n = 0; n < 2; ++n) _Pragma("unroll") for (int k = 0; k < 2; ++k) \
;         acc[ai][bj][m][n] = __builtin_amdgcn_mfma_f32_16x16x32_bf16(Bt[n][k], At[m][k], acc[ai][bj][m][n], 0, 0, 0); __builtin_amdgcn_s_setprio(0); } while (0)
; #define PG8_WAIT_V(n) asm volatile("s_waitcnt vmcnt(" #n ")" ::: "memory")
; #define PG8_WAIT_L(n) asm volatile("s_waitcnt lgkmcnt(" #n ")" ::: "memory")
; #define PG8_BAR __builtin_amdgcn_s_barrier()
; #define PG8_SCHED __builtin_amdgcn_sched_barrier(0)
; template <class Epi, class Sched>
; __device__ __forceinline__ void gemm_phase(PG8_LAS unsigned char* lds, PG8_LAS unsigned char* xl, const Gemm g, const Sched& S, const Epi& E) {
;     ...
;             PG8_LDA(At, 1, 1); PG8_STAGE(PG8_SB(1, 0), b3, voffB); PG8_STAGE(PG8_SB(1, 1), b3 + hsB, voffB); PG8_STAGE(PG8_SA(1, 0), a3, voffA);
;             PG8_WAIT_V(8); PG8_WAIT_L(0); PG8_BAR; PG8_MMA(1, 0, At, B0); PG8_MMA(1, 1, At, B1); PG8_BAR; PG8_SCHED;
;         }
	s_add_i32 s30, s68, s42
	v_lshl_add_u64 v[218:219], v[218:219], 0, s[12:13]
	s_mov_b32 m0, s30
	ds_read_b128 v[186:189], v155 offset:49152
	ds_read_b128 v[190:193], v155 offset:50176
	ds_read_b128 v[194:197], v155 offset:51200
	ds_read_b128 v[198:201], v155 offset:52224
	ds_read_b128 v[202:205], v155 offset:53248
	ds_read_b128 v[206:209], v155 offset:54272
	ds_read_b128 v[210:213], v155 offset:55296
	ds_read_b128 v[214:217], v155 offset:56320
	global_load_lds_dwordx4 v[218:219], off
	s_add_i32 m0, s30, 0x2000
	s_add_u32 s28, s28, 0x40080
	v_lshl_add_u64 v[218:219], v[222:223], 0, s[12:13]
	s_addc_u32 s29, s29, 0
	s_add_i32 s30, s80, s42
	global_load_lds_dwordx4 v[218:219], off
	v_lshl_add_u64 v[218:219], s[28:29], 0, v[132:133]
	s_mov_b32 m0, s30
	s_nop 0
	global_load_lds_dwordx4 v[218:219], off
	v_lshl_add_u64 v[218:219], s[28:29], 0, v[128:129]
	s_add_i32 m0, s30, 0x2000
	s_nop 0
	global_load_lds_dwordx4 v[218:219], off
	v_lshl_add_u64 v[218:219], v[224:225], 0, s[12:13]
	s_mov_b32 m0, s58
	s_nop 0
	global_load_lds_dwordx4 v[218:219], off
	v_lshl_add_u64 v[218:219], v[226:227], 0, s[12:13]
	s_mov_b32 m0, s59
	s_nop 0
	global_load_lds_dwordx4 v[218:219], off
	s_waitcnt vmcnt(8) lgkmcnt(0)
	s_barrier
	s_setprio 1
	v_mfma_f32_16x16x32_bf16 v[60:63], v[148:151], v[186:189], v[60:63]
	v_mfma_f32_16x16x32_bf16 v[52:55], v[162:165], v[186:189], v[52:55]
	v_mfma_f32_16x16x32_bf16 v[44:47], v[148:151], v[194:197], v[44:47]
	v_mfma_f32_16x16x32_bf16 v[36:39], v[162:165], v[194:197], v[36:39]
	v_mfma_f32_16x16x32_bf16 v[28:31], v[148:151], v[202:205], v[28:31]
	v_mfma_f32_16x16x32_bf16 v[20:23], v[162:165], v[202:205], v[20:23]
	v_mfma_f32_16x16x32_bf16 v[12:15], v[148:151], v[210:213], v[12:15]
	v_mfma_f32_16x16x32_bf16 v[4:7], v[162:165], v[210:213], v[4:7]
	v_mfma_f32_16x16x32_bf16 v[60:63], v[158:161], v[190:193], v[60:63]
	v_mfma_f32_16x16x32_bf16 v[52:55], v[166:169], v[190:193], v[52:55]
	v_mfma_f32_16x16x32_bf16 v[44:47], v[158:161], v[198:201], v[44:47]
	v_mfma_f32_16x16x32_bf16 v[36:39], v[166:169], v[198:201], v[36:39]
	v_mfma_f32_16x16x32_bf16 v[28:31], v[158:161], v[206:209], v[28:31]
	v_mfma_f32_16x16x32_bf16 v[20:23], v[166:169], v[206:209], v[20:23]
	v_mfma_f32_16x16x32_bf16 v[12:15], v[158:161], v[214:217], v[12:15]
	v_mfma_f32_16x16x32_bf16 v[4:7], v[166:169], v[214:217], v[4:7]
	s_setprio 0
	s_setprio 1
	v_mfma_f32_16x16x32_bf16 v[56:59], v[170:173], v[186:189], v[56:59]
	s_add_i32 s79, s79, 2
	v_mfma_f32_16x16x32_bf16 v[48:51], v[178:181], v[186:189], v[48:51]
	s_add_u32 s77, s77, 0x100
	v_mfma_f32_16x16x32_bf16 v[40:43], v[170:173], v[194:197], v[40:43]
	s_addc_u32 s78, s78, 0
	v_mfma_f32_16x16x32_bf16 v[32:35], v[178:181], v[194:197], v[32:35]
	s_add_u32 s26, s26, 0x100
	v_mfma_f32_16x16x32_bf16 v[24:27], v[170:173], v[202:205], v[24:27]
	s_addc_u32 s27, s27, 0
	v_mfma_f32_16x16x32_bf16 v[16:19], v[178:181], v[202:205], v[16:19]
	s_cmp_gt_u32 s79, 13
	v_mfma_f32_16x16x32_bf16 v[8:11], v[170:173], v[210:213], v[8:11]
	v_mfma_f32_16x16x32_bf16 v[0:3], v[178:181], v[210:213], v[0:3]
	v_mfma_f32_16x16x32_bf16 v[56:59], v[174:177], v[190:193], v[56:59]
	v_mfma_f32_16x16x32_bf16 v[48:51], v[182:185], v[190:193], v[48:51]
	v_mfma_f32_16x16x32_bf16 v[40:43], v[174:177], v[198:201], v[40:43]
	v_mfma_f32_16x16x32_bf16 v[32:35], v[182:185], v[198:201], v[32:35]
	v_mfma_f32_16x16x32_bf16 v[24:27], v[174:177], v[206:209], v[24:27]
	v_mfma_f32_16x16x32_bf16 v[16:19], v[182:185], v[206:209], v[16:19]
	v_mfma_f32_16x16x32_bf16 v[8:11], v[174:177], v[214:217], v[8:11]
	v_mfma_f32_16x16x32_bf16 v[0:3], v[182:185], v[214:217], v[0:3]
	s_setprio 0
	s_barrier
	s_cbranch_scc0 .LBB0_102

; #define PG8_STAGE(bufoff, gbase, voff) do { _Pragma("unroll") for (int _i = 0; _i < 2; ++_i) \
;         __builtin_amdgcn_global_load_lds((const unsigned*)((const char*)(gbase) + (voff)[_i]), (PG8_LAS unsigned*)(lds + (bufoff) + ldsw + _i * 8192), 16, 0, 0); } while (0)
; #define PG8_LDA(dst, b, h) do { _Pragma("unroll") for (int m = 0; m < 4; ++m) _Pragma("unroll") for (int k = 0; k < 2; ++k) dst[m][k] = *(const PG8_LAS bf16x8*)(lds + PG8_SA(b, h) + aoff + m * 2048 + k * 1024); } while (0)
; #define PG8_LDB(dst, b, h) do { _Pragma("unroll") for (int n = 0; n < 2; ++n) _Pragma("unroll") for (int k = 0; k < 2; ++k) dst[n][k] = *(const PG8_LAS bf16x8*)(lds + PG8_SB(b, h) + boff + n * 2048 + k * 1024); } while (0)
; #define PG8_MMA(ai, bj, At, Bt) do { __builtin_amdgcn_s_setprio(1); _Pragma("unroll") for (int m = 0; m < 4; ++m) _Pragma("unroll") for (int n = 0; n < 2; ++n) _Pragma("unroll") for (int k = 0; k < 2; ++k) \
;         acc[ai][bj][m][n] = __builtin_amdgcn_mfma_f32_16x16x32_bf16(Bt[n][k], At[m][k], acc[ai][bj][m][n], 0, 0, 0); __builtin_amdgcn_s_setprio(0); } while (0)
; #define PG8_WAIT_V(n) asm volatile("s_waitcnt vmcnt(" #n ")" ::: "memory")
; #define PG8_BAR __builtin_amdgcn_s_barrier()
; template <class Epi, class Sched>
; __device__ __forceinline__ void gemm_phase(PG8_LAS unsigned char* lds, PG8_LAS unsigned char* xl, const Gemm g, const Sched& S, const Epi& E) {
;     ...
;     for (;;) {
;         const bool has_next = S.next(ui + 1, nxt);
;         const char* nA = has_next ? (const char*)g.A + nxt.aoff : cA; const char* nB = has_next ? (const char*)g.Bt + nxt.boff : cB;
; #pragma unroll 1
;         for (int t = 0; t < nt; t += 2) {
;             const bool last = (t == nt - 2);
;             const char* a1 = cA + (size_t)(t + 1) * kstep;
;             const char* a2 = last ? nA : cA + (size_t)(t + 2) * kstep; const char* b2 = last ? nB : cB + (size_t)(t + 2) * kstep;
;             const char* a3 = a2 + kstep; const char* b3 = b2 + kstep;
;             PG8_LDB(B0, 0, 0); PG8_LDB(B1, 0, 1); PG8_SCHED; PG8_LDA(At, 0, 0); PG8_STAGE(PG8_SA(1, 1), a1 + hsA, voffA);
;             PG8_WAIT_V(8); PG8_WAIT_L(0); PG8_BAR; PG8_MMA(0, 0, At, B0); PG8_MMA(0, 1, At, B1); PG8_BAR; PG8_SCHED;
;             PG8_LDA(At, 0, 1); PG8_STAGE(PG8_SB(0, 0), b2, voffB); PG8_STAGE(PG8_SB(0, 1), b2 + hsB, voffB); PG8_STAGE(PG8_SA(0, 0), a2, voffA);
.LBB0_129:
	s_add_u32 s18, s35, s14
	s_addc_u32 s19, s36, s15
	s_and_b64 s[20:21], s[4:5], exec
	s_cselect_b32 s70, s19, s29
	s_cselect_b32 s72, s18, s28
	s_add_u32 s20, s37, s16
	s_addc_u32 s21, s42, s17
	s_and_b64 s[30:31], s[4:5], exec
	s_cselect_b32 s73, s21, s27
	s_cselect_b32 s74, s20, s26
	s_add_u32 s75, s26, 0x100
	s_addc_u32 s76, s27, 0
	s_add_u32 s26, s28, 0x40080
	v_mov_b32_e32 v0, 0
	s_addc_u32 s27, s29, 0
	s_mov_b32 s77, -2
	ds_read_b128 v[154:157], v150
	ds_read_b128 v[158:161], v150 offset:1024
	ds_read_b128 v[162:165], v150 offset:2048
	ds_read_b128 v[166:169], v150 offset:3072
	ds_read_b128 v[170:173], v151
	ds_read_b128 v[174:177], v151 offset:1024
	ds_read_b128 v[178:181], v151 offset:2048
	ds_read_b128 v[182:185], v151 offset:3072
	s_add_u32 s28, s26, 0xfffc0080
	s_addc_u32 s29, s27, -1
	s_cmp_eq_u32 s77, 12
	s_cselect_b32 s31, s70, s29
	s_cselect_b32 s30, s72, s28
	s_cselect_b32 s29, s73, s76
	s_cselect_b32 s28, s74, s75
	v_lshl_add_u64 v[146:147], s[26:27], 0, v[140:141]
	s_add_i32 m0, s46, 0xc000
	ds_read_b128 v[186:189], v152
	ds_read_b128 v[190:193], v152 offset:1024
	ds_read_b128 v[194:197], v152 offset:2048
	ds_read_b128 v[198:201], v152 offset:3072
	ds_read_b128 v[202:205], v152 offset:4096
	ds_read_b128 v[206:209], v152 offset:5120
	ds_read_b128 v[210:213], v152 offset:6144
	ds_read_b128 v[214:217], v152 offset:7168
	global_load_lds_dwordx4 v[146:147], off
	v_lshl_add_u64 v[146:147], s[26:27], 0, v[138:139]
	s_add_i32 m0, s46, 0xe000
	s_nop 0
	global_load_lds_dwordx4 v[146:147], off
	s_waitcnt vmcnt(8) lgkmcnt(0)
	s_barrier
	s_setprio 1
	v_mfma_f32_16x16x32_bf16 v[124:127], v[154:157], v[186:189], 0
	v_mfma_f32_16x16x32_bf16 v[120:123], v[162:165], v[186:189], 0
	v_mfma_f32_16x16x32_bf16 v[116:119], v[154:157], v[194:197], 0
	v_mfma_f32_16x16x32_bf16 v[108:111], v[162:165], v[194:197], 0
	v_mfma_f32_16x16x32_bf16 v[100:103], v[154:157], v[202:205], 0
	v_mfma_f32_16x16x32_bf16 v[92:95], v[162:165], v[202:205], 0
	v_mfma_f32_16x16x32_bf16 v[84:87], v[154:157], v[210:213], 0
	v_mfma_f32_16x16x32_bf16 v[76:79], v[162:165], v[210:213], 0
	v_mfma_f32_16x16x32_bf16 v[124:127], v[158:161], v[190:193], v[124:127]
	v_mfma_f32_16x16x32_bf16 v[120:123], v[166:169], v[190:193], v[120:123]
	v_mfma_f32_16x16x32_bf16 v[116:119], v[158:161], v[198:201], v[116:119]
	v_mfma_f32_16x16x32_bf16 v[108:111], v[166:169], v[198:201], v[108:111]
	v_mfma_f32_16x16x32_bf16 v[100:103], v[158:161], v[206:209], v[100:103]
	v_mfma_f32_16x16x32_bf16 v[92:95], v[166:169], v[206:209], v[92:95]
	v_mfma_f32_16x16x32_bf16 v[84:87], v[158:161], v[214:217], v[84:87]
	v_mfma_f32_16x16x32_bf16 v[76:79], v[166:169], v[214:217], v[76:79]
	s_setprio 0
	s_setprio 1
	v_mfma_f32_16x16x32_bf16 v[112:115], v[170:173], v[186:189], 0
	v_mfma_f32_16x16x32_bf16 v[104:107], v[178:181], v[186:189], 0
	v_mfma_f32_16x16x32_bf16 v[96:99], v[170:173], v[194:197], 0
	v_mfma_f32_16x16x32_bf16 v[88:91], v[178:181], v[194:197], 0
	v_mfma_f32_16x16x32_bf16 v[80:83], v[170:173], v[202:205], 0
	v_mfma_f32_16x16x32_bf16 v[72:75], v[178:181], v[202:205], 0
	v_mfma_f32_16x16x32_bf16 v[68:71], v[170:173], v[210:213], 0
	v_mfma_f32_16x16x32_bf16 v[64:67], v[178:181], v[210:213], 0
	v_mfma_f32_16x16x32_bf16 v[112:115], v[174:177], v[190:193], v[112:115]
	v_mfma_f32_16x16x32_bf16 v[104:107], v[182:185], v[190:193], v[104:107]
	v_mfma_f32_16x16x32_bf16 v[96:99], v[174:177], v[198:201], v[96:99]
	v_mfma_f32_16x16x32_bf16 v[88:91], v[182:185], v[198:201], v[88:91]
	v_mfma_f32_16x16x32_bf16 v[80:83], v[174:177], v[206:209], v[80:83]
	v_mfma_f32_16x16x32_bf16 v[72:75], v[182:185], v[206:209], v[72:75]
	v_mfma_f32_16x16x32_bf16 v[68:71], v[174:177], v[214:217], v[68:71]
	v_mfma_f32_16x16x32_bf16 v[64:67], v[182:185], v[214:217], v[64:67]
	s_setprio 0
	s_barrier
	s_add_i32 s68, s57, s43
	v_lshl_add_u64 v[146:147], s[28:29], 0, v[130:131]
	s_mov_b32 m0, s68
	ds_read_b128 v[186:189], v152 offset:16384
	ds_read_b128 v[190:193], v152 offset:17408
	ds_read_b128 v[194:197], v152 offset:18432
	ds_read_b128 v[198:201], v152 offset:19456
	ds_read_b128 v[202:205], v152 offset:20480
	ds_read_b128 v[206:209], v152 offset:21504
	ds_read_b128 v[210:213], v152 offset:22528
	ds_read_b128 v[214:217], v152 offset:23552
	global_load_lds_dwordx4 v[146:147], off
	s_add_i32 m0, s68, 0x2000
	s_add_u32 s78, s28, 0x40000
	v_lshl_add_u64 v[218:219], s[28:29], 0, v[134:135]
	s_addc_u32 s79, s29, 0
	s_add_i32 s68, s58, s43
	global_load_lds_dwordx4 v[218:219], off
	v_lshl_add_u64 v[222:223], s[78:79], 0, v[130:131]
	s_mov_b32 m0, s68
	v_lshl_add_u64 v[224:225], s[30:31], 0, v[132:133]
	global_load_lds_dwordx4 v[222:223], off
	v_lshl_add_u64 v[222:223], s[78:79], 0, v[134:135]
	s_add_i32 m0, s68, 0x2000
	s_nop 0
	global_load_lds_dwordx4 v[222:223], off
	v_lshl_add_u64 v[222:223], s[30:31], 0, v[128:129]
	s_mov_b32 m0, s46
	s_nop 0
	global_load_lds_dwordx4 v[222:223], off
	s_mov_b32 m0, s47
	s_nop 0
	global_load_lds_dwordx4 v[224:225], off
	s_waitcnt vmcnt(8) lgkmcnt(0)
	s_barrier
; #define PG8_STAGE(bufoff, gbase, voff) do { _Pragma("unroll") for (int _i = 0; _i < 2; ++_i) \
;         __builtin_amdgcn_global_load_lds((const unsigned*)((const char*)(gbase) + (voff)[_i]), (PG8_LAS unsigned*)(lds + (bufoff) + ldsw + _i * 8192), 16, 0, 0); } while (0)
; #define PG8_LDA(dst, b, h) do { _Pragma("unroll") for (int m = 0; m < 4; ++m) _Pragma("unroll") for (int k = 0; k < 2; ++k) dst[m][k] = *(const PG8_LAS bf16x8*)(lds + PG8_SA(b, h) + aoff + m * 2048 + k * 1024); } while (0)
; #define PG8_LDB(dst, b, h) do { _Pragma("unroll") for (int n = 0; n < 2; ++n) _Pragma("unroll") for (int k = 0; k < 2; ++k) dst[n][k] = *(const PG8_LAS bf16x8*)(lds + PG8_SB(b, h) + boff + n * 2048 + k * 1024); } while (0)
; #define PG8_MMA(ai, bj, At, Bt) do { __builtin_amdgcn_s_setprio(1); _Pragma("unroll") for (int m = 0; m < 4; ++m) _Pragma("unroll") for (int n = 0; n < 2; ++n) _Pragma("unroll") for (int k = 0; k < 2; ++k) \
;         acc[ai][bj][m][n] = __builtin_amdgcn_mfma_f32_16x16x32_bf16(Bt[n][k], At[m][k], acc[ai][bj][m][n], 0, 0, 0); __builtin_amdgcn_s_setprio(0); } while (0)
; #define PG8_WAIT_V(n) asm volatile("s_waitcnt vmcnt(" #n ")" ::: "memory")
; #define PG8_WAIT_L(n) asm volatile("s_waitcnt lgkmcnt(" #n ")" ::: "memory")
; #define PG8_BAR __builtin_amdgcn_s_barrier()
; #define PG8_SCHED __builtin_amdgcn_sched_barrier(0)
; template <class Epi, class Sched>
; __device__ __forceinline__ void gemm_phase(PG8_LAS unsigned char* lds, PG8_LAS unsigned char* xl, const Gemm g, const Sched& S, const Epi& E) {
;     ...
;             PG8_WAIT_V(8); PG8_WAIT_L(0); PG8_BAR; PG8_MMA(1, 0, At, B0); PG8_MMA(1, 1, At, B1); PG8_BAR; PG8_SCHED;
;             PG8_LDB(B0, 1, 0); PG8_LDB(B1, 1, 1); PG8_SCHED; PG8_LDA(At, 1, 0); PG8_STAGE(PG8_SA(0, 1), a2 + hsA, voffA);
;             PG8_WAIT_V(8); PG8_WAIT_L(0); PG8_BAR; PG8_MMA(0, 0, At, B0); PG8_MMA(0, 1, At, B1); PG8_BAR; PG8_SCHED;
	s_setprio 1
	v_mfma_f32_16x16x32_bf16 v[60:63], v[154:157], v[186:189], 0
	v_mfma_f32_16x16x32_bf16 v[56:59], v[162:165], v[186:189], 0
	v_mfma_f32_16x16x32_bf16 v[52:55], v[154:157], v[194:197], 0
	v_mfma_f32_16x16x32_bf16 v[44:47], v[162:165], v[194:197], 0
	v_mfma_f32_16x16x32_bf16 v[36:39], v[154:157], v[202:205], 0
	v_mfma_f32_16x16x32_bf16 v[28:31], v[162:165], v[202:205], 0
	v_mfma_f32_16x16x32_bf16 v[20:23], v[154:157], v[210:213], 0
	v_mfma_f32_16x16x32_bf16 v[12:15], v[162:165], v[210:213], 0
	v_mfma_f32_16x16x32_bf16 v[60:63], v[158:161], v[190:193], v[60:63]
	v_mfma_f32_16x16x32_bf16 v[56:59], v[166:169], v[190:193], v[56:59]
	v_mfma_f32_16x16x32_bf16 v[52:55], v[158:161], v[198:201], v[52:55]
	v_mfma_f32_16x16x32_bf16 v[44:47], v[166:169], v[198:201], v[44:47]
	v_mfma_f32_16x16x32_bf16 v[36:39], v[158:161], v[206:209], v[36:39]
	v_mfma_f32_16x16x32_bf16 v[28:31], v[166:169], v[206:209], v[28:31]
	v_mfma_f32_16x16x32_bf16 v[20:23], v[158:161], v[214:217], v[20:23]
	v_mfma_f32_16x16x32_bf16 v[12:15], v[166:169], v[214:217], v[12:15]
	s_setprio 0
	s_setprio 1
	v_mfma_f32_16x16x32_bf16 v[48:51], v[170:173], v[186:189], 0
	v_mfma_f32_16x16x32_bf16 v[40:43], v[178:181], v[186:189], 0
	v_mfma_f32_16x16x32_bf16 v[32:35], v[170:173], v[194:197], 0
	v_mfma_f32_16x16x32_bf16 v[24:27], v[178:181], v[194:197], 0
	v_mfma_f32_16x16x32_bf16 v[16:19], v[170:173], v[202:205], 0
	v_mfma_f32_16x16x32_bf16 v[8:11], v[178:181], v[202:205], 0
	v_mfma_f32_16x16x32_bf16 v[4:7], v[170:173], v[210:213], 0
	v_mfma_f32_16x16x32_bf16 v[0:3], v[178:181], v[210:213], 0
	v_mfma_f32_16x16x32_bf16 v[48:51], v[174:177], v[190:193], v[48:51]
	v_mfma_f32_16x16x32_bf16 v[40:43], v[182:185], v[190:193], v[40:43]
	v_mfma_f32_16x16x32_bf16 v[32:35], v[174:177], v[198:201], v[32:35]
	v_mfma_f32_16x16x32_bf16 v[24:27], v[182:185], v[198:201], v[24:27]
	v_mfma_f32_16x16x32_bf16 v[16:19], v[174:177], v[206:209], v[16:19]
	v_mfma_f32_16x16x32_bf16 v[8:11], v[182:185], v[206:209], v[8:11]
	v_mfma_f32_16x16x32_bf16 v[4:7], v[174:177], v[214:217], v[4:7]
	v_mfma_f32_16x16x32_bf16 v[0:3], v[182:185], v[214:217], v[0:3]
	s_setprio 0
	s_barrier
	s_add_i32 s68, 0, 0x18000
	v_add_u32_e32 v153, s68, v149
	s_add_i32 s78, 0, 0x1c000
	ds_read_b128 v[154:157], v153
	ds_read_b128 v[158:161], v153 offset:1024
	ds_read_b128 v[162:165], v153 offset:2048
	ds_read_b128 v[166:169], v153 offset:3072
	v_add_u32_e32 v153, s78, v149
	ds_read_b128 v[170:173], v153
	ds_read_b128 v[174:177], v153 offset:1024
	ds_read_b128 v[178:181], v153 offset:2048
	ds_read_b128 v[182:185], v153 offset:3072
	s_add_u32 s30, s30, 0x40000
	s_addc_u32 s31, s31, 0
	s_mov_b32 m0, s52
	v_lshl_add_u64 v[226:227], s[30:31], 0, v[128:129]
	ds_read_b128 v[186:189], v152 offset:32768
	ds_read_b128 v[190:193], v152 offset:33792
	ds_read_b128 v[194:197], v152 offset:34816
	ds_read_b128 v[198:201], v152 offset:35840
	ds_read_b128 v[202:205], v152 offset:36864
	ds_read_b128 v[206:209], v152 offset:37888
	ds_read_b128 v[210:213], v152 offset:38912
	ds_read_b128 v[214:217], v152 offset:39936
	global_load_lds_dwordx4 v[226:227], off
	v_lshl_add_u64 v[226:227], s[30:31], 0, v[132:133]
	s_mov_b32 m0, s53
	s_nop 0
	global_load_lds_dwordx4 v[226:227], off
	s_waitcnt vmcnt(8) lgkmcnt(0)
	s_barrier
	s_setprio 1
	v_mfma_f32_16x16x32_bf16 v[124:127], v[154:157], v[186:189], v[124:127]
	v_mfma_f32_16x16x32_bf16 v[120:123], v[162:165], v[186:189], v[120:123]
	v_mfma_f32_16x16x32_bf16 v[116:119], v[154:157], v[194:197], v[116:119]
	v_mfma_f32_16x16x32_bf16 v[108:111], v[162:165], v[194:197], v[108:111]
	v_mfma_f32_16x16x32_bf16 v[100:103], v[154:157], v[202:205], v[100:103]
	v_mfma_f32_16x16x32_bf16 v[92:95], v[162:165], v[202:205], v[92:95]
	v_mfma_f32_16x16x32_bf16 v[84:87], v[154:157], v[210:213], v[84:87]
	v_mfma_f32_16x16x32_bf16 v[76:79], v[162:165], v[210:213], v[76:79]
	v_mfma_f32_16x16x32_bf16 v[124:127], v[158:161], v[190:193], v[124:127]
	v_mfma_f32_16x16x32_bf16 v[120:123], v[166:169], v[190:193], v[120:123]
	v_mfma_f32_16x16x32_bf16 v[116:119], v[158:161], v[198:201], v[116:119]
	v_mfma_f32_16x16x32_bf16 v[108:111], v[166:169], v[198:201], v[108:111]
	v_mfma_f32_16x16x32_bf16 v[100:103], v[158:161], v[206:209], v[100:103]
	v_mfma_f32_16x16x32_bf16 v[92:95], v[166:169], v[206:209], v[92:95]
	v_mfma_f32_16x16x32_bf16 v[84:87], v[158:161], v[214:217], v[84:87]
	v_mfma_f32_16x16x32_bf16 v[76:79], v[166:169], v[214:217], v[76:79]
	s_setprio 0
	s_setprio 1
	v_mfma_f32_16x16x32_bf16 v[112:115], v[170:173], v[186:189], v[112:115]
	v_mfma_f32_16x16x32_bf16 v[104:107], v[178:181], v[186:189], v[104:107]
	v_mfma_f32_16x16x32_bf16 v[96:99], v[170:173], v[194:197], v[96:99]
	v_mfma_f32_16x16x32_bf16 v[88:91], v[178:181], v[194:197], v[88:91]
	v_mfma_f32_16x16x32_bf16 v[80:83], v[170:173], v[202:205], v[80:83]
	v_mfma_f32_16x16x32_bf16 v[72:75], v[178:181], v[202:205], v[72:75]
	v_mfma_f32_16x16x32_bf16 v[68:71], v[170:173], v[210:213], v[68:71]
	v_mfma_f32_16x16x32_bf16 v[64:67], v[178:181], v[210:213], v[64:67]
	v_mfma_f32_16x16x32_bf16 v[112:115], v[174:177], v[190:193], v[112:115]
	v_mfma_f32_16x16x32_bf16 v[104:107], v[182:185], v[190:193], v[104:107]
	v_mfma_f32_16x16x32_bf16 v[96:99], v[174:177], v[198:201], v[96:99]
	v_mfma_f32_16x16x32_bf16 v[88:91], v[182:185], v[198:201], v[88:91]
	v_mfma_f32_16x16x32_bf16 v[80:83], v[174:177], v[206:209], v[80:83]
	v_mfma_f32_16x16x32_bf16 v[72:75], v[182:185], v[206:209], v[72:75]
	v_mfma_f32_16x16x32_bf16 v[68:71], v[174:177], v[214:217], v[68:71]
	v_mfma_f32_16x16x32_bf16 v[64:67], v[182:185], v[214:217], v[64:67]
	s_setprio 0
	s_barrier
; #define PG8_STAGE(bufoff, gbase, voff) do { _Pragma("unroll") for (int _i = 0; _i < 2; ++_i) \
;         __builtin_amdgcn_global_load_lds((const unsigned*)((const char*)(gbase) + (voff)[_i]), (PG8_LAS unsigned*)(lds + (bufoff) + ldsw + _i * 8192), 16, 0, 0); } while (0)
; #define PG8_LDA(dst, b, h) do { _Pragma("unroll") for (int m = 0; m < 4; ++m) _Pragma("unroll") for (int k = 0; k < 2; ++k) dst[m][k] = *(const PG8_LAS bf16x8*)(lds + PG8_SA(b, h) + aoff + m * 2048 + k * 1024); } while (0)
; #define PG8_LDB(dst, b, h) do { _Pragma("unroll") for (int n = 0; n < 2; ++n) _Pragma("unroll") for (int k = 0; k < 2; ++k) dst[n][k] = *(const PG8_LAS bf16x8*)(lds + PG8_SB(b, h) + boff + n * 2048 + k * 1024); } while (0)
; #define PG8_MMA(ai, bj, At, Bt) do { __builtin_amdgcn_s_setprio(1); _Pragma("unroll") for (int m = 0; m < 4; ++m) _Pragma("unroll") for (int n = 0; n < 2; ++n) _Pragma("unroll") for (int k = 0; k < 2; ++k) \
;         acc[ai][bj][m][n] = __builtin_amdgcn_mfma_f32_16x16x32_bf16(Bt[n][k], At[m][k], acc[ai][bj][m][n], 0, 0, 0); __builtin_amdgcn_s_setprio(0); } while (0)
; #define PG8_WAIT_V(n) asm volatile("s_waitcnt vmcnt(" #n ")" ::: "memory")
; #define PG8_WAIT_L(n) asm volatile("s_waitcnt lgkmcnt(" #n ")" ::: "memory")
; #define PG8_BAR __builtin_amdgcn_s_barrier()
; #define PG8_SCHED __builtin_amdgcn_sched_barrier(0)
; template <class Epi, class Sched>
; __device__ __forceinline__ void gemm_phase(PG8_LAS unsigned char* lds, PG8_LAS unsigned char* xl, const Gemm g, const Sched& S, const Epi& E) {
;     ...
;             PG8_LDB(B0, 0, 0); PG8_LDB(B1, 0, 1); PG8_SCHED; PG8_LDA(At, 0, 0); PG8_STAGE(PG8_SA(1, 1), a1 + hsA, voffA);
;             PG8_WAIT_V(8); PG8_WAIT_L(0); PG8_BAR; PG8_MMA(0, 0, At, B0); PG8_MMA(0, 1, At, B1); PG8_BAR; PG8_SCHED;
;     ...
;             PG8_LDA(At, 1, 1); PG8_STAGE(PG8_SB(1, 0), b3, voffB); PG8_STAGE(PG8_SB(1, 1), b3 + hsB, voffB); PG8_STAGE(PG8_SA(1, 0), a3, voffA);
;             PG8_WAIT_V(8); PG8_WAIT_L(0); PG8_BAR; PG8_MMA(1, 0, At, B0); PG8_MMA(1, 1, At, B1); PG8_BAR; PG8_SCHED;
;         }
	s_add_i32 s30, s68, s43
	v_lshl_add_u64 v[146:147], v[146:147], 0, s[10:11]
	s_mov_b32 m0, s30
	ds_read_b128 v[186:189], v152 offset:49152
	ds_read_b128 v[190:193], v152 offset:50176
	ds_read_b128 v[194:197], v152 offset:51200
	ds_read_b128 v[198:201], v152 offset:52224
	ds_read_b128 v[202:205], v152 offset:53248
	ds_read_b128 v[206:209], v152 offset:54272
	ds_read_b128 v[210:213], v152 offset:55296
	ds_read_b128 v[214:217], v152 offset:56320
	global_load_lds_dwordx4 v[146:147], off
	s_add_i32 m0, s30, 0x2000
	s_add_u32 s28, s28, 0x40080
	v_lshl_add_u64 v[146:147], v[218:219], 0, s[10:11]
	s_addc_u32 s29, s29, 0
	s_add_i32 s30, s78, s43
	global_load_lds_dwordx4 v[146:147], off
	v_lshl_add_u64 v[146:147], s[28:29], 0, v[130:131]
	s_mov_b32 m0, s30
	s_nop 0
	global_load_lds_dwordx4 v[146:147], off
	v_lshl_add_u64 v[146:147], s[28:29], 0, v[134:135]
	s_add_i32 m0, s30, 0x2000
	s_nop 0
	global_load_lds_dwordx4 v[146:147], off
	v_lshl_add_u64 v[146:147], v[222:223], 0, s[10:11]
	s_mov_b32 m0, s55
	s_nop 0
	global_load_lds_dwordx4 v[146:147], off
	v_lshl_add_u64 v[146:147], v[224:225], 0, s[10:11]
	s_mov_b32 m0, s56
	s_nop 0
	global_load_lds_dwordx4 v[146:147], off
	s_waitcnt vmcnt(8) lgkmcnt(0)
	s_barrier
	s_setprio 1
	v_mfma_f32_16x16x32_bf16 v[60:63], v[154:157], v[186:189], v[60:63]
	v_mfma_f32_16x16x32_bf16 v[56:59], v[162:165], v[186:189], v[56:59]
	v_mfma_f32_16x16x32_bf16 v[52:55], v[154:157], v[194:197], v[52:55]
	v_mfma_f32_16x16x32_bf16 v[44:47], v[162:165], v[194:197], v[44:47]
	v_mfma_f32_16x16x32_bf16 v[36:39], v[154:157], v[202:205], v[36:39]
	v_mfma_f32_16x16x32_bf16 v[28:31], v[162:165], v[202:205], v[28:31]
	v_mfma_f32_16x16x32_bf16 v[20:23], v[154:157], v[210:213], v[20:23]
	v_mfma_f32_16x16x32_bf16 v[12:15], v[162:165], v[210:213], v[12:15]
	v_mfma_f32_16x16x32_bf16 v[60:63], v[158:161], v[190:193], v[60:63]
	v_mfma_f32_16x16x32_bf16 v[56:59], v[166:169], v[190:193], v[56:59]
	v_mfma_f32_16x16x32_bf16 v[52:55], v[158:161], v[198:201], v[52:55]
	v_mfma_f32_16x16x32_bf16 v[44:47], v[166:169], v[198:201], v[44:47]
	v_mfma_f32_16x16x32_bf16 v[36:39], v[158:161], v[206:209], v[36:39]
	v_mfma_f32_16x16x32_bf16 v[28:31], v[166:169], v[206:209], v[28:31]
	v_mfma_f32_16x16x32_bf16 v[20:23], v[158:161], v[214:217], v[20:23]
	v_mfma_f32_16x16x32_bf16 v[12:15], v[166:169], v[214:217], v[12:15]
	s_setprio 0
	s_setprio 1
	v_mfma_f32_16x16x32_bf16 v[48:51], v[170:173], v[186:189], v[48:51]
	s_add_i32 s77, s77, 2
	v_mfma_f32_16x16x32_bf16 v[40:43], v[178:181], v[186:189], v[40:43]
	s_add_u32 s75, s75, 0x100
	v_mfma_f32_16x16x32_bf16 v[32:35], v[170:173], v[194:197], v[32:35]
	s_addc_u32 s76, s76, 0
	v_mfma_f32_16x16x32_bf16 v[24:27], v[178:181], v[194:197], v[24:27]
	s_add_u32 s26, s26, 0x100
	v_mfma_f32_16x16x32_bf16 v[16:19], v[170:173], v[202:205], v[16:19]
	s_addc_u32 s27, s27, 0
	v_mfma_f32_16x16x32_bf16 v[8:11], v[178:181], v[202:205], v[8:11]
	s_cmp_gt_u32 s77, 13
	v_mfma_f32_16x16x32_bf16 v[4:7], v[170:173], v[210:213], v[4:7]
	v_mfma_f32_16x16x32_bf16 v[0:3], v[178:181], v[210:213], v[0:3]
	v_mfma_f32_16x16x32_bf16 v[48:51], v[174:177], v[190:193], v[48:51]
	v_mfma_f32_16x16x32_bf16 v[40:43], v[182:185], v[190:193], v[40:43]
	v_mfma_f32_16x16x32_bf16 v[32:35], v[174:177], v[198:201], v[32:35]
	v_mfma_f32_16x16x32_bf16 v[24:27], v[182:185], v[198:201], v[24:27]
	v_mfma_f32_16x16x32_bf16 v[16:19], v[174:177], v[206:209], v[16:19]
	v_mfma_f32_16x16x32_bf16 v[8:11], v[182:185], v[206:209], v[8:11]
	v_mfma_f32_16x16x32_bf16 v[4:7], v[174:177], v[214:217], v[4:7]
	v_mfma_f32_16x16x32_bf16 v[0:3], v[182:185], v[214:217], v[0:3]
	s_setprio 0
	s_barrier
	s_cbranch_scc1 .Lpeel_after_P11
.LBB0_130:
	ds_read_b128 v[154:157], v150
	ds_read_b128 v[158:161], v150 offset:1024
	ds_read_b128 v[162:165], v150 offset:2048
	ds_read_b128 v[166:169], v150 offset:3072
	ds_read_b128 v[170:173], v151
	ds_read_b128 v[174:177], v151 offset:1024
	ds_read_b128 v[178:181], v151 offset:2048
	ds_read_b128 v[182:185], v151 offset:3072
	s_add_u32 s28, s26, 0xfffc0080
	s_addc_u32 s29, s27, -1
	s_cmp_eq_u32 s77, 12
	s_cselect_b32 s31, s70, s29
	s_cselect_b32 s30, s72, s28
	s_cselect_b32 s29, s73, s76
	s_cselect_b32 s28, s74, s75
	v_lshl_add_u64 v[146:147], s[26:27], 0, v[140:141]
	s_add_i32 m0, s46, 0xc000
	ds_read_b128 v[186:189], v152
	ds_read_b128 v[190:193], v152 offset:1024
	ds_read_b128 v[194:197], v152 offset:2048
	ds_read_b128 v[198:201], v152 offset:3072
	ds_read_b128 v[202:205], v152 offset:4096
	ds_read_b128 v[206:209], v152 offset:5120
	ds_read_b128 v[210:213], v152 offset:6144
	ds_read_b128 v[214:217], v152 offset:7168
	global_load_lds_dwordx4 v[146:147], off
	v_lshl_add_u64 v[146:147], s[26:27], 0, v[138:139]
	s_add_i32 m0, s46, 0xe000
	s_nop 0
	global_load_lds_dwordx4 v[146:147], off
	s_waitcnt vmcnt(8) lgkmcnt(0)
	s_barrier
; #define PG8_STAGE(bufoff, gbase, voff) do { _Pragma("unroll") for (int _i = 0; _i < 2; ++_i) \
;         __builtin_amdgcn_global_load_lds((const unsigned*)((const char*)(gbase) + (voff)[_i]), (PG8_LAS unsigned*)(lds + (bufoff) + ldsw + _i * 8192), 16, 0, 0); } while (0)
; #define PG8_LDA(dst, b, h) do { _Pragma("unroll") for (int m = 0; m < 4; ++m) _Pragma("unroll") for (int k = 0; k < 2; ++k) dst[m][k] = *(const PG8_LAS bf16x8*)(lds + PG8_SA(b, h) + aoff + m * 2048 + k * 1024); } while (0)
; #define PG8_MMA(ai, bj, At, Bt) do { __builtin_amdgcn_s_setprio(1); _Pragma("unroll") for (int m = 0; m < 4; ++m) _Pragma("unroll") for (int n = 0; n < 2; ++n) _Pragma("unroll") for (int k = 0; k < 2; ++k) \
;         acc[ai][bj][m][n] = __builtin_amdgcn_mfma_f32_16x16x32_bf16(Bt[n][k], At[m][k], acc[ai][bj][m][n], 0, 0, 0); __builtin_amdgcn_s_setprio(0); } while (0)
; #define PG8_WAIT_V(n) asm volatile("s_waitcnt vmcnt(" #n ")" ::: "memory")
; #define PG8_WAIT_L(n) asm volatile("s_waitcnt lgkmcnt(" #n ")" ::: "memory")
; #define PG8_BAR __builtin_amdgcn_s_barrier()
; #define PG8_SCHED __builtin_amdgcn_sched_barrier(0)
; template <class Epi, class Sched>
; __device__ __forceinline__ void gemm_phase(PG8_LAS unsigned char* lds, PG8_LAS unsigned char* xl, const Gemm g, const Sched& S, const Epi& E) {
;     ...
;             PG8_WAIT_V(8); PG8_WAIT_L(0); PG8_BAR; PG8_MMA(0, 0, At, B0); PG8_MMA(0, 1, At, B1); PG8_BAR; PG8_SCHED;
;             PG8_LDA(At, 0, 1); PG8_STAGE(PG8_SB(0, 0), b2, voffB); PG8_STAGE(PG8_SB(0, 1), b2 + hsB, voffB); PG8_STAGE(PG8_SA(0, 0), a2, voffA);
;             PG8_WAIT_V(8); PG8_WAIT_L(0); PG8_BAR; PG8_MMA(1, 0, At, B0); PG8_MMA(1, 1, At, B1); PG8_BAR; PG8_SCHED;
	s_setprio 1
	v_mfma_f32_16x16x32_bf16 v[124:127], v[154:157], v[186:189], v[124:127]
	v_mfma_f32_16x16x32_bf16 v[120:123], v[162:165], v[186:189], v[120:123]
	v_mfma_f32_16x16x32_bf16 v[116:119], v[154:157], v[194:197], v[116:119]
	v_mfma_f32_16x16x32_bf16 v[108:111], v[162:165], v[194:197], v[108:111]
	v_mfma_f32_16x16x32_bf16 v[100:103], v[154:157], v[202:205], v[100:103]
	v_mfma_f32_16x16x32_bf16 v[92:95], v[162:165], v[202:205], v[92:95]
	v_mfma_f32_16x16x32_bf16 v[84:87], v[154:157], v[210:213], v[84:87]
	v_mfma_f32_16x16x32_bf16 v[76:79], v[162:165], v[210:213], v[76:79]
	v_mfma_f32_16x16x32_bf16 v[124:127], v[158:161], v[190:193], v[124:127]
	v_mfma_f32_16x16x32_bf16 v[120:123], v[166:169], v[190:193], v[120:123]
	v_mfma_f32_16x16x32_bf16 v[116:119], v[158:161], v[198:201], v[116:119]
	v_mfma_f32_16x16x32_bf16 v[108:111], v[166:169], v[198:201], v[108:111]
	v_mfma_f32_16x16x32_bf16 v[100:103], v[158:161], v[206:209], v[100:103]
	v_mfma_f32_16x16x32_bf16 v[92:95], v[166:169], v[206:209], v[92:95]
	v_mfma_f32_16x16x32_bf16 v[84:87], v[158:161], v[214:217], v[84:87]
	v_mfma_f32_16x16x32_bf16 v[76:79], v[166:169], v[214:217], v[76:79]
	s_setprio 0
	s_setprio 1
	v_mfma_f32_16x16x32_bf16 v[112:115], v[170:173], v[186:189], v[112:115]
	v_mfma_f32_16x16x32_bf16 v[104:107], v[178:181], v[186:189], v[104:107]
	v_mfma_f32_16x16x32_bf16 v[96:99], v[170:173], v[194:197], v[96:99]
	v_mfma_f32_16x16x32_bf16 v[88:91], v[178:181], v[194:197], v[88:91]
	v_mfma_f32_16x16x32_bf16 v[80:83], v[170:173], v[202:205], v[80:83]
	v_mfma_f32_16x16x32_bf16 v[72:75], v[178:181], v[202:205], v[72:75]
	v_mfma_f32_16x16x32_bf16 v[68:71], v[170:173], v[210:213], v[68:71]
	v_mfma_f32_16x16x32_bf16 v[64:67], v[178:181], v[210:213], v[64:67]
	v_mfma_f32_16x16x32_bf16 v[112:115], v[174:177], v[190:193], v[112:115]
	v_mfma_f32_16x16x32_bf16 v[104:107], v[182:185], v[190:193], v[104:107]
	v_mfma_f32_16x16x32_bf16 v[96:99], v[174:177], v[198:201], v[96:99]
	v_mfma_f32_16x16x32_bf16 v[88:91], v[182:185], v[198:201], v[88:91]
	v_mfma_f32_16x16x32_bf16 v[80:83], v[174:177], v[206:209], v[80:83]
	v_mfma_f32_16x16x32_bf16 v[72:75], v[182:185], v[206:209], v[72:75]
	v_mfma_f32_16x16x32_bf16 v[68:71], v[174:177], v[214:217], v[68:71]
	v_mfma_f32_16x16x32_bf16 v[64:67], v[182:185], v[214:217], v[64:67]
	s_setprio 0
	s_barrier
	s_add_i32 s68, s57, s43
	v_lshl_add_u64 v[146:147], s[28:29], 0, v[130:131]
	s_mov_b32 m0, s68
	ds_read_b128 v[186:189], v152 offset:16384
	ds_read_b128 v[190:193], v152 offset:17408
	ds_read_b128 v[194:197], v152 offset:18432
	ds_read_b128 v[198:201], v152 offset:19456
	ds_read_b128 v[202:205], v152 offset:20480
	ds_read_b128 v[206:209], v152 offset:21504
	ds_read_b128 v[210:213], v152 offset:22528
	ds_read_b128 v[214:217], v152 offset:23552
	global_load_lds_dwordx4 v[146:147], off
	s_add_i32 m0, s68, 0x2000
	s_add_u32 s78, s28, 0x40000
	v_lshl_add_u64 v[218:219], s[28:29], 0, v[134:135]
	s_addc_u32 s79, s29, 0
	s_add_i32 s68, s58, s43
	global_load_lds_dwordx4 v[218:219], off
	v_lshl_add_u64 v[222:223], s[78:79], 0, v[130:131]
	s_mov_b32 m0, s68
	v_lshl_add_u64 v[224:225], s[30:31], 0, v[132:133]
	global_load_lds_dwordx4 v[222:223], off
	v_lshl_add_u64 v[222:223], s[78:79], 0, v[134:135]
	s_add_i32 m0, s68, 0x2000
	s_nop 0
	global_load_lds_dwordx4 v[222:223], off
	v_lshl_add_u64 v[222:223], s[30:31], 0, v[128:129]
	s_mov_b32 m0, s46
	s_nop 0
	global_load_lds_dwordx4 v[222:223], off
	s_mov_b32 m0, s47
	s_nop 0
	global_load_lds_dwordx4 v[224:225], off
	s_waitcnt vmcnt(8) lgkmcnt(0)
	s_barrier
	s_setprio 1
	v_mfma_f32_16x16x32_bf16 v[60:63], v[154:157], v[186:189], v[60:63]
	v_mfma_f32_16x16x32_bf16 v[56:59], v[162:165], v[186:189], v[56:59]
	v_mfma_f32_16x16x32_bf16 v[52:55], v[154:157], v[194:197], v[52:55]
	v_mfma_f32_16x16x32_bf16 v[44:47], v[162:165], v[194:197], v[44:47]
	v_mfma_f32_16x16x32_bf16 v[36:39], v[154:157], v[202:205], v[36:39]
	v_mfma_f32_16x16x32_bf16 v[28:31], v[162:165], v[202:205], v[28:31]
	v_mfma_f32_16x16x32_bf16 v[20:23], v[154:157], v[210:213], v[20:23]
	v_mfma_f32_16x16x32_bf16 v[12:15], v[162:165], v[210:213], v[12:15]
	v_mfma_f32_16x16x32_bf16 v[60:63], v[158:161], v[190:193], v[60:63]
	v_mfma_f32_16x16x32_bf16 v[56:59], v[166:169], v[190:193], v[56:59]
	v_mfma_f32_16x16x32_bf16 v[52:55], v[158:161], v[198:201], v[52:55]
	v_mfma_f32_16x16x32_bf16 v[44:47], v[166:169], v[198:201], v[44:47]
	v_mfma_f32_16x16x32_bf16 v[36:39], v[158:161], v[206:209], v[36:39]
	v_mfma_f32_16x16x32_bf16 v[28:31], v[166:169], v[206:209], v[28:31]
	v_mfma_f32_16x16x32_bf16 v[20:23], v[158:161], v[214:217], v[20:23]
	v_mfma_f32_16x16x32_bf16 v[12:15], v[166:169], v[214:217], v[12:15]
	s_setprio 0
	s_setprio 1
	v_mfma_f32_16x16x32_bf16 v[48:51], v[170:173], v[186:189], v[48:51]
	v_mfma_f32_16x16x32_bf16 v[40:43], v[178:181], v[186:189], v[40:43]
	v_mfma_f32_16x16x32_bf16 v[32:35], v[170:173], v[194:197], v[32:35]
	v_mfma_f32_16x16x32_bf16 v[24:27], v[178:181], v[194:197], v[24:27]
	v_mfma_f32_16x16x32_bf16 v[16:19], v[170:173], v[202:205], v[16:19]
	v_mfma_f32_16x16x32_bf16 v[8:11], v[178:181], v[202:205], v[8:11]
	v_mfma_f32_16x16x32_bf16 v[4:7], v[170:173], v[210:213], v[4:7]
	v_mfma_f32_16x16x32_bf16 v[0:3], v[178:181], v[210:213], v[0:3]
	v_mfma_f32_16x16x32_bf16 v[48:51], v[174:177], v[190:193], v[48:51]
	v_mfma_f32_16x16x32_bf16 v[40:43], v[182:185], v[190:193], v[40:43]
	v_mfma_f32_16x16x32_bf16 v[32:35], v[174:177], v[198:201], v[32:35]
	v_mfma_f32_16x16x32_bf16 v[24:27], v[182:185], v[198:201], v[24:27]
	v_mfma_f32_16x16x32_bf16 v[16:19], v[174:177], v[206:209], v[16:19]
	v_mfma_f32_16x16x32_bf16 v[8:11], v[182:185], v[206:209], v[8:11]
	v_mfma_f32_16x16x32_bf16 v[4:7], v[174:177], v[214:217], v[4:7]
	v_mfma_f32_16x16x32_bf16 v[0:3], v[182:185], v[214:217], v[0:3]
	s_setprio 0
	s_barrier
; #define PG8_STAGE(bufoff, gbase, voff) do { _Pragma("unroll") for (int _i = 0; _i < 2; ++_i) \
;         __builtin_amdgcn_global_load_lds((const unsigned*)((const char*)(gbase) + (voff)[_i]), (PG8_LAS unsigned*)(lds + (bufoff) + ldsw + _i * 8192), 16, 0, 0); } while (0)
; #define PG8_LDA(dst, b, h) do { _Pragma("unroll") for (int m = 0; m < 4; ++m) _Pragma("unroll") for (int k = 0; k < 2; ++k) dst[m][k] = *(const PG8_LAS bf16x8*)(lds + PG8_SA(b, h) + aoff + m * 2048 + k * 1024); } while (0)
; #define PG8_LDB(dst, b, h) do { _Pragma("unroll") for (int n = 0; n < 2; ++n) _Pragma("unroll") for (int k = 0; k < 2; ++k) dst[n][k] = *(const PG8_LAS bf16x8*)(lds + PG8_SB(b, h) + boff + n * 2048 + k * 1024); } while (0)
; #define PG8_MMA(ai, bj, At, Bt) do { __builtin_amdgcn_s_setprio(1); _Pragma("unroll") for (int m = 0; m < 4; ++m) _Pragma("unroll") for (int n = 0; n < 2; ++n) _Pragma("unroll") for (int k = 0; k < 2; ++k) \
;         acc[ai][bj][m][n] = __builtin_amdgcn_mfma_f32_16x16x32_bf16(Bt[n][k], At[m][k], acc[ai][bj][m][n], 0, 0, 0); __builtin_amdgcn_s_setprio(0); } while (0)
; #define PG8_WAIT_V(n) asm volatile("s_waitcnt vmcnt(" #n ")" ::: "memory")
; #define PG8_WAIT_L(n) asm volatile("s_waitcnt lgkmcnt(" #n ")" ::: "memory")
; #define PG8_BAR __builtin_amdgcn_s_barrier()
; #define PG8_SCHED __builtin_amdgcn_sched_barrier(0)
; template <class Epi, class Sched>
; __device__ __forceinline__ void gemm_phase(PG8_LAS unsigned char* lds, PG8_LAS unsigned char* xl, const Gemm g, const Sched& S, const Epi& E) {
;     ...
;             PG8_LDB(B0, 1, 0); PG8_LDB(B1, 1, 1); PG8_SCHED; PG8_LDA(At, 1, 0); PG8_STAGE(PG8_SA(0, 1), a2 + hsA, voffA);
;             PG8_WAIT_V(8); PG8_WAIT_L(0); PG8_BAR; PG8_MMA(0, 0, At, B0); PG8_MMA(0, 1, At, B1); PG8_BAR; PG8_SCHED;
	s_add_i32 s68, 0, 0x18000
	v_add_u32_e32 v153, s68, v149
	s_add_i32 s78, 0, 0x1c000
	ds_read_b128 v[154:157], v153
	ds_read_b128 v[158:161], v153 offset:1024
	ds_read_b128 v[162:165], v153 offset:2048
	ds_read_b128 v[166:169], v153 offset:3072
	v_add_u32_e32 v153, s78, v149
	ds_read_b128 v[170:173], v153
	ds_read_b128 v[174:177], v153 offset:1024
	ds_read_b128 v[178:181], v153 offset:2048
	ds_read_b128 v[182:185], v153 offset:3072
	s_add_u32 s30, s30, 0x40000
	s_addc_u32 s31, s31, 0
	s_mov_b32 m0, s52
	v_lshl_add_u64 v[226:227], s[30:31], 0, v[128:129]
	ds_read_b128 v[186:189], v152 offset:32768
	ds_read_b128 v[190:193], v152 offset:33792
	ds_read_b128 v[194:197], v152 offset:34816
	ds_read_b128 v[198:201], v152 offset:35840
	ds_read_b128 v[202:205], v152 offset:36864
	ds_read_b128 v[206:209], v152 offset:37888
	ds_read_b128 v[210:213], v152 offset:38912
	ds_read_b128 v[214:217], v152 offset:39936
	global_load_lds_dwordx4 v[226:227], off
	v_lshl_add_u64 v[226:227], s[30:31], 0, v[132:133]
	s_mov_b32 m0, s53
	s_nop 0
	global_load_lds_dwordx4 v[226:227], off
	s_waitcnt vmcnt(8) lgkmcnt(0)
	s_barrier
	s_setprio 1
	v_mfma_f32_16x16x32_bf16 v[124:127], v[154:157], v[186:189], v[124:127]
	v_mfma_f32_16x16x32_bf16 v[120:123], v[162:165], v[186:189], v[120:123]
	v_mfma_f32_16x16x32_bf16 v[116:119], v[154:157], v[194:197], v[116:119]
	v_mfma_f32_16x16x32_bf16 v[108:111], v[162:165], v[194:197], v[108:111]
	v_mfma_f32_16x16x32_bf16 v[100:103], v[154:157], v[202:205], v[100:103]
	v_mfma_f32_16x16x32_bf16 v[92:95], v[162:165], v[202:205], v[92:95]
	v_mfma_f32_16x16x32_bf16 v[84:87], v[154:157], v[210:213], v[84:87]
	v_mfma_f32_16x16x32_bf16 v[76:79], v[162:165], v[210:213], v[76:79]
	v_mfma_f32_16x16x32_bf16 v[124:127], v[158:161], v[190:193], v[124:127]
	v_mfma_f32_16x16x32_bf16 v[120:123], v[166:169], v[190:193], v[120:123]
	v_mfma_f32_16x16x32_bf16 v[116:119], v[158:161], v[198:201], v[116:119]
	v_mfma_f32_16x16x32_bf16 v[108:111], v[166:169], v[198:201], v[108:111]
	v_mfma_f32_16x16x32_bf16 v[100:103], v[158:161], v[206:209], v[100:103]
	v_mfma_f32_16x16x32_bf16 v[92:95], v[166:169], v[206:209], v[92:95]
	v_mfma_f32_16x16x32_bf16 v[84:87], v[158:161], v[214:217], v[84:87]
	v_mfma_f32_16x16x32_bf16 v[76:79], v[166:169], v[214:217], v[76:79]
	s_setprio 0
	s_setprio 1
	v_mfma_f32_16x16x32_bf16 v[112:115], v[170:173], v[186:189], v[112:115]
	v_mfma_f32_16x16x32_bf16 v[104:107], v[178:181], v[186:189], v[104:107]
	v_mfma_f32_16x16x32_bf16 v[96:99], v[170:173], v[194:197], v[96:99]
	v_mfma_f32_16x16x32_bf16 v[88:91], v[178:181], v[194:197], v[88:91]
	v_mfma_f32_16x16x32_bf16 v[80:83], v[170:173], v[202:205], v[80:83]
	v_mfma_f32_16x16x32_bf16 v[72:75], v[178:181], v[202:205], v[72:75]
	v_mfma_f32_16x16x32_bf16 v[68:71], v[170:173], v[210:213], v[68:71]
	v_mfma_f32_16x16x32_bf16 v[64:67], v[178:181], v[210:213], v[64:67]
	v_mfma_f32_16x16x32_bf16 v[112:115], v[174:177], v[190:193], v[112:115]
	v_mfma_f32_16x16x32_bf16 v[104:107], v[182:185], v[190:193], v[104:107]
	v_mfma_f32_16x16x32_bf16 v[96:99], v[174:177], v[198:201], v[96:99]
	v_mfma_f32_16x16x32_bf16 v[88:91], v[182:185], v[198:201], v[88:91]
	v_mfma_f32_16x16x32_bf16 v[80:83], v[174:177], v[206:209], v[80:83]
	v_mfma_f32_16x16x32_bf16 v[72:75], v[182:185], v[206:209], v[72:75]
	v_mfma_f32_16x16x32_bf16 v[68:71], v[174:177], v[214:217], v[68:71]
	v_mfma_f32_16x16x32_bf16 v[64:67], v[182:185], v[214:217], v[64:67]
	s_setprio 0
	s_barrier
; #define PG8_STAGE(bufoff, gbase, voff) do { _Pragma("unroll") for (int _i = 0; _i < 2; ++_i) \
;         __builtin_amdgcn_global_load_lds((const unsigned*)((const char*)(gbase) + (voff)[_i]), (PG8_LAS unsigned*)(lds + (bufoff) + ldsw + _i * 8192), 16, 0, 0); } while (0)
; #define PG8_LDA(dst, b, h) do { _Pragma("unroll") for (int m = 0; m < 4; ++m) _Pragma("unroll") for (int k = 0; k < 2; ++k) dst[m][k] = *(const PG8_LAS bf16x8*)(lds + PG8_SA(b, h) + aoff + m * 2048 + k * 1024); } while (0)
; #define PG8_MMA(ai, bj, At, Bt) do { __builtin_amdgcn_s_setprio(1); _Pragma("unroll") for (int m = 0; m < 4; ++m) _Pragma("unroll") for (int n = 0; n < 2; ++n) _Pragma("unroll") for (int k = 0; k < 2; ++k) \
;         acc[ai][bj][m][n] = __builtin_amdgcn_mfma_f32_16x16x32_bf16(Bt[n][k], At[m][k], acc[ai][bj][m][n], 0, 0, 0); __builtin_amdgcn_s_setprio(0); } while (0)
; #define PG8_WAIT_V(n) asm volatile("s_waitcnt vmcnt(" #n ")" ::: "memory")
; #define PG8_WAIT_L(n) asm volatile("s_waitcnt lgkmcnt(" #n ")" ::: "memory")
; #define PG8_BAR __builtin_amdgcn_s_barrier()
; #define PG8_SCHED __builtin_amdgcn_sched_barrier(0)
; template <class Epi, class Sched>
; __device__ __forceinline__ void gemm_phase(PG8_LAS unsigned char* lds, PG8_LAS unsigned char* xl, const Gemm g, const Sched& S, const Epi& E) {
;     ...
;             PG8_LDA(At, 1, 1); PG8_STAGE(PG8_SB(1, 0), b3, voffB); PG8_STAGE(PG8_SB(1, 1), b3 + hsB, voffB); PG8_STAGE(PG8_SA(1, 0), a3, voffA);
;             PG8_WAIT_V(8); PG8_WAIT_L(0); PG8_BAR; PG8_MMA(1, 0, At, B0); PG8_MMA(1, 1, At, B1); PG8_BAR; PG8_SCHED;
;         }
	s_add_i32 s30, s68, s43
	v_lshl_add_u64 v[146:147], v[146:147], 0, s[10:11]
	s_mov_b32 m0, s30
	ds_read_b128 v[186:189], v152 offset:49152
	ds_read_b128 v[190:193], v152 offset:50176
	ds_read_b128 v[194:197], v152 offset:51200
	ds_read_b128 v[198:201], v152 offset:52224
	ds_read_b128 v[202:205], v152 offset:53248
	ds_read_b128 v[206:209], v152 offset:54272
	ds_read_b128 v[210:213], v152 offset:55296
	ds_read_b128 v[214:217], v152 offset:56320
	global_load_lds_dwordx4 v[146:147], off
	s_add_i32 m0, s30, 0x2000
	s_add_u32 s28, s28, 0x40080
	v_lshl_add_u64 v[146:147], v[218:219], 0, s[10:11]
	s_addc_u32 s29, s29, 0
	s_add_i32 s30, s78, s43
	global_load_lds_dwordx4 v[146:147], off
	v_lshl_add_u64 v[146:147], s[28:29], 0, v[130:131]
	s_mov_b32 m0, s30
	s_nop 0
	global_load_lds_dwordx4 v[146:147], off
	v_lshl_add_u64 v[146:147], s[28:29], 0, v[134:135]
	s_add_i32 m0, s30, 0x2000
	s_nop 0
	global_load_lds_dwordx4 v[146:147], off
	v_lshl_add_u64 v[146:147], v[222:223], 0, s[10:11]
	s_mov_b32 m0, s55
	s_nop 0
	global_load_lds_dwordx4 v[146:147], off
	v_lshl_add_u64 v[146:147], v[224:225], 0, s[10:11]
	s_mov_b32 m0, s56
	s_nop 0
	global_load_lds_dwordx4 v[146:147], off
	s_waitcnt vmcnt(8) lgkmcnt(0)
	s_barrier
	s_setprio 1
	v_mfma_f32_16x16x32_bf16 v[60:63], v[154:157], v[186:189], v[60:63]
	v_mfma_f32_16x16x32_bf16 v[56:59], v[162:165], v[186:189], v[56:59]
	v_mfma_f32_16x16x32_bf16 v[52:55], v[154:157], v[194:197], v[52:55]
	v_mfma_f32_16x16x32_bf16 v[44:47], v[162:165], v[194:197], v[44:47]
	v_mfma_f32_16x16x32_bf16 v[36:39], v[154:157], v[202:205], v[36:39]
	v_mfma_f32_16x16x32_bf16 v[28:31], v[162:165], v[202:205], v[28:31]
	v_mfma_f32_16x16x32_bf16 v[20:23], v[154:157], v[210:213], v[20:23]
	v_mfma_f32_16x16x32_bf16 v[12:15], v[162:165], v[210:213], v[12:15]
	v_mfma_f32_16x16x32_bf16 v[60:63], v[158:161], v[190:193], v[60:63]
	v_mfma_f32_16x16x32_bf16 v[56:59], v[166:169], v[190:193], v[56:59]
	v_mfma_f32_16x16x32_bf16 v[52:55], v[158:161], v[198:201], v[52:55]
	v_mfma_f32_16x16x32_bf16 v[44:47], v[166:169], v[198:201], v[44:47]
	v_mfma_f32_16x16x32_bf16 v[36:39], v[158:161], v[206:209], v[36:39]
	v_mfma_f32_16x16x32_bf16 v[28:31], v[166:169], v[206:209], v[28:31]
	v_mfma_f32_16x16x32_bf16 v[20:23], v[158:161], v[214:217], v[20:23]
	v_mfma_f32_16x16x32_bf16 v[12:15], v[166:169], v[214:217], v[12:15]
	s_setprio 0
	s_setprio 1
	v_mfma_f32_16x16x32_bf16 v[48:51], v[170:173], v[186:189], v[48:51]
	s_add_i32 s77, s77, 2
	v_mfma_f32_16x16x32_bf16 v[40:43], v[178:181], v[186:189], v[40:43]
	s_add_u32 s75, s75, 0x100
	v_mfma_f32_16x16x32_bf16 v[32:35], v[170:173], v[194:197], v[32:35]
	s_addc_u32 s76, s76, 0
	v_mfma_f32_16x16x32_bf16 v[24:27], v[178:181], v[194:197], v[24:27]
	s_add_u32 s26, s26, 0x100
	v_mfma_f32_16x16x32_bf16 v[16:19], v[170:173], v[202:205], v[16:19]
	s_addc_u32 s27, s27, 0
	v_mfma_f32_16x16x32_bf16 v[8:11], v[178:181], v[202:205], v[8:11]
	s_cmp_gt_u32 s77, 13
	v_mfma_f32_16x16x32_bf16 v[4:7], v[170:173], v[210:213], v[4:7]
	v_mfma_f32_16x16x32_bf16 v[0:3], v[178:181], v[210:213], v[0:3]
	v_mfma_f32_16x16x32_bf16 v[48:51], v[174:177], v[190:193], v[48:51]
	v_mfma_f32_16x16x32_bf16 v[40:43], v[182:185], v[190:193], v[40:43]
	v_mfma_f32_16x16x32_bf16 v[32:35], v[174:177], v[198:201], v[32:35]
	v_mfma_f32_16x16x32_bf16 v[24:27], v[182:185], v[198:201], v[24:27]
	v_mfma_f32_16x16x32_bf16 v[16:19], v[174:177], v[206:209], v[16:19]
	v_mfma_f32_16x16x32_bf16 v[8:11], v[182:185], v[206:209], v[8:11]
	v_mfma_f32_16x16x32_bf16 v[4:7], v[174:177], v[214:217], v[4:7]
	v_mfma_f32_16x16x32_bf16 v[0:3], v[182:185], v[214:217], v[0:3]
	s_setprio 0
	s_barrier
	s_cbranch_scc0 .LBB0_130

; #define PG8_STAGE(bufoff, gbase, voff) do { _Pragma("unroll") for (int _i = 0; _i < 2; ++_i) \
;         __builtin_amdgcn_global_load_lds((const unsigned*)((const char*)(gbase) + (voff)[_i]), (PG8_LAS unsigned*)(lds + (bufoff) + ldsw + _i * 8192), 16, 0, 0); } while (0)
; #define PG8_LDA(dst, b, h) do { _Pragma("unroll") for (int m = 0; m < 4; ++m) _Pragma("unroll") for (int k = 0; k < 2; ++k) dst[m][k] = *(const PG8_LAS bf16x8*)(lds + PG8_SA(b, h) + aoff + m * 2048 + k * 1024); } while (0)
; #define PG8_LDB(dst, b, h) do { _Pragma("unroll") for (int n = 0; n < 2; ++n) _Pragma("unroll") for (int k = 0; k < 2; ++k) dst[n][k] = *(const PG8_LAS bf16x8*)(lds + PG8_SB(b, h) + boff + n * 2048 + k * 1024); } while (0)
; #define PG8_MMA(ai, bj, At, Bt) do { __builtin_amdgcn_s_setprio(1); _Pragma("unroll") for (int m = 0; m < 4; ++m) _Pragma("unroll") for (int n = 0; n < 2; ++n) _Pragma("unroll") for (int k = 0; k < 2; ++k) \
;         acc[ai][bj][m][n] = __builtin_amdgcn_mfma_f32_16x16x32_bf16(Bt[n][k], At[m][k], acc[ai][bj][m][n], 0, 0, 0); __builtin_amdgcn_s_setprio(0); } while (0)
; #define PG8_WAIT_V(n) asm volatile("s_waitcnt vmcnt(" #n ")" ::: "memory")
; #define PG8_BAR __builtin_amdgcn_s_barrier()
; template <class Epi, class Sched>
; __device__ __forceinline__ void gemm_phase(PG8_LAS unsigned char* lds, PG8_LAS unsigned char* xl, const Gemm g, const Sched& S, const Epi& E) {
;     ...
;     for (;;) {
;         const bool has_next = S.next(ui + 1, nxt);
;         const char* nA = has_next ? (const char*)g.A + nxt.aoff : cA; const char* nB = has_next ? (const char*)g.Bt + nxt.boff : cB;
; #pragma unroll 1
;         for (int t = 0; t < nt; t += 2) {
;             const bool last = (t == nt - 2);
;             const char* a1 = cA + (size_t)(t + 1) * kstep;
;             const char* a2 = last ? nA : cA + (size_t)(t + 2) * kstep; const char* b2 = last ? nB : cB + (size_t)(t + 2) * kstep;
;             const char* a3 = a2 + kstep; const char* b3 = b2 + kstep;
;             PG8_LDB(B0, 0, 0); PG8_LDB(B1, 0, 1); PG8_SCHED; PG8_LDA(At, 0, 0); PG8_STAGE(PG8_SA(1, 1), a1 + hsA, voffA);
;             PG8_WAIT_V(8); PG8_WAIT_L(0); PG8_BAR; PG8_MMA(0, 0, At, B0); PG8_MMA(0, 1, At, B1); PG8_BAR; PG8_SCHED;
;             PG8_LDA(At, 0, 1); PG8_STAGE(PG8_SB(0, 0), b2, voffB); PG8_STAGE(PG8_SB(0, 1), b2 + hsB, voffB); PG8_STAGE(PG8_SA(0, 0), a2, voffA);
.LBB0_376:
	s_add_u32 s20, s2, s16
	s_addc_u32 s21, s3, s17
	s_and_b64 s[22:23], s[4:5], exec
	s_cselect_b32 s82, s21, s31
	s_cselect_b32 s83, s20, s30
	s_add_u32 s22, s2, s18
	s_addc_u32 s23, s3, s19
	s_and_b64 s[34:35], s[4:5], exec
	v_mov_b32_e32 v0, 0
	s_cselect_b32 s84, s23, s29
	s_cselect_b32 s85, s22, s28
	s_mov_b64 s[50:51], 0
	s_mov_b64 s[34:35], -1
	s_mov_b64 s[36:37], 0
	s_add_u32 s56, s30, s50
	s_addc_u32 s57, s31, s51
	s_add_u32 s54, s56, 0x100
	s_addc_u32 s55, s57, 0
	s_and_b64 s[52:53], s[36:37], exec
	s_cselect_b32 s53, s82, s55
	s_cselect_b32 s52, s83, s54
	s_add_u32 s50, s28, s50
	s_addc_u32 s51, s29, s51
	s_add_u32 s50, s50, 0x100
	s_addc_u32 s51, s51, 0
	s_and_b64 s[36:37], s[36:37], exec
	s_cselect_b32 s55, s84, s51
	s_cselect_b32 s54, s85, s50
	s_add_u32 s58, s56, 0x80080
	ds_read_b128 v[152:155], v147
	ds_read_b128 v[156:159], v147 offset:1024
	ds_read_b128 v[160:163], v147 offset:2048
	ds_read_b128 v[164:167], v147 offset:3072
	ds_read_b128 v[168:171], v148
	ds_read_b128 v[172:175], v148 offset:1024
	ds_read_b128 v[176:179], v148 offset:2048
	ds_read_b128 v[180:183], v148 offset:3072
	s_addc_u32 s59, s57, 0
	s_add_i32 s94, s73, s33
	s_add_i32 m0, s43, 0xc000
	s_add_i32 s95, s43, 0xe000
	s_add_i32 s91, s94, 0x2000
	s_add_u32 s56, s54, 0x80000
	s_addc_u32 s57, s55, 0
	s_add_i32 s93, s74, s33
	s_add_i32 s92, s93, 0x2000
	s_add_i32 s90, 0, 0x18000
	s_add_i32 s89, 0, 0x1c000
	s_add_u32 s50, s52, 0x80000
	s_addc_u32 s51, s53, 0
	s_add_i32 s88, s90, s33
	s_add_i32 s86, s88, 0x2000
	s_add_u32 s36, s54, 0x80080
	s_addc_u32 s37, s55, 0
	s_add_i32 s87, s89, s33
	s_add_i32 s68, s87, 0x2000
	v_lshl_add_u64 v[144:145], s[58:59], 0, v[128:129]
	ds_read_b128 v[184:187], v149
	ds_read_b128 v[188:191], v149 offset:1024
	ds_read_b128 v[192:195], v149 offset:2048
	ds_read_b128 v[196:199], v149 offset:3072
	ds_read_b128 v[200:203], v149 offset:4096
	ds_read_b128 v[204:207], v149 offset:5120
	ds_read_b128 v[208:211], v149 offset:6144
	ds_read_b128 v[212:215], v149 offset:7168
	global_load_lds_dwordx4 v[144:145], off
	v_lshl_add_u64 v[144:145], s[58:59], 0, v[132:133]
	s_mov_b32 m0, s95
	s_nop 0
	global_load_lds_dwordx4 v[144:145], off
	s_waitcnt vmcnt(8) lgkmcnt(0)
	s_barrier
	s_setprio 1
	v_mfma_f32_16x16x32_bf16 v[124:127], v[152:155], v[184:187], 0
	v_mfma_f32_16x16x32_bf16 v[120:123], v[160:163], v[184:187], 0
	v_mfma_f32_16x16x32_bf16 v[112:115], v[152:155], v[192:195], 0
	v_mfma_f32_16x16x32_bf16 v[104:107], v[160:163], v[192:195], 0
	v_mfma_f32_16x16x32_bf16 v[96:99], v[152:155], v[200:203], 0
	v_mfma_f32_16x16x32_bf16 v[88:91], v[160:163], v[200:203], 0
	v_mfma_f32_16x16x32_bf16 v[80:83], v[152:155], v[208:211], 0
	v_mfma_f32_16x16x32_bf16 v[72:75], v[160:163], v[208:211], 0
	v_mfma_f32_16x16x32_bf16 v[124:127], v[156:159], v[188:191], v[124:127]
	v_mfma_f32_16x16x32_bf16 v[120:123], v[164:167], v[188:191], v[120:123]
	v_mfma_f32_16x16x32_bf16 v[112:115], v[156:159], v[196:199], v[112:115]
	v_mfma_f32_16x16x32_bf16 v[104:107], v[164:167], v[196:199], v[104:107]
	v_mfma_f32_16x16x32_bf16 v[96:99], v[156:159], v[204:207], v[96:99]
	v_mfma_f32_16x16x32_bf16 v[88:91], v[164:167], v[204:207], v[88:91]
	v_mfma_f32_16x16x32_bf16 v[80:83], v[156:159], v[212:215], v[80:83]
	v_mfma_f32_16x16x32_bf16 v[72:75], v[164:167], v[212:215], v[72:75]
	s_setprio 0
	s_setprio 1
	v_mfma_f32_16x16x32_bf16 v[116:119], v[168:171], v[184:187], 0
	v_mfma_f32_16x16x32_bf16 v[108:111], v[176:179], v[184:187], 0
	v_mfma_f32_16x16x32_bf16 v[100:103], v[168:171], v[192:195], 0
	v_mfma_f32_16x16x32_bf16 v[92:95], v[176:179], v[192:195], 0
	v_mfma_f32_16x16x32_bf16 v[84:87], v[168:171], v[200:203], 0
	v_mfma_f32_16x16x32_bf16 v[76:79], v[176:179], v[200:203], 0
	v_mfma_f32_16x16x32_bf16 v[68:71], v[168:171], v[208:211], 0
	v_mfma_f32_16x16x32_bf16 v[64:67], v[176:179], v[208:211], 0
	v_mfma_f32_16x16x32_bf16 v[116:119], v[172:175], v[188:191], v[116:119]
	v_mfma_f32_16x16x32_bf16 v[108:111], v[180:183], v[188:191], v[108:111]
	v_mfma_f32_16x16x32_bf16 v[100:103], v[172:175], v[196:199], v[100:103]
	v_mfma_f32_16x16x32_bf16 v[92:95], v[180:183], v[196:199], v[92:95]
	v_mfma_f32_16x16x32_bf16 v[84:87], v[172:175], v[204:207], v[84:87]
	v_mfma_f32_16x16x32_bf16 v[76:79], v[180:183], v[204:207], v[76:79]
	v_mfma_f32_16x16x32_bf16 v[68:71], v[172:175], v[212:215], v[68:71]
	v_mfma_f32_16x16x32_bf16 v[64:67], v[180:183], v[212:215], v[64:67]
	s_setprio 0
	s_barrier
	s_mov_b32 m0, s94
	v_lshl_add_u64 v[144:145], s[54:55], 0, v[130:131]
	ds_read_b128 v[184:187], v149 offset:16384
	ds_read_b128 v[188:191], v149 offset:17408
	ds_read_b128 v[192:195], v149 offset:18432
	ds_read_b128 v[196:199], v149 offset:19456
	ds_read_b128 v[200:203], v149 offset:20480
	ds_read_b128 v[204:207], v149 offset:21504
	ds_read_b128 v[208:211], v149 offset:22528
	ds_read_b128 v[212:215], v149 offset:23552
	global_load_lds_dwordx4 v[144:145], off
	v_lshl_add_u64 v[216:217], s[54:55], 0, v[134:135]
	s_mov_b32 m0, s91
	v_lshl_add_u64 v[218:219], s[56:57], 0, v[130:131]
	global_load_lds_dwordx4 v[216:217], off
	s_mov_b32 m0, s93
	v_lshl_add_u64 v[222:223], s[52:53], 0, v[132:133]
	global_load_lds_dwordx4 v[218:219], off
	v_lshl_add_u64 v[218:219], s[56:57], 0, v[134:135]
	s_mov_b32 m0, s92
	s_nop 0
	global_load_lds_dwordx4 v[218:219], off
	v_lshl_add_u64 v[218:219], s[52:53], 0, v[128:129]
	s_mov_b32 m0, s43
	s_nop 0
	global_load_lds_dwordx4 v[218:219], off
	s_mov_b32 m0, s46
	s_nop 0
	global_load_lds_dwordx4 v[222:223], off
	s_waitcnt vmcnt(8) lgkmcnt(0)
	s_barrier
; #define PG8_STAGE(bufoff, gbase, voff) do { _Pragma("unroll") for (int _i = 0; _i < 2; ++_i) \
;         __builtin_amdgcn_global_load_lds((const unsigned*)((const char*)(gbase) + (voff)[_i]), (PG8_LAS unsigned*)(lds + (bufoff) + ldsw + _i * 8192), 16, 0, 0); } while (0)
; #define PG8_LDA(dst, b, h) do { _Pragma("unroll") for (int m = 0; m < 4; ++m) _Pragma("unroll") for (int k = 0; k < 2; ++k) dst[m][k] = *(const PG8_LAS bf16x8*)(lds + PG8_SA(b, h) + aoff + m * 2048 + k * 1024); } while (0)
; #define PG8_LDB(dst, b, h) do { _Pragma("unroll") for (int n = 0; n < 2; ++n) _Pragma("unroll") for (int k = 0; k < 2; ++k) dst[n][k] = *(const PG8_LAS bf16x8*)(lds + PG8_SB(b, h) + boff + n * 2048 + k * 1024); } while (0)
; #define PG8_MMA(ai, bj, At, Bt) do { __builtin_amdgcn_s_setprio(1); _Pragma("unroll") for (int m = 0; m < 4; ++m) _Pragma("unroll") for (int n = 0; n < 2; ++n) _Pragma("unroll") for (int k = 0; k < 2; ++k) \
;         acc[ai][bj][m][n] = __builtin_amdgcn_mfma_f32_16x16x32_bf16(Bt[n][k], At[m][k], acc[ai][bj][m][n], 0, 0, 0); __builtin_amdgcn_s_setprio(0); } while (0)
; #define PG8_WAIT_V(n) asm volatile("s_waitcnt vmcnt(" #n ")" ::: "memory")
; #define PG8_WAIT_L(n) asm volatile("s_waitcnt lgkmcnt(" #n ")" ::: "memory")
; #define PG8_BAR __builtin_amdgcn_s_barrier()
; #define PG8_SCHED __builtin_amdgcn_sched_barrier(0)
; template <class Epi, class Sched>
; __device__ __forceinline__ void gemm_phase(PG8_LAS unsigned char* lds, PG8_LAS unsigned char* xl, const Gemm g, const Sched& S, const Epi& E) {
;     ...
;             PG8_WAIT_V(8); PG8_WAIT_L(0); PG8_BAR; PG8_MMA(1, 0, At, B0); PG8_MMA(1, 1, At, B1); PG8_BAR; PG8_SCHED;
;             PG8_LDB(B0, 1, 0); PG8_LDB(B1, 1, 1); PG8_SCHED; PG8_LDA(At, 1, 0); PG8_STAGE(PG8_SA(0, 1), a2 + hsA, voffA);
;             PG8_WAIT_V(8); PG8_WAIT_L(0); PG8_BAR; PG8_MMA(0, 0, At, B0); PG8_MMA(0, 1, At, B1); PG8_BAR; PG8_SCHED;
	s_setprio 1
	v_mfma_f32_16x16x32_bf16 v[60:63], v[152:155], v[184:187], 0
	v_mfma_f32_16x16x32_bf16 v[56:59], v[160:163], v[184:187], 0
	v_mfma_f32_16x16x32_bf16 v[48:51], v[152:155], v[192:195], 0
	v_mfma_f32_16x16x32_bf16 v[40:43], v[160:163], v[192:195], 0
	v_mfma_f32_16x16x32_bf16 v[32:35], v[152:155], v[200:203], 0
	v_mfma_f32_16x16x32_bf16 v[24:27], v[160:163], v[200:203], 0
	v_mfma_f32_16x16x32_bf16 v[16:19], v[152:155], v[208:211], 0
	v_mfma_f32_16x16x32_bf16 v[8:11], v[160:163], v[208:211], 0
	v_mfma_f32_16x16x32_bf16 v[60:63], v[156:159], v[188:191], v[60:63]
	v_mfma_f32_16x16x32_bf16 v[56:59], v[164:167], v[188:191], v[56:59]
	v_mfma_f32_16x16x32_bf16 v[48:51], v[156:159], v[196:199], v[48:51]
	v_mfma_f32_16x16x32_bf16 v[40:43], v[164:167], v[196:199], v[40:43]
	v_mfma_f32_16x16x32_bf16 v[32:35], v[156:159], v[204:207], v[32:35]
	v_mfma_f32_16x16x32_bf16 v[24:27], v[164:167], v[204:207], v[24:27]
	v_mfma_f32_16x16x32_bf16 v[16:19], v[156:159], v[212:215], v[16:19]
	v_mfma_f32_16x16x32_bf16 v[8:11], v[164:167], v[212:215], v[8:11]
	s_setprio 0
	s_setprio 1
	v_mfma_f32_16x16x32_bf16 v[52:55], v[168:171], v[184:187], 0
	v_mfma_f32_16x16x32_bf16 v[44:47], v[176:179], v[184:187], 0
	v_mfma_f32_16x16x32_bf16 v[36:39], v[168:171], v[192:195], 0
	v_mfma_f32_16x16x32_bf16 v[28:31], v[176:179], v[192:195], 0
	v_mfma_f32_16x16x32_bf16 v[20:23], v[168:171], v[200:203], 0
	v_mfma_f32_16x16x32_bf16 v[12:15], v[176:179], v[200:203], 0
	v_mfma_f32_16x16x32_bf16 v[4:7], v[168:171], v[208:211], 0
	v_mfma_f32_16x16x32_bf16 v[0:3], v[176:179], v[208:211], 0
	v_mfma_f32_16x16x32_bf16 v[52:55], v[172:175], v[188:191], v[52:55]
	v_mfma_f32_16x16x32_bf16 v[44:47], v[180:183], v[188:191], v[44:47]
	v_mfma_f32_16x16x32_bf16 v[36:39], v[172:175], v[196:199], v[36:39]
	v_mfma_f32_16x16x32_bf16 v[28:31], v[180:183], v[196:199], v[28:31]
	v_mfma_f32_16x16x32_bf16 v[20:23], v[172:175], v[204:207], v[20:23]
	v_mfma_f32_16x16x32_bf16 v[12:15], v[180:183], v[204:207], v[12:15]
	v_mfma_f32_16x16x32_bf16 v[4:7], v[172:175], v[212:215], v[4:7]
	v_mfma_f32_16x16x32_bf16 v[0:3], v[180:183], v[212:215], v[0:3]
	s_setprio 0
	s_barrier
	v_add_u32_e32 v142, s90, v146
	ds_read_b128 v[152:155], v142
	ds_read_b128 v[156:159], v142 offset:1024
	ds_read_b128 v[160:163], v142 offset:2048
	ds_read_b128 v[164:167], v142 offset:3072
	v_add_u32_e32 v142, s89, v146
	ds_read_b128 v[168:171], v142
	ds_read_b128 v[172:175], v142 offset:1024
	ds_read_b128 v[176:179], v142 offset:2048
	ds_read_b128 v[180:183], v142 offset:3072
	s_mov_b32 m0, s47
	v_lshl_add_u64 v[224:225], s[50:51], 0, v[128:129]
	ds_read_b128 v[184:187], v149 offset:32768
	ds_read_b128 v[188:191], v149 offset:33792
	ds_read_b128 v[192:195], v149 offset:34816
	ds_read_b128 v[196:199], v149 offset:35840
	ds_read_b128 v[200:203], v149 offset:36864
	ds_read_b128 v[204:207], v149 offset:37888
	ds_read_b128 v[208:211], v149 offset:38912
	ds_read_b128 v[212:215], v149 offset:39936
	global_load_lds_dwordx4 v[224:225], off
	v_lshl_add_u64 v[224:225], s[50:51], 0, v[132:133]
	s_mov_b32 m0, s60
	s_nop 0
	global_load_lds_dwordx4 v[224:225], off
	s_waitcnt vmcnt(8) lgkmcnt(0)
	s_barrier
	s_setprio 1
	v_mfma_f32_16x16x32_bf16 v[124:127], v[152:155], v[184:187], v[124:127]
	v_mfma_f32_16x16x32_bf16 v[120:123], v[160:163], v[184:187], v[120:123]
	v_mfma_f32_16x16x32_bf16 v[112:115], v[152:155], v[192:195], v[112:115]
	v_mfma_f32_16x16x32_bf16 v[104:107], v[160:163], v[192:195], v[104:107]
	v_mfma_f32_16x16x32_bf16 v[96:99], v[152:155], v[200:203], v[96:99]
	v_mfma_f32_16x16x32_bf16 v[88:91], v[160:163], v[200:203], v[88:91]
	v_mfma_f32_16x16x32_bf16 v[80:83], v[152:155], v[208:211], v[80:83]
	v_mfma_f32_16x16x32_bf16 v[72:75], v[160:163], v[208:211], v[72:75]
	v_mfma_f32_16x16x32_bf16 v[124:127], v[156:159], v[188:191], v[124:127]
	v_mfma_f32_16x16x32_bf16 v[120:123], v[164:167], v[188:191], v[120:123]
	v_mfma_f32_16x16x32_bf16 v[112:115], v[156:159], v[196:199], v[112:115]
	v_mfma_f32_16x16x32_bf16 v[104:107], v[164:167], v[196:199], v[104:107]
	v_mfma_f32_16x16x32_bf16 v[96:99], v[156:159], v[204:207], v[96:99]
	v_mfma_f32_16x16x32_bf16 v[88:91], v[164:167], v[204:207], v[88:91]
	v_mfma_f32_16x16x32_bf16 v[80:83], v[156:159], v[212:215], v[80:83]
	v_mfma_f32_16x16x32_bf16 v[72:75], v[164:167], v[212:215], v[72:75]
	s_setprio 0
	s_setprio 1
	v_mfma_f32_16x16x32_bf16 v[116:119], v[168:171], v[184:187], v[116:119]
	v_mfma_f32_16x16x32_bf16 v[108:111], v[176:179], v[184:187], v[108:111]
	v_mfma_f32_16x16x32_bf16 v[100:103], v[168:171], v[192:195], v[100:103]
	v_mfma_f32_16x16x32_bf16 v[92:95], v[176:179], v[192:195], v[92:95]
	v_mfma_f32_16x16x32_bf16 v[84:87], v[168:171], v[200:203], v[84:87]
	v_mfma_f32_16x16x32_bf16 v[76:79], v[176:179], v[200:203], v[76:79]
	v_mfma_f32_16x16x32_bf16 v[68:71], v[168:171], v[208:211], v[68:71]
	v_mfma_f32_16x16x32_bf16 v[64:67], v[176:179], v[208:211], v[64:67]
	v_mfma_f32_16x16x32_bf16 v[116:119], v[172:175], v[188:191], v[116:119]
	v_mfma_f32_16x16x32_bf16 v[108:111], v[180:183], v[188:191], v[108:111]
	v_mfma_f32_16x16x32_bf16 v[100:103], v[172:175], v[196:199], v[100:103]
	v_mfma_f32_16x16x32_bf16 v[92:95], v[180:183], v[196:199], v[92:95]
	v_mfma_f32_16x16x32_bf16 v[84:87], v[172:175], v[204:207], v[84:87]
	v_mfma_f32_16x16x32_bf16 v[76:79], v[180:183], v[204:207], v[76:79]
	v_mfma_f32_16x16x32_bf16 v[68:71], v[172:175], v[212:215], v[68:71]
	v_mfma_f32_16x16x32_bf16 v[64:67], v[180:183], v[212:215], v[64:67]
	s_setprio 0
	s_barrier
; #define PG8_STAGE(bufoff, gbase, voff) do { _Pragma("unroll") for (int _i = 0; _i < 2; ++_i) \
;         __builtin_amdgcn_global_load_lds((const unsigned*)((const char*)(gbase) + (voff)[_i]), (PG8_LAS unsigned*)(lds + (bufoff) + ldsw + _i * 8192), 16, 0, 0); } while (0)
; #define PG8_LDA(dst, b, h) do { _Pragma("unroll") for (int m = 0; m < 4; ++m) _Pragma("unroll") for (int k = 0; k < 2; ++k) dst[m][k] = *(const PG8_LAS bf16x8*)(lds + PG8_SA(b, h) + aoff + m * 2048 + k * 1024); } while (0)
; #define PG8_LDB(dst, b, h) do { _Pragma("unroll") for (int n = 0; n < 2; ++n) _Pragma("unroll") for (int k = 0; k < 2; ++k) dst[n][k] = *(const PG8_LAS bf16x8*)(lds + PG8_SB(b, h) + boff + n * 2048 + k * 1024); } while (0)
; #define PG8_WAIT_V(n) asm volatile("s_waitcnt vmcnt(" #n ")" ::: "memory")
; template <class Epi, class Sched>
; __device__ __forceinline__ void gemm_phase(PG8_LAS unsigned char* lds, PG8_LAS unsigned char* xl, const Gemm g, const Sched& S, const Epi& E) {
;     ...
;         for (int t = 0; t < nt; t += 2) {
;             const bool last = (t == nt - 2);
;             const char* a1 = cA + (size_t)(t + 1) * kstep;
;             const char* a2 = last ? nA : cA + (size_t)(t + 2) * kstep; const char* b2 = last ? nB : cB + (size_t)(t + 2) * kstep;
;             const char* a3 = a2 + kstep; const char* b3 = b2 + kstep;
;             PG8_LDB(B0, 0, 0); PG8_LDB(B1, 0, 1); PG8_SCHED; PG8_LDA(At, 0, 0); PG8_STAGE(PG8_SA(1, 1), a1 + hsA, voffA);
;             PG8_WAIT_V(8); PG8_WAIT_L(0); PG8_BAR; PG8_MMA(0, 0, At, B0); PG8_MMA(0, 1, At, B1); PG8_BAR; PG8_SCHED;
;             PG8_LDA(At, 0, 1); PG8_STAGE(PG8_SB(0, 0), b2, voffB); PG8_STAGE(PG8_SB(0, 1), b2 + hsB, voffB); PG8_STAGE(PG8_SA(0, 0), a2, voffA);
;             PG8_WAIT_V(8); PG8_WAIT_L(0); PG8_BAR; PG8_MMA(1, 0, At, B0); PG8_MMA(1, 1, At, B1); PG8_BAR; PG8_SCHED;
;             PG8_LDB(B0, 1, 0); PG8_LDB(B1, 1, 1); PG8_SCHED; PG8_LDA(At, 1, 0); PG8_STAGE(PG8_SA(0, 1), a2 + hsA, voffA);
;             PG8_WAIT_V(8); PG8_WAIT_L(0); PG8_BAR; PG8_MMA(0, 0, At, B0); PG8_MMA(0, 1, At, B1); PG8_BAR; PG8_SCHED;
;             PG8_LDA(At, 1, 1); PG8_STAGE(PG8_SB(1, 0), b3, voffB); PG8_STAGE(PG8_SB(1, 1), b3 + hsB, voffB); PG8_STAGE(PG8_SA(1, 0), a3, voffA);
;             PG8_WAIT_V(8); PG8_WAIT_L(0); PG8_BAR; PG8_MMA(1, 0, At, B0); PG8_MMA(1, 1, At, B1); PG8_BAR; PG8_SCHED;
	s_mov_b32 m0, s88
	v_lshl_add_u64 v[144:145], v[144:145], 0, s[10:11]
	ds_read_b128 v[184:187], v149 offset:49152
	ds_read_b128 v[188:191], v149 offset:50176
	ds_read_b128 v[192:195], v149 offset:51200
	ds_read_b128 v[196:199], v149 offset:52224
	ds_read_b128 v[200:203], v149 offset:53248
	ds_read_b128 v[204:207], v149 offset:54272
	ds_read_b128 v[208:211], v149 offset:55296
	ds_read_b128 v[212:215], v149 offset:56320
	global_load_lds_dwordx4 v[144:145], off
	v_lshl_add_u64 v[144:145], v[216:217], 0, s[10:11]
	s_mov_b32 m0, s86
	s_nop 0
	global_load_lds_dwordx4 v[144:145], off
	v_lshl_add_u64 v[144:145], s[36:37], 0, v[130:131]
	s_mov_b32 m0, s87
	s_nop 0
	global_load_lds_dwordx4 v[144:145], off
	v_lshl_add_u64 v[144:145], s[36:37], 0, v[134:135]
	s_mov_b32 m0, s68
	s_nop 0
	global_load_lds_dwordx4 v[144:145], off
	v_lshl_add_u64 v[144:145], v[218:219], 0, s[10:11]
	s_mov_b32 m0, s65
	s_nop 0
	global_load_lds_dwordx4 v[144:145], off
	v_lshl_add_u64 v[144:145], v[222:223], 0, s[10:11]
	s_mov_b32 m0, s66
	s_nop 0
	global_load_lds_dwordx4 v[144:145], off
	s_waitcnt vmcnt(8) lgkmcnt(0)
	s_barrier
	s_setprio 1
	v_mfma_f32_16x16x32_bf16 v[60:63], v[152:155], v[184:187], v[60:63]
	v_mfma_f32_16x16x32_bf16 v[56:59], v[160:163], v[184:187], v[56:59]
	v_mfma_f32_16x16x32_bf16 v[48:51], v[152:155], v[192:195], v[48:51]
	v_mfma_f32_16x16x32_bf16 v[40:43], v[160:163], v[192:195], v[40:43]
	v_mfma_f32_16x16x32_bf16 v[32:35], v[152:155], v[200:203], v[32:35]
	v_mfma_f32_16x16x32_bf16 v[24:27], v[160:163], v[200:203], v[24:27]
	v_mfma_f32_16x16x32_bf16 v[16:19], v[152:155], v[208:211], v[16:19]
	v_mfma_f32_16x16x32_bf16 v[8:11], v[160:163], v[208:211], v[8:11]
	v_mfma_f32_16x16x32_bf16 v[60:63], v[156:159], v[188:191], v[60:63]
	v_mfma_f32_16x16x32_bf16 v[56:59], v[164:167], v[188:191], v[56:59]
	v_mfma_f32_16x16x32_bf16 v[48:51], v[156:159], v[196:199], v[48:51]
	v_mfma_f32_16x16x32_bf16 v[40:43], v[164:167], v[196:199], v[40:43]
	v_mfma_f32_16x16x32_bf16 v[32:35], v[156:159], v[204:207], v[32:35]
	v_mfma_f32_16x16x32_bf16 v[24:27], v[164:167], v[204:207], v[24:27]
	v_mfma_f32_16x16x32_bf16 v[16:19], v[156:159], v[212:215], v[16:19]
	v_mfma_f32_16x16x32_bf16 v[8:11], v[164:167], v[212:215], v[8:11]
	s_setprio 0
	s_setprio 1
	v_mfma_f32_16x16x32_bf16 v[52:55], v[168:171], v[184:187], v[52:55]
	v_mfma_f32_16x16x32_bf16 v[44:47], v[176:179], v[184:187], v[44:47]
	v_mfma_f32_16x16x32_bf16 v[36:39], v[168:171], v[192:195], v[36:39]
	v_mfma_f32_16x16x32_bf16 v[28:31], v[176:179], v[192:195], v[28:31]
	v_mfma_f32_16x16x32_bf16 v[20:23], v[168:171], v[200:203], v[20:23]
	v_mfma_f32_16x16x32_bf16 v[12:15], v[176:179], v[200:203], v[12:15]
	v_mfma_f32_16x16x32_bf16 v[4:7], v[168:171], v[208:211], v[4:7]
	v_mfma_f32_16x16x32_bf16 v[0:3], v[176:179], v[208:211], v[0:3]
	v_mfma_f32_16x16x32_bf16 v[52:55], v[172:175], v[188:191], v[52:55]
	v_mfma_f32_16x16x32_bf16 v[44:47], v[180:183], v[188:191], v[44:47]
	v_mfma_f32_16x16x32_bf16 v[36:39], v[172:175], v[196:199], v[36:39]
	v_mfma_f32_16x16x32_bf16 v[28:31], v[180:183], v[196:199], v[28:31]
	v_mfma_f32_16x16x32_bf16 v[20:23], v[172:175], v[204:207], v[20:23]
	v_mfma_f32_16x16x32_bf16 v[12:15], v[180:183], v[204:207], v[12:15]
	v_mfma_f32_16x16x32_bf16 v[4:7], v[172:175], v[212:215], v[4:7]
	v_mfma_f32_16x16x32_bf16 v[0:3], v[180:183], v[212:215], v[0:3]
	s_setprio 0
	s_barrier
	s_andn2_b64 vcc, exec, s[34:35]
	s_mov_b64 s[36:37], -1
	s_mov_b64 s[34:35], 0
	s_mov_b64 s[50:51], 0x100
	s_cbranch_vccnz .Lpeel_after_PX
.LBB0_377:
	s_add_u32 s56, s30, s50
	s_addc_u32 s57, s31, s51
	s_add_u32 s54, s56, 0x100
	s_addc_u32 s55, s57, 0
	s_and_b64 s[52:53], s[36:37], exec
	s_cselect_b32 s53, s82, s55
	s_cselect_b32 s52, s83, s54
	s_add_u32 s50, s28, s50
	s_addc_u32 s51, s29, s51
	s_add_u32 s50, s50, 0x100
	s_addc_u32 s51, s51, 0
	s_and_b64 s[36:37], s[36:37], exec
	s_cselect_b32 s55, s84, s51
	s_cselect_b32 s54, s85, s50
	s_add_u32 s58, s56, 0x80080
	ds_read_b128 v[152:155], v147
	ds_read_b128 v[156:159], v147 offset:1024
	ds_read_b128 v[160:163], v147 offset:2048
	ds_read_b128 v[164:167], v147 offset:3072
	ds_read_b128 v[168:171], v148
	ds_read_b128 v[172:175], v148 offset:1024
	ds_read_b128 v[176:179], v148 offset:2048
	ds_read_b128 v[180:183], v148 offset:3072
	s_addc_u32 s59, s57, 0
	s_add_i32 s94, s73, s33
	s_add_i32 m0, s43, 0xc000
	s_add_i32 s95, s43, 0xe000
	s_add_i32 s91, s94, 0x2000
	s_add_u32 s56, s54, 0x80000
	s_addc_u32 s57, s55, 0
	s_add_i32 s93, s74, s33
	s_add_i32 s92, s93, 0x2000
	s_add_i32 s90, 0, 0x18000
	s_add_i32 s89, 0, 0x1c000
	s_add_u32 s50, s52, 0x80000
	s_addc_u32 s51, s53, 0
	s_add_i32 s88, s90, s33
	s_add_i32 s86, s88, 0x2000
	s_add_u32 s36, s54, 0x80080
	s_addc_u32 s37, s55, 0
	s_add_i32 s87, s89, s33
	s_add_i32 s68, s87, 0x2000
	v_lshl_add_u64 v[144:145], s[58:59], 0, v[128:129]
	ds_read_b128 v[184:187], v149
	ds_read_b128 v[188:191], v149 offset:1024
	ds_read_b128 v[192:195], v149 offset:2048
	ds_read_b128 v[196:199], v149 offset:3072
	ds_read_b128 v[200:203], v149 offset:4096
	ds_read_b128 v[204:207], v149 offset:5120
	ds_read_b128 v[208:211], v149 offset:6144
	ds_read_b128 v[212:215], v149 offset:7168
	global_load_lds_dwordx4 v[144:145], off
	v_lshl_add_u64 v[144:145], s[58:59], 0, v[132:133]
	s_mov_b32 m0, s95
	s_nop 0
	global_load_lds_dwordx4 v[144:145], off
	s_waitcnt vmcnt(8) lgkmcnt(0)
	s_barrier
; #define PG8_STAGE(bufoff, gbase, voff) do { _Pragma("unroll") for (int _i = 0; _i < 2; ++_i) \
;         __builtin_amdgcn_global_load_lds((const unsigned*)((const char*)(gbase) + (voff)[_i]), (PG8_LAS unsigned*)(lds + (bufoff) + ldsw + _i * 8192), 16, 0, 0); } while (0)
; #define PG8_LDA(dst, b, h) do { _Pragma("unroll") for (int m = 0; m < 4; ++m) _Pragma("unroll") for (int k = 0; k < 2; ++k) dst[m][k] = *(const PG8_LAS bf16x8*)(lds + PG8_SA(b, h) + aoff + m * 2048 + k * 1024); } while (0)
; #define PG8_MMA(ai, bj, At, Bt) do { __builtin_amdgcn_s_setprio(1); _Pragma("unroll") for (int m = 0; m < 4; ++m) _Pragma("unroll") for (int n = 0; n < 2; ++n) _Pragma("unroll") for (int k = 0; k < 2; ++k) \
;         acc[ai][bj][m][n] = __builtin_amdgcn_mfma_f32_16x16x32_bf16(Bt[n][k], At[m][k], acc[ai][bj][m][n], 0, 0, 0); __builtin_amdgcn_s_setprio(0); } while (0)
; #define PG8_WAIT_V(n) asm volatile("s_waitcnt vmcnt(" #n ")" ::: "memory")
; #define PG8_WAIT_L(n) asm volatile("s_waitcnt lgkmcnt(" #n ")" ::: "memory")
; #define PG8_BAR __builtin_amdgcn_s_barrier()
; #define PG8_SCHED __builtin_amdgcn_sched_barrier(0)
; template <class Epi, class Sched>
; __device__ __forceinline__ void gemm_phase(PG8_LAS unsigned char* lds, PG8_LAS unsigned char* xl, const Gemm g, const Sched& S, const Epi& E) {
;     ...
;             PG8_WAIT_V(8); PG8_WAIT_L(0); PG8_BAR; PG8_MMA(0, 0, At, B0); PG8_MMA(0, 1, At, B1); PG8_BAR; PG8_SCHED;
;             PG8_LDA(At, 0, 1); PG8_STAGE(PG8_SB(0, 0), b2, voffB); PG8_STAGE(PG8_SB(0, 1), b2 + hsB, voffB); PG8_STAGE(PG8_SA(0, 0), a2, voffA);
;             PG8_WAIT_V(8); PG8_WAIT_L(0); PG8_BAR; PG8_MMA(1, 0, At, B0); PG8_MMA(1, 1, At, B1); PG8_BAR; PG8_SCHED;
	s_setprio 1
	v_mfma_f32_16x16x32_bf16 v[124:127], v[152:155], v[184:187], v[124:127]
	v_mfma_f32_16x16x32_bf16 v[120:123], v[160:163], v[184:187], v[120:123]
	v_mfma_f32_16x16x32_bf16 v[112:115], v[152:155], v[192:195], v[112:115]
	v_mfma_f32_16x16x32_bf16 v[104:107], v[160:163], v[192:195], v[104:107]
	v_mfma_f32_16x16x32_bf16 v[96:99], v[152:155], v[200:203], v[96:99]
	v_mfma_f32_16x16x32_bf16 v[88:91], v[160:163], v[200:203], v[88:91]
	v_mfma_f32_16x16x32_bf16 v[80:83], v[152:155], v[208:211], v[80:83]
	v_mfma_f32_16x16x32_bf16 v[72:75], v[160:163], v[208:211], v[72:75]
	v_mfma_f32_16x16x32_bf16 v[124:127], v[156:159], v[188:191], v[124:127]
	v_mfma_f32_16x16x32_bf16 v[120:123], v[164:167], v[188:191], v[120:123]
	v_mfma_f32_16x16x32_bf16 v[112:115], v[156:159], v[196:199], v[112:115]
	v_mfma_f32_16x16x32_bf16 v[104:107], v[164:167], v[196:199], v[104:107]
	v_mfma_f32_16x16x32_bf16 v[96:99], v[156:159], v[204:207], v[96:99]
	v_mfma_f32_16x16x32_bf16 v[88:91], v[164:167], v[204:207], v[88:91]
	v_mfma_f32_16x16x32_bf16 v[80:83], v[156:159], v[212:215], v[80:83]
	v_mfma_f32_16x16x32_bf16 v[72:75], v[164:167], v[212:215], v[72:75]
	s_setprio 0
	s_setprio 1
	v_mfma_f32_16x16x32_bf16 v[116:119], v[168:171], v[184:187], v[116:119]
	v_mfma_f32_16x16x32_bf16 v[108:111], v[176:179], v[184:187], v[108:111]
	v_mfma_f32_16x16x32_bf16 v[100:103], v[168:171], v[192:195], v[100:103]
	v_mfma_f32_16x16x32_bf16 v[92:95], v[176:179], v[192:195], v[92:95]
	v_mfma_f32_16x16x32_bf16 v[84:87], v[168:171], v[200:203], v[84:87]
	v_mfma_f32_16x16x32_bf16 v[76:79], v[176:179], v[200:203], v[76:79]
	v_mfma_f32_16x16x32_bf16 v[68:71], v[168:171], v[208:211], v[68:71]
	v_mfma_f32_16x16x32_bf16 v[64:67], v[176:179], v[208:211], v[64:67]
	v_mfma_f32_16x16x32_bf16 v[116:119], v[172:175], v[188:191], v[116:119]
	v_mfma_f32_16x16x32_bf16 v[108:111], v[180:183], v[188:191], v[108:111]
	v_mfma_f32_16x16x32_bf16 v[100:103], v[172:175], v[196:199], v[100:103]
	v_mfma_f32_16x16x32_bf16 v[92:95], v[180:183], v[196:199], v[92:95]
	v_mfma_f32_16x16x32_bf16 v[84:87], v[172:175], v[204:207], v[84:87]
	v_mfma_f32_16x16x32_bf16 v[76:79], v[180:183], v[204:207], v[76:79]
	v_mfma_f32_16x16x32_bf16 v[68:71], v[172:175], v[212:215], v[68:71]
	v_mfma_f32_16x16x32_bf16 v[64:67], v[180:183], v[212:215], v[64:67]
	s_setprio 0
	s_barrier
	s_mov_b32 m0, s94
	v_lshl_add_u64 v[144:145], s[54:55], 0, v[130:131]
	ds_read_b128 v[184:187], v149 offset:16384
	ds_read_b128 v[188:191], v149 offset:17408
	ds_read_b128 v[192:195], v149 offset:18432
	ds_read_b128 v[196:199], v149 offset:19456
	ds_read_b128 v[200:203], v149 offset:20480
	ds_read_b128 v[204:207], v149 offset:21504
	ds_read_b128 v[208:211], v149 offset:22528
	ds_read_b128 v[212:215], v149 offset:23552
	global_load_lds_dwordx4 v[144:145], off
	v_lshl_add_u64 v[216:217], s[54:55], 0, v[134:135]
	s_mov_b32 m0, s91
	v_lshl_add_u64 v[218:219], s[56:57], 0, v[130:131]
	global_load_lds_dwordx4 v[216:217], off
	s_mov_b32 m0, s93
	v_lshl_add_u64 v[222:223], s[52:53], 0, v[132:133]
	global_load_lds_dwordx4 v[218:219], off
	v_lshl_add_u64 v[218:219], s[56:57], 0, v[134:135]
	s_mov_b32 m0, s92
	s_nop 0
	global_load_lds_dwordx4 v[218:219], off
	v_lshl_add_u64 v[218:219], s[52:53], 0, v[128:129]
	s_mov_b32 m0, s43
	s_nop 0
	global_load_lds_dwordx4 v[218:219], off
	s_mov_b32 m0, s46
	s_nop 0
	global_load_lds_dwordx4 v[222:223], off
	s_waitcnt vmcnt(8) lgkmcnt(0)
	s_barrier
	s_setprio 1
	v_mfma_f32_16x16x32_bf16 v[60:63], v[152:155], v[184:187], v[60:63]
	v_mfma_f32_16x16x32_bf16 v[56:59], v[160:163], v[184:187], v[56:59]
	v_mfma_f32_16x16x32_bf16 v[48:51], v[152:155], v[192:195], v[48:51]
	v_mfma_f32_16x16x32_bf16 v[40:43], v[160:163], v[192:195], v[40:43]
	v_mfma_f32_16x16x32_bf16 v[32:35], v[152:155], v[200:203], v[32:35]
	v_mfma_f32_16x16x32_bf16 v[24:27], v[160:163], v[200:203], v[24:27]
	v_mfma_f32_16x16x32_bf16 v[16:19], v[152:155], v[208:211], v[16:19]
	v_mfma_f32_16x16x32_bf16 v[8:11], v[160:163], v[208:211], v[8:11]
	v_mfma_f32_16x16x32_bf16 v[60:63], v[156:159], v[188:191], v[60:63]
	v_mfma_f32_16x16x32_bf16 v[56:59], v[164:167], v[188:191], v[56:59]
	v_mfma_f32_16x16x32_bf16 v[48:51], v[156:159], v[196:199], v[48:51]
	v_mfma_f32_16x16x32_bf16 v[40:43], v[164:167], v[196:199], v[40:43]
	v_mfma_f32_16x16x32_bf16 v[32:35], v[156:159], v[204:207], v[32:35]
	v_mfma_f32_16x16x32_bf16 v[24:27], v[164:167], v[204:207], v[24:27]
	v_mfma_f32_16x16x32_bf16 v[16:19], v[156:159], v[212:215], v[16:19]
	v_mfma_f32_16x16x32_bf16 v[8:11], v[164:167], v[212:215], v[8:11]
	s_setprio 0
	s_setprio 1
	v_mfma_f32_16x16x32_bf16 v[52:55], v[168:171], v[184:187], v[52:55]
	v_mfma_f32_16x16x32_bf16 v[44:47], v[176:179], v[184:187], v[44:47]
	v_mfma_f32_16x16x32_bf16 v[36:39], v[168:171], v[192:195], v[36:39]
	v_mfma_f32_16x16x32_bf16 v[28:31], v[176:179], v[192:195], v[28:31]
	v_mfma_f32_16x16x32_bf16 v[20:23], v[168:171], v[200:203], v[20:23]
	v_mfma_f32_16x16x32_bf16 v[12:15], v[176:179], v[200:203], v[12:15]
	v_mfma_f32_16x16x32_bf16 v[4:7], v[168:171], v[208:211], v[4:7]
	v_mfma_f32_16x16x32_bf16 v[0:3], v[176:179], v[208:211], v[0:3]
	v_mfma_f32_16x16x32_bf16 v[52:55], v[172:175], v[188:191], v[52:55]
	v_mfma_f32_16x16x32_bf16 v[44:47], v[180:183], v[188:191], v[44:47]
	v_mfma_f32_16x16x32_bf16 v[36:39], v[172:175], v[196:199], v[36:39]
	v_mfma_f32_16x16x32_bf16 v[28:31], v[180:183], v[196:199], v[28:31]
	v_mfma_f32_16x16x32_bf16 v[20:23], v[172:175], v[204:207], v[20:23]
	v_mfma_f32_16x16x32_bf16 v[12:15], v[180:183], v[204:207], v[12:15]
	v_mfma_f32_16x16x32_bf16 v[4:7], v[172:175], v[212:215], v[4:7]
	v_mfma_f32_16x16x32_bf16 v[0:3], v[180:183], v[212:215], v[0:3]
	s_setprio 0
	s_barrier
; #define PG8_STAGE(bufoff, gbase, voff) do { _Pragma("unroll") for (int _i = 0; _i < 2; ++_i) \
;         __builtin_amdgcn_global_load_lds((const unsigned*)((const char*)(gbase) + (voff)[_i]), (PG8_LAS unsigned*)(lds + (bufoff) + ldsw + _i * 8192), 16, 0, 0); } while (0)
; #define PG8_LDA(dst, b, h) do { _Pragma("unroll") for (int m = 0; m < 4; ++m) _Pragma("unroll") for (int k = 0; k < 2; ++k) dst[m][k] = *(const PG8_LAS bf16x8*)(lds + PG8_SA(b, h) + aoff + m * 2048 + k * 1024); } while (0)
; #define PG8_LDB(dst, b, h) do { _Pragma("unroll") for (int n = 0; n < 2; ++n) _Pragma("unroll") for (int k = 0; k < 2; ++k) dst[n][k] = *(const PG8_LAS bf16x8*)(lds + PG8_SB(b, h) + boff + n * 2048 + k * 1024); } while (0)
; #define PG8_MMA(ai, bj, At, Bt) do { __builtin_amdgcn_s_setprio(1); _Pragma("unroll") for (int m = 0; m < 4; ++m) _Pragma("unroll") for (int n = 0; n < 2; ++n) _Pragma("unroll") for (int k = 0; k < 2; ++k) \
;         acc[ai][bj][m][n] = __builtin_amdgcn_mfma_f32_16x16x32_bf16(Bt[n][k], At[m][k], acc[ai][bj][m][n], 0, 0, 0); __builtin_amdgcn_s_setprio(0); } while (0)
; #define PG8_WAIT_V(n) asm volatile("s_waitcnt vmcnt(" #n ")" ::: "memory")
; #define PG8_WAIT_L(n) asm volatile("s_waitcnt lgkmcnt(" #n ")" ::: "memory")
; #define PG8_BAR __builtin_amdgcn_s_barrier()
; #define PG8_SCHED __builtin_amdgcn_sched_barrier(0)
; template <class Epi, class Sched>
; __device__ __forceinline__ void gemm_phase(PG8_LAS unsigned char* lds, PG8_LAS unsigned char* xl, const Gemm g, const Sched& S, const Epi& E) {
;     ...
;             PG8_LDB(B0, 1, 0); PG8_LDB(B1, 1, 1); PG8_SCHED; PG8_LDA(At, 1, 0); PG8_STAGE(PG8_SA(0, 1), a2 + hsA, voffA);
;             PG8_WAIT_V(8); PG8_WAIT_L(0); PG8_BAR; PG8_MMA(0, 0, At, B0); PG8_MMA(0, 1, At, B1); PG8_BAR; PG8_SCHED;
;             PG8_LDA(At, 1, 1); PG8_STAGE(PG8_SB(1, 0), b3, voffB); PG8_STAGE(PG8_SB(1, 1), b3 + hsB, voffB); PG8_STAGE(PG8_SA(1, 0), a3, voffA);
;             PG8_WAIT_V(8); PG8_WAIT_L(0); PG8_BAR; PG8_MMA(1, 0, At, B0); PG8_MMA(1, 1, At, B1); PG8_BAR; PG8_SCHED;
	v_add_u32_e32 v142, s90, v146
	ds_read_b128 v[152:155], v142
	ds_read_b128 v[156:159], v142 offset:1024
	ds_read_b128 v[160:163], v142 offset:2048
	ds_read_b128 v[164:167], v142 offset:3072
	v_add_u32_e32 v142, s89, v146
	ds_read_b128 v[168:171], v142
	ds_read_b128 v[172:175], v142 offset:1024
	ds_read_b128 v[176:179], v142 offset:2048
	ds_read_b128 v[180:183], v142 offset:3072
	s_mov_b32 m0, s47
	v_lshl_add_u64 v[224:225], s[50:51], 0, v[128:129]
	ds_read_b128 v[184:187], v149 offset:32768
	ds_read_b128 v[188:191], v149 offset:33792
	ds_read_b128 v[192:195], v149 offset:34816
	ds_read_b128 v[196:199], v149 offset:35840
	ds_read_b128 v[200:203], v149 offset:36864
	ds_read_b128 v[204:207], v149 offset:37888
	ds_read_b128 v[208:211], v149 offset:38912
	ds_read_b128 v[212:215], v149 offset:39936
	global_load_lds_dwordx4 v[224:225], off
	v_lshl_add_u64 v[224:225], s[50:51], 0, v[132:133]
	s_mov_b32 m0, s60
	s_nop 0
	global_load_lds_dwordx4 v[224:225], off
	s_waitcnt vmcnt(8) lgkmcnt(0)
	s_barrier
	s_setprio 1
	v_mfma_f32_16x16x32_bf16 v[124:127], v[152:155], v[184:187], v[124:127]
	v_mfma_f32_16x16x32_bf16 v[120:123], v[160:163], v[184:187], v[120:123]
	v_mfma_f32_16x16x32_bf16 v[112:115], v[152:155], v[192:195], v[112:115]
	v_mfma_f32_16x16x32_bf16 v[104:107], v[160:163], v[192:195], v[104:107]
	v_mfma_f32_16x16x32_bf16 v[96:99], v[152:155], v[200:203], v[96:99]
	v_mfma_f32_16x16x32_bf16 v[88:91], v[160:163], v[200:203], v[88:91]
	v_mfma_f32_16x16x32_bf16 v[80:83], v[152:155], v[208:211], v[80:83]
	v_mfma_f32_16x16x32_bf16 v[72:75], v[160:163], v[208:211], v[72:75]
	v_mfma_f32_16x16x32_bf16 v[124:127], v[156:159], v[188:191], v[124:127]
	v_mfma_f32_16x16x32_bf16 v[120:123], v[164:167], v[188:191], v[120:123]
	v_mfma_f32_16x16x32_bf16 v[112:115], v[156:159], v[196:199], v[112:115]
	v_mfma_f32_16x16x32_bf16 v[104:107], v[164:167], v[196:199], v[104:107]
	v_mfma_f32_16x16x32_bf16 v[96:99], v[156:159], v[204:207], v[96:99]
	v_mfma_f32_16x16x32_bf16 v[88:91], v[164:167], v[204:207], v[88:91]
	v_mfma_f32_16x16x32_bf16 v[80:83], v[156:159], v[212:215], v[80:83]
	v_mfma_f32_16x16x32_bf16 v[72:75], v[164:167], v[212:215], v[72:75]
	s_setprio 0
	s_setprio 1
	v_mfma_f32_16x16x32_bf16 v[116:119], v[168:171], v[184:187], v[116:119]
	v_mfma_f32_16x16x32_bf16 v[108:111], v[176:179], v[184:187], v[108:111]
	v_mfma_f32_16x16x32_bf16 v[100:103], v[168:171], v[192:195], v[100:103]
	v_mfma_f32_16x16x32_bf16 v[92:95], v[176:179], v[192:195], v[92:95]
	v_mfma_f32_16x16x32_bf16 v[84:87], v[168:171], v[200:203], v[84:87]
	v_mfma_f32_16x16x32_bf16 v[76:79], v[176:179], v[200:203], v[76:79]
	v_mfma_f32_16x16x32_bf16 v[68:71], v[168:171], v[208:211], v[68:71]
	v_mfma_f32_16x16x32_bf16 v[64:67], v[176:179], v[208:211], v[64:67]
	v_mfma_f32_16x16x32_bf16 v[116:119], v[172:175], v[188:191], v[116:119]
	v_mfma_f32_16x16x32_bf16 v[108:111], v[180:183], v[188:191], v[108:111]
	v_mfma_f32_16x16x32_bf16 v[100:103], v[172:175], v[196:199], v[100:103]
	v_mfma_f32_16x16x32_bf16 v[92:95], v[180:183], v[196:199], v[92:95]
	v_mfma_f32_16x16x32_bf16 v[84:87], v[172:175], v[204:207], v[84:87]
	v_mfma_f32_16x16x32_bf16 v[76:79], v[180:183], v[204:207], v[76:79]
	v_mfma_f32_16x16x32_bf16 v[68:71], v[172:175], v[212:215], v[68:71]
	v_mfma_f32_16x16x32_bf16 v[64:67], v[180:183], v[212:215], v[64:67]
	s_setprio 0
	s_barrier
	s_mov_b32 m0, s88
	v_lshl_add_u64 v[144:145], v[144:145], 0, s[10:11]
	ds_read_b128 v[184:187], v149 offset:49152
	ds_read_b128 v[188:191], v149 offset:50176
	ds_read_b128 v[192:195], v149 offset:51200
	ds_read_b128 v[196:199], v149 offset:52224
	ds_read_b128 v[200:203], v149 offset:53248
	ds_read_b128 v[204:207], v149 offset:54272
	ds_read_b128 v[208:211], v149 offset:55296
	ds_read_b128 v[212:215], v149 offset:56320
	global_load_lds_dwordx4 v[144:145], off
	v_lshl_add_u64 v[144:145], v[216:217], 0, s[10:11]
	s_mov_b32 m0, s86
	s_nop 0
	global_load_lds_dwordx4 v[144:145], off
	v_lshl_add_u64 v[144:145], s[36:37], 0, v[130:131]
	s_mov_b32 m0, s87
	s_nop 0
	global_load_lds_dwordx4 v[144:145], off
	v_lshl_add_u64 v[144:145], s[36:37], 0, v[134:135]
	s_mov_b32 m0, s68
	s_nop 0
	global_load_lds_dwordx4 v[144:145], off
	v_lshl_add_u64 v[144:145], v[218:219], 0, s[10:11]
	s_mov_b32 m0, s65
	s_nop 0
	global_load_lds_dwordx4 v[144:145], off
	v_lshl_add_u64 v[144:145], v[222:223], 0, s[10:11]
	s_mov_b32 m0, s66
	s_nop 0
	global_load_lds_dwordx4 v[144:145], off
	s_waitcnt vmcnt(8) lgkmcnt(0)
	s_barrier
	s_setprio 1
	v_mfma_f32_16x16x32_bf16 v[60:63], v[152:155], v[184:187], v[60:63]
	v_mfma_f32_16x16x32_bf16 v[56:59], v[160:163], v[184:187], v[56:59]
	v_mfma_f32_16x16x32_bf16 v[48:51], v[152:155], v[192:195], v[48:51]
	v_mfma_f32_16x16x32_bf16 v[40:43], v[160:163], v[192:195], v[40:43]
	v_mfma_f32_16x16x32_bf16 v[32:35], v[152:155], v[200:203], v[32:35]
	v_mfma_f32_16x16x32_bf16 v[24:27], v[160:163], v[200:203], v[24:27]
	v_mfma_f32_16x16x32_bf16 v[16:19], v[152:155], v[208:211], v[16:19]
	v_mfma_f32_16x16x32_bf16 v[8:11], v[160:163], v[208:211], v[8:11]
	v_mfma_f32_16x16x32_bf16 v[60:63], v[156:159], v[188:191], v[60:63]
	v_mfma_f32_16x16x32_bf16 v[56:59], v[164:167], v[188:191], v[56:59]
	v_mfma_f32_16x16x32_bf16 v[48:51], v[156:159], v[196:199], v[48:51]
	v_mfma_f32_16x16x32_bf16 v[40:43], v[164:167], v[196:199], v[40:43]
	v_mfma_f32_16x16x32_bf16 v[32:35], v[156:159], v[204:207], v[32:35]
	v_mfma_f32_16x16x32_bf16 v[24:27], v[164:167], v[204:207], v[24:27]
	v_mfma_f32_16x16x32_bf16 v[16:19], v[156:159], v[212:215], v[16:19]
	v_mfma_f32_16x16x32_bf16 v[8:11], v[164:167], v[212:215], v[8:11]
	s_setprio 0
	s_setprio 1
	v_mfma_f32_16x16x32_bf16 v[52:55], v[168:171], v[184:187], v[52:55]
	v_mfma_f32_16x16x32_bf16 v[44:47], v[176:179], v[184:187], v[44:47]
	v_mfma_f32_16x16x32_bf16 v[36:39], v[168:171], v[192:195], v[36:39]
	v_mfma_f32_16x16x32_bf16 v[28:31], v[176:179], v[192:195], v[28:31]
	v_mfma_f32_16x16x32_bf16 v[20:23], v[168:171], v[200:203], v[20:23]
	v_mfma_f32_16x16x32_bf16 v[12:15], v[176:179], v[200:203], v[12:15]
	v_mfma_f32_16x16x32_bf16 v[4:7], v[168:171], v[208:211], v[4:7]
	v_mfma_f32_16x16x32_bf16 v[0:3], v[176:179], v[208:211], v[0:3]
	v_mfma_f32_16x16x32_bf16 v[52:55], v[172:175], v[188:191], v[52:55]
	v_mfma_f32_16x16x32_bf16 v[44:47], v[180:183], v[188:191], v[44:47]
	v_mfma_f32_16x16x32_bf16 v[36:39], v[172:175], v[196:199], v[36:39]
	v_mfma_f32_16x16x32_bf16 v[28:31], v[180:183], v[196:199], v[28:31]
	v_mfma_f32_16x16x32_bf16 v[20:23], v[172:175], v[204:207], v[20:23]
	v_mfma_f32_16x16x32_bf16 v[12:15], v[180:183], v[204:207], v[12:15]
	v_mfma_f32_16x16x32_bf16 v[4:7], v[172:175], v[212:215], v[4:7]
	v_mfma_f32_16x16x32_bf16 v[0:3], v[180:183], v[212:215], v[0:3]
	s_setprio 0
	s_barrier
	s_andn2_b64 vcc, exec, s[34:35]
	s_mov_b64 s[36:37], -1
	s_mov_b64 s[34:35], 0
	s_mov_b64 s[50:51], 0x100
	s_cbranch_vccz .LBB0_377

; #define PG8_STAGE(bufoff, gbase, voff) do { _Pragma("unroll") for (int _i = 0; _i < 2; ++_i) \
;         __builtin_amdgcn_global_load_lds((const unsigned*)((const char*)(gbase) + (voff)[_i]), (PG8_LAS unsigned*)(lds + (bufoff) + ldsw + _i * 8192), 16, 0, 0); } while (0)
; #define PG8_LDA(dst, b, h) do { _Pragma("unroll") for (int m = 0; m < 4; ++m) _Pragma("unroll") for (int k = 0; k < 2; ++k) dst[m][k] = *(const PG8_LAS bf16x8*)(lds + PG8_SA(b, h) + aoff + m * 2048 + k * 1024); } while (0)
; #define PG8_LDB(dst, b, h) do { _Pragma("unroll") for (int n = 0; n < 2; ++n) _Pragma("unroll") for (int k = 0; k < 2; ++k) dst[n][k] = *(const PG8_LAS bf16x8*)(lds + PG8_SB(b, h) + boff + n * 2048 + k * 1024); } while (0)
; #define PG8_MMA(ai, bj, At, Bt) do { __builtin_amdgcn_s_setprio(1); _Pragma("unroll") for (int m = 0; m < 4; ++m) _Pragma("unroll") for (int n = 0; n < 2; ++n) _Pragma("unroll") for (int k = 0; k < 2; ++k) \
;         acc[ai][bj][m][n] = __builtin_amdgcn_mfma_f32_16x16x32_bf16(Bt[n][k], At[m][k], acc[ai][bj][m][n], 0, 0, 0); __builtin_amdgcn_s_setprio(0); } while (0)
; #define PG8_WAIT_V(n) asm volatile("s_waitcnt vmcnt(" #n ")" ::: "memory")
; #define PG8_WAIT_L(n) asm volatile("s_waitcnt lgkmcnt(" #n ")" ::: "memory")
; #define PG8_BAR __builtin_amdgcn_s_barrier()
; template <class Epi, class Sched>
; __device__ __forceinline__ void gemm_phase(PG8_LAS unsigned char* lds, PG8_LAS unsigned char* xl, const Gemm g, const Sched& S, const Epi& E) {
;     ...
;         const char* nA = has_next ? (const char*)g.A + nxt.aoff : cA; const char* nB = has_next ? (const char*)g.Bt + nxt.boff : cB;
; #pragma unroll 1
;         for (int t = 0; t < nt; t += 2) {
;             const bool last = (t == nt - 2);
;             const char* a1 = cA + (size_t)(t + 1) * kstep;
;             const char* a2 = last ? nA : cA + (size_t)(t + 2) * kstep; const char* b2 = last ? nB : cB + (size_t)(t + 2) * kstep;
;             const char* a3 = a2 + kstep; const char* b3 = b2 + kstep;
;             PG8_LDB(B0, 0, 0); PG8_LDB(B1, 0, 1); PG8_SCHED; PG8_LDA(At, 0, 0); PG8_STAGE(PG8_SA(1, 1), a1 + hsA, voffA);
;             PG8_WAIT_V(8); PG8_WAIT_L(0); PG8_BAR; PG8_MMA(0, 0, At, B0); PG8_MMA(0, 1, At, B1); PG8_BAR; PG8_SCHED;
;             PG8_LDA(At, 0, 1); PG8_STAGE(PG8_SB(0, 0), b2, voffB); PG8_STAGE(PG8_SB(0, 1), b2 + hsB, voffB); PG8_STAGE(PG8_SA(0, 0), a2, voffA);
.LBB0_470:
	s_add_u32 s26, s43, s20
	s_addc_u32 s27, s50, s21
	s_and_b64 s[28:29], s[8:9], exec
	s_cselect_b32 s33, s27, s35
	s_cselect_b32 s46, s26, s34
	s_add_u32 s28, s51, s22
	s_addc_u32 s29, s52, s23
	s_and_b64 s[36:37], s[8:9], exec
	s_cselect_b32 s47, s29, s31
	s_cselect_b32 s70, s28, s30
	s_add_u32 s72, s30, 0x100
	s_addc_u32 s73, s31, 0
	s_add_u32 s30, s34, 0x40080
	v_mov_b32_e32 v0, 0
	s_addc_u32 s31, s35, 0
	s_mov_b32 s74, -2
	s_waitcnt lgkmcnt(0)
	ds_read_b128 v[168:171], v156
	ds_read_b128 v[172:175], v156 offset:1024
	ds_read_b128 v[180:183], v156 offset:2048
	ds_read_b128 v[184:187], v156 offset:3072
	ds_read_b128 v[188:191], v157
	ds_read_b128 v[192:195], v157 offset:1024
	ds_read_b128 v[196:199], v157 offset:2048
	ds_read_b128 v[200:203], v157 offset:3072
	s_add_u32 s34, s30, 0xfffc0080
	s_addc_u32 s35, s31, -1
	s_cmp_eq_u32 s74, 12
	s_cselect_b32 s37, s33, s35
	s_cselect_b32 s36, s46, s34
	s_cselect_b32 s35, s47, s73
	s_cselect_b32 s34, s70, s72
	v_lshl_add_u64 v[144:145], s[30:31], 0, v[138:139]
	s_add_i32 m0, s56, 0xc000
	ds_read_b128 v[204:207], v158
	ds_read_b128 v[208:211], v158 offset:1024
	ds_read_b128 v[212:215], v158 offset:2048
	ds_read_b128 v[216:219], v158 offset:3072
	ds_read_b128 v[222:225], v158 offset:4096
	ds_read_b128 v[226:229], v158 offset:5120
	ds_read_b128 v[230:233], v158 offset:6144
	ds_read_b128 v[234:237], v158 offset:7168
	global_load_lds_dwordx4 v[144:145], off
	v_lshl_add_u64 v[144:145], s[30:31], 0, v[136:137]
	s_add_i32 m0, s56, 0xe000
	s_nop 0
	global_load_lds_dwordx4 v[144:145], off
	s_waitcnt vmcnt(8) lgkmcnt(0)
	s_barrier
	s_setprio 1
	v_mfma_f32_16x16x32_bf16 v[124:127], v[168:171], v[204:207], 0
	v_mfma_f32_16x16x32_bf16 v[120:123], v[180:183], v[204:207], 0
	v_mfma_f32_16x16x32_bf16 v[108:111], v[168:171], v[212:215], 0
	v_mfma_f32_16x16x32_bf16 v[104:107], v[180:183], v[212:215], 0
	v_mfma_f32_16x16x32_bf16 v[92:95], v[168:171], v[222:225], 0
	v_mfma_f32_16x16x32_bf16 v[88:91], v[180:183], v[222:225], 0
	v_mfma_f32_16x16x32_bf16 v[76:79], v[168:171], v[230:233], 0
	v_mfma_f32_16x16x32_bf16 v[72:75], v[180:183], v[230:233], 0
	v_mfma_f32_16x16x32_bf16 v[124:127], v[172:175], v[208:211], v[124:127]
	v_mfma_f32_16x16x32_bf16 v[120:123], v[184:187], v[208:211], v[120:123]
	v_mfma_f32_16x16x32_bf16 v[108:111], v[172:175], v[216:219], v[108:111]
	v_mfma_f32_16x16x32_bf16 v[104:107], v[184:187], v[216:219], v[104:107]
	v_mfma_f32_16x16x32_bf16 v[92:95], v[172:175], v[226:229], v[92:95]
	v_mfma_f32_16x16x32_bf16 v[88:91], v[184:187], v[226:229], v[88:91]
	v_mfma_f32_16x16x32_bf16 v[76:79], v[172:175], v[234:237], v[76:79]
	v_mfma_f32_16x16x32_bf16 v[72:75], v[184:187], v[234:237], v[72:75]
	s_setprio 0
	s_setprio 1
	v_mfma_f32_16x16x32_bf16 v[116:119], v[188:191], v[204:207], 0
	v_mfma_f32_16x16x32_bf16 v[112:115], v[196:199], v[204:207], 0
	v_mfma_f32_16x16x32_bf16 v[100:103], v[188:191], v[212:215], 0
	v_mfma_f32_16x16x32_bf16 v[96:99], v[196:199], v[212:215], 0
	v_mfma_f32_16x16x32_bf16 v[84:87], v[188:191], v[222:225], 0
	v_mfma_f32_16x16x32_bf16 v[80:83], v[196:199], v[222:225], 0
	v_mfma_f32_16x16x32_bf16 v[68:71], v[188:191], v[230:233], 0
	v_mfma_f32_16x16x32_bf16 v[64:67], v[196:199], v[230:233], 0
	v_mfma_f32_16x16x32_bf16 v[116:119], v[192:195], v[208:211], v[116:119]
	v_mfma_f32_16x16x32_bf16 v[112:115], v[200:203], v[208:211], v[112:115]
	v_mfma_f32_16x16x32_bf16 v[100:103], v[192:195], v[216:219], v[100:103]
	v_mfma_f32_16x16x32_bf16 v[96:99], v[200:203], v[216:219], v[96:99]
	v_mfma_f32_16x16x32_bf16 v[84:87], v[192:195], v[226:229], v[84:87]
	v_mfma_f32_16x16x32_bf16 v[80:83], v[200:203], v[226:229], v[80:83]
	v_mfma_f32_16x16x32_bf16 v[68:71], v[192:195], v[234:237], v[68:71]
	v_mfma_f32_16x16x32_bf16 v[64:67], v[200:203], v[234:237], v[64:67]
	s_setprio 0
	s_barrier
	s_add_i32 s68, s64, s55
	v_lshl_add_u64 v[144:145], s[34:35], 0, v[130:131]
	s_mov_b32 m0, s68
	ds_read_b128 v[204:207], v158 offset:16384
	ds_read_b128 v[208:211], v158 offset:17408
	ds_read_b128 v[212:215], v158 offset:18432
	ds_read_b128 v[216:219], v158 offset:19456
	ds_read_b128 v[222:225], v158 offset:20480
	ds_read_b128 v[226:229], v158 offset:21504
	ds_read_b128 v[230:233], v158 offset:22528
	ds_read_b128 v[234:237], v158 offset:23552
	global_load_lds_dwordx4 v[144:145], off
	s_add_i32 m0, s68, 0x2000
	s_add_u32 s76, s34, 0x40000
	v_lshl_add_u64 v[176:177], s[34:35], 0, v[134:135]
	s_addc_u32 s77, s35, 0
	s_add_i32 s68, s65, s55
	global_load_lds_dwordx4 v[176:177], off
	v_lshl_add_u64 v[238:239], s[76:77], 0, v[130:131]
	s_mov_b32 m0, s68
	v_lshl_add_u64 v[240:241], s[36:37], 0, v[132:133]
	global_load_lds_dwordx4 v[238:239], off
	v_lshl_add_u64 v[238:239], s[76:77], 0, v[134:135]
	s_add_i32 m0, s68, 0x2000
	s_nop 0
	global_load_lds_dwordx4 v[238:239], off
	v_lshl_add_u64 v[238:239], s[36:37], 0, v[128:129]
	s_mov_b32 m0, s56
	s_nop 0
	global_load_lds_dwordx4 v[238:239], off
	s_mov_b32 m0, s57
	s_nop 0
	global_load_lds_dwordx4 v[240:241], off
	s_waitcnt vmcnt(8) lgkmcnt(0)
	s_barrier
; #define PG8_STAGE(bufoff, gbase, voff) do { _Pragma("unroll") for (int _i = 0; _i < 2; ++_i) \
;         __builtin_amdgcn_global_load_lds((const unsigned*)((const char*)(gbase) + (voff)[_i]), (PG8_LAS unsigned*)(lds + (bufoff) + ldsw + _i * 8192), 16, 0, 0); } while (0)
; #define PG8_LDA(dst, b, h) do { _Pragma("unroll") for (int m = 0; m < 4; ++m) _Pragma("unroll") for (int k = 0; k < 2; ++k) dst[m][k] = *(const PG8_LAS bf16x8*)(lds + PG8_SA(b, h) + aoff + m * 2048 + k * 1024); } while (0)
; #define PG8_LDB(dst, b, h) do { _Pragma("unroll") for (int n = 0; n < 2; ++n) _Pragma("unroll") for (int k = 0; k < 2; ++k) dst[n][k] = *(const PG8_LAS bf16x8*)(lds + PG8_SB(b, h) + boff + n * 2048 + k * 1024); } while (0)
; #define PG8_MMA(ai, bj, At, Bt) do { __builtin_amdgcn_s_setprio(1); _Pragma("unroll") for (int m = 0; m < 4; ++m) _Pragma("unroll") for (int n = 0; n < 2; ++n) _Pragma("unroll") for (int k = 0; k < 2; ++k) \
;         acc[ai][bj][m][n] = __builtin_amdgcn_mfma_f32_16x16x32_bf16(Bt[n][k], At[m][k], acc[ai][bj][m][n], 0, 0, 0); __builtin_amdgcn_s_setprio(0); } while (0)
; #define PG8_WAIT_V(n) asm volatile("s_waitcnt vmcnt(" #n ")" ::: "memory")
; #define PG8_WAIT_L(n) asm volatile("s_waitcnt lgkmcnt(" #n ")" ::: "memory")
; #define PG8_BAR __builtin_amdgcn_s_barrier()
; #define PG8_SCHED __builtin_amdgcn_sched_barrier(0)
; template <class Epi, class Sched>
; __device__ __forceinline__ void gemm_phase(PG8_LAS unsigned char* lds, PG8_LAS unsigned char* xl, const Gemm g, const Sched& S, const Epi& E) {
;     ...
;             PG8_WAIT_V(8); PG8_WAIT_L(0); PG8_BAR; PG8_MMA(1, 0, At, B0); PG8_MMA(1, 1, At, B1); PG8_BAR; PG8_SCHED;
;             PG8_LDB(B0, 1, 0); PG8_LDB(B1, 1, 1); PG8_SCHED; PG8_LDA(At, 1, 0); PG8_STAGE(PG8_SA(0, 1), a2 + hsA, voffA);
;             PG8_WAIT_V(8); PG8_WAIT_L(0); PG8_BAR; PG8_MMA(0, 0, At, B0); PG8_MMA(0, 1, At, B1); PG8_BAR; PG8_SCHED;
	s_setprio 1
	v_mfma_f32_16x16x32_bf16 v[60:63], v[168:171], v[204:207], 0
	v_mfma_f32_16x16x32_bf16 v[56:59], v[180:183], v[204:207], 0
	v_mfma_f32_16x16x32_bf16 v[44:47], v[168:171], v[212:215], 0
	v_mfma_f32_16x16x32_bf16 v[40:43], v[180:183], v[212:215], 0
	v_mfma_f32_16x16x32_bf16 v[28:31], v[168:171], v[222:225], 0
	v_mfma_f32_16x16x32_bf16 v[24:27], v[180:183], v[222:225], 0
	v_mfma_f32_16x16x32_bf16 v[12:15], v[168:171], v[230:233], 0
	v_mfma_f32_16x16x32_bf16 v[8:11], v[180:183], v[230:233], 0
	v_mfma_f32_16x16x32_bf16 v[60:63], v[172:175], v[208:211], v[60:63]
	v_mfma_f32_16x16x32_bf16 v[56:59], v[184:187], v[208:211], v[56:59]
	v_mfma_f32_16x16x32_bf16 v[44:47], v[172:175], v[216:219], v[44:47]
	v_mfma_f32_16x16x32_bf16 v[40:43], v[184:187], v[216:219], v[40:43]
	v_mfma_f32_16x16x32_bf16 v[28:31], v[172:175], v[226:229], v[28:31]
	v_mfma_f32_16x16x32_bf16 v[24:27], v[184:187], v[226:229], v[24:27]
	v_mfma_f32_16x16x32_bf16 v[12:15], v[172:175], v[234:237], v[12:15]
	v_mfma_f32_16x16x32_bf16 v[8:11], v[184:187], v[234:237], v[8:11]
	s_setprio 0
	s_setprio 1
	v_mfma_f32_16x16x32_bf16 v[52:55], v[188:191], v[204:207], 0
	v_mfma_f32_16x16x32_bf16 v[48:51], v[196:199], v[204:207], 0
	v_mfma_f32_16x16x32_bf16 v[36:39], v[188:191], v[212:215], 0
	v_mfma_f32_16x16x32_bf16 v[32:35], v[196:199], v[212:215], 0
	v_mfma_f32_16x16x32_bf16 v[20:23], v[188:191], v[222:225], 0
	v_mfma_f32_16x16x32_bf16 v[16:19], v[196:199], v[222:225], 0
	v_mfma_f32_16x16x32_bf16 v[4:7], v[188:191], v[230:233], 0
	v_mfma_f32_16x16x32_bf16 v[0:3], v[196:199], v[230:233], 0
	v_mfma_f32_16x16x32_bf16 v[52:55], v[192:195], v[208:211], v[52:55]
	v_mfma_f32_16x16x32_bf16 v[48:51], v[200:203], v[208:211], v[48:51]
	v_mfma_f32_16x16x32_bf16 v[36:39], v[192:195], v[216:219], v[36:39]
	v_mfma_f32_16x16x32_bf16 v[32:35], v[200:203], v[216:219], v[32:35]
	v_mfma_f32_16x16x32_bf16 v[20:23], v[192:195], v[226:229], v[20:23]
	v_mfma_f32_16x16x32_bf16 v[16:19], v[200:203], v[226:229], v[16:19]
	v_mfma_f32_16x16x32_bf16 v[4:7], v[192:195], v[234:237], v[4:7]
	v_mfma_f32_16x16x32_bf16 v[0:3], v[200:203], v[234:237], v[0:3]
	s_setprio 0
	s_barrier
	s_add_i32 s68, 0, 0x18000
	v_add_u32_e32 v179, s68, v147
	s_add_i32 s75, 0, 0x1c000
	ds_read_b128 v[168:171], v179
	ds_read_b128 v[172:175], v179 offset:1024
	ds_read_b128 v[180:183], v179 offset:2048
	ds_read_b128 v[184:187], v179 offset:3072
	v_add_u32_e32 v179, s75, v147
	ds_read_b128 v[188:191], v179
	ds_read_b128 v[192:195], v179 offset:1024
	ds_read_b128 v[196:199], v179 offset:2048
	ds_read_b128 v[200:203], v179 offset:3072
	s_add_u32 s36, s36, 0x40000
	s_addc_u32 s37, s37, 0
	s_mov_b32 m0, s58
	v_lshl_add_u64 v[242:243], s[36:37], 0, v[128:129]
	ds_read_b128 v[204:207], v158 offset:32768
	ds_read_b128 v[208:211], v158 offset:33792
	ds_read_b128 v[212:215], v158 offset:34816
	ds_read_b128 v[216:219], v158 offset:35840
	ds_read_b128 v[222:225], v158 offset:36864
	ds_read_b128 v[226:229], v158 offset:37888
	ds_read_b128 v[230:233], v158 offset:38912
	ds_read_b128 v[234:237], v158 offset:39936
	global_load_lds_dwordx4 v[242:243], off
	v_lshl_add_u64 v[242:243], s[36:37], 0, v[132:133]
	s_mov_b32 m0, s59
	s_nop 0
	global_load_lds_dwordx4 v[242:243], off
	s_waitcnt vmcnt(8) lgkmcnt(0)
	s_barrier
	s_setprio 1
	v_mfma_f32_16x16x32_bf16 v[124:127], v[168:171], v[204:207], v[124:127]
	v_mfma_f32_16x16x32_bf16 v[120:123], v[180:183], v[204:207], v[120:123]
	v_mfma_f32_16x16x32_bf16 v[108:111], v[168:171], v[212:215], v[108:111]
	v_mfma_f32_16x16x32_bf16 v[104:107], v[180:183], v[212:215], v[104:107]
	v_mfma_f32_16x16x32_bf16 v[92:95], v[168:171], v[222:225], v[92:95]
	v_mfma_f32_16x16x32_bf16 v[88:91], v[180:183], v[222:225], v[88:91]
	v_mfma_f32_16x16x32_bf16 v[76:79], v[168:171], v[230:233], v[76:79]
	v_mfma_f32_16x16x32_bf16 v[72:75], v[180:183], v[230:233], v[72:75]
	v_mfma_f32_16x16x32_bf16 v[124:127], v[172:175], v[208:211], v[124:127]
	v_mfma_f32_16x16x32_bf16 v[120:123], v[184:187], v[208:211], v[120:123]
	v_mfma_f32_16x16x32_bf16 v[108:111], v[172:175], v[216:219], v[108:111]
	v_mfma_f32_16x16x32_bf16 v[104:107], v[184:187], v[216:219], v[104:107]
	v_mfma_f32_16x16x32_bf16 v[92:95], v[172:175], v[226:229], v[92:95]
	v_mfma_f32_16x16x32_bf16 v[88:91], v[184:187], v[226:229], v[88:91]
	v_mfma_f32_16x16x32_bf16 v[76:79], v[172:175], v[234:237], v[76:79]
	v_mfma_f32_16x16x32_bf16 v[72:75], v[184:187], v[234:237], v[72:75]
	s_setprio 0
	s_setprio 1
	v_mfma_f32_16x16x32_bf16 v[116:119], v[188:191], v[204:207], v[116:119]
	v_mfma_f32_16x16x32_bf16 v[112:115], v[196:199], v[204:207], v[112:115]
	v_mfma_f32_16x16x32_bf16 v[100:103], v[188:191], v[212:215], v[100:103]
	v_mfma_f32_16x16x32_bf16 v[96:99], v[196:199], v[212:215], v[96:99]
	v_mfma_f32_16x16x32_bf16 v[84:87], v[188:191], v[222:225], v[84:87]
	v_mfma_f32_16x16x32_bf16 v[80:83], v[196:199], v[222:225], v[80:83]
	v_mfma_f32_16x16x32_bf16 v[68:71], v[188:191], v[230:233], v[68:71]
	v_mfma_f32_16x16x32_bf16 v[64:67], v[196:199], v[230:233], v[64:67]
	v_mfma_f32_16x16x32_bf16 v[116:119], v[192:195], v[208:211], v[116:119]
	v_mfma_f32_16x16x32_bf16 v[112:115], v[200:203], v[208:211], v[112:115]
	v_mfma_f32_16x16x32_bf16 v[100:103], v[192:195], v[216:219], v[100:103]
	v_mfma_f32_16x16x32_bf16 v[96:99], v[200:203], v[216:219], v[96:99]
	v_mfma_f32_16x16x32_bf16 v[84:87], v[192:195], v[226:229], v[84:87]
	v_mfma_f32_16x16x32_bf16 v[80:83], v[200:203], v[226:229], v[80:83]
	v_mfma_f32_16x16x32_bf16 v[68:71], v[192:195], v[234:237], v[68:71]
	v_mfma_f32_16x16x32_bf16 v[64:67], v[200:203], v[234:237], v[64:67]
	s_setprio 0
	s_barrier
; #define PG8_STAGE(bufoff, gbase, voff) do { _Pragma("unroll") for (int _i = 0; _i < 2; ++_i) \
;         __builtin_amdgcn_global_load_lds((const unsigned*)((const char*)(gbase) + (voff)[_i]), (PG8_LAS unsigned*)(lds + (bufoff) + ldsw + _i * 8192), 16, 0, 0); } while (0)
; #define PG8_LDA(dst, b, h) do { _Pragma("unroll") for (int m = 0; m < 4; ++m) _Pragma("unroll") for (int k = 0; k < 2; ++k) dst[m][k] = *(const PG8_LAS bf16x8*)(lds + PG8_SA(b, h) + aoff + m * 2048 + k * 1024); } while (0)
; #define PG8_LDB(dst, b, h) do { _Pragma("unroll") for (int n = 0; n < 2; ++n) _Pragma("unroll") for (int k = 0; k < 2; ++k) dst[n][k] = *(const PG8_LAS bf16x8*)(lds + PG8_SB(b, h) + boff + n * 2048 + k * 1024); } while (0)
; #define PG8_WAIT_V(n) asm volatile("s_waitcnt vmcnt(" #n ")" ::: "memory")
; template <class Epi, class Sched>
; __device__ __forceinline__ void gemm_phase(PG8_LAS unsigned char* lds, PG8_LAS unsigned char* xl, const Gemm g, const Sched& S, const Epi& E) {
;     ...
;         for (int t = 0; t < nt; t += 2) {
;             const bool last = (t == nt - 2);
;             const char* a1 = cA + (size_t)(t + 1) * kstep;
;             const char* a2 = last ? nA : cA + (size_t)(t + 2) * kstep; const char* b2 = last ? nB : cB + (size_t)(t + 2) * kstep;
;             const char* a3 = a2 + kstep; const char* b3 = b2 + kstep;
;             PG8_LDB(B0, 0, 0); PG8_LDB(B1, 0, 1); PG8_SCHED; PG8_LDA(At, 0, 0); PG8_STAGE(PG8_SA(1, 1), a1 + hsA, voffA);
;             PG8_WAIT_V(8); PG8_WAIT_L(0); PG8_BAR; PG8_MMA(0, 0, At, B0); PG8_MMA(0, 1, At, B1); PG8_BAR; PG8_SCHED;
;             PG8_LDA(At, 0, 1); PG8_STAGE(PG8_SB(0, 0), b2, voffB); PG8_STAGE(PG8_SB(0, 1), b2 + hsB, voffB); PG8_STAGE(PG8_SA(0, 0), a2, voffA);
;             PG8_WAIT_V(8); PG8_WAIT_L(0); PG8_BAR; PG8_MMA(1, 0, At, B0); PG8_MMA(1, 1, At, B1); PG8_BAR; PG8_SCHED;
;             PG8_LDB(B0, 1, 0); PG8_LDB(B1, 1, 1); PG8_SCHED; PG8_LDA(At, 1, 0); PG8_STAGE(PG8_SA(0, 1), a2 + hsA, voffA);
;             PG8_WAIT_V(8); PG8_WAIT_L(0); PG8_BAR; PG8_MMA(0, 0, At, B0); PG8_MMA(0, 1, At, B1); PG8_BAR; PG8_SCHED;
;             PG8_LDA(At, 1, 1); PG8_STAGE(PG8_SB(1, 0), b3, voffB); PG8_STAGE(PG8_SB(1, 1), b3 + hsB, voffB); PG8_STAGE(PG8_SA(1, 0), a3, voffA);
;             PG8_WAIT_V(8); PG8_WAIT_L(0); PG8_BAR; PG8_MMA(1, 0, At, B0); PG8_MMA(1, 1, At, B1); PG8_BAR; PG8_SCHED;
	s_add_i32 s36, s68, s55
	v_lshl_add_u64 v[144:145], v[144:145], 0, s[16:17]
	s_mov_b32 m0, s36
	ds_read_b128 v[204:207], v158 offset:49152
	ds_read_b128 v[208:211], v158 offset:50176
	ds_read_b128 v[212:215], v158 offset:51200
	ds_read_b128 v[216:219], v158 offset:52224
	ds_read_b128 v[222:225], v158 offset:53248
	ds_read_b128 v[226:229], v158 offset:54272
	ds_read_b128 v[230:233], v158 offset:55296
	ds_read_b128 v[234:237], v158 offset:56320
	global_load_lds_dwordx4 v[144:145], off
	s_add_i32 m0, s36, 0x2000
	s_add_u32 s34, s34, 0x40080
	v_lshl_add_u64 v[144:145], v[176:177], 0, s[16:17]
	s_addc_u32 s35, s35, 0
	s_add_i32 s36, s75, s55
	global_load_lds_dwordx4 v[144:145], off
	v_lshl_add_u64 v[144:145], s[34:35], 0, v[130:131]
	s_mov_b32 m0, s36
	s_nop 0
	global_load_lds_dwordx4 v[144:145], off
	v_lshl_add_u64 v[144:145], s[34:35], 0, v[134:135]
	s_add_i32 m0, s36, 0x2000
	s_nop 0
	global_load_lds_dwordx4 v[144:145], off
	v_lshl_add_u64 v[144:145], v[238:239], 0, s[16:17]
	s_mov_b32 m0, s61
	s_nop 0
	global_load_lds_dwordx4 v[144:145], off
	v_lshl_add_u64 v[144:145], v[240:241], 0, s[16:17]
	s_mov_b32 m0, s62
	s_nop 0
	global_load_lds_dwordx4 v[144:145], off
	s_waitcnt vmcnt(8) lgkmcnt(0)
	s_barrier
	s_setprio 1
	v_mfma_f32_16x16x32_bf16 v[60:63], v[168:171], v[204:207], v[60:63]
	v_mfma_f32_16x16x32_bf16 v[56:59], v[180:183], v[204:207], v[56:59]
	v_mfma_f32_16x16x32_bf16 v[44:47], v[168:171], v[212:215], v[44:47]
	v_mfma_f32_16x16x32_bf16 v[40:43], v[180:183], v[212:215], v[40:43]
	v_mfma_f32_16x16x32_bf16 v[28:31], v[168:171], v[222:225], v[28:31]
	v_mfma_f32_16x16x32_bf16 v[24:27], v[180:183], v[222:225], v[24:27]
	v_mfma_f32_16x16x32_bf16 v[12:15], v[168:171], v[230:233], v[12:15]
	v_mfma_f32_16x16x32_bf16 v[8:11], v[180:183], v[230:233], v[8:11]
	v_mfma_f32_16x16x32_bf16 v[60:63], v[172:175], v[208:211], v[60:63]
	v_mfma_f32_16x16x32_bf16 v[56:59], v[184:187], v[208:211], v[56:59]
	v_mfma_f32_16x16x32_bf16 v[44:47], v[172:175], v[216:219], v[44:47]
	v_mfma_f32_16x16x32_bf16 v[40:43], v[184:187], v[216:219], v[40:43]
	v_mfma_f32_16x16x32_bf16 v[28:31], v[172:175], v[226:229], v[28:31]
	v_mfma_f32_16x16x32_bf16 v[24:27], v[184:187], v[226:229], v[24:27]
	v_mfma_f32_16x16x32_bf16 v[12:15], v[172:175], v[234:237], v[12:15]
	v_mfma_f32_16x16x32_bf16 v[8:11], v[184:187], v[234:237], v[8:11]
	s_setprio 0
	s_setprio 1
	v_mfma_f32_16x16x32_bf16 v[52:55], v[188:191], v[204:207], v[52:55]
	s_add_i32 s74, s74, 2
	v_mfma_f32_16x16x32_bf16 v[48:51], v[196:199], v[204:207], v[48:51]
	s_add_u32 s72, s72, 0x100
	v_mfma_f32_16x16x32_bf16 v[36:39], v[188:191], v[212:215], v[36:39]
	s_addc_u32 s73, s73, 0
	v_mfma_f32_16x16x32_bf16 v[32:35], v[196:199], v[212:215], v[32:35]
	s_add_u32 s30, s30, 0x100
	v_mfma_f32_16x16x32_bf16 v[20:23], v[188:191], v[222:225], v[20:23]
	s_addc_u32 s31, s31, 0
	v_mfma_f32_16x16x32_bf16 v[16:19], v[196:199], v[222:225], v[16:19]
	s_cmp_gt_u32 s74, 13
	v_mfma_f32_16x16x32_bf16 v[4:7], v[188:191], v[230:233], v[4:7]
	v_mfma_f32_16x16x32_bf16 v[0:3], v[196:199], v[230:233], v[0:3]
	v_mfma_f32_16x16x32_bf16 v[52:55], v[192:195], v[208:211], v[52:55]
	v_mfma_f32_16x16x32_bf16 v[48:51], v[200:203], v[208:211], v[48:51]
	v_mfma_f32_16x16x32_bf16 v[36:39], v[192:195], v[216:219], v[36:39]
	v_mfma_f32_16x16x32_bf16 v[32:35], v[200:203], v[216:219], v[32:35]
	v_mfma_f32_16x16x32_bf16 v[20:23], v[192:195], v[226:229], v[20:23]
	v_mfma_f32_16x16x32_bf16 v[16:19], v[200:203], v[226:229], v[16:19]
	v_mfma_f32_16x16x32_bf16 v[4:7], v[192:195], v[234:237], v[4:7]
	v_mfma_f32_16x16x32_bf16 v[0:3], v[200:203], v[234:237], v[0:3]
	s_setprio 0
	s_barrier
	s_cbranch_scc1 .Lpeel_after_P3
.LBB0_471:
	ds_read_b128 v[168:171], v156
	ds_read_b128 v[172:175], v156 offset:1024
	ds_read_b128 v[180:183], v156 offset:2048
	ds_read_b128 v[184:187], v156 offset:3072
	ds_read_b128 v[188:191], v157
	ds_read_b128 v[192:195], v157 offset:1024
	ds_read_b128 v[196:199], v157 offset:2048
	ds_read_b128 v[200:203], v157 offset:3072
	s_add_u32 s34, s30, 0xfffc0080
	s_addc_u32 s35, s31, -1
	s_cmp_eq_u32 s74, 12
	s_cselect_b32 s37, s33, s35
	s_cselect_b32 s36, s46, s34
	s_cselect_b32 s35, s47, s73
	s_cselect_b32 s34, s70, s72
	v_lshl_add_u64 v[144:145], s[30:31], 0, v[138:139]
	s_add_i32 m0, s56, 0xc000
	ds_read_b128 v[204:207], v158
	ds_read_b128 v[208:211], v158 offset:1024
	ds_read_b128 v[212:215], v158 offset:2048
	ds_read_b128 v[216:219], v158 offset:3072
	ds_read_b128 v[222:225], v158 offset:4096
	ds_read_b128 v[226:229], v158 offset:5120
	ds_read_b128 v[230:233], v158 offset:6144
	ds_read_b128 v[234:237], v158 offset:7168
	global_load_lds_dwordx4 v[144:145], off
	v_lshl_add_u64 v[144:145], s[30:31], 0, v[136:137]
	s_add_i32 m0, s56, 0xe000
	s_nop 0
	global_load_lds_dwordx4 v[144:145], off
	s_waitcnt vmcnt(8) lgkmcnt(0)
	s_barrier
; #define PG8_STAGE(bufoff, gbase, voff) do { _Pragma("unroll") for (int _i = 0; _i < 2; ++_i) \
;         __builtin_amdgcn_global_load_lds((const unsigned*)((const char*)(gbase) + (voff)[_i]), (PG8_LAS unsigned*)(lds + (bufoff) + ldsw + _i * 8192), 16, 0, 0); } while (0)
; #define PG8_LDA(dst, b, h) do { _Pragma("unroll") for (int m = 0; m < 4; ++m) _Pragma("unroll") for (int k = 0; k < 2; ++k) dst[m][k] = *(const PG8_LAS bf16x8*)(lds + PG8_SA(b, h) + aoff + m * 2048 + k * 1024); } while (0)
; #define PG8_MMA(ai, bj, At, Bt) do { __builtin_amdgcn_s_setprio(1); _Pragma("unroll") for (int m = 0; m < 4; ++m) _Pragma("unroll") for (int n = 0; n < 2; ++n) _Pragma("unroll") for (int k = 0; k < 2; ++k) \
;         acc[ai][bj][m][n] = __builtin_amdgcn_mfma_f32_16x16x32_bf16(Bt[n][k], At[m][k], acc[ai][bj][m][n], 0, 0, 0); __builtin_amdgcn_s_setprio(0); } while (0)
; #define PG8_WAIT_V(n) asm volatile("s_waitcnt vmcnt(" #n ")" ::: "memory")
; #define PG8_WAIT_L(n) asm volatile("s_waitcnt lgkmcnt(" #n ")" ::: "memory")
; #define PG8_BAR __builtin_amdgcn_s_barrier()
; #define PG8_SCHED __builtin_amdgcn_sched_barrier(0)
; template <class Epi, class Sched>
; __device__ __forceinline__ void gemm_phase(PG8_LAS unsigned char* lds, PG8_LAS unsigned char* xl, const Gemm g, const Sched& S, const Epi& E) {
;     ...
;             PG8_WAIT_V(8); PG8_WAIT_L(0); PG8_BAR; PG8_MMA(0, 0, At, B0); PG8_MMA(0, 1, At, B1); PG8_BAR; PG8_SCHED;
;             PG8_LDA(At, 0, 1); PG8_STAGE(PG8_SB(0, 0), b2, voffB); PG8_STAGE(PG8_SB(0, 1), b2 + hsB, voffB); PG8_STAGE(PG8_SA(0, 0), a2, voffA);
;             PG8_WAIT_V(8); PG8_WAIT_L(0); PG8_BAR; PG8_MMA(1, 0, At, B0); PG8_MMA(1, 1, At, B1); PG8_BAR; PG8_SCHED;
	s_setprio 1
	v_mfma_f32_16x16x32_bf16 v[124:127], v[168:171], v[204:207], v[124:127]
	v_mfma_f32_16x16x32_bf16 v[120:123], v[180:183], v[204:207], v[120:123]
	v_mfma_f32_16x16x32_bf16 v[108:111], v[168:171], v[212:215], v[108:111]
	v_mfma_f32_16x16x32_bf16 v[104:107], v[180:183], v[212:215], v[104:107]
	v_mfma_f32_16x16x32_bf16 v[92:95], v[168:171], v[222:225], v[92:95]
	v_mfma_f32_16x16x32_bf16 v[88:91], v[180:183], v[222:225], v[88:91]
	v_mfma_f32_16x16x32_bf16 v[76:79], v[168:171], v[230:233], v[76:79]
	v_mfma_f32_16x16x32_bf16 v[72:75], v[180:183], v[230:233], v[72:75]
	v_mfma_f32_16x16x32_bf16 v[124:127], v[172:175], v[208:211], v[124:127]
	v_mfma_f32_16x16x32_bf16 v[120:123], v[184:187], v[208:211], v[120:123]
	v_mfma_f32_16x16x32_bf16 v[108:111], v[172:175], v[216:219], v[108:111]
	v_mfma_f32_16x16x32_bf16 v[104:107], v[184:187], v[216:219], v[104:107]
	v_mfma_f32_16x16x32_bf16 v[92:95], v[172:175], v[226:229], v[92:95]
	v_mfma_f32_16x16x32_bf16 v[88:91], v[184:187], v[226:229], v[88:91]
	v_mfma_f32_16x16x32_bf16 v[76:79], v[172:175], v[234:237], v[76:79]
	v_mfma_f32_16x16x32_bf16 v[72:75], v[184:187], v[234:237], v[72:75]
	s_setprio 0
	s_setprio 1
	v_mfma_f32_16x16x32_bf16 v[116:119], v[188:191], v[204:207], v[116:119]
	v_mfma_f32_16x16x32_bf16 v[112:115], v[196:199], v[204:207], v[112:115]
	v_mfma_f32_16x16x32_bf16 v[100:103], v[188:191], v[212:215], v[100:103]
	v_mfma_f32_16x16x32_bf16 v[96:99], v[196:199], v[212:215], v[96:99]
	v_mfma_f32_16x16x32_bf16 v[84:87], v[188:191], v[222:225], v[84:87]
	v_mfma_f32_16x16x32_bf16 v[80:83], v[196:199], v[222:225], v[80:83]
	v_mfma_f32_16x16x32_bf16 v[68:71], v[188:191], v[230:233], v[68:71]
	v_mfma_f32_16x16x32_bf16 v[64:67], v[196:199], v[230:233], v[64:67]
	v_mfma_f32_16x16x32_bf16 v[116:119], v[192:195], v[208:211], v[116:119]
	v_mfma_f32_16x16x32_bf16 v[112:115], v[200:203], v[208:211], v[112:115]
	v_mfma_f32_16x16x32_bf16 v[100:103], v[192:195], v[216:219], v[100:103]
	v_mfma_f32_16x16x32_bf16 v[96:99], v[200:203], v[216:219], v[96:99]
	v_mfma_f32_16x16x32_bf16 v[84:87], v[192:195], v[226:229], v[84:87]
	v_mfma_f32_16x16x32_bf16 v[80:83], v[200:203], v[226:229], v[80:83]
	v_mfma_f32_16x16x32_bf16 v[68:71], v[192:195], v[234:237], v[68:71]
	v_mfma_f32_16x16x32_bf16 v[64:67], v[200:203], v[234:237], v[64:67]
	s_setprio 0
	s_barrier
	s_add_i32 s68, s64, s55
	v_lshl_add_u64 v[144:145], s[34:35], 0, v[130:131]
	s_mov_b32 m0, s68
	ds_read_b128 v[204:207], v158 offset:16384
	ds_read_b128 v[208:211], v158 offset:17408
	ds_read_b128 v[212:215], v158 offset:18432
	ds_read_b128 v[216:219], v158 offset:19456
	ds_read_b128 v[222:225], v158 offset:20480
	ds_read_b128 v[226:229], v158 offset:21504
	ds_read_b128 v[230:233], v158 offset:22528
	ds_read_b128 v[234:237], v158 offset:23552
	global_load_lds_dwordx4 v[144:145], off
	s_add_i32 m0, s68, 0x2000
	s_add_u32 s76, s34, 0x40000
	v_lshl_add_u64 v[176:177], s[34:35], 0, v[134:135]
	s_addc_u32 s77, s35, 0
	s_add_i32 s68, s65, s55
	global_load_lds_dwordx4 v[176:177], off
	v_lshl_add_u64 v[238:239], s[76:77], 0, v[130:131]
	s_mov_b32 m0, s68
	v_lshl_add_u64 v[240:241], s[36:37], 0, v[132:133]
	global_load_lds_dwordx4 v[238:239], off
	v_lshl_add_u64 v[238:239], s[76:77], 0, v[134:135]
	s_add_i32 m0, s68, 0x2000
	s_nop 0
	global_load_lds_dwordx4 v[238:239], off
	v_lshl_add_u64 v[238:239], s[36:37], 0, v[128:129]
	s_mov_b32 m0, s56
	s_nop 0
	global_load_lds_dwordx4 v[238:239], off
	s_mov_b32 m0, s57
	s_nop 0
	global_load_lds_dwordx4 v[240:241], off
	s_waitcnt vmcnt(8) lgkmcnt(0)
	s_barrier
	s_setprio 1
	v_mfma_f32_16x16x32_bf16 v[60:63], v[168:171], v[204:207], v[60:63]
	v_mfma_f32_16x16x32_bf16 v[56:59], v[180:183], v[204:207], v[56:59]
	v_mfma_f32_16x16x32_bf16 v[44:47], v[168:171], v[212:215], v[44:47]
	v_mfma_f32_16x16x32_bf16 v[40:43], v[180:183], v[212:215], v[40:43]
	v_mfma_f32_16x16x32_bf16 v[28:31], v[168:171], v[222:225], v[28:31]
	v_mfma_f32_16x16x32_bf16 v[24:27], v[180:183], v[222:225], v[24:27]
	v_mfma_f32_16x16x32_bf16 v[12:15], v[168:171], v[230:233], v[12:15]
	v_mfma_f32_16x16x32_bf16 v[8:11], v[180:183], v[230:233], v[8:11]
	v_mfma_f32_16x16x32_bf16 v[60:63], v[172:175], v[208:211], v[60:63]
	v_mfma_f32_16x16x32_bf16 v[56:59], v[184:187], v[208:211], v[56:59]
	v_mfma_f32_16x16x32_bf16 v[44:47], v[172:175], v[216:219], v[44:47]
	v_mfma_f32_16x16x32_bf16 v[40:43], v[184:187], v[216:219], v[40:43]
	v_mfma_f32_16x16x32_bf16 v[28:31], v[172:175], v[226:229], v[28:31]
	v_mfma_f32_16x16x32_bf16 v[24:27], v[184:187], v[226:229], v[24:27]
	v_mfma_f32_16x16x32_bf16 v[12:15], v[172:175], v[234:237], v[12:15]
	v_mfma_f32_16x16x32_bf16 v[8:11], v[184:187], v[234:237], v[8:11]
	s_setprio 0
	s_setprio 1
	v_mfma_f32_16x16x32_bf16 v[52:55], v[188:191], v[204:207], v[52:55]
	v_mfma_f32_16x16x32_bf16 v[48:51], v[196:199], v[204:207], v[48:51]
	v_mfma_f32_16x16x32_bf16 v[36:39], v[188:191], v[212:215], v[36:39]
	v_mfma_f32_16x16x32_bf16 v[32:35], v[196:199], v[212:215], v[32:35]
	v_mfma_f32_16x16x32_bf16 v[20:23], v[188:191], v[222:225], v[20:23]
	v_mfma_f32_16x16x32_bf16 v[16:19], v[196:199], v[222:225], v[16:19]
	v_mfma_f32_16x16x32_bf16 v[4:7], v[188:191], v[230:233], v[4:7]
	v_mfma_f32_16x16x32_bf16 v[0:3], v[196:199], v[230:233], v[0:3]
	v_mfma_f32_16x16x32_bf16 v[52:55], v[192:195], v[208:211], v[52:55]
	v_mfma_f32_16x16x32_bf16 v[48:51], v[200:203], v[208:211], v[48:51]
	v_mfma_f32_16x16x32_bf16 v[36:39], v[192:195], v[216:219], v[36:39]
	v_mfma_f32_16x16x32_bf16 v[32:35], v[200:203], v[216:219], v[32:35]
	v_mfma_f32_16x16x32_bf16 v[20:23], v[192:195], v[226:229], v[20:23]
	v_mfma_f32_16x16x32_bf16 v[16:19], v[200:203], v[226:229], v[16:19]
	v_mfma_f32_16x16x32_bf16 v[4:7], v[192:195], v[234:237], v[4:7]
	v_mfma_f32_16x16x32_bf16 v[0:3], v[200:203], v[234:237], v[0:3]
	s_setprio 0
	s_barrier
; #define PG8_STAGE(bufoff, gbase, voff) do { _Pragma("unroll") for (int _i = 0; _i < 2; ++_i) \
;         __builtin_amdgcn_global_load_lds((const unsigned*)((const char*)(gbase) + (voff)[_i]), (PG8_LAS unsigned*)(lds + (bufoff) + ldsw + _i * 8192), 16, 0, 0); } while (0)
; #define PG8_LDA(dst, b, h) do { _Pragma("unroll") for (int m = 0; m < 4; ++m) _Pragma("unroll") for (int k = 0; k < 2; ++k) dst[m][k] = *(const PG8_LAS bf16x8*)(lds + PG8_SA(b, h) + aoff + m * 2048 + k * 1024); } while (0)
; #define PG8_LDB(dst, b, h) do { _Pragma("unroll") for (int n = 0; n < 2; ++n) _Pragma("unroll") for (int k = 0; k < 2; ++k) dst[n][k] = *(const PG8_LAS bf16x8*)(lds + PG8_SB(b, h) + boff + n * 2048 + k * 1024); } while (0)
; #define PG8_MMA(ai, bj, At, Bt) do { __builtin_amdgcn_s_setprio(1); _Pragma("unroll") for (int m = 0; m < 4; ++m) _Pragma("unroll") for (int n = 0; n < 2; ++n) _Pragma("unroll") for (int k = 0; k < 2; ++k) \
;         acc[ai][bj][m][n] = __builtin_amdgcn_mfma_f32_16x16x32_bf16(Bt[n][k], At[m][k], acc[ai][bj][m][n], 0, 0, 0); __builtin_amdgcn_s_setprio(0); } while (0)
; #define PG8_WAIT_V(n) asm volatile("s_waitcnt vmcnt(" #n ")" ::: "memory")
; #define PG8_WAIT_L(n) asm volatile("s_waitcnt lgkmcnt(" #n ")" ::: "memory")
; #define PG8_BAR __builtin_amdgcn_s_barrier()
; #define PG8_SCHED __builtin_amdgcn_sched_barrier(0)
; template <class Epi, class Sched>
; __device__ __forceinline__ void gemm_phase(PG8_LAS unsigned char* lds, PG8_LAS unsigned char* xl, const Gemm g, const Sched& S, const Epi& E) {
;     ...
;             PG8_LDB(B0, 1, 0); PG8_LDB(B1, 1, 1); PG8_SCHED; PG8_LDA(At, 1, 0); PG8_STAGE(PG8_SA(0, 1), a2 + hsA, voffA);
;             PG8_WAIT_V(8); PG8_WAIT_L(0); PG8_BAR; PG8_MMA(0, 0, At, B0); PG8_MMA(0, 1, At, B1); PG8_BAR; PG8_SCHED;
	s_add_i32 s68, 0, 0x18000
	v_add_u32_e32 v179, s68, v147
	s_add_i32 s75, 0, 0x1c000
	ds_read_b128 v[168:171], v179
	ds_read_b128 v[172:175], v179 offset:1024
	ds_read_b128 v[180:183], v179 offset:2048
	ds_read_b128 v[184:187], v179 offset:3072
	v_add_u32_e32 v179, s75, v147
	ds_read_b128 v[188:191], v179
	ds_read_b128 v[192:195], v179 offset:1024
	ds_read_b128 v[196:199], v179 offset:2048
	ds_read_b128 v[200:203], v179 offset:3072
	s_add_u32 s36, s36, 0x40000
	s_addc_u32 s37, s37, 0
	s_mov_b32 m0, s58
	v_lshl_add_u64 v[242:243], s[36:37], 0, v[128:129]
	ds_read_b128 v[204:207], v158 offset:32768
	ds_read_b128 v[208:211], v158 offset:33792
	ds_read_b128 v[212:215], v158 offset:34816
	ds_read_b128 v[216:219], v158 offset:35840
	ds_read_b128 v[222:225], v158 offset:36864
	ds_read_b128 v[226:229], v158 offset:37888
	ds_read_b128 v[230:233], v158 offset:38912
	ds_read_b128 v[234:237], v158 offset:39936
	global_load_lds_dwordx4 v[242:243], off
	v_lshl_add_u64 v[242:243], s[36:37], 0, v[132:133]
	s_mov_b32 m0, s59
	s_nop 0
	global_load_lds_dwordx4 v[242:243], off
	s_waitcnt vmcnt(8) lgkmcnt(0)
	s_barrier
	s_setprio 1
	v_mfma_f32_16x16x32_bf16 v[124:127], v[168:171], v[204:207], v[124:127]
	v_mfma_f32_16x16x32_bf16 v[120:123], v[180:183], v[204:207], v[120:123]
	v_mfma_f32_16x16x32_bf16 v[108:111], v[168:171], v[212:215], v[108:111]
	v_mfma_f32_16x16x32_bf16 v[104:107], v[180:183], v[212:215], v[104:107]
	v_mfma_f32_16x16x32_bf16 v[92:95], v[168:171], v[222:225], v[92:95]
	v_mfma_f32_16x16x32_bf16 v[88:91], v[180:183], v[222:225], v[88:91]
	v_mfma_f32_16x16x32_bf16 v[76:79], v[168:171], v[230:233], v[76:79]
	v_mfma_f32_16x16x32_bf16 v[72:75], v[180:183], v[230:233], v[72:75]
	v_mfma_f32_16x16x32_bf16 v[124:127], v[172:175], v[208:211], v[124:127]
	v_mfma_f32_16x16x32_bf16 v[120:123], v[184:187], v[208:211], v[120:123]
	v_mfma_f32_16x16x32_bf16 v[108:111], v[172:175], v[216:219], v[108:111]
	v_mfma_f32_16x16x32_bf16 v[104:107], v[184:187], v[216:219], v[104:107]
	v_mfma_f32_16x16x32_bf16 v[92:95], v[172:175], v[226:229], v[92:95]
	v_mfma_f32_16x16x32_bf16 v[88:91], v[184:187], v[226:229], v[88:91]
	v_mfma_f32_16x16x32_bf16 v[76:79], v[172:175], v[234:237], v[76:79]
	v_mfma_f32_16x16x32_bf16 v[72:75], v[184:187], v[234:237], v[72:75]
	s_setprio 0
	s_setprio 1
	v_mfma_f32_16x16x32_bf16 v[116:119], v[188:191], v[204:207], v[116:119]
	v_mfma_f32_16x16x32_bf16 v[112:115], v[196:199], v[204:207], v[112:115]
	v_mfma_f32_16x16x32_bf16 v[100:103], v[188:191], v[212:215], v[100:103]
	v_mfma_f32_16x16x32_bf16 v[96:99], v[196:199], v[212:215], v[96:99]
	v_mfma_f32_16x16x32_bf16 v[84:87], v[188:191], v[222:225], v[84:87]
	v_mfma_f32_16x16x32_bf16 v[80:83], v[196:199], v[222:225], v[80:83]
	v_mfma_f32_16x16x32_bf16 v[68:71], v[188:191], v[230:233], v[68:71]
	v_mfma_f32_16x16x32_bf16 v[64:67], v[196:199], v[230:233], v[64:67]
	v_mfma_f32_16x16x32_bf16 v[116:119], v[192:195], v[208:211], v[116:119]
	v_mfma_f32_16x16x32_bf16 v[112:115], v[200:203], v[208:211], v[112:115]
	v_mfma_f32_16x16x32_bf16 v[100:103], v[192:195], v[216:219], v[100:103]
	v_mfma_f32_16x16x32_bf16 v[96:99], v[200:203], v[216:219], v[96:99]
	v_mfma_f32_16x16x32_bf16 v[84:87], v[192:195], v[226:229], v[84:87]
	v_mfma_f32_16x16x32_bf16 v[80:83], v[200:203], v[226:229], v[80:83]
	v_mfma_f32_16x16x32_bf16 v[68:71], v[192:195], v[234:237], v[68:71]
	v_mfma_f32_16x16x32_bf16 v[64:67], v[200:203], v[234:237], v[64:67]
	s_setprio 0
	s_barrier
; #define PG8_STAGE(bufoff, gbase, voff) do { _Pragma("unroll") for (int _i = 0; _i < 2; ++_i) \
;         __builtin_amdgcn_global_load_lds((const unsigned*)((const char*)(gbase) + (voff)[_i]), (PG8_LAS unsigned*)(lds + (bufoff) + ldsw + _i * 8192), 16, 0, 0); } while (0)
; #define PG8_LDA(dst, b, h) do { _Pragma("unroll") for (int m = 0; m < 4; ++m) _Pragma("unroll") for (int k = 0; k < 2; ++k) dst[m][k] = *(const PG8_LAS bf16x8*)(lds + PG8_SA(b, h) + aoff + m * 2048 + k * 1024); } while (0)
; #define PG8_MMA(ai, bj, At, Bt) do { __builtin_amdgcn_s_setprio(1); _Pragma("unroll") for (int m = 0; m < 4; ++m) _Pragma("unroll") for (int n = 0; n < 2; ++n) _Pragma("unroll") for (int k = 0; k < 2; ++k) \
;         acc[ai][bj][m][n] = __builtin_amdgcn_mfma_f32_16x16x32_bf16(Bt[n][k], At[m][k], acc[ai][bj][m][n], 0, 0, 0); __builtin_amdgcn_s_setprio(0); } while (0)
; #define PG8_WAIT_V(n) asm volatile("s_waitcnt vmcnt(" #n ")" ::: "memory")
; #define PG8_WAIT_L(n) asm volatile("s_waitcnt lgkmcnt(" #n ")" ::: "memory")
; #define PG8_BAR __builtin_amdgcn_s_barrier()
; #define PG8_SCHED __builtin_amdgcn_sched_barrier(0)
; template <class Epi, class Sched>
; __device__ __forceinline__ void gemm_phase(PG8_LAS unsigned char* lds, PG8_LAS unsigned char* xl, const Gemm g, const Sched& S, const Epi& E) {
;     ...
;             PG8_LDA(At, 1, 1); PG8_STAGE(PG8_SB(1, 0), b3, voffB); PG8_STAGE(PG8_SB(1, 1), b3 + hsB, voffB); PG8_STAGE(PG8_SA(1, 0), a3, voffA);
;             PG8_WAIT_V(8); PG8_WAIT_L(0); PG8_BAR; PG8_MMA(1, 0, At, B0); PG8_MMA(1, 1, At, B1); PG8_BAR; PG8_SCHED;
	s_add_i32 s36, s68, s55
	v_lshl_add_u64 v[144:145], v[144:145], 0, s[16:17]
	s_mov_b32 m0, s36
	ds_read_b128 v[204:207], v158 offset:49152
	ds_read_b128 v[208:211], v158 offset:50176
	ds_read_b128 v[212:215], v158 offset:51200
	ds_read_b128 v[216:219], v158 offset:52224
	ds_read_b128 v[222:225], v158 offset:53248
	ds_read_b128 v[226:229], v158 offset:54272
	ds_read_b128 v[230:233], v158 offset:55296
	ds_read_b128 v[234:237], v158 offset:56320
	global_load_lds_dwordx4 v[144:145], off
	s_add_i32 m0, s36, 0x2000
	s_add_u32 s34, s34, 0x40080
	v_lshl_add_u64 v[144:145], v[176:177], 0, s[16:17]
	s_addc_u32 s35, s35, 0
	s_add_i32 s36, s75, s55
	global_load_lds_dwordx4 v[144:145], off
	v_lshl_add_u64 v[144:145], s[34:35], 0, v[130:131]
	s_mov_b32 m0, s36
	s_nop 0
	global_load_lds_dwordx4 v[144:145], off
	v_lshl_add_u64 v[144:145], s[34:35], 0, v[134:135]
	s_add_i32 m0, s36, 0x2000
	s_nop 0
	global_load_lds_dwordx4 v[144:145], off
	v_lshl_add_u64 v[144:145], v[238:239], 0, s[16:17]
	s_mov_b32 m0, s61
	s_nop 0
	global_load_lds_dwordx4 v[144:145], off
	v_lshl_add_u64 v[144:145], v[240:241], 0, s[16:17]
	s_mov_b32 m0, s62
	s_nop 0
	global_load_lds_dwordx4 v[144:145], off
	s_waitcnt vmcnt(8) lgkmcnt(0)
	s_barrier
	s_setprio 1
	v_mfma_f32_16x16x32_bf16 v[60:63], v[168:171], v[204:207], v[60:63]
	v_mfma_f32_16x16x32_bf16 v[56:59], v[180:183], v[204:207], v[56:59]
	v_mfma_f32_16x16x32_bf16 v[44:47], v[168:171], v[212:215], v[44:47]
	v_mfma_f32_16x16x32_bf16 v[40:43], v[180:183], v[212:215], v[40:43]
	v_mfma_f32_16x16x32_bf16 v[28:31], v[168:171], v[222:225], v[28:31]
	v_mfma_f32_16x16x32_bf16 v[24:27], v[180:183], v[222:225], v[24:27]
	v_mfma_f32_16x16x32_bf16 v[12:15], v[168:171], v[230:233], v[12:15]
	v_mfma_f32_16x16x32_bf16 v[8:11], v[180:183], v[230:233], v[8:11]
	v_mfma_f32_16x16x32_bf16 v[60:63], v[172:175], v[208:211], v[60:63]
	v_mfma_f32_16x16x32_bf16 v[56:59], v[184:187], v[208:211], v[56:59]
	v_mfma_f32_16x16x32_bf16 v[44:47], v[172:175], v[216:219], v[44:47]
	v_mfma_f32_16x16x32_bf16 v[40:43], v[184:187], v[216:219], v[40:43]
	v_mfma_f32_16x16x32_bf16 v[28:31], v[172:175], v[226:229], v[28:31]
	v_mfma_f32_16x16x32_bf16 v[24:27], v[184:187], v[226:229], v[24:27]
	v_mfma_f32_16x16x32_bf16 v[12:15], v[172:175], v[234:237], v[12:15]
	v_mfma_f32_16x16x32_bf16 v[8:11], v[184:187], v[234:237], v[8:11]
	s_setprio 0
	s_setprio 1
	v_mfma_f32_16x16x32_bf16 v[52:55], v[188:191], v[204:207], v[52:55]
	s_add_i32 s74, s74, 2
	v_mfma_f32_16x16x32_bf16 v[48:51], v[196:199], v[204:207], v[48:51]
	s_add_u32 s72, s72, 0x100
	v_mfma_f32_16x16x32_bf16 v[36:39], v[188:191], v[212:215], v[36:39]
	s_addc_u32 s73, s73, 0
	v_mfma_f32_16x16x32_bf16 v[32:35], v[196:199], v[212:215], v[32:35]
	s_add_u32 s30, s30, 0x100
	v_mfma_f32_16x16x32_bf16 v[20:23], v[188:191], v[222:225], v[20:23]
	s_addc_u32 s31, s31, 0
	v_mfma_f32_16x16x32_bf16 v[16:19], v[196:199], v[222:225], v[16:19]
	s_cmp_gt_u32 s74, 13
	v_mfma_f32_16x16x32_bf16 v[4:7], v[188:191], v[230:233], v[4:7]
	v_mfma_f32_16x16x32_bf16 v[0:3], v[196:199], v[230:233], v[0:3]
	v_mfma_f32_16x16x32_bf16 v[52:55], v[192:195], v[208:211], v[52:55]
	v_mfma_f32_16x16x32_bf16 v[48:51], v[200:203], v[208:211], v[48:51]
	v_mfma_f32_16x16x32_bf16 v[36:39], v[192:195], v[216:219], v[36:39]
	v_mfma_f32_16x16x32_bf16 v[32:35], v[200:203], v[216:219], v[32:35]
	v_mfma_f32_16x16x32_bf16 v[20:23], v[192:195], v[226:229], v[20:23]
	v_mfma_f32_16x16x32_bf16 v[16:19], v[200:203], v[226:229], v[16:19]
	v_mfma_f32_16x16x32_bf16 v[4:7], v[192:195], v[234:237], v[4:7]
	v_mfma_f32_16x16x32_bf16 v[0:3], v[200:203], v[234:237], v[0:3]
	s_setprio 0
	s_barrier
	s_cbranch_scc0 .LBB0_471

; #define PG8_STAGE(bufoff, gbase, voff) do { _Pragma("unroll") for (int _i = 0; _i < 2; ++_i) \
;         __builtin_amdgcn_global_load_lds((const unsigned*)((const char*)(gbase) + (voff)[_i]), (PG8_LAS unsigned*)(lds + (bufoff) + ldsw + _i * 8192), 16, 0, 0); } while (0)
; #define PG8_LDA(dst, b, h) do { _Pragma("unroll") for (int m = 0; m < 4; ++m) _Pragma("unroll") for (int k = 0; k < 2; ++k) dst[m][k] = *(const PG8_LAS bf16x8*)(lds + PG8_SA(b, h) + aoff + m * 2048 + k * 1024); } while (0)
; #define PG8_LDB(dst, b, h) do { _Pragma("unroll") for (int n = 0; n < 2; ++n) _Pragma("unroll") for (int k = 0; k < 2; ++k) dst[n][k] = *(const PG8_LAS bf16x8*)(lds + PG8_SB(b, h) + boff + n * 2048 + k * 1024); } while (0)
; #define PG8_MMA(ai, bj, At, Bt) do { __builtin_amdgcn_s_setprio(1); _Pragma("unroll") for (int m = 0; m < 4; ++m) _Pragma("unroll") for (int n = 0; n < 2; ++n) _Pragma("unroll") for (int k = 0; k < 2; ++k) \
;         acc[ai][bj][m][n] = __builtin_amdgcn_mfma_f32_16x16x32_bf16(Bt[n][k], At[m][k], acc[ai][bj][m][n], 0, 0, 0); __builtin_amdgcn_s_setprio(0); } while (0)
; #define PG8_WAIT_V(n) asm volatile("s_waitcnt vmcnt(" #n ")" ::: "memory")
; #define PG8_WAIT_L(n) asm volatile("s_waitcnt lgkmcnt(" #n ")" ::: "memory")
; #define PG8_BAR __builtin_amdgcn_s_barrier()
; template <class Epi, class Sched>
; __device__ __forceinline__ void gemm_phase(PG8_LAS unsigned char* lds, PG8_LAS unsigned char* xl, const Gemm g, const Sched& S, const Epi& E) {
;     ...
;         const char* nA = has_next ? (const char*)g.A + nxt.aoff : cA; const char* nB = has_next ? (const char*)g.Bt + nxt.boff : cB;
; #pragma unroll 1
;         for (int t = 0; t < nt; t += 2) {
;             const bool last = (t == nt - 2);
;             const char* a1 = cA + (size_t)(t + 1) * kstep;
;             const char* a2 = last ? nA : cA + (size_t)(t + 2) * kstep; const char* b2 = last ? nB : cB + (size_t)(t + 2) * kstep;
;             const char* a3 = a2 + kstep; const char* b3 = b2 + kstep;
;             PG8_LDB(B0, 0, 0); PG8_LDB(B1, 0, 1); PG8_SCHED; PG8_LDA(At, 0, 0); PG8_STAGE(PG8_SA(1, 1), a1 + hsA, voffA);
;             PG8_WAIT_V(8); PG8_WAIT_L(0); PG8_BAR; PG8_MMA(0, 0, At, B0); PG8_MMA(0, 1, At, B1); PG8_BAR; PG8_SCHED;
;             PG8_LDA(At, 0, 1); PG8_STAGE(PG8_SB(0, 0), b2, voffB); PG8_STAGE(PG8_SB(0, 1), b2 + hsB, voffB); PG8_STAGE(PG8_SA(0, 0), a2, voffA);
.LBB0_576:
	s_add_u32 s34, s43, s28
	s_addc_u32 s35, s55, s29
	s_and_b64 s[36:37], s[10:11], exec
	s_cselect_b32 s13, s35, s51
	s_cselect_b32 s33, s34, s50
	s_add_u32 s36, s56, s30
	s_addc_u32 s37, s57, s31
	s_and_b64 s[46:47], s[10:11], exec
	s_cselect_b32 s46, s37, s3
	s_cselect_b32 s47, s36, s2
	s_add_u32 s79, s2, 0x100
	s_addc_u32 s80, s3, 0
	s_add_u32 s2, s50, 0x40080
	v_mov_b32_e32 v0, 0
	s_addc_u32 s3, s51, 0
	s_mov_b32 s81, -2
	ds_read_b128 v[146:149], v181
	ds_read_b128 v[150:153], v181 offset:1024
	ds_read_b128 v[188:191], v181 offset:2048
	ds_read_b128 v[192:195], v181 offset:3072
	ds_read_b128 v[196:199], v182
	ds_read_b128 v[200:203], v182 offset:1024
	ds_read_b128 v[204:207], v182 offset:2048
	ds_read_b128 v[208:211], v182 offset:3072
	s_add_u32 s50, s2, 0xfffc0080
	s_addc_u32 s51, s3, -1
	s_cmp_eq_u32 s81, 12
	s_cselect_b32 s53, s13, s51
	s_cselect_b32 s52, s33, s50
	s_cselect_b32 s51, s46, s80
	s_cselect_b32 s50, s47, s79
	v_lshl_add_u64 v[246:247], s[2:3], 0, v[140:141]
	s_add_i32 m0, s60, 0xc000
	ds_read_b128 v[212:215], v183
	ds_read_b128 v[216:219], v183 offset:1024
	ds_read_b128 v[222:225], v183 offset:2048
	ds_read_b128 v[226:229], v183 offset:3072
	ds_read_b128 v[230:233], v183 offset:4096
	ds_read_b128 v[234:237], v183 offset:5120
	ds_read_b128 v[238:241], v183 offset:6144
	ds_read_b128 v[242:245], v183 offset:7168
	global_load_lds_dwordx4 v[246:247], off
	v_lshl_add_u64 v[246:247], s[2:3], 0, v[138:139]
	s_add_i32 m0, s60, 0xe000
	s_nop 0
	global_load_lds_dwordx4 v[246:247], off
	s_waitcnt vmcnt(8) lgkmcnt(0)
	s_barrier
	s_setprio 1
	v_mfma_f32_16x16x32_bf16 v[124:127], v[146:149], v[212:215], 0
	v_mfma_f32_16x16x32_bf16 v[120:123], v[188:191], v[212:215], 0
	v_mfma_f32_16x16x32_bf16 v[108:111], v[146:149], v[222:225], 0
	v_mfma_f32_16x16x32_bf16 v[104:107], v[188:191], v[222:225], 0
	v_mfma_f32_16x16x32_bf16 v[92:95], v[146:149], v[230:233], 0
	v_mfma_f32_16x16x32_bf16 v[88:91], v[188:191], v[230:233], 0
	v_mfma_f32_16x16x32_bf16 v[76:79], v[146:149], v[238:241], 0
	v_mfma_f32_16x16x32_bf16 v[72:75], v[188:191], v[238:241], 0
	v_mfma_f32_16x16x32_bf16 v[124:127], v[150:153], v[216:219], v[124:127]
	v_mfma_f32_16x16x32_bf16 v[120:123], v[192:195], v[216:219], v[120:123]
	v_mfma_f32_16x16x32_bf16 v[108:111], v[150:153], v[226:229], v[108:111]
	v_mfma_f32_16x16x32_bf16 v[104:107], v[192:195], v[226:229], v[104:107]
	v_mfma_f32_16x16x32_bf16 v[92:95], v[150:153], v[234:237], v[92:95]
	v_mfma_f32_16x16x32_bf16 v[88:91], v[192:195], v[234:237], v[88:91]
	v_mfma_f32_16x16x32_bf16 v[76:79], v[150:153], v[242:245], v[76:79]
	v_mfma_f32_16x16x32_bf16 v[72:75], v[192:195], v[242:245], v[72:75]
	s_setprio 0
	s_setprio 1
	v_mfma_f32_16x16x32_bf16 v[116:119], v[196:199], v[212:215], 0
	v_mfma_f32_16x16x32_bf16 v[112:115], v[204:207], v[212:215], 0
	v_mfma_f32_16x16x32_bf16 v[100:103], v[196:199], v[222:225], 0
	v_mfma_f32_16x16x32_bf16 v[96:99], v[204:207], v[222:225], 0
	v_mfma_f32_16x16x32_bf16 v[84:87], v[196:199], v[230:233], 0
	v_mfma_f32_16x16x32_bf16 v[80:83], v[204:207], v[230:233], 0
	v_mfma_f32_16x16x32_bf16 v[68:71], v[196:199], v[238:241], 0
	v_mfma_f32_16x16x32_bf16 v[64:67], v[204:207], v[238:241], 0
	v_mfma_f32_16x16x32_bf16 v[116:119], v[200:203], v[216:219], v[116:119]
	v_mfma_f32_16x16x32_bf16 v[112:115], v[208:211], v[216:219], v[112:115]
	v_mfma_f32_16x16x32_bf16 v[100:103], v[200:203], v[226:229], v[100:103]
	v_mfma_f32_16x16x32_bf16 v[96:99], v[208:211], v[226:229], v[96:99]
	v_mfma_f32_16x16x32_bf16 v[84:87], v[200:203], v[234:237], v[84:87]
	v_mfma_f32_16x16x32_bf16 v[80:83], v[208:211], v[234:237], v[80:83]
	v_mfma_f32_16x16x32_bf16 v[68:71], v[200:203], v[242:245], v[68:71]
	v_mfma_f32_16x16x32_bf16 v[64:67], v[208:211], v[242:245], v[64:67]
	s_setprio 0
	s_barrier
	s_add_i32 s68, s72, s59
	v_lshl_add_u64 v[246:247], s[50:51], 0, v[130:131]
	s_mov_b32 m0, s68
	ds_read_b128 v[212:215], v183 offset:16384
	ds_read_b128 v[216:219], v183 offset:17408
	ds_read_b128 v[222:225], v183 offset:18432
	ds_read_b128 v[226:229], v183 offset:19456
	ds_read_b128 v[230:233], v183 offset:20480
	ds_read_b128 v[234:237], v183 offset:21504
	ds_read_b128 v[238:241], v183 offset:22528
	ds_read_b128 v[242:245], v183 offset:23552
	global_load_lds_dwordx4 v[246:247], off
	s_add_i32 m0, s68, 0x2000
	s_add_u32 s82, s50, 0x40000
	v_lshl_add_u64 v[248:249], s[50:51], 0, v[134:135]
	s_addc_u32 s83, s51, 0
	s_add_i32 s68, s73, s59
	global_load_lds_dwordx4 v[248:249], off
	v_lshl_add_u64 v[250:251], s[82:83], 0, v[130:131]
	s_mov_b32 m0, s68
	v_lshl_add_u64 v[252:253], s[52:53], 0, v[132:133]
	global_load_lds_dwordx4 v[250:251], off
	v_lshl_add_u64 v[250:251], s[82:83], 0, v[134:135]
	s_add_i32 m0, s68, 0x2000
	s_nop 0
	global_load_lds_dwordx4 v[250:251], off
	v_lshl_add_u64 v[250:251], s[52:53], 0, v[128:129]
	s_mov_b32 m0, s60
	s_nop 0
	global_load_lds_dwordx4 v[250:251], off
	s_mov_b32 m0, s61
	s_nop 0
	global_load_lds_dwordx4 v[252:253], off
	s_waitcnt vmcnt(8) lgkmcnt(0)
	s_barrier
; #define PG8_STAGE(bufoff, gbase, voff) do { _Pragma("unroll") for (int _i = 0; _i < 2; ++_i) \
;         __builtin_amdgcn_global_load_lds((const unsigned*)((const char*)(gbase) + (voff)[_i]), (PG8_LAS unsigned*)(lds + (bufoff) + ldsw + _i * 8192), 16, 0, 0); } while (0)
; #define PG8_LDA(dst, b, h) do { _Pragma("unroll") for (int m = 0; m < 4; ++m) _Pragma("unroll") for (int k = 0; k < 2; ++k) dst[m][k] = *(const PG8_LAS bf16x8*)(lds + PG8_SA(b, h) + aoff + m * 2048 + k * 1024); } while (0)
; #define PG8_LDB(dst, b, h) do { _Pragma("unroll") for (int n = 0; n < 2; ++n) _Pragma("unroll") for (int k = 0; k < 2; ++k) dst[n][k] = *(const PG8_LAS bf16x8*)(lds + PG8_SB(b, h) + boff + n * 2048 + k * 1024); } while (0)
; #define PG8_MMA(ai, bj, At, Bt) do { __builtin_amdgcn_s_setprio(1); _Pragma("unroll") for (int m = 0; m < 4; ++m) _Pragma("unroll") for (int n = 0; n < 2; ++n) _Pragma("unroll") for (int k = 0; k < 2; ++k) \
;         acc[ai][bj][m][n] = __builtin_amdgcn_mfma_f32_16x16x32_bf16(Bt[n][k], At[m][k], acc[ai][bj][m][n], 0, 0, 0); __builtin_amdgcn_s_setprio(0); } while (0)
; #define PG8_WAIT_V(n) asm volatile("s_waitcnt vmcnt(" #n ")" ::: "memory")
; #define PG8_WAIT_L(n) asm volatile("s_waitcnt lgkmcnt(" #n ")" ::: "memory")
; #define PG8_BAR __builtin_amdgcn_s_barrier()
; #define PG8_SCHED __builtin_amdgcn_sched_barrier(0)
; template <class Epi, class Sched>
; __device__ __forceinline__ void gemm_phase(PG8_LAS unsigned char* lds, PG8_LAS unsigned char* xl, const Gemm g, const Sched& S, const Epi& E) {
;     ...
;             PG8_WAIT_V(8); PG8_WAIT_L(0); PG8_BAR; PG8_MMA(1, 0, At, B0); PG8_MMA(1, 1, At, B1); PG8_BAR; PG8_SCHED;
;             PG8_LDB(B0, 1, 0); PG8_LDB(B1, 1, 1); PG8_SCHED; PG8_LDA(At, 1, 0); PG8_STAGE(PG8_SA(0, 1), a2 + hsA, voffA);
;             PG8_WAIT_V(8); PG8_WAIT_L(0); PG8_BAR; PG8_MMA(0, 0, At, B0); PG8_MMA(0, 1, At, B1); PG8_BAR; PG8_SCHED;
	s_setprio 1
	v_mfma_f32_16x16x32_bf16 v[60:63], v[146:149], v[212:215], 0
	v_mfma_f32_16x16x32_bf16 v[56:59], v[188:191], v[212:215], 0
	v_mfma_f32_16x16x32_bf16 v[44:47], v[146:149], v[222:225], 0
	v_mfma_f32_16x16x32_bf16 v[40:43], v[188:191], v[222:225], 0
	v_mfma_f32_16x16x32_bf16 v[28:31], v[146:149], v[230:233], 0
	v_mfma_f32_16x16x32_bf16 v[24:27], v[188:191], v[230:233], 0
	v_mfma_f32_16x16x32_bf16 v[12:15], v[146:149], v[238:241], 0
	v_mfma_f32_16x16x32_bf16 v[8:11], v[188:191], v[238:241], 0
	v_mfma_f32_16x16x32_bf16 v[60:63], v[150:153], v[216:219], v[60:63]
	v_mfma_f32_16x16x32_bf16 v[56:59], v[192:195], v[216:219], v[56:59]
	v_mfma_f32_16x16x32_bf16 v[44:47], v[150:153], v[226:229], v[44:47]
	v_mfma_f32_16x16x32_bf16 v[40:43], v[192:195], v[226:229], v[40:43]
	v_mfma_f32_16x16x32_bf16 v[28:31], v[150:153], v[234:237], v[28:31]
	v_mfma_f32_16x16x32_bf16 v[24:27], v[192:195], v[234:237], v[24:27]
	v_mfma_f32_16x16x32_bf16 v[12:15], v[150:153], v[242:245], v[12:15]
	v_mfma_f32_16x16x32_bf16 v[8:11], v[192:195], v[242:245], v[8:11]
	s_setprio 0
	s_setprio 1
	v_mfma_f32_16x16x32_bf16 v[52:55], v[196:199], v[212:215], 0
	v_mfma_f32_16x16x32_bf16 v[48:51], v[204:207], v[212:215], 0
	v_mfma_f32_16x16x32_bf16 v[36:39], v[196:199], v[222:225], 0
	v_mfma_f32_16x16x32_bf16 v[32:35], v[204:207], v[222:225], 0
	v_mfma_f32_16x16x32_bf16 v[20:23], v[196:199], v[230:233], 0
	v_mfma_f32_16x16x32_bf16 v[16:19], v[204:207], v[230:233], 0
	v_mfma_f32_16x16x32_bf16 v[4:7], v[196:199], v[238:241], 0
	v_mfma_f32_16x16x32_bf16 v[0:3], v[204:207], v[238:241], 0
	v_mfma_f32_16x16x32_bf16 v[52:55], v[200:203], v[216:219], v[52:55]
	v_mfma_f32_16x16x32_bf16 v[48:51], v[208:211], v[216:219], v[48:51]
	v_mfma_f32_16x16x32_bf16 v[36:39], v[200:203], v[226:229], v[36:39]
	v_mfma_f32_16x16x32_bf16 v[32:35], v[208:211], v[226:229], v[32:35]
	v_mfma_f32_16x16x32_bf16 v[20:23], v[200:203], v[234:237], v[20:23]
	v_mfma_f32_16x16x32_bf16 v[16:19], v[208:211], v[234:237], v[16:19]
	v_mfma_f32_16x16x32_bf16 v[4:7], v[200:203], v[242:245], v[4:7]
	v_mfma_f32_16x16x32_bf16 v[0:3], v[208:211], v[242:245], v[0:3]
	s_setprio 0
	s_barrier
	s_add_i32 s68, 0, 0x18000
	v_add_u32_e32 v184, s68, v156
	s_add_i32 s82, 0, 0x1c000
	ds_read_b128 v[146:149], v184
	ds_read_b128 v[150:153], v184 offset:1024
	ds_read_b128 v[188:191], v184 offset:2048
	ds_read_b128 v[192:195], v184 offset:3072
	v_add_u32_e32 v184, s82, v156
	ds_read_b128 v[196:199], v184
	ds_read_b128 v[200:203], v184 offset:1024
	ds_read_b128 v[204:207], v184 offset:2048
	ds_read_b128 v[208:211], v184 offset:3072
	s_add_u32 s52, s52, 0x40000
	s_addc_u32 s53, s53, 0
	s_mov_b32 m0, s62
	v_lshl_add_u64 v[184:185], s[52:53], 0, v[128:129]
	ds_read_b128 v[212:215], v183 offset:32768
	ds_read_b128 v[216:219], v183 offset:33792
	ds_read_b128 v[222:225], v183 offset:34816
	ds_read_b128 v[226:229], v183 offset:35840
	ds_read_b128 v[230:233], v183 offset:36864
	ds_read_b128 v[234:237], v183 offset:37888
	ds_read_b128 v[238:241], v183 offset:38912
	ds_read_b128 v[242:245], v183 offset:39936
	global_load_lds_dwordx4 v[184:185], off
	v_lshl_add_u64 v[184:185], s[52:53], 0, v[132:133]
	s_mov_b32 m0, s63
	s_nop 0
	global_load_lds_dwordx4 v[184:185], off
	s_waitcnt vmcnt(8) lgkmcnt(0)
	s_barrier
	s_setprio 1
	v_mfma_f32_16x16x32_bf16 v[124:127], v[146:149], v[212:215], v[124:127]
	v_mfma_f32_16x16x32_bf16 v[120:123], v[188:191], v[212:215], v[120:123]
	v_mfma_f32_16x16x32_bf16 v[108:111], v[146:149], v[222:225], v[108:111]
	v_mfma_f32_16x16x32_bf16 v[104:107], v[188:191], v[222:225], v[104:107]
	v_mfma_f32_16x16x32_bf16 v[92:95], v[146:149], v[230:233], v[92:95]
	v_mfma_f32_16x16x32_bf16 v[88:91], v[188:191], v[230:233], v[88:91]
	v_mfma_f32_16x16x32_bf16 v[76:79], v[146:149], v[238:241], v[76:79]
	v_mfma_f32_16x16x32_bf16 v[72:75], v[188:191], v[238:241], v[72:75]
	v_mfma_f32_16x16x32_bf16 v[124:127], v[150:153], v[216:219], v[124:127]
	v_mfma_f32_16x16x32_bf16 v[120:123], v[192:195], v[216:219], v[120:123]
	v_mfma_f32_16x16x32_bf16 v[108:111], v[150:153], v[226:229], v[108:111]
	v_mfma_f32_16x16x32_bf16 v[104:107], v[192:195], v[226:229], v[104:107]
	v_mfma_f32_16x16x32_bf16 v[92:95], v[150:153], v[234:237], v[92:95]
	v_mfma_f32_16x16x32_bf16 v[88:91], v[192:195], v[234:237], v[88:91]
	v_mfma_f32_16x16x32_bf16 v[76:79], v[150:153], v[242:245], v[76:79]
	v_mfma_f32_16x16x32_bf16 v[72:75], v[192:195], v[242:245], v[72:75]
	s_setprio 0
	s_setprio 1
	v_mfma_f32_16x16x32_bf16 v[116:119], v[196:199], v[212:215], v[116:119]
	v_mfma_f32_16x16x32_bf16 v[112:115], v[204:207], v[212:215], v[112:115]
	v_mfma_f32_16x16x32_bf16 v[100:103], v[196:199], v[222:225], v[100:103]
	v_mfma_f32_16x16x32_bf16 v[96:99], v[204:207], v[222:225], v[96:99]
	v_mfma_f32_16x16x32_bf16 v[84:87], v[196:199], v[230:233], v[84:87]
	v_mfma_f32_16x16x32_bf16 v[80:83], v[204:207], v[230:233], v[80:83]
	v_mfma_f32_16x16x32_bf16 v[68:71], v[196:199], v[238:241], v[68:71]
	v_mfma_f32_16x16x32_bf16 v[64:67], v[204:207], v[238:241], v[64:67]
	v_mfma_f32_16x16x32_bf16 v[116:119], v[200:203], v[216:219], v[116:119]
	v_mfma_f32_16x16x32_bf16 v[112:115], v[208:211], v[216:219], v[112:115]
	v_mfma_f32_16x16x32_bf16 v[100:103], v[200:203], v[226:229], v[100:103]
	v_mfma_f32_16x16x32_bf16 v[96:99], v[208:211], v[226:229], v[96:99]
	v_mfma_f32_16x16x32_bf16 v[84:87], v[200:203], v[234:237], v[84:87]
	v_mfma_f32_16x16x32_bf16 v[80:83], v[208:211], v[234:237], v[80:83]
	v_mfma_f32_16x16x32_bf16 v[68:71], v[200:203], v[242:245], v[68:71]
	v_mfma_f32_16x16x32_bf16 v[64:67], v[208:211], v[242:245], v[64:67]
	s_setprio 0
	s_barrier
; #define PG8_STAGE(bufoff, gbase, voff) do { _Pragma("unroll") for (int _i = 0; _i < 2; ++_i) \
;         __builtin_amdgcn_global_load_lds((const unsigned*)((const char*)(gbase) + (voff)[_i]), (PG8_LAS unsigned*)(lds + (bufoff) + ldsw + _i * 8192), 16, 0, 0); } while (0)
; #define PG8_LDA(dst, b, h) do { _Pragma("unroll") for (int m = 0; m < 4; ++m) _Pragma("unroll") for (int k = 0; k < 2; ++k) dst[m][k] = *(const PG8_LAS bf16x8*)(lds + PG8_SA(b, h) + aoff + m * 2048 + k * 1024); } while (0)
; #define PG8_LDB(dst, b, h) do { _Pragma("unroll") for (int n = 0; n < 2; ++n) _Pragma("unroll") for (int k = 0; k < 2; ++k) dst[n][k] = *(const PG8_LAS bf16x8*)(lds + PG8_SB(b, h) + boff + n * 2048 + k * 1024); } while (0)
; #define PG8_WAIT_V(n) asm volatile("s_waitcnt vmcnt(" #n ")" ::: "memory")
; template <class Epi, class Sched>
; __device__ __forceinline__ void gemm_phase(PG8_LAS unsigned char* lds, PG8_LAS unsigned char* xl, const Gemm g, const Sched& S, const Epi& E) {
;     ...
;         for (int t = 0; t < nt; t += 2) {
;             const bool last = (t == nt - 2);
;             const char* a1 = cA + (size_t)(t + 1) * kstep;
;             const char* a2 = last ? nA : cA + (size_t)(t + 2) * kstep; const char* b2 = last ? nB : cB + (size_t)(t + 2) * kstep;
;             const char* a3 = a2 + kstep; const char* b3 = b2 + kstep;
;             PG8_LDB(B0, 0, 0); PG8_LDB(B1, 0, 1); PG8_SCHED; PG8_LDA(At, 0, 0); PG8_STAGE(PG8_SA(1, 1), a1 + hsA, voffA);
;             PG8_WAIT_V(8); PG8_WAIT_L(0); PG8_BAR; PG8_MMA(0, 0, At, B0); PG8_MMA(0, 1, At, B1); PG8_BAR; PG8_SCHED;
;             PG8_LDA(At, 0, 1); PG8_STAGE(PG8_SB(0, 0), b2, voffB); PG8_STAGE(PG8_SB(0, 1), b2 + hsB, voffB); PG8_STAGE(PG8_SA(0, 0), a2, voffA);
;             PG8_WAIT_V(8); PG8_WAIT_L(0); PG8_BAR; PG8_MMA(1, 0, At, B0); PG8_MMA(1, 1, At, B1); PG8_BAR; PG8_SCHED;
;             PG8_LDB(B0, 1, 0); PG8_LDB(B1, 1, 1); PG8_SCHED; PG8_LDA(At, 1, 0); PG8_STAGE(PG8_SA(0, 1), a2 + hsA, voffA);
;             PG8_WAIT_V(8); PG8_WAIT_L(0); PG8_BAR; PG8_MMA(0, 0, At, B0); PG8_MMA(0, 1, At, B1); PG8_BAR; PG8_SCHED;
;             PG8_LDA(At, 1, 1); PG8_STAGE(PG8_SB(1, 0), b3, voffB); PG8_STAGE(PG8_SB(1, 1), b3 + hsB, voffB); PG8_STAGE(PG8_SA(1, 0), a3, voffA);
;             PG8_WAIT_V(8); PG8_WAIT_L(0); PG8_BAR; PG8_MMA(1, 0, At, B0); PG8_MMA(1, 1, At, B1); PG8_BAR; PG8_SCHED;
	s_add_i32 s52, s68, s59
	v_lshl_add_u64 v[184:185], v[246:247], 0, s[20:21]
	s_mov_b32 m0, s52
	ds_read_b128 v[212:215], v183 offset:49152
	ds_read_b128 v[216:219], v183 offset:50176
	ds_read_b128 v[222:225], v183 offset:51200
	ds_read_b128 v[226:229], v183 offset:52224
	ds_read_b128 v[230:233], v183 offset:53248
	ds_read_b128 v[234:237], v183 offset:54272
	ds_read_b128 v[238:241], v183 offset:55296
	ds_read_b128 v[242:245], v183 offset:56320
	global_load_lds_dwordx4 v[184:185], off
	s_add_i32 m0, s52, 0x2000
	s_add_u32 s50, s50, 0x40080
	v_lshl_add_u64 v[184:185], v[248:249], 0, s[20:21]
	s_addc_u32 s51, s51, 0
	s_add_i32 s52, s82, s59
	global_load_lds_dwordx4 v[184:185], off
	v_lshl_add_u64 v[184:185], s[50:51], 0, v[130:131]
	s_mov_b32 m0, s52
	s_nop 0
	global_load_lds_dwordx4 v[184:185], off
	v_lshl_add_u64 v[184:185], s[50:51], 0, v[134:135]
	s_add_i32 m0, s52, 0x2000
	s_nop 0
	global_load_lds_dwordx4 v[184:185], off
	v_lshl_add_u64 v[184:185], v[250:251], 0, s[20:21]
	s_mov_b32 m0, s65
	s_nop 0
	global_load_lds_dwordx4 v[184:185], off
	v_lshl_add_u64 v[184:185], v[252:253], 0, s[20:21]
	s_mov_b32 m0, s66
	s_nop 0
	global_load_lds_dwordx4 v[184:185], off
	s_waitcnt vmcnt(8) lgkmcnt(0)
	s_barrier
	s_setprio 1
	v_mfma_f32_16x16x32_bf16 v[60:63], v[146:149], v[212:215], v[60:63]
	v_mfma_f32_16x16x32_bf16 v[56:59], v[188:191], v[212:215], v[56:59]
	v_mfma_f32_16x16x32_bf16 v[44:47], v[146:149], v[222:225], v[44:47]
	v_mfma_f32_16x16x32_bf16 v[40:43], v[188:191], v[222:225], v[40:43]
	v_mfma_f32_16x16x32_bf16 v[28:31], v[146:149], v[230:233], v[28:31]
	v_mfma_f32_16x16x32_bf16 v[24:27], v[188:191], v[230:233], v[24:27]
	v_mfma_f32_16x16x32_bf16 v[12:15], v[146:149], v[238:241], v[12:15]
	v_mfma_f32_16x16x32_bf16 v[8:11], v[188:191], v[238:241], v[8:11]
	v_mfma_f32_16x16x32_bf16 v[60:63], v[150:153], v[216:219], v[60:63]
	v_mfma_f32_16x16x32_bf16 v[56:59], v[192:195], v[216:219], v[56:59]
	v_mfma_f32_16x16x32_bf16 v[44:47], v[150:153], v[226:229], v[44:47]
	v_mfma_f32_16x16x32_bf16 v[40:43], v[192:195], v[226:229], v[40:43]
	v_mfma_f32_16x16x32_bf16 v[28:31], v[150:153], v[234:237], v[28:31]
	v_mfma_f32_16x16x32_bf16 v[24:27], v[192:195], v[234:237], v[24:27]
	v_mfma_f32_16x16x32_bf16 v[12:15], v[150:153], v[242:245], v[12:15]
	v_mfma_f32_16x16x32_bf16 v[8:11], v[192:195], v[242:245], v[8:11]
	s_setprio 0
	s_setprio 1
	v_mfma_f32_16x16x32_bf16 v[52:55], v[196:199], v[212:215], v[52:55]
	s_add_i32 s81, s81, 2
	v_mfma_f32_16x16x32_bf16 v[48:51], v[204:207], v[212:215], v[48:51]
	s_add_u32 s79, s79, 0x100
	v_mfma_f32_16x16x32_bf16 v[36:39], v[196:199], v[222:225], v[36:39]
	s_addc_u32 s80, s80, 0
	v_mfma_f32_16x16x32_bf16 v[32:35], v[204:207], v[222:225], v[32:35]
	s_add_u32 s2, s2, 0x100
	v_mfma_f32_16x16x32_bf16 v[20:23], v[196:199], v[230:233], v[20:23]
	s_addc_u32 s3, s3, 0
	v_mfma_f32_16x16x32_bf16 v[16:19], v[204:207], v[230:233], v[16:19]
	s_cmp_gt_u32 s81, 13
	v_mfma_f32_16x16x32_bf16 v[4:7], v[196:199], v[238:241], v[4:7]
	v_mfma_f32_16x16x32_bf16 v[0:3], v[204:207], v[238:241], v[0:3]
	v_mfma_f32_16x16x32_bf16 v[52:55], v[200:203], v[216:219], v[52:55]
	v_mfma_f32_16x16x32_bf16 v[48:51], v[208:211], v[216:219], v[48:51]
	v_mfma_f32_16x16x32_bf16 v[36:39], v[200:203], v[226:229], v[36:39]
	v_mfma_f32_16x16x32_bf16 v[32:35], v[208:211], v[226:229], v[32:35]
	v_mfma_f32_16x16x32_bf16 v[20:23], v[200:203], v[234:237], v[20:23]
	v_mfma_f32_16x16x32_bf16 v[16:19], v[208:211], v[234:237], v[16:19]
	v_mfma_f32_16x16x32_bf16 v[4:7], v[200:203], v[242:245], v[4:7]
	v_mfma_f32_16x16x32_bf16 v[0:3], v[208:211], v[242:245], v[0:3]
	s_setprio 0
	s_barrier
	s_cbranch_scc1 .Lpeel_after_P4
.LBB0_577:
	ds_read_b128 v[146:149], v181
	ds_read_b128 v[150:153], v181 offset:1024
	ds_read_b128 v[188:191], v181 offset:2048
	ds_read_b128 v[192:195], v181 offset:3072
	ds_read_b128 v[196:199], v182
	ds_read_b128 v[200:203], v182 offset:1024
	ds_read_b128 v[204:207], v182 offset:2048
	ds_read_b128 v[208:211], v182 offset:3072
	s_add_u32 s50, s2, 0xfffc0080
	s_addc_u32 s51, s3, -1
	s_cmp_eq_u32 s81, 12
	s_cselect_b32 s53, s13, s51
	s_cselect_b32 s52, s33, s50
	s_cselect_b32 s51, s46, s80
	s_cselect_b32 s50, s47, s79
	v_lshl_add_u64 v[246:247], s[2:3], 0, v[140:141]
	s_add_i32 m0, s60, 0xc000
	ds_read_b128 v[212:215], v183
	ds_read_b128 v[216:219], v183 offset:1024
	ds_read_b128 v[222:225], v183 offset:2048
	ds_read_b128 v[226:229], v183 offset:3072
	ds_read_b128 v[230:233], v183 offset:4096
	ds_read_b128 v[234:237], v183 offset:5120
	ds_read_b128 v[238:241], v183 offset:6144
	ds_read_b128 v[242:245], v183 offset:7168
	global_load_lds_dwordx4 v[246:247], off
	v_lshl_add_u64 v[246:247], s[2:3], 0, v[138:139]
	s_add_i32 m0, s60, 0xe000
	s_nop 0
	global_load_lds_dwordx4 v[246:247], off
	s_waitcnt vmcnt(8) lgkmcnt(0)
	s_barrier
; #define PG8_STAGE(bufoff, gbase, voff) do { _Pragma("unroll") for (int _i = 0; _i < 2; ++_i) \
;         __builtin_amdgcn_global_load_lds((const unsigned*)((const char*)(gbase) + (voff)[_i]), (PG8_LAS unsigned*)(lds + (bufoff) + ldsw + _i * 8192), 16, 0, 0); } while (0)
; #define PG8_LDA(dst, b, h) do { _Pragma("unroll") for (int m = 0; m < 4; ++m) _Pragma("unroll") for (int k = 0; k < 2; ++k) dst[m][k] = *(const PG8_LAS bf16x8*)(lds + PG8_SA(b, h) + aoff + m * 2048 + k * 1024); } while (0)
; #define PG8_MMA(ai, bj, At, Bt) do { __builtin_amdgcn_s_setprio(1); _Pragma("unroll") for (int m = 0; m < 4; ++m) _Pragma("unroll") for (int n = 0; n < 2; ++n) _Pragma("unroll") for (int k = 0; k < 2; ++k) \
;         acc[ai][bj][m][n] = __builtin_amdgcn_mfma_f32_16x16x32_bf16(Bt[n][k], At[m][k], acc[ai][bj][m][n], 0, 0, 0); __builtin_amdgcn_s_setprio(0); } while (0)
; #define PG8_WAIT_V(n) asm volatile("s_waitcnt vmcnt(" #n ")" ::: "memory")
; #define PG8_WAIT_L(n) asm volatile("s_waitcnt lgkmcnt(" #n ")" ::: "memory")
; #define PG8_BAR __builtin_amdgcn_s_barrier()
; #define PG8_SCHED __builtin_amdgcn_sched_barrier(0)
; template <class Epi, class Sched>
; __device__ __forceinline__ void gemm_phase(PG8_LAS unsigned char* lds, PG8_LAS unsigned char* xl, const Gemm g, const Sched& S, const Epi& E) {
;     ...
;             PG8_WAIT_V(8); PG8_WAIT_L(0); PG8_BAR; PG8_MMA(0, 0, At, B0); PG8_MMA(0, 1, At, B1); PG8_BAR; PG8_SCHED;
;             PG8_LDA(At, 0, 1); PG8_STAGE(PG8_SB(0, 0), b2, voffB); PG8_STAGE(PG8_SB(0, 1), b2 + hsB, voffB); PG8_STAGE(PG8_SA(0, 0), a2, voffA);
;             PG8_WAIT_V(8); PG8_WAIT_L(0); PG8_BAR; PG8_MMA(1, 0, At, B0); PG8_MMA(1, 1, At, B1); PG8_BAR; PG8_SCHED;
	s_setprio 1
	v_mfma_f32_16x16x32_bf16 v[124:127], v[146:149], v[212:215], v[124:127]
	v_mfma_f32_16x16x32_bf16 v[120:123], v[188:191], v[212:215], v[120:123]
	v_mfma_f32_16x16x32_bf16 v[108:111], v[146:149], v[222:225], v[108:111]
	v_mfma_f32_16x16x32_bf16 v[104:107], v[188:191], v[222:225], v[104:107]
	v_mfma_f32_16x16x32_bf16 v[92:95], v[146:149], v[230:233], v[92:95]
	v_mfma_f32_16x16x32_bf16 v[88:91], v[188:191], v[230:233], v[88:91]
	v_mfma_f32_16x16x32_bf16 v[76:79], v[146:149], v[238:241], v[76:79]
	v_mfma_f32_16x16x32_bf16 v[72:75], v[188:191], v[238:241], v[72:75]
	v_mfma_f32_16x16x32_bf16 v[124:127], v[150:153], v[216:219], v[124:127]
	v_mfma_f32_16x16x32_bf16 v[120:123], v[192:195], v[216:219], v[120:123]
	v_mfma_f32_16x16x32_bf16 v[108:111], v[150:153], v[226:229], v[108:111]
	v_mfma_f32_16x16x32_bf16 v[104:107], v[192:195], v[226:229], v[104:107]
	v_mfma_f32_16x16x32_bf16 v[92:95], v[150:153], v[234:237], v[92:95]
	v_mfma_f32_16x16x32_bf16 v[88:91], v[192:195], v[234:237], v[88:91]
	v_mfma_f32_16x16x32_bf16 v[76:79], v[150:153], v[242:245], v[76:79]
	v_mfma_f32_16x16x32_bf16 v[72:75], v[192:195], v[242:245], v[72:75]
	s_setprio 0
	s_setprio 1
	v_mfma_f32_16x16x32_bf16 v[116:119], v[196:199], v[212:215], v[116:119]
	v_mfma_f32_16x16x32_bf16 v[112:115], v[204:207], v[212:215], v[112:115]
	v_mfma_f32_16x16x32_bf16 v[100:103], v[196:199], v[222:225], v[100:103]
	v_mfma_f32_16x16x32_bf16 v[96:99], v[204:207], v[222:225], v[96:99]
	v_mfma_f32_16x16x32_bf16 v[84:87], v[196:199], v[230:233], v[84:87]
	v_mfma_f32_16x16x32_bf16 v[80:83], v[204:207], v[230:233], v[80:83]
	v_mfma_f32_16x16x32_bf16 v[68:71], v[196:199], v[238:241], v[68:71]
	v_mfma_f32_16x16x32_bf16 v[64:67], v[204:207], v[238:241], v[64:67]
	v_mfma_f32_16x16x32_bf16 v[116:119], v[200:203], v[216:219], v[116:119]
	v_mfma_f32_16x16x32_bf16 v[112:115], v[208:211], v[216:219], v[112:115]
	v_mfma_f32_16x16x32_bf16 v[100:103], v[200:203], v[226:229], v[100:103]
	v_mfma_f32_16x16x32_bf16 v[96:99], v[208:211], v[226:229], v[96:99]
	v_mfma_f32_16x16x32_bf16 v[84:87], v[200:203], v[234:237], v[84:87]
	v_mfma_f32_16x16x32_bf16 v[80:83], v[208:211], v[234:237], v[80:83]
	v_mfma_f32_16x16x32_bf16 v[68:71], v[200:203], v[242:245], v[68:71]
	v_mfma_f32_16x16x32_bf16 v[64:67], v[208:211], v[242:245], v[64:67]
	s_setprio 0
	s_barrier
	s_add_i32 s68, s72, s59
	v_lshl_add_u64 v[246:247], s[50:51], 0, v[130:131]
	s_mov_b32 m0, s68
	ds_read_b128 v[212:215], v183 offset:16384
	ds_read_b128 v[216:219], v183 offset:17408
	ds_read_b128 v[222:225], v183 offset:18432
	ds_read_b128 v[226:229], v183 offset:19456
	ds_read_b128 v[230:233], v183 offset:20480
	ds_read_b128 v[234:237], v183 offset:21504
	ds_read_b128 v[238:241], v183 offset:22528
	ds_read_b128 v[242:245], v183 offset:23552
	global_load_lds_dwordx4 v[246:247], off
	s_add_i32 m0, s68, 0x2000
	s_add_u32 s82, s50, 0x40000
	v_lshl_add_u64 v[248:249], s[50:51], 0, v[134:135]
	s_addc_u32 s83, s51, 0
	s_add_i32 s68, s73, s59
	global_load_lds_dwordx4 v[248:249], off
	v_lshl_add_u64 v[250:251], s[82:83], 0, v[130:131]
	s_mov_b32 m0, s68
	v_lshl_add_u64 v[252:253], s[52:53], 0, v[132:133]
	global_load_lds_dwordx4 v[250:251], off
	v_lshl_add_u64 v[250:251], s[82:83], 0, v[134:135]
	s_add_i32 m0, s68, 0x2000
	s_nop 0
	global_load_lds_dwordx4 v[250:251], off
	v_lshl_add_u64 v[250:251], s[52:53], 0, v[128:129]
	s_mov_b32 m0, s60
	s_nop 0
	global_load_lds_dwordx4 v[250:251], off
	s_mov_b32 m0, s61
	s_nop 0
	global_load_lds_dwordx4 v[252:253], off
	s_waitcnt vmcnt(8) lgkmcnt(0)
	s_barrier
	s_setprio 1
	v_mfma_f32_16x16x32_bf16 v[60:63], v[146:149], v[212:215], v[60:63]
	v_mfma_f32_16x16x32_bf16 v[56:59], v[188:191], v[212:215], v[56:59]
	v_mfma_f32_16x16x32_bf16 v[44:47], v[146:149], v[222:225], v[44:47]
	v_mfma_f32_16x16x32_bf16 v[40:43], v[188:191], v[222:225], v[40:43]
	v_mfma_f32_16x16x32_bf16 v[28:31], v[146:149], v[230:233], v[28:31]
	v_mfma_f32_16x16x32_bf16 v[24:27], v[188:191], v[230:233], v[24:27]
	v_mfma_f32_16x16x32_bf16 v[12:15], v[146:149], v[238:241], v[12:15]
	v_mfma_f32_16x16x32_bf16 v[8:11], v[188:191], v[238:241], v[8:11]
	v_mfma_f32_16x16x32_bf16 v[60:63], v[150:153], v[216:219], v[60:63]
	v_mfma_f32_16x16x32_bf16 v[56:59], v[192:195], v[216:219], v[56:59]
	v_mfma_f32_16x16x32_bf16 v[44:47], v[150:153], v[226:229], v[44:47]
	v_mfma_f32_16x16x32_bf16 v[40:43], v[192:195], v[226:229], v[40:43]
	v_mfma_f32_16x16x32_bf16 v[28:31], v[150:153], v[234:237], v[28:31]
	v_mfma_f32_16x16x32_bf16 v[24:27], v[192:195], v[234:237], v[24:27]
	v_mfma_f32_16x16x32_bf16 v[12:15], v[150:153], v[242:245], v[12:15]
	v_mfma_f32_16x16x32_bf16 v[8:11], v[192:195], v[242:245], v[8:11]
	s_setprio 0
	s_setprio 1
	v_mfma_f32_16x16x32_bf16 v[52:55], v[196:199], v[212:215], v[52:55]
	v_mfma_f32_16x16x32_bf16 v[48:51], v[204:207], v[212:215], v[48:51]
	v_mfma_f32_16x16x32_bf16 v[36:39], v[196:199], v[222:225], v[36:39]
	v_mfma_f32_16x16x32_bf16 v[32:35], v[204:207], v[222:225], v[32:35]
	v_mfma_f32_16x16x32_bf16 v[20:23], v[196:199], v[230:233], v[20:23]
	v_mfma_f32_16x16x32_bf16 v[16:19], v[204:207], v[230:233], v[16:19]
	v_mfma_f32_16x16x32_bf16 v[4:7], v[196:199], v[238:241], v[4:7]
	v_mfma_f32_16x16x32_bf16 v[0:3], v[204:207], v[238:241], v[0:3]
	v_mfma_f32_16x16x32_bf16 v[52:55], v[200:203], v[216:219], v[52:55]
	v_mfma_f32_16x16x32_bf16 v[48:51], v[208:211], v[216:219], v[48:51]
	v_mfma_f32_16x16x32_bf16 v[36:39], v[200:203], v[226:229], v[36:39]
	v_mfma_f32_16x16x32_bf16 v[32:35], v[208:211], v[226:229], v[32:35]
	v_mfma_f32_16x16x32_bf16 v[20:23], v[200:203], v[234:237], v[20:23]
	v_mfma_f32_16x16x32_bf16 v[16:19], v[208:211], v[234:237], v[16:19]
	v_mfma_f32_16x16x32_bf16 v[4:7], v[200:203], v[242:245], v[4:7]
	v_mfma_f32_16x16x32_bf16 v[0:3], v[208:211], v[242:245], v[0:3]
	s_setprio 0
	s_barrier
; #define PG8_STAGE(bufoff, gbase, voff) do { _Pragma("unroll") for (int _i = 0; _i < 2; ++_i) \
;         __builtin_amdgcn_global_load_lds((const unsigned*)((const char*)(gbase) + (voff)[_i]), (PG8_LAS unsigned*)(lds + (bufoff) + ldsw + _i * 8192), 16, 0, 0); } while (0)
; #define PG8_LDA(dst, b, h) do { _Pragma("unroll") for (int m = 0; m < 4; ++m) _Pragma("unroll") for (int k = 0; k < 2; ++k) dst[m][k] = *(const PG8_LAS bf16x8*)(lds + PG8_SA(b, h) + aoff + m * 2048 + k * 1024); } while (0)
; #define PG8_LDB(dst, b, h) do { _Pragma("unroll") for (int n = 0; n < 2; ++n) _Pragma("unroll") for (int k = 0; k < 2; ++k) dst[n][k] = *(const PG8_LAS bf16x8*)(lds + PG8_SB(b, h) + boff + n * 2048 + k * 1024); } while (0)
; #define PG8_MMA(ai, bj, At, Bt) do { __builtin_amdgcn_s_setprio(1); _Pragma("unroll") for (int m = 0; m < 4; ++m) _Pragma("unroll") for (int n = 0; n < 2; ++n) _Pragma("unroll") for (int k = 0; k < 2; ++k) \
;         acc[ai][bj][m][n] = __builtin_amdgcn_mfma_f32_16x16x32_bf16(Bt[n][k], At[m][k], acc[ai][bj][m][n], 0, 0, 0); __builtin_amdgcn_s_setprio(0); } while (0)
; #define PG8_WAIT_V(n) asm volatile("s_waitcnt vmcnt(" #n ")" ::: "memory")
; #define PG8_WAIT_L(n) asm volatile("s_waitcnt lgkmcnt(" #n ")" ::: "memory")
; #define PG8_BAR __builtin_amdgcn_s_barrier()
; #define PG8_SCHED __builtin_amdgcn_sched_barrier(0)
; template <class Epi, class Sched>
; __device__ __forceinline__ void gemm_phase(PG8_LAS unsigned char* lds, PG8_LAS unsigned char* xl, const Gemm g, const Sched& S, const Epi& E) {
;     ...
;             PG8_LDB(B0, 1, 0); PG8_LDB(B1, 1, 1); PG8_SCHED; PG8_LDA(At, 1, 0); PG8_STAGE(PG8_SA(0, 1), a2 + hsA, voffA);
;             PG8_WAIT_V(8); PG8_WAIT_L(0); PG8_BAR; PG8_MMA(0, 0, At, B0); PG8_MMA(0, 1, At, B1); PG8_BAR; PG8_SCHED;
	s_add_i32 s68, 0, 0x18000
	v_add_u32_e32 v184, s68, v156
	s_add_i32 s82, 0, 0x1c000
	ds_read_b128 v[146:149], v184
	ds_read_b128 v[150:153], v184 offset:1024
	ds_read_b128 v[188:191], v184 offset:2048
	ds_read_b128 v[192:195], v184 offset:3072
	v_add_u32_e32 v184, s82, v156
	ds_read_b128 v[196:199], v184
	ds_read_b128 v[200:203], v184 offset:1024
	ds_read_b128 v[204:207], v184 offset:2048
	ds_read_b128 v[208:211], v184 offset:3072
	s_add_u32 s52, s52, 0x40000
	s_addc_u32 s53, s53, 0
	s_mov_b32 m0, s62
	v_lshl_add_u64 v[184:185], s[52:53], 0, v[128:129]
	ds_read_b128 v[212:215], v183 offset:32768
	ds_read_b128 v[216:219], v183 offset:33792
	ds_read_b128 v[222:225], v183 offset:34816
	ds_read_b128 v[226:229], v183 offset:35840
	ds_read_b128 v[230:233], v183 offset:36864
	ds_read_b128 v[234:237], v183 offset:37888
	ds_read_b128 v[238:241], v183 offset:38912
	ds_read_b128 v[242:245], v183 offset:39936
	global_load_lds_dwordx4 v[184:185], off
	v_lshl_add_u64 v[184:185], s[52:53], 0, v[132:133]
	s_mov_b32 m0, s63
	s_nop 0
	global_load_lds_dwordx4 v[184:185], off
	s_waitcnt vmcnt(8) lgkmcnt(0)
	s_barrier
	s_setprio 1
	v_mfma_f32_16x16x32_bf16 v[124:127], v[146:149], v[212:215], v[124:127]
	v_mfma_f32_16x16x32_bf16 v[120:123], v[188:191], v[212:215], v[120:123]
	v_mfma_f32_16x16x32_bf16 v[108:111], v[146:149], v[222:225], v[108:111]
	v_mfma_f32_16x16x32_bf16 v[104:107], v[188:191], v[222:225], v[104:107]
	v_mfma_f32_16x16x32_bf16 v[92:95], v[146:149], v[230:233], v[92:95]
	v_mfma_f32_16x16x32_bf16 v[88:91], v[188:191], v[230:233], v[88:91]
	v_mfma_f32_16x16x32_bf16 v[76:79], v[146:149], v[238:241], v[76:79]
	v_mfma_f32_16x16x32_bf16 v[72:75], v[188:191], v[238:241], v[72:75]
	v_mfma_f32_16x16x32_bf16 v[124:127], v[150:153], v[216:219], v[124:127]
	v_mfma_f32_16x16x32_bf16 v[120:123], v[192:195], v[216:219], v[120:123]
	v_mfma_f32_16x16x32_bf16 v[108:111], v[150:153], v[226:229], v[108:111]
	v_mfma_f32_16x16x32_bf16 v[104:107], v[192:195], v[226:229], v[104:107]
	v_mfma_f32_16x16x32_bf16 v[92:95], v[150:153], v[234:237], v[92:95]
	v_mfma_f32_16x16x32_bf16 v[88:91], v[192:195], v[234:237], v[88:91]
	v_mfma_f32_16x16x32_bf16 v[76:79], v[150:153], v[242:245], v[76:79]
	v_mfma_f32_16x16x32_bf16 v[72:75], v[192:195], v[242:245], v[72:75]
	s_setprio 0
	s_setprio 1
	v_mfma_f32_16x16x32_bf16 v[116:119], v[196:199], v[212:215], v[116:119]
	v_mfma_f32_16x16x32_bf16 v[112:115], v[204:207], v[212:215], v[112:115]
	v_mfma_f32_16x16x32_bf16 v[100:103], v[196:199], v[222:225], v[100:103]
	v_mfma_f32_16x16x32_bf16 v[96:99], v[204:207], v[222:225], v[96:99]
	v_mfma_f32_16x16x32_bf16 v[84:87], v[196:199], v[230:233], v[84:87]
	v_mfma_f32_16x16x32_bf16 v[80:83], v[204:207], v[230:233], v[80:83]
	v_mfma_f32_16x16x32_bf16 v[68:71], v[196:199], v[238:241], v[68:71]
	v_mfma_f32_16x16x32_bf16 v[64:67], v[204:207], v[238:241], v[64:67]
	v_mfma_f32_16x16x32_bf16 v[116:119], v[200:203], v[216:219], v[116:119]
	v_mfma_f32_16x16x32_bf16 v[112:115], v[208:211], v[216:219], v[112:115]
	v_mfma_f32_16x16x32_bf16 v[100:103], v[200:203], v[226:229], v[100:103]
	v_mfma_f32_16x16x32_bf16 v[96:99], v[208:211], v[226:229], v[96:99]
	v_mfma_f32_16x16x32_bf16 v[84:87], v[200:203], v[234:237], v[84:87]
	v_mfma_f32_16x16x32_bf16 v[80:83], v[208:211], v[234:237], v[80:83]
	v_mfma_f32_16x16x32_bf16 v[68:71], v[200:203], v[242:245], v[68:71]
	v_mfma_f32_16x16x32_bf16 v[64:67], v[208:211], v[242:245], v[64:67]
	s_setprio 0
	s_barrier
; #define PG8_STAGE(bufoff, gbase, voff) do { _Pragma("unroll") for (int _i = 0; _i < 2; ++_i) \
;         __builtin_amdgcn_global_load_lds((const unsigned*)((const char*)(gbase) + (voff)[_i]), (PG8_LAS unsigned*)(lds + (bufoff) + ldsw + _i * 8192), 16, 0, 0); } while (0)
; #define PG8_LDA(dst, b, h) do { _Pragma("unroll") for (int m = 0; m < 4; ++m) _Pragma("unroll") for (int k = 0; k < 2; ++k) dst[m][k] = *(const PG8_LAS bf16x8*)(lds + PG8_SA(b, h) + aoff + m * 2048 + k * 1024); } while (0)
; #define PG8_MMA(ai, bj, At, Bt) do { __builtin_amdgcn_s_setprio(1); _Pragma("unroll") for (int m = 0; m < 4; ++m) _Pragma("unroll") for (int n = 0; n < 2; ++n) _Pragma("unroll") for (int k = 0; k < 2; ++k) \
;         acc[ai][bj][m][n] = __builtin_amdgcn_mfma_f32_16x16x32_bf16(Bt[n][k], At[m][k], acc[ai][bj][m][n], 0, 0, 0); __builtin_amdgcn_s_setprio(0); } while (0)
; #define PG8_WAIT_V(n) asm volatile("s_waitcnt vmcnt(" #n ")" ::: "memory")
; #define PG8_WAIT_L(n) asm volatile("s_waitcnt lgkmcnt(" #n ")" ::: "memory")
; #define PG8_BAR __builtin_amdgcn_s_barrier()
; #define PG8_SCHED __builtin_amdgcn_sched_barrier(0)
; template <class Epi, class Sched>
; __device__ __forceinline__ void gemm_phase(PG8_LAS unsigned char* lds, PG8_LAS unsigned char* xl, const Gemm g, const Sched& S, const Epi& E) {
;     ...
;             PG8_LDA(At, 1, 1); PG8_STAGE(PG8_SB(1, 0), b3, voffB); PG8_STAGE(PG8_SB(1, 1), b3 + hsB, voffB); PG8_STAGE(PG8_SA(1, 0), a3, voffA);
;             PG8_WAIT_V(8); PG8_WAIT_L(0); PG8_BAR; PG8_MMA(1, 0, At, B0); PG8_MMA(1, 1, At, B1); PG8_BAR; PG8_SCHED;
	s_add_i32 s52, s68, s59
	v_lshl_add_u64 v[184:185], v[246:247], 0, s[20:21]
	s_mov_b32 m0, s52
	ds_read_b128 v[212:215], v183 offset:49152
	ds_read_b128 v[216:219], v183 offset:50176
	ds_read_b128 v[222:225], v183 offset:51200
	ds_read_b128 v[226:229], v183 offset:52224
	ds_read_b128 v[230:233], v183 offset:53248
	ds_read_b128 v[234:237], v183 offset:54272
	ds_read_b128 v[238:241], v183 offset:55296
	ds_read_b128 v[242:245], v183 offset:56320
	global_load_lds_dwordx4 v[184:185], off
	s_add_i32 m0, s52, 0x2000
	s_add_u32 s50, s50, 0x40080
	v_lshl_add_u64 v[184:185], v[248:249], 0, s[20:21]
	s_addc_u32 s51, s51, 0
	s_add_i32 s52, s82, s59
	global_load_lds_dwordx4 v[184:185], off
	v_lshl_add_u64 v[184:185], s[50:51], 0, v[130:131]
	s_mov_b32 m0, s52
	s_nop 0
	global_load_lds_dwordx4 v[184:185], off
	v_lshl_add_u64 v[184:185], s[50:51], 0, v[134:135]
	s_add_i32 m0, s52, 0x2000
	s_nop 0
	global_load_lds_dwordx4 v[184:185], off
	v_lshl_add_u64 v[184:185], v[250:251], 0, s[20:21]
	s_mov_b32 m0, s65
	s_nop 0
	global_load_lds_dwordx4 v[184:185], off
	v_lshl_add_u64 v[184:185], v[252:253], 0, s[20:21]
	s_mov_b32 m0, s66
	s_nop 0
	global_load_lds_dwordx4 v[184:185], off
	s_waitcnt vmcnt(8) lgkmcnt(0)
	s_barrier
	s_setprio 1
	v_mfma_f32_16x16x32_bf16 v[60:63], v[146:149], v[212:215], v[60:63]
	v_mfma_f32_16x16x32_bf16 v[56:59], v[188:191], v[212:215], v[56:59]
	v_mfma_f32_16x16x32_bf16 v[44:47], v[146:149], v[222:225], v[44:47]
	v_mfma_f32_16x16x32_bf16 v[40:43], v[188:191], v[222:225], v[40:43]
	v_mfma_f32_16x16x32_bf16 v[28:31], v[146:149], v[230:233], v[28:31]
	v_mfma_f32_16x16x32_bf16 v[24:27], v[188:191], v[230:233], v[24:27]
	v_mfma_f32_16x16x32_bf16 v[12:15], v[146:149], v[238:241], v[12:15]
	v_mfma_f32_16x16x32_bf16 v[8:11], v[188:191], v[238:241], v[8:11]
	v_mfma_f32_16x16x32_bf16 v[60:63], v[150:153], v[216:219], v[60:63]
	v_mfma_f32_16x16x32_bf16 v[56:59], v[192:195], v[216:219], v[56:59]
	v_mfma_f32_16x16x32_bf16 v[44:47], v[150:153], v[226:229], v[44:47]
	v_mfma_f32_16x16x32_bf16 v[40:43], v[192:195], v[226:229], v[40:43]
	v_mfma_f32_16x16x32_bf16 v[28:31], v[150:153], v[234:237], v[28:31]
	v_mfma_f32_16x16x32_bf16 v[24:27], v[192:195], v[234:237], v[24:27]
	v_mfma_f32_16x16x32_bf16 v[12:15], v[150:153], v[242:245], v[12:15]
	v_mfma_f32_16x16x32_bf16 v[8:11], v[192:195], v[242:245], v[8:11]
	s_setprio 0
	s_setprio 1
	v_mfma_f32_16x16x32_bf16 v[52:55], v[196:199], v[212:215], v[52:55]
	s_add_i32 s81, s81, 2
	v_mfma_f32_16x16x32_bf16 v[48:51], v[204:207], v[212:215], v[48:51]
	s_add_u32 s79, s79, 0x100
	v_mfma_f32_16x16x32_bf16 v[36:39], v[196:199], v[222:225], v[36:39]
	s_addc_u32 s80, s80, 0
	v_mfma_f32_16x16x32_bf16 v[32:35], v[204:207], v[222:225], v[32:35]
	s_add_u32 s2, s2, 0x100
	v_mfma_f32_16x16x32_bf16 v[20:23], v[196:199], v[230:233], v[20:23]
	s_addc_u32 s3, s3, 0
	v_mfma_f32_16x16x32_bf16 v[16:19], v[204:207], v[230:233], v[16:19]
	s_cmp_gt_u32 s81, 13
	v_mfma_f32_16x16x32_bf16 v[4:7], v[196:199], v[238:241], v[4:7]
	v_mfma_f32_16x16x32_bf16 v[0:3], v[204:207], v[238:241], v[0:3]
	v_mfma_f32_16x16x32_bf16 v[52:55], v[200:203], v[216:219], v[52:55]
	v_mfma_f32_16x16x32_bf16 v[48:51], v[208:211], v[216:219], v[48:51]
	v_mfma_f32_16x16x32_bf16 v[36:39], v[200:203], v[226:229], v[36:39]
	v_mfma_f32_16x16x32_bf16 v[32:35], v[208:211], v[226:229], v[32:35]
	v_mfma_f32_16x16x32_bf16 v[20:23], v[200:203], v[234:237], v[20:23]
	v_mfma_f32_16x16x32_bf16 v[16:19], v[208:211], v[234:237], v[16:19]
	v_mfma_f32_16x16x32_bf16 v[4:7], v[200:203], v[242:245], v[4:7]
	v_mfma_f32_16x16x32_bf16 v[0:3], v[208:211], v[242:245], v[0:3]
	s_setprio 0
	s_barrier
	s_cbranch_scc0 .LBB0_577

; #define PG8_STAGE(bufoff, gbase, voff) do { _Pragma("unroll") for (int _i = 0; _i < 2; ++_i) \
;         __builtin_amdgcn_global_load_lds((const unsigned*)((const char*)(gbase) + (voff)[_i]), (PG8_LAS unsigned*)(lds + (bufoff) + ldsw + _i * 8192), 16, 0, 0); } while (0)
; #define PG8_LDA(dst, b, h) do { _Pragma("unroll") for (int m = 0; m < 4; ++m) _Pragma("unroll") for (int k = 0; k < 2; ++k) dst[m][k] = *(const PG8_LAS bf16x8*)(lds + PG8_SA(b, h) + aoff + m * 2048 + k * 1024); } while (0)
; #define PG8_LDB(dst, b, h) do { _Pragma("unroll") for (int n = 0; n < 2; ++n) _Pragma("unroll") for (int k = 0; k < 2; ++k) dst[n][k] = *(const PG8_LAS bf16x8*)(lds + PG8_SB(b, h) + boff + n * 2048 + k * 1024); } while (0)
; #define PG8_MMA(ai, bj, At, Bt) do { __builtin_amdgcn_s_setprio(1); _Pragma("unroll") for (int m = 0; m < 4; ++m) _Pragma("unroll") for (int n = 0; n < 2; ++n) _Pragma("unroll") for (int k = 0; k < 2; ++k) \
;         acc[ai][bj][m][n] = __builtin_amdgcn_mfma_f32_16x16x32_bf16(Bt[n][k], At[m][k], acc[ai][bj][m][n], 0, 0, 0); __builtin_amdgcn_s_setprio(0); } while (0)
; #define PG8_WAIT_V(n) asm volatile("s_waitcnt vmcnt(" #n ")" ::: "memory")
; #define PG8_WAIT_L(n) asm volatile("s_waitcnt lgkmcnt(" #n ")" ::: "memory")
; #define PG8_BAR __builtin_amdgcn_s_barrier()
; template <class Epi, class Sched>
; __device__ __forceinline__ void gemm_phase(PG8_LAS unsigned char* lds, PG8_LAS unsigned char* xl, const Gemm g, const Sched& S, const Epi& E) {
;     ...
;         const char* nA = has_next ? (const char*)g.A + nxt.aoff : cA; const char* nB = has_next ? (const char*)g.Bt + nxt.boff : cB;
; #pragma unroll 1
;         for (int t = 0; t < nt; t += 2) {
;             const bool last = (t == nt - 2);
;             const char* a1 = cA + (size_t)(t + 1) * kstep;
;             const char* a2 = last ? nA : cA + (size_t)(t + 2) * kstep; const char* b2 = last ? nB : cB + (size_t)(t + 2) * kstep;
;             const char* a3 = a2 + kstep; const char* b3 = b2 + kstep;
;             PG8_LDB(B0, 0, 0); PG8_LDB(B1, 0, 1); PG8_SCHED; PG8_LDA(At, 0, 0); PG8_STAGE(PG8_SA(1, 1), a1 + hsA, voffA);
;             PG8_WAIT_V(8); PG8_WAIT_L(0); PG8_BAR; PG8_MMA(0, 0, At, B0); PG8_MMA(0, 1, At, B1); PG8_BAR; PG8_SCHED;
;             PG8_LDA(At, 0, 1); PG8_STAGE(PG8_SB(0, 0), b2, voffB); PG8_STAGE(PG8_SB(0, 1), b2 + hsB, voffB); PG8_STAGE(PG8_SA(0, 0), a2, voffA);
.LBB0_724:
	s_add_u32 s26, s43, s20
	s_addc_u32 s27, s50, s21
	s_and_b64 s[28:29], s[8:9], exec
	s_cselect_b32 s33, s27, s35
	s_cselect_b32 s46, s26, s34
	s_add_u32 s28, s51, s22
	s_addc_u32 s29, s52, s23
	s_and_b64 s[36:37], s[8:9], exec
	s_cselect_b32 s47, s29, s31
	s_cselect_b32 s72, s28, s30
	s_add_u32 s73, s30, 0x100
	s_addc_u32 s74, s31, 0
	s_add_u32 s30, s34, 0x40080
	v_mov_b32_e32 v0, 0
	s_addc_u32 s31, s35, 0
	s_mov_b32 s75, -2
	s_waitcnt lgkmcnt(0)
	ds_read_b128 v[170:173], v157
	ds_read_b128 v[174:177], v157 offset:1024
	ds_read_b128 v[180:183], v157 offset:2048
	ds_read_b128 v[184:187], v157 offset:3072
	ds_read_b128 v[188:191], v158
	ds_read_b128 v[192:195], v158 offset:1024
	ds_read_b128 v[196:199], v158 offset:2048
	ds_read_b128 v[200:203], v158 offset:3072
	s_add_u32 s34, s30, 0xfffc0080
	s_addc_u32 s35, s31, -1
	s_cmp_eq_u32 s75, 12
	s_cselect_b32 s37, s33, s35
	s_cselect_b32 s36, s46, s34
	s_cselect_b32 s35, s47, s74
	s_cselect_b32 s34, s72, s73
	v_lshl_add_u64 v[144:145], s[30:31], 0, v[138:139]
	s_add_i32 m0, s57, 0xc000
	ds_read_b128 v[204:207], v159
	ds_read_b128 v[208:211], v159 offset:1024
	ds_read_b128 v[212:215], v159 offset:2048
	ds_read_b128 v[216:219], v159 offset:3072
	ds_read_b128 v[222:225], v159 offset:4096
	ds_read_b128 v[226:229], v159 offset:5120
	ds_read_b128 v[230:233], v159 offset:6144
	ds_read_b128 v[234:237], v159 offset:7168
	global_load_lds_dwordx4 v[144:145], off
	v_lshl_add_u64 v[144:145], s[30:31], 0, v[136:137]
	s_add_i32 m0, s57, 0xe000
	s_nop 0
	global_load_lds_dwordx4 v[144:145], off
	s_waitcnt vmcnt(8) lgkmcnt(0)
	s_barrier
	s_setprio 1
	v_mfma_f32_16x16x32_bf16 v[124:127], v[170:173], v[204:207], 0
	v_mfma_f32_16x16x32_bf16 v[120:123], v[180:183], v[204:207], 0
	v_mfma_f32_16x16x32_bf16 v[108:111], v[170:173], v[212:215], 0
	v_mfma_f32_16x16x32_bf16 v[104:107], v[180:183], v[212:215], 0
	v_mfma_f32_16x16x32_bf16 v[92:95], v[170:173], v[222:225], 0
	v_mfma_f32_16x16x32_bf16 v[88:91], v[180:183], v[222:225], 0
	v_mfma_f32_16x16x32_bf16 v[76:79], v[170:173], v[230:233], 0
	v_mfma_f32_16x16x32_bf16 v[72:75], v[180:183], v[230:233], 0
	v_mfma_f32_16x16x32_bf16 v[124:127], v[174:177], v[208:211], v[124:127]
	v_mfma_f32_16x16x32_bf16 v[120:123], v[184:187], v[208:211], v[120:123]
	v_mfma_f32_16x16x32_bf16 v[108:111], v[174:177], v[216:219], v[108:111]
	v_mfma_f32_16x16x32_bf16 v[104:107], v[184:187], v[216:219], v[104:107]
	v_mfma_f32_16x16x32_bf16 v[92:95], v[174:177], v[226:229], v[92:95]
	v_mfma_f32_16x16x32_bf16 v[88:91], v[184:187], v[226:229], v[88:91]
	v_mfma_f32_16x16x32_bf16 v[76:79], v[174:177], v[234:237], v[76:79]
	v_mfma_f32_16x16x32_bf16 v[72:75], v[184:187], v[234:237], v[72:75]
	s_setprio 0
	s_setprio 1
	v_mfma_f32_16x16x32_bf16 v[116:119], v[188:191], v[204:207], 0
	v_mfma_f32_16x16x32_bf16 v[112:115], v[196:199], v[204:207], 0
	v_mfma_f32_16x16x32_bf16 v[100:103], v[188:191], v[212:215], 0
	v_mfma_f32_16x16x32_bf16 v[96:99], v[196:199], v[212:215], 0
	v_mfma_f32_16x16x32_bf16 v[84:87], v[188:191], v[222:225], 0
	v_mfma_f32_16x16x32_bf16 v[80:83], v[196:199], v[222:225], 0
	v_mfma_f32_16x16x32_bf16 v[68:71], v[188:191], v[230:233], 0
	v_mfma_f32_16x16x32_bf16 v[64:67], v[196:199], v[230:233], 0
	v_mfma_f32_16x16x32_bf16 v[116:119], v[192:195], v[208:211], v[116:119]
	v_mfma_f32_16x16x32_bf16 v[112:115], v[200:203], v[208:211], v[112:115]
	v_mfma_f32_16x16x32_bf16 v[100:103], v[192:195], v[216:219], v[100:103]
	v_mfma_f32_16x16x32_bf16 v[96:99], v[200:203], v[216:219], v[96:99]
	v_mfma_f32_16x16x32_bf16 v[84:87], v[192:195], v[226:229], v[84:87]
	v_mfma_f32_16x16x32_bf16 v[80:83], v[200:203], v[226:229], v[80:83]
	v_mfma_f32_16x16x32_bf16 v[68:71], v[192:195], v[234:237], v[68:71]
	v_mfma_f32_16x16x32_bf16 v[64:67], v[200:203], v[234:237], v[64:67]
	s_setprio 0
	s_barrier
	s_add_i32 s68, s65, s56
	v_lshl_add_u64 v[144:145], s[34:35], 0, v[130:131]
	s_mov_b32 m0, s68
	ds_read_b128 v[204:207], v159 offset:16384
	ds_read_b128 v[208:211], v159 offset:17408
	ds_read_b128 v[212:215], v159 offset:18432
	ds_read_b128 v[216:219], v159 offset:19456
	ds_read_b128 v[222:225], v159 offset:20480
	ds_read_b128 v[226:229], v159 offset:21504
	ds_read_b128 v[230:233], v159 offset:22528
	ds_read_b128 v[234:237], v159 offset:23552
	global_load_lds_dwordx4 v[144:145], off
	s_add_i32 m0, s68, 0x2000
	s_add_u32 s76, s34, 0x40000
	v_lshl_add_u64 v[238:239], s[34:35], 0, v[134:135]
	s_addc_u32 s77, s35, 0
	s_add_i32 s68, s66, s56
	global_load_lds_dwordx4 v[238:239], off
	v_lshl_add_u64 v[240:241], s[76:77], 0, v[130:131]
	s_mov_b32 m0, s68
	v_lshl_add_u64 v[242:243], s[36:37], 0, v[132:133]
	global_load_lds_dwordx4 v[240:241], off
	v_lshl_add_u64 v[240:241], s[76:77], 0, v[134:135]
	s_add_i32 m0, s68, 0x2000
	s_nop 0
	global_load_lds_dwordx4 v[240:241], off
	v_lshl_add_u64 v[240:241], s[36:37], 0, v[128:129]
	s_mov_b32 m0, s57
	s_nop 0
	global_load_lds_dwordx4 v[240:241], off
	s_mov_b32 m0, s58
	s_nop 0
	global_load_lds_dwordx4 v[242:243], off
	s_waitcnt vmcnt(8) lgkmcnt(0)
	s_barrier
; #define PG8_STAGE(bufoff, gbase, voff) do { _Pragma("unroll") for (int _i = 0; _i < 2; ++_i) \
;         __builtin_amdgcn_global_load_lds((const unsigned*)((const char*)(gbase) + (voff)[_i]), (PG8_LAS unsigned*)(lds + (bufoff) + ldsw + _i * 8192), 16, 0, 0); } while (0)
; #define PG8_LDA(dst, b, h) do { _Pragma("unroll") for (int m = 0; m < 4; ++m) _Pragma("unroll") for (int k = 0; k < 2; ++k) dst[m][k] = *(const PG8_LAS bf16x8*)(lds + PG8_SA(b, h) + aoff + m * 2048 + k * 1024); } while (0)
; #define PG8_LDB(dst, b, h) do { _Pragma("unroll") for (int n = 0; n < 2; ++n) _Pragma("unroll") for (int k = 0; k < 2; ++k) dst[n][k] = *(const PG8_LAS bf16x8*)(lds + PG8_SB(b, h) + boff + n * 2048 + k * 1024); } while (0)
; #define PG8_MMA(ai, bj, At, Bt) do { __builtin_amdgcn_s_setprio(1); _Pragma("unroll") for (int m = 0; m < 4; ++m) _Pragma("unroll") for (int n = 0; n < 2; ++n) _Pragma("unroll") for (int k = 0; k < 2; ++k) \
;         acc[ai][bj][m][n] = __builtin_amdgcn_mfma_f32_16x16x32_bf16(Bt[n][k], At[m][k], acc[ai][bj][m][n], 0, 0, 0); __builtin_amdgcn_s_setprio(0); } while (0)
; #define PG8_WAIT_V(n) asm volatile("s_waitcnt vmcnt(" #n ")" ::: "memory")
; #define PG8_WAIT_L(n) asm volatile("s_waitcnt lgkmcnt(" #n ")" ::: "memory")
; #define PG8_BAR __builtin_amdgcn_s_barrier()
; #define PG8_SCHED __builtin_amdgcn_sched_barrier(0)
; template <class Epi, class Sched>
; __device__ __forceinline__ void gemm_phase(PG8_LAS unsigned char* lds, PG8_LAS unsigned char* xl, const Gemm g, const Sched& S, const Epi& E) {
;     ...
;             PG8_WAIT_V(8); PG8_WAIT_L(0); PG8_BAR; PG8_MMA(1, 0, At, B0); PG8_MMA(1, 1, At, B1); PG8_BAR; PG8_SCHED;
;             PG8_LDB(B0, 1, 0); PG8_LDB(B1, 1, 1); PG8_SCHED; PG8_LDA(At, 1, 0); PG8_STAGE(PG8_SA(0, 1), a2 + hsA, voffA);
;             PG8_WAIT_V(8); PG8_WAIT_L(0); PG8_BAR; PG8_MMA(0, 0, At, B0); PG8_MMA(0, 1, At, B1); PG8_BAR; PG8_SCHED;
	s_setprio 1
	v_mfma_f32_16x16x32_bf16 v[60:63], v[170:173], v[204:207], 0
	v_mfma_f32_16x16x32_bf16 v[56:59], v[180:183], v[204:207], 0
	v_mfma_f32_16x16x32_bf16 v[44:47], v[170:173], v[212:215], 0
	v_mfma_f32_16x16x32_bf16 v[40:43], v[180:183], v[212:215], 0
	v_mfma_f32_16x16x32_bf16 v[28:31], v[170:173], v[222:225], 0
	v_mfma_f32_16x16x32_bf16 v[24:27], v[180:183], v[222:225], 0
	v_mfma_f32_16x16x32_bf16 v[12:15], v[170:173], v[230:233], 0
	v_mfma_f32_16x16x32_bf16 v[8:11], v[180:183], v[230:233], 0
	v_mfma_f32_16x16x32_bf16 v[60:63], v[174:177], v[208:211], v[60:63]
	v_mfma_f32_16x16x32_bf16 v[56:59], v[184:187], v[208:211], v[56:59]
	v_mfma_f32_16x16x32_bf16 v[44:47], v[174:177], v[216:219], v[44:47]
	v_mfma_f32_16x16x32_bf16 v[40:43], v[184:187], v[216:219], v[40:43]
	v_mfma_f32_16x16x32_bf16 v[28:31], v[174:177], v[226:229], v[28:31]
	v_mfma_f32_16x16x32_bf16 v[24:27], v[184:187], v[226:229], v[24:27]
	v_mfma_f32_16x16x32_bf16 v[12:15], v[174:177], v[234:237], v[12:15]
	v_mfma_f32_16x16x32_bf16 v[8:11], v[184:187], v[234:237], v[8:11]
	s_setprio 0
	s_setprio 1
	v_mfma_f32_16x16x32_bf16 v[52:55], v[188:191], v[204:207], 0
	v_mfma_f32_16x16x32_bf16 v[48:51], v[196:199], v[204:207], 0
	v_mfma_f32_16x16x32_bf16 v[36:39], v[188:191], v[212:215], 0
	v_mfma_f32_16x16x32_bf16 v[32:35], v[196:199], v[212:215], 0
	v_mfma_f32_16x16x32_bf16 v[20:23], v[188:191], v[222:225], 0
	v_mfma_f32_16x16x32_bf16 v[16:19], v[196:199], v[222:225], 0
	v_mfma_f32_16x16x32_bf16 v[4:7], v[188:191], v[230:233], 0
	v_mfma_f32_16x16x32_bf16 v[0:3], v[196:199], v[230:233], 0
	v_mfma_f32_16x16x32_bf16 v[52:55], v[192:195], v[208:211], v[52:55]
	v_mfma_f32_16x16x32_bf16 v[48:51], v[200:203], v[208:211], v[48:51]
	v_mfma_f32_16x16x32_bf16 v[36:39], v[192:195], v[216:219], v[36:39]
	v_mfma_f32_16x16x32_bf16 v[32:35], v[200:203], v[216:219], v[32:35]
	v_mfma_f32_16x16x32_bf16 v[20:23], v[192:195], v[226:229], v[20:23]
	v_mfma_f32_16x16x32_bf16 v[16:19], v[200:203], v[226:229], v[16:19]
	v_mfma_f32_16x16x32_bf16 v[4:7], v[192:195], v[234:237], v[4:7]
	v_mfma_f32_16x16x32_bf16 v[0:3], v[200:203], v[234:237], v[0:3]
	s_setprio 0
	s_barrier
	s_add_i32 s68, 0, 0x18000
	v_add_u32_e32 v169, s68, v147
	s_add_i32 s76, 0, 0x1c000
	ds_read_b128 v[170:173], v169
	ds_read_b128 v[174:177], v169 offset:1024
	ds_read_b128 v[180:183], v169 offset:2048
	ds_read_b128 v[184:187], v169 offset:3072
	v_add_u32_e32 v169, s76, v147
	ds_read_b128 v[188:191], v169
	ds_read_b128 v[192:195], v169 offset:1024
	ds_read_b128 v[196:199], v169 offset:2048
	ds_read_b128 v[200:203], v169 offset:3072
	s_add_u32 s36, s36, 0x40000
	s_addc_u32 s37, s37, 0
	s_mov_b32 m0, s59
	v_lshl_add_u64 v[244:245], s[36:37], 0, v[128:129]
	ds_read_b128 v[204:207], v159 offset:32768
	ds_read_b128 v[208:211], v159 offset:33792
	ds_read_b128 v[212:215], v159 offset:34816
	ds_read_b128 v[216:219], v159 offset:35840
	ds_read_b128 v[222:225], v159 offset:36864
	ds_read_b128 v[226:229], v159 offset:37888
	ds_read_b128 v[230:233], v159 offset:38912
	ds_read_b128 v[234:237], v159 offset:39936
	global_load_lds_dwordx4 v[244:245], off
	v_lshl_add_u64 v[244:245], s[36:37], 0, v[132:133]
	s_mov_b32 m0, s60
	s_nop 0
	global_load_lds_dwordx4 v[244:245], off
	s_waitcnt vmcnt(8) lgkmcnt(0)
	s_barrier
	s_setprio 1
	v_mfma_f32_16x16x32_bf16 v[124:127], v[170:173], v[204:207], v[124:127]
	v_mfma_f32_16x16x32_bf16 v[120:123], v[180:183], v[204:207], v[120:123]
	v_mfma_f32_16x16x32_bf16 v[108:111], v[170:173], v[212:215], v[108:111]
	v_mfma_f32_16x16x32_bf16 v[104:107], v[180:183], v[212:215], v[104:107]
	v_mfma_f32_16x16x32_bf16 v[92:95], v[170:173], v[222:225], v[92:95]
	v_mfma_f32_16x16x32_bf16 v[88:91], v[180:183], v[222:225], v[88:91]
	v_mfma_f32_16x16x32_bf16 v[76:79], v[170:173], v[230:233], v[76:79]
	v_mfma_f32_16x16x32_bf16 v[72:75], v[180:183], v[230:233], v[72:75]
	v_mfma_f32_16x16x32_bf16 v[124:127], v[174:177], v[208:211], v[124:127]
	v_mfma_f32_16x16x32_bf16 v[120:123], v[184:187], v[208:211], v[120:123]
	v_mfma_f32_16x16x32_bf16 v[108:111], v[174:177], v[216:219], v[108:111]
	v_mfma_f32_16x16x32_bf16 v[104:107], v[184:187], v[216:219], v[104:107]
	v_mfma_f32_16x16x32_bf16 v[92:95], v[174:177], v[226:229], v[92:95]
	v_mfma_f32_16x16x32_bf16 v[88:91], v[184:187], v[226:229], v[88:91]
	v_mfma_f32_16x16x32_bf16 v[76:79], v[174:177], v[234:237], v[76:79]
	v_mfma_f32_16x16x32_bf16 v[72:75], v[184:187], v[234:237], v[72:75]
	s_setprio 0
	s_setprio 1
	v_mfma_f32_16x16x32_bf16 v[116:119], v[188:191], v[204:207], v[116:119]
	v_mfma_f32_16x16x32_bf16 v[112:115], v[196:199], v[204:207], v[112:115]
	v_mfma_f32_16x16x32_bf16 v[100:103], v[188:191], v[212:215], v[100:103]
	v_mfma_f32_16x16x32_bf16 v[96:99], v[196:199], v[212:215], v[96:99]
	v_mfma_f32_16x16x32_bf16 v[84:87], v[188:191], v[222:225], v[84:87]
	v_mfma_f32_16x16x32_bf16 v[80:83], v[196:199], v[222:225], v[80:83]
	v_mfma_f32_16x16x32_bf16 v[68:71], v[188:191], v[230:233], v[68:71]
	v_mfma_f32_16x16x32_bf16 v[64:67], v[196:199], v[230:233], v[64:67]
	v_mfma_f32_16x16x32_bf16 v[116:119], v[192:195], v[208:211], v[116:119]
	v_mfma_f32_16x16x32_bf16 v[112:115], v[200:203], v[208:211], v[112:115]
	v_mfma_f32_16x16x32_bf16 v[100:103], v[192:195], v[216:219], v[100:103]
	v_mfma_f32_16x16x32_bf16 v[96:99], v[200:203], v[216:219], v[96:99]
	v_mfma_f32_16x16x32_bf16 v[84:87], v[192:195], v[226:229], v[84:87]
	v_mfma_f32_16x16x32_bf16 v[80:83], v[200:203], v[226:229], v[80:83]
	v_mfma_f32_16x16x32_bf16 v[68:71], v[192:195], v[234:237], v[68:71]
	v_mfma_f32_16x16x32_bf16 v[64:67], v[200:203], v[234:237], v[64:67]
	s_setprio 0
	s_barrier
; #define PG8_STAGE(bufoff, gbase, voff) do { _Pragma("unroll") for (int _i = 0; _i < 2; ++_i) \
;         __builtin_amdgcn_global_load_lds((const unsigned*)((const char*)(gbase) + (voff)[_i]), (PG8_LAS unsigned*)(lds + (bufoff) + ldsw + _i * 8192), 16, 0, 0); } while (0)
; #define PG8_LDA(dst, b, h) do { _Pragma("unroll") for (int m = 0; m < 4; ++m) _Pragma("unroll") for (int k = 0; k < 2; ++k) dst[m][k] = *(const PG8_LAS bf16x8*)(lds + PG8_SA(b, h) + aoff + m * 2048 + k * 1024); } while (0)
; #define PG8_LDB(dst, b, h) do { _Pragma("unroll") for (int n = 0; n < 2; ++n) _Pragma("unroll") for (int k = 0; k < 2; ++k) dst[n][k] = *(const PG8_LAS bf16x8*)(lds + PG8_SB(b, h) + boff + n * 2048 + k * 1024); } while (0)
; #define PG8_WAIT_V(n) asm volatile("s_waitcnt vmcnt(" #n ")" ::: "memory")
; template <class Epi, class Sched>
; __device__ __forceinline__ void gemm_phase(PG8_LAS unsigned char* lds, PG8_LAS unsigned char* xl, const Gemm g, const Sched& S, const Epi& E) {
;     ...
;         for (int t = 0; t < nt; t += 2) {
;             const bool last = (t == nt - 2);
;             const char* a1 = cA + (size_t)(t + 1) * kstep;
;             const char* a2 = last ? nA : cA + (size_t)(t + 2) * kstep; const char* b2 = last ? nB : cB + (size_t)(t + 2) * kstep;
;             const char* a3 = a2 + kstep; const char* b3 = b2 + kstep;
;             PG8_LDB(B0, 0, 0); PG8_LDB(B1, 0, 1); PG8_SCHED; PG8_LDA(At, 0, 0); PG8_STAGE(PG8_SA(1, 1), a1 + hsA, voffA);
;             PG8_WAIT_V(8); PG8_WAIT_L(0); PG8_BAR; PG8_MMA(0, 0, At, B0); PG8_MMA(0, 1, At, B1); PG8_BAR; PG8_SCHED;
;             PG8_LDA(At, 0, 1); PG8_STAGE(PG8_SB(0, 0), b2, voffB); PG8_STAGE(PG8_SB(0, 1), b2 + hsB, voffB); PG8_STAGE(PG8_SA(0, 0), a2, voffA);
;             PG8_WAIT_V(8); PG8_WAIT_L(0); PG8_BAR; PG8_MMA(1, 0, At, B0); PG8_MMA(1, 1, At, B1); PG8_BAR; PG8_SCHED;
;             PG8_LDB(B0, 1, 0); PG8_LDB(B1, 1, 1); PG8_SCHED; PG8_LDA(At, 1, 0); PG8_STAGE(PG8_SA(0, 1), a2 + hsA, voffA);
;             PG8_WAIT_V(8); PG8_WAIT_L(0); PG8_BAR; PG8_MMA(0, 0, At, B0); PG8_MMA(0, 1, At, B1); PG8_BAR; PG8_SCHED;
;             PG8_LDA(At, 1, 1); PG8_STAGE(PG8_SB(1, 0), b3, voffB); PG8_STAGE(PG8_SB(1, 1), b3 + hsB, voffB); PG8_STAGE(PG8_SA(1, 0), a3, voffA);
;             PG8_WAIT_V(8); PG8_WAIT_L(0); PG8_BAR; PG8_MMA(1, 0, At, B0); PG8_MMA(1, 1, At, B1); PG8_BAR; PG8_SCHED;
	s_add_i32 s36, s68, s56
	v_lshl_add_u64 v[144:145], v[144:145], 0, s[16:17]
	s_mov_b32 m0, s36
	ds_read_b128 v[204:207], v159 offset:49152
	ds_read_b128 v[208:211], v159 offset:50176
	ds_read_b128 v[212:215], v159 offset:51200
	ds_read_b128 v[216:219], v159 offset:52224
	ds_read_b128 v[222:225], v159 offset:53248
	ds_read_b128 v[226:229], v159 offset:54272
	ds_read_b128 v[230:233], v159 offset:55296
	ds_read_b128 v[234:237], v159 offset:56320
	global_load_lds_dwordx4 v[144:145], off
	s_add_i32 m0, s36, 0x2000
	s_add_u32 s34, s34, 0x40080
	v_lshl_add_u64 v[144:145], v[238:239], 0, s[16:17]
	s_addc_u32 s35, s35, 0
	s_add_i32 s36, s76, s56
	global_load_lds_dwordx4 v[144:145], off
	v_lshl_add_u64 v[144:145], s[34:35], 0, v[130:131]
	s_mov_b32 m0, s36
	s_nop 0
	global_load_lds_dwordx4 v[144:145], off
	v_lshl_add_u64 v[144:145], s[34:35], 0, v[134:135]
	s_add_i32 m0, s36, 0x2000
	s_nop 0
	global_load_lds_dwordx4 v[144:145], off
	v_lshl_add_u64 v[144:145], v[240:241], 0, s[16:17]
	s_mov_b32 m0, s62
	s_nop 0
	global_load_lds_dwordx4 v[144:145], off
	v_lshl_add_u64 v[144:145], v[242:243], 0, s[16:17]
	s_mov_b32 m0, s63
	s_nop 0
	global_load_lds_dwordx4 v[144:145], off
	s_waitcnt vmcnt(8) lgkmcnt(0)
	s_barrier
	s_setprio 1
	v_mfma_f32_16x16x32_bf16 v[60:63], v[170:173], v[204:207], v[60:63]
	v_mfma_f32_16x16x32_bf16 v[56:59], v[180:183], v[204:207], v[56:59]
	v_mfma_f32_16x16x32_bf16 v[44:47], v[170:173], v[212:215], v[44:47]
	v_mfma_f32_16x16x32_bf16 v[40:43], v[180:183], v[212:215], v[40:43]
	v_mfma_f32_16x16x32_bf16 v[28:31], v[170:173], v[222:225], v[28:31]
	v_mfma_f32_16x16x32_bf16 v[24:27], v[180:183], v[222:225], v[24:27]
	v_mfma_f32_16x16x32_bf16 v[12:15], v[170:173], v[230:233], v[12:15]
	v_mfma_f32_16x16x32_bf16 v[8:11], v[180:183], v[230:233], v[8:11]
	v_mfma_f32_16x16x32_bf16 v[60:63], v[174:177], v[208:211], v[60:63]
	v_mfma_f32_16x16x32_bf16 v[56:59], v[184:187], v[208:211], v[56:59]
	v_mfma_f32_16x16x32_bf16 v[44:47], v[174:177], v[216:219], v[44:47]
	v_mfma_f32_16x16x32_bf16 v[40:43], v[184:187], v[216:219], v[40:43]
	v_mfma_f32_16x16x32_bf16 v[28:31], v[174:177], v[226:229], v[28:31]
	v_mfma_f32_16x16x32_bf16 v[24:27], v[184:187], v[226:229], v[24:27]
	v_mfma_f32_16x16x32_bf16 v[12:15], v[174:177], v[234:237], v[12:15]
	v_mfma_f32_16x16x32_bf16 v[8:11], v[184:187], v[234:237], v[8:11]
	s_setprio 0
	s_setprio 1
	v_mfma_f32_16x16x32_bf16 v[52:55], v[188:191], v[204:207], v[52:55]
	s_add_i32 s75, s75, 2
	v_mfma_f32_16x16x32_bf16 v[48:51], v[196:199], v[204:207], v[48:51]
	s_add_u32 s73, s73, 0x100
	v_mfma_f32_16x16x32_bf16 v[36:39], v[188:191], v[212:215], v[36:39]
	s_addc_u32 s74, s74, 0
	v_mfma_f32_16x16x32_bf16 v[32:35], v[196:199], v[212:215], v[32:35]
	s_add_u32 s30, s30, 0x100
	v_mfma_f32_16x16x32_bf16 v[20:23], v[188:191], v[222:225], v[20:23]
	s_addc_u32 s31, s31, 0
	v_mfma_f32_16x16x32_bf16 v[16:19], v[196:199], v[222:225], v[16:19]
	s_cmp_gt_u32 s75, 13
	v_mfma_f32_16x16x32_bf16 v[4:7], v[188:191], v[230:233], v[4:7]
	v_mfma_f32_16x16x32_bf16 v[0:3], v[196:199], v[230:233], v[0:3]
	v_mfma_f32_16x16x32_bf16 v[52:55], v[192:195], v[208:211], v[52:55]
	v_mfma_f32_16x16x32_bf16 v[48:51], v[200:203], v[208:211], v[48:51]
	v_mfma_f32_16x16x32_bf16 v[36:39], v[192:195], v[216:219], v[36:39]
	v_mfma_f32_16x16x32_bf16 v[32:35], v[200:203], v[216:219], v[32:35]
	v_mfma_f32_16x16x32_bf16 v[20:23], v[192:195], v[226:229], v[20:23]
	v_mfma_f32_16x16x32_bf16 v[16:19], v[200:203], v[226:229], v[16:19]
	v_mfma_f32_16x16x32_bf16 v[4:7], v[192:195], v[234:237], v[4:7]
	v_mfma_f32_16x16x32_bf16 v[0:3], v[200:203], v[234:237], v[0:3]
	s_setprio 0
	s_barrier
	s_cbranch_scc1 .Lpeel_after_P7
.LBB0_725:
	ds_read_b128 v[170:173], v157
	ds_read_b128 v[174:177], v157 offset:1024
	ds_read_b128 v[180:183], v157 offset:2048
	ds_read_b128 v[184:187], v157 offset:3072
	ds_read_b128 v[188:191], v158
	ds_read_b128 v[192:195], v158 offset:1024
	ds_read_b128 v[196:199], v158 offset:2048
	ds_read_b128 v[200:203], v158 offset:3072
	s_add_u32 s34, s30, 0xfffc0080
	s_addc_u32 s35, s31, -1
	s_cmp_eq_u32 s75, 12
	s_cselect_b32 s37, s33, s35
	s_cselect_b32 s36, s46, s34
	s_cselect_b32 s35, s47, s74
	s_cselect_b32 s34, s72, s73
	v_lshl_add_u64 v[144:145], s[30:31], 0, v[138:139]
	s_add_i32 m0, s57, 0xc000
	ds_read_b128 v[204:207], v159
	ds_read_b128 v[208:211], v159 offset:1024
	ds_read_b128 v[212:215], v159 offset:2048
	ds_read_b128 v[216:219], v159 offset:3072
	ds_read_b128 v[222:225], v159 offset:4096
	ds_read_b128 v[226:229], v159 offset:5120
	ds_read_b128 v[230:233], v159 offset:6144
	ds_read_b128 v[234:237], v159 offset:7168
	global_load_lds_dwordx4 v[144:145], off
	v_lshl_add_u64 v[144:145], s[30:31], 0, v[136:137]
	s_add_i32 m0, s57, 0xe000
	s_nop 0
	global_load_lds_dwordx4 v[144:145], off
	s_waitcnt vmcnt(8) lgkmcnt(0)
	s_barrier
; #define PG8_STAGE(bufoff, gbase, voff) do { _Pragma("unroll") for (int _i = 0; _i < 2; ++_i) \
;         __builtin_amdgcn_global_load_lds((const unsigned*)((const char*)(gbase) + (voff)[_i]), (PG8_LAS unsigned*)(lds + (bufoff) + ldsw + _i * 8192), 16, 0, 0); } while (0)
; #define PG8_LDA(dst, b, h) do { _Pragma("unroll") for (int m = 0; m < 4; ++m) _Pragma("unroll") for (int k = 0; k < 2; ++k) dst[m][k] = *(const PG8_LAS bf16x8*)(lds + PG8_SA(b, h) + aoff + m * 2048 + k * 1024); } while (0)
; #define PG8_MMA(ai, bj, At, Bt) do { __builtin_amdgcn_s_setprio(1); _Pragma("unroll") for (int m = 0; m < 4; ++m) _Pragma("unroll") for (int n = 0; n < 2; ++n) _Pragma("unroll") for (int k = 0; k < 2; ++k) \
;         acc[ai][bj][m][n] = __builtin_amdgcn_mfma_f32_16x16x32_bf16(Bt[n][k], At[m][k], acc[ai][bj][m][n], 0, 0, 0); __builtin_amdgcn_s_setprio(0); } while (0)
; #define PG8_WAIT_V(n) asm volatile("s_waitcnt vmcnt(" #n ")" ::: "memory")
; #define PG8_WAIT_L(n) asm volatile("s_waitcnt lgkmcnt(" #n ")" ::: "memory")
; #define PG8_BAR __builtin_amdgcn_s_barrier()
; #define PG8_SCHED __builtin_amdgcn_sched_barrier(0)
; template <class Epi, class Sched>
; __device__ __forceinline__ void gemm_phase(PG8_LAS unsigned char* lds, PG8_LAS unsigned char* xl, const Gemm g, const Sched& S, const Epi& E) {
;     ...
;             PG8_WAIT_V(8); PG8_WAIT_L(0); PG8_BAR; PG8_MMA(0, 0, At, B0); PG8_MMA(0, 1, At, B1); PG8_BAR; PG8_SCHED;
;             PG8_LDA(At, 0, 1); PG8_STAGE(PG8_SB(0, 0), b2, voffB); PG8_STAGE(PG8_SB(0, 1), b2 + hsB, voffB); PG8_STAGE(PG8_SA(0, 0), a2, voffA);
;             PG8_WAIT_V(8); PG8_WAIT_L(0); PG8_BAR; PG8_MMA(1, 0, At, B0); PG8_MMA(1, 1, At, B1); PG8_BAR; PG8_SCHED;
	s_setprio 1
	v_mfma_f32_16x16x32_bf16 v[124:127], v[170:173], v[204:207], v[124:127]
	v_mfma_f32_16x16x32_bf16 v[120:123], v[180:183], v[204:207], v[120:123]
	v_mfma_f32_16x16x32_bf16 v[108:111], v[170:173], v[212:215], v[108:111]
	v_mfma_f32_16x16x32_bf16 v[104:107], v[180:183], v[212:215], v[104:107]
	v_mfma_f32_16x16x32_bf16 v[92:95], v[170:173], v[222:225], v[92:95]
	v_mfma_f32_16x16x32_bf16 v[88:91], v[180:183], v[222:225], v[88:91]
	v_mfma_f32_16x16x32_bf16 v[76:79], v[170:173], v[230:233], v[76:79]
	v_mfma_f32_16x16x32_bf16 v[72:75], v[180:183], v[230:233], v[72:75]
	v_mfma_f32_16x16x32_bf16 v[124:127], v[174:177], v[208:211], v[124:127]
	v_mfma_f32_16x16x32_bf16 v[120:123], v[184:187], v[208:211], v[120:123]
	v_mfma_f32_16x16x32_bf16 v[108:111], v[174:177], v[216:219], v[108:111]
	v_mfma_f32_16x16x32_bf16 v[104:107], v[184:187], v[216:219], v[104:107]
	v_mfma_f32_16x16x32_bf16 v[92:95], v[174:177], v[226:229], v[92:95]
	v_mfma_f32_16x16x32_bf16 v[88:91], v[184:187], v[226:229], v[88:91]
	v_mfma_f32_16x16x32_bf16 v[76:79], v[174:177], v[234:237], v[76:79]
	v_mfma_f32_16x16x32_bf16 v[72:75], v[184:187], v[234:237], v[72:75]
	s_setprio 0
	s_setprio 1
	v_mfma_f32_16x16x32_bf16 v[116:119], v[188:191], v[204:207], v[116:119]
	v_mfma_f32_16x16x32_bf16 v[112:115], v[196:199], v[204:207], v[112:115]
	v_mfma_f32_16x16x32_bf16 v[100:103], v[188:191], v[212:215], v[100:103]
	v_mfma_f32_16x16x32_bf16 v[96:99], v[196:199], v[212:215], v[96:99]
	v_mfma_f32_16x16x32_bf16 v[84:87], v[188:191], v[222:225], v[84:87]
	v_mfma_f32_16x16x32_bf16 v[80:83], v[196:199], v[222:225], v[80:83]
	v_mfma_f32_16x16x32_bf16 v[68:71], v[188:191], v[230:233], v[68:71]
	v_mfma_f32_16x16x32_bf16 v[64:67], v[196:199], v[230:233], v[64:67]
	v_mfma_f32_16x16x32_bf16 v[116:119], v[192:195], v[208:211], v[116:119]
	v_mfma_f32_16x16x32_bf16 v[112:115], v[200:203], v[208:211], v[112:115]
	v_mfma_f32_16x16x32_bf16 v[100:103], v[192:195], v[216:219], v[100:103]
	v_mfma_f32_16x16x32_bf16 v[96:99], v[200:203], v[216:219], v[96:99]
	v_mfma_f32_16x16x32_bf16 v[84:87], v[192:195], v[226:229], v[84:87]
	v_mfma_f32_16x16x32_bf16 v[80:83], v[200:203], v[226:229], v[80:83]
	v_mfma_f32_16x16x32_bf16 v[68:71], v[192:195], v[234:237], v[68:71]
	v_mfma_f32_16x16x32_bf16 v[64:67], v[200:203], v[234:237], v[64:67]
	s_setprio 0
	s_barrier
	s_add_i32 s68, s65, s56
	v_lshl_add_u64 v[144:145], s[34:35], 0, v[130:131]
	s_mov_b32 m0, s68
	ds_read_b128 v[204:207], v159 offset:16384
	ds_read_b128 v[208:211], v159 offset:17408
	ds_read_b128 v[212:215], v159 offset:18432
	ds_read_b128 v[216:219], v159 offset:19456
	ds_read_b128 v[222:225], v159 offset:20480
	ds_read_b128 v[226:229], v159 offset:21504
	ds_read_b128 v[230:233], v159 offset:22528
	ds_read_b128 v[234:237], v159 offset:23552
	global_load_lds_dwordx4 v[144:145], off
	s_add_i32 m0, s68, 0x2000
	s_add_u32 s76, s34, 0x40000
	v_lshl_add_u64 v[238:239], s[34:35], 0, v[134:135]
	s_addc_u32 s77, s35, 0
	s_add_i32 s68, s66, s56
	global_load_lds_dwordx4 v[238:239], off
	v_lshl_add_u64 v[240:241], s[76:77], 0, v[130:131]
	s_mov_b32 m0, s68
	v_lshl_add_u64 v[242:243], s[36:37], 0, v[132:133]
	global_load_lds_dwordx4 v[240:241], off
	v_lshl_add_u64 v[240:241], s[76:77], 0, v[134:135]
	s_add_i32 m0, s68, 0x2000
	s_nop 0
	global_load_lds_dwordx4 v[240:241], off
	v_lshl_add_u64 v[240:241], s[36:37], 0, v[128:129]
	s_mov_b32 m0, s57
	s_nop 0
	global_load_lds_dwordx4 v[240:241], off
	s_mov_b32 m0, s58
	s_nop 0
	global_load_lds_dwordx4 v[242:243], off
	s_waitcnt vmcnt(8) lgkmcnt(0)
	s_barrier
	s_setprio 1
	v_mfma_f32_16x16x32_bf16 v[60:63], v[170:173], v[204:207], v[60:63]
	v_mfma_f32_16x16x32_bf16 v[56:59], v[180:183], v[204:207], v[56:59]
	v_mfma_f32_16x16x32_bf16 v[44:47], v[170:173], v[212:215], v[44:47]
	v_mfma_f32_16x16x32_bf16 v[40:43], v[180:183], v[212:215], v[40:43]
	v_mfma_f32_16x16x32_bf16 v[28:31], v[170:173], v[222:225], v[28:31]
	v_mfma_f32_16x16x32_bf16 v[24:27], v[180:183], v[222:225], v[24:27]
	v_mfma_f32_16x16x32_bf16 v[12:15], v[170:173], v[230:233], v[12:15]
	v_mfma_f32_16x16x32_bf16 v[8:11], v[180:183], v[230:233], v[8:11]
	v_mfma_f32_16x16x32_bf16 v[60:63], v[174:177], v[208:211], v[60:63]
	v_mfma_f32_16x16x32_bf16 v[56:59], v[184:187], v[208:211], v[56:59]
	v_mfma_f32_16x16x32_bf16 v[44:47], v[174:177], v[216:219], v[44:47]
	v_mfma_f32_16x16x32_bf16 v[40:43], v[184:187], v[216:219], v[40:43]
	v_mfma_f32_16x16x32_bf16 v[28:31], v[174:177], v[226:229], v[28:31]
	v_mfma_f32_16x16x32_bf16 v[24:27], v[184:187], v[226:229], v[24:27]
	v_mfma_f32_16x16x32_bf16 v[12:15], v[174:177], v[234:237], v[12:15]
	v_mfma_f32_16x16x32_bf16 v[8:11], v[184:187], v[234:237], v[8:11]
	s_setprio 0
	s_setprio 1
	v_mfma_f32_16x16x32_bf16 v[52:55], v[188:191], v[204:207], v[52:55]
	v_mfma_f32_16x16x32_bf16 v[48:51], v[196:199], v[204:207], v[48:51]
	v_mfma_f32_16x16x32_bf16 v[36:39], v[188:191], v[212:215], v[36:39]
	v_mfma_f32_16x16x32_bf16 v[32:35], v[196:199], v[212:215], v[32:35]
	v_mfma_f32_16x16x32_bf16 v[20:23], v[188:191], v[222:225], v[20:23]
	v_mfma_f32_16x16x32_bf16 v[16:19], v[196:199], v[222:225], v[16:19]
	v_mfma_f32_16x16x32_bf16 v[4:7], v[188:191], v[230:233], v[4:7]
	v_mfma_f32_16x16x32_bf16 v[0:3], v[196:199], v[230:233], v[0:3]
	v_mfma_f32_16x16x32_bf16 v[52:55], v[192:195], v[208:211], v[52:55]
	v_mfma_f32_16x16x32_bf16 v[48:51], v[200:203], v[208:211], v[48:51]
	v_mfma_f32_16x16x32_bf16 v[36:39], v[192:195], v[216:219], v[36:39]
	v_mfma_f32_16x16x32_bf16 v[32:35], v[200:203], v[216:219], v[32:35]
	v_mfma_f32_16x16x32_bf16 v[20:23], v[192:195], v[226:229], v[20:23]
	v_mfma_f32_16x16x32_bf16 v[16:19], v[200:203], v[226:229], v[16:19]
	v_mfma_f32_16x16x32_bf16 v[4:7], v[192:195], v[234:237], v[4:7]
	v_mfma_f32_16x16x32_bf16 v[0:3], v[200:203], v[234:237], v[0:3]
	s_setprio 0
	s_barrier
; #define PG8_STAGE(bufoff, gbase, voff) do { _Pragma("unroll") for (int _i = 0; _i < 2; ++_i) \
;         __builtin_amdgcn_global_load_lds((const unsigned*)((const char*)(gbase) + (voff)[_i]), (PG8_LAS unsigned*)(lds + (bufoff) + ldsw + _i * 8192), 16, 0, 0); } while (0)
; #define PG8_LDA(dst, b, h) do { _Pragma("unroll") for (int m = 0; m < 4; ++m) _Pragma("unroll") for (int k = 0; k < 2; ++k) dst[m][k] = *(const PG8_LAS bf16x8*)(lds + PG8_SA(b, h) + aoff + m * 2048 + k * 1024); } while (0)
; #define PG8_LDB(dst, b, h) do { _Pragma("unroll") for (int n = 0; n < 2; ++n) _Pragma("unroll") for (int k = 0; k < 2; ++k) dst[n][k] = *(const PG8_LAS bf16x8*)(lds + PG8_SB(b, h) + boff + n * 2048 + k * 1024); } while (0)
; #define PG8_MMA(ai, bj, At, Bt) do { __builtin_amdgcn_s_setprio(1); _Pragma("unroll") for (int m = 0; m < 4; ++m) _Pragma("unroll") for (int n = 0; n < 2; ++n) _Pragma("unroll") for (int k = 0; k < 2; ++k) \
;         acc[ai][bj][m][n] = __builtin_amdgcn_mfma_f32_16x16x32_bf16(Bt[n][k], At[m][k], acc[ai][bj][m][n], 0, 0, 0); __builtin_amdgcn_s_setprio(0); } while (0)
; #define PG8_WAIT_V(n) asm volatile("s_waitcnt vmcnt(" #n ")" ::: "memory")
; #define PG8_WAIT_L(n) asm volatile("s_waitcnt lgkmcnt(" #n ")" ::: "memory")
; #define PG8_BAR __builtin_amdgcn_s_barrier()
; #define PG8_SCHED __builtin_amdgcn_sched_barrier(0)
; template <class Epi, class Sched>
; __device__ __forceinline__ void gemm_phase(PG8_LAS unsigned char* lds, PG8_LAS unsigned char* xl, const Gemm g, const Sched& S, const Epi& E) {
;     ...
;             PG8_LDB(B0, 1, 0); PG8_LDB(B1, 1, 1); PG8_SCHED; PG8_LDA(At, 1, 0); PG8_STAGE(PG8_SA(0, 1), a2 + hsA, voffA);
;             PG8_WAIT_V(8); PG8_WAIT_L(0); PG8_BAR; PG8_MMA(0, 0, At, B0); PG8_MMA(0, 1, At, B1); PG8_BAR; PG8_SCHED;
	s_add_i32 s68, 0, 0x18000
	v_add_u32_e32 v169, s68, v147
	s_add_i32 s76, 0, 0x1c000
	ds_read_b128 v[170:173], v169
	ds_read_b128 v[174:177], v169 offset:1024
	ds_read_b128 v[180:183], v169 offset:2048
	ds_read_b128 v[184:187], v169 offset:3072
	v_add_u32_e32 v169, s76, v147
	ds_read_b128 v[188:191], v169
	ds_read_b128 v[192:195], v169 offset:1024
	ds_read_b128 v[196:199], v169 offset:2048
	ds_read_b128 v[200:203], v169 offset:3072
	s_add_u32 s36, s36, 0x40000
	s_addc_u32 s37, s37, 0
	s_mov_b32 m0, s59
	v_lshl_add_u64 v[244:245], s[36:37], 0, v[128:129]
	ds_read_b128 v[204:207], v159 offset:32768
	ds_read_b128 v[208:211], v159 offset:33792
	ds_read_b128 v[212:215], v159 offset:34816
	ds_read_b128 v[216:219], v159 offset:35840
	ds_read_b128 v[222:225], v159 offset:36864
	ds_read_b128 v[226:229], v159 offset:37888
	ds_read_b128 v[230:233], v159 offset:38912
	ds_read_b128 v[234:237], v159 offset:39936
	global_load_lds_dwordx4 v[244:245], off
	v_lshl_add_u64 v[244:245], s[36:37], 0, v[132:133]
	s_mov_b32 m0, s60
	s_nop 0
	global_load_lds_dwordx4 v[244:245], off
	s_waitcnt vmcnt(8) lgkmcnt(0)
	s_barrier
	s_setprio 1
	v_mfma_f32_16x16x32_bf16 v[124:127], v[170:173], v[204:207], v[124:127]
	v_mfma_f32_16x16x32_bf16 v[120:123], v[180:183], v[204:207], v[120:123]
	v_mfma_f32_16x16x32_bf16 v[108:111], v[170:173], v[212:215], v[108:111]
	v_mfma_f32_16x16x32_bf16 v[104:107], v[180:183], v[212:215], v[104:107]
	v_mfma_f32_16x16x32_bf16 v[92:95], v[170:173], v[222:225], v[92:95]
	v_mfma_f32_16x16x32_bf16 v[88:91], v[180:183], v[222:225], v[88:91]
	v_mfma_f32_16x16x32_bf16 v[76:79], v[170:173], v[230:233], v[76:79]
	v_mfma_f32_16x16x32_bf16 v[72:75], v[180:183], v[230:233], v[72:75]
	v_mfma_f32_16x16x32_bf16 v[124:127], v[174:177], v[208:211], v[124:127]
	v_mfma_f32_16x16x32_bf16 v[120:123], v[184:187], v[208:211], v[120:123]
	v_mfma_f32_16x16x32_bf16 v[108:111], v[174:177], v[216:219], v[108:111]
	v_mfma_f32_16x16x32_bf16 v[104:107], v[184:187], v[216:219], v[104:107]
	v_mfma_f32_16x16x32_bf16 v[92:95], v[174:177], v[226:229], v[92:95]
	v_mfma_f32_16x16x32_bf16 v[88:91], v[184:187], v[226:229], v[88:91]
	v_mfma_f32_16x16x32_bf16 v[76:79], v[174:177], v[234:237], v[76:79]
	v_mfma_f32_16x16x32_bf16 v[72:75], v[184:187], v[234:237], v[72:75]
	s_setprio 0
	s_setprio 1
	v_mfma_f32_16x16x32_bf16 v[116:119], v[188:191], v[204:207], v[116:119]
	v_mfma_f32_16x16x32_bf16 v[112:115], v[196:199], v[204:207], v[112:115]
	v_mfma_f32_16x16x32_bf16 v[100:103], v[188:191], v[212:215], v[100:103]
	v_mfma_f32_16x16x32_bf16 v[96:99], v[196:199], v[212:215], v[96:99]
	v_mfma_f32_16x16x32_bf16 v[84:87], v[188:191], v[222:225], v[84:87]
	v_mfma_f32_16x16x32_bf16 v[80:83], v[196:199], v[222:225], v[80:83]
	v_mfma_f32_16x16x32_bf16 v[68:71], v[188:191], v[230:233], v[68:71]
	v_mfma_f32_16x16x32_bf16 v[64:67], v[196:199], v[230:233], v[64:67]
	v_mfma_f32_16x16x32_bf16 v[116:119], v[192:195], v[208:211], v[116:119]
	v_mfma_f32_16x16x32_bf16 v[112:115], v[200:203], v[208:211], v[112:115]
	v_mfma_f32_16x16x32_bf16 v[100:103], v[192:195], v[216:219], v[100:103]
	v_mfma_f32_16x16x32_bf16 v[96:99], v[200:203], v[216:219], v[96:99]
	v_mfma_f32_16x16x32_bf16 v[84:87], v[192:195], v[226:229], v[84:87]
	v_mfma_f32_16x16x32_bf16 v[80:83], v[200:203], v[226:229], v[80:83]
	v_mfma_f32_16x16x32_bf16 v[68:71], v[192:195], v[234:237], v[68:71]
	v_mfma_f32_16x16x32_bf16 v[64:67], v[200:203], v[234:237], v[64:67]
	s_setprio 0
	s_barrier
; #define PG8_STAGE(bufoff, gbase, voff) do { _Pragma("unroll") for (int _i = 0; _i < 2; ++_i) \
;         __builtin_amdgcn_global_load_lds((const unsigned*)((const char*)(gbase) + (voff)[_i]), (PG8_LAS unsigned*)(lds + (bufoff) + ldsw + _i * 8192), 16, 0, 0); } while (0)
; #define PG8_LDA(dst, b, h) do { _Pragma("unroll") for (int m = 0; m < 4; ++m) _Pragma("unroll") for (int k = 0; k < 2; ++k) dst[m][k] = *(const PG8_LAS bf16x8*)(lds + PG8_SA(b, h) + aoff + m * 2048 + k * 1024); } while (0)
; #define PG8_MMA(ai, bj, At, Bt) do { __builtin_amdgcn_s_setprio(1); _Pragma("unroll") for (int m = 0; m < 4; ++m) _Pragma("unroll") for (int n = 0; n < 2; ++n) _Pragma("unroll") for (int k = 0; k < 2; ++k) \
;         acc[ai][bj][m][n] = __builtin_amdgcn_mfma_f32_16x16x32_bf16(Bt[n][k], At[m][k], acc[ai][bj][m][n], 0, 0, 0); __builtin_amdgcn_s_setprio(0); } while (0)
; #define PG8_WAIT_V(n) asm volatile("s_waitcnt vmcnt(" #n ")" ::: "memory")
; #define PG8_WAIT_L(n) asm volatile("s_waitcnt lgkmcnt(" #n ")" ::: "memory")
; #define PG8_BAR __builtin_amdgcn_s_barrier()
; #define PG8_SCHED __builtin_amdgcn_sched_barrier(0)
; template <class Epi, class Sched>
; __device__ __forceinline__ void gemm_phase(PG8_LAS unsigned char* lds, PG8_LAS unsigned char* xl, const Gemm g, const Sched& S, const Epi& E) {
;     ...
;             PG8_LDA(At, 1, 1); PG8_STAGE(PG8_SB(1, 0), b3, voffB); PG8_STAGE(PG8_SB(1, 1), b3 + hsB, voffB); PG8_STAGE(PG8_SA(1, 0), a3, voffA);
;             PG8_WAIT_V(8); PG8_WAIT_L(0); PG8_BAR; PG8_MMA(1, 0, At, B0); PG8_MMA(1, 1, At, B1); PG8_BAR; PG8_SCHED;
	s_add_i32 s36, s68, s56
	v_lshl_add_u64 v[144:145], v[144:145], 0, s[16:17]
	s_mov_b32 m0, s36
	ds_read_b128 v[204:207], v159 offset:49152
	ds_read_b128 v[208:211], v159 offset:50176
	ds_read_b128 v[212:215], v159 offset:51200
	ds_read_b128 v[216:219], v159 offset:52224
	ds_read_b128 v[222:225], v159 offset:53248
	ds_read_b128 v[226:229], v159 offset:54272
	ds_read_b128 v[230:233], v159 offset:55296
	ds_read_b128 v[234:237], v159 offset:56320
	global_load_lds_dwordx4 v[144:145], off
	s_add_i32 m0, s36, 0x2000
	s_add_u32 s34, s34, 0x40080
	v_lshl_add_u64 v[144:145], v[238:239], 0, s[16:17]
	s_addc_u32 s35, s35, 0
	s_add_i32 s36, s76, s56
	global_load_lds_dwordx4 v[144:145], off
	v_lshl_add_u64 v[144:145], s[34:35], 0, v[130:131]
	s_mov_b32 m0, s36
	s_nop 0
	global_load_lds_dwordx4 v[144:145], off
	v_lshl_add_u64 v[144:145], s[34:35], 0, v[134:135]
	s_add_i32 m0, s36, 0x2000
	s_nop 0
	global_load_lds_dwordx4 v[144:145], off
	v_lshl_add_u64 v[144:145], v[240:241], 0, s[16:17]
	s_mov_b32 m0, s62
	s_nop 0
	global_load_lds_dwordx4 v[144:145], off
	v_lshl_add_u64 v[144:145], v[242:243], 0, s[16:17]
	s_mov_b32 m0, s63
	s_nop 0
	global_load_lds_dwordx4 v[144:145], off
	s_waitcnt vmcnt(8) lgkmcnt(0)
	s_barrier
	s_setprio 1
	v_mfma_f32_16x16x32_bf16 v[60:63], v[170:173], v[204:207], v[60:63]
	v_mfma_f32_16x16x32_bf16 v[56:59], v[180:183], v[204:207], v[56:59]
	v_mfma_f32_16x16x32_bf16 v[44:47], v[170:173], v[212:215], v[44:47]
	v_mfma_f32_16x16x32_bf16 v[40:43], v[180:183], v[212:215], v[40:43]
	v_mfma_f32_16x16x32_bf16 v[28:31], v[170:173], v[222:225], v[28:31]
	v_mfma_f32_16x16x32_bf16 v[24:27], v[180:183], v[222:225], v[24:27]
	v_mfma_f32_16x16x32_bf16 v[12:15], v[170:173], v[230:233], v[12:15]
	v_mfma_f32_16x16x32_bf16 v[8:11], v[180:183], v[230:233], v[8:11]
	v_mfma_f32_16x16x32_bf16 v[60:63], v[174:177], v[208:211], v[60:63]
	v_mfma_f32_16x16x32_bf16 v[56:59], v[184:187], v[208:211], v[56:59]
	v_mfma_f32_16x16x32_bf16 v[44:47], v[174:177], v[216:219], v[44:47]
	v_mfma_f32_16x16x32_bf16 v[40:43], v[184:187], v[216:219], v[40:43]
	v_mfma_f32_16x16x32_bf16 v[28:31], v[174:177], v[226:229], v[28:31]
	v_mfma_f32_16x16x32_bf16 v[24:27], v[184:187], v[226:229], v[24:27]
	v_mfma_f32_16x16x32_bf16 v[12:15], v[174:177], v[234:237], v[12:15]
	v_mfma_f32_16x16x32_bf16 v[8:11], v[184:187], v[234:237], v[8:11]
	s_setprio 0
	s_setprio 1
	v_mfma_f32_16x16x32_bf16 v[52:55], v[188:191], v[204:207], v[52:55]
	s_add_i32 s75, s75, 2
	v_mfma_f32_16x16x32_bf16 v[48:51], v[196:199], v[204:207], v[48:51]
	s_add_u32 s73, s73, 0x100
	v_mfma_f32_16x16x32_bf16 v[36:39], v[188:191], v[212:215], v[36:39]
	s_addc_u32 s74, s74, 0
	v_mfma_f32_16x16x32_bf16 v[32:35], v[196:199], v[212:215], v[32:35]
	s_add_u32 s30, s30, 0x100
	v_mfma_f32_16x16x32_bf16 v[20:23], v[188:191], v[222:225], v[20:23]
	s_addc_u32 s31, s31, 0
	v_mfma_f32_16x16x32_bf16 v[16:19], v[196:199], v[222:225], v[16:19]
	s_cmp_gt_u32 s75, 13
	v_mfma_f32_16x16x32_bf16 v[4:7], v[188:191], v[230:233], v[4:7]
	v_mfma_f32_16x16x32_bf16 v[0:3], v[196:199], v[230:233], v[0:3]
	v_mfma_f32_16x16x32_bf16 v[52:55], v[192:195], v[208:211], v[52:55]
	v_mfma_f32_16x16x32_bf16 v[48:51], v[200:203], v[208:211], v[48:51]
	v_mfma_f32_16x16x32_bf16 v[36:39], v[192:195], v[216:219], v[36:39]
	v_mfma_f32_16x16x32_bf16 v[32:35], v[200:203], v[216:219], v[32:35]
	v_mfma_f32_16x16x32_bf16 v[20:23], v[192:195], v[226:229], v[20:23]
	v_mfma_f32_16x16x32_bf16 v[16:19], v[200:203], v[226:229], v[16:19]
	v_mfma_f32_16x16x32_bf16 v[4:7], v[192:195], v[234:237], v[4:7]
	v_mfma_f32_16x16x32_bf16 v[0:3], v[200:203], v[234:237], v[0:3]
	s_setprio 0
	s_barrier
	s_cbranch_scc0 .LBB0_725

; #define PG8_STAGE(bufoff, gbase, voff) do { _Pragma("unroll") for (int _i = 0; _i < 2; ++_i) \
;         __builtin_amdgcn_global_load_lds((const unsigned*)((const char*)(gbase) + (voff)[_i]), (PG8_LAS unsigned*)(lds + (bufoff) + ldsw + _i * 8192), 16, 0, 0); } while (0)
; #define PG8_LDA(dst, b, h) do { _Pragma("unroll") for (int m = 0; m < 4; ++m) _Pragma("unroll") for (int k = 0; k < 2; ++k) dst[m][k] = *(const PG8_LAS bf16x8*)(lds + PG8_SA(b, h) + aoff + m * 2048 + k * 1024); } while (0)
; #define PG8_LDB(dst, b, h) do { _Pragma("unroll") for (int n = 0; n < 2; ++n) _Pragma("unroll") for (int k = 0; k < 2; ++k) dst[n][k] = *(const PG8_LAS bf16x8*)(lds + PG8_SB(b, h) + boff + n * 2048 + k * 1024); } while (0)
; #define PG8_MMA(ai, bj, At, Bt) do { __builtin_amdgcn_s_setprio(1); _Pragma("unroll") for (int m = 0; m < 4; ++m) _Pragma("unroll") for (int n = 0; n < 2; ++n) _Pragma("unroll") for (int k = 0; k < 2; ++k) \
;         acc[ai][bj][m][n] = __builtin_amdgcn_mfma_f32_16x16x32_bf16(Bt[n][k], At[m][k], acc[ai][bj][m][n], 0, 0, 0); __builtin_amdgcn_s_setprio(0); } while (0)
; #define PG8_WAIT_V(n) asm volatile("s_waitcnt vmcnt(" #n ")" ::: "memory")
; #define PG8_WAIT_L(n) asm volatile("s_waitcnt lgkmcnt(" #n ")" ::: "memory")
; #define PG8_BAR __builtin_amdgcn_s_barrier()
; template <class Epi, class Sched>
; __device__ __forceinline__ void gemm_phase(PG8_LAS unsigned char* lds, PG8_LAS unsigned char* xl, const Gemm g, const Sched& S, const Epi& E) {
;     ...
;         const char* nA = has_next ? (const char*)g.A + nxt.aoff : cA; const char* nB = has_next ? (const char*)g.Bt + nxt.boff : cB;
; #pragma unroll 1
;         for (int t = 0; t < nt; t += 2) {
;             const bool last = (t == nt - 2);
;             const char* a1 = cA + (size_t)(t + 1) * kstep;
;             const char* a2 = last ? nA : cA + (size_t)(t + 2) * kstep; const char* b2 = last ? nB : cB + (size_t)(t + 2) * kstep;
;             const char* a3 = a2 + kstep; const char* b3 = b2 + kstep;
;             PG8_LDB(B0, 0, 0); PG8_LDB(B1, 0, 1); PG8_SCHED; PG8_LDA(At, 0, 0); PG8_STAGE(PG8_SA(1, 1), a1 + hsA, voffA);
;             PG8_WAIT_V(8); PG8_WAIT_L(0); PG8_BAR; PG8_MMA(0, 0, At, B0); PG8_MMA(0, 1, At, B1); PG8_BAR; PG8_SCHED;
;             PG8_LDA(At, 0, 1); PG8_STAGE(PG8_SB(0, 0), b2, voffB); PG8_STAGE(PG8_SB(0, 1), b2 + hsB, voffB); PG8_STAGE(PG8_SA(0, 0), a2, voffA);
.LBB0_824:
	s_add_u32 s26, s37, s20
	s_addc_u32 s27, s42, s21
	s_and_b64 s[28:29], s[6:7], exec
	s_cselect_b32 s46, s27, s31
	s_cselect_b32 s47, s26, s30
	s_add_u32 s28, s43, s22
	s_addc_u32 s29, s50, s23
	s_and_b64 s[34:35], s[6:7], exec
	s_cselect_b32 s70, s29, s3
	s_cselect_b32 s72, s28, s2
	s_add_u32 s73, s2, 0x100
	s_addc_u32 s74, s3, 0
	s_add_u32 s2, s30, 0x40080
	v_mov_b32_e32 v0, 0
	s_addc_u32 s3, s31, 0
	s_mov_b32 s75, -2
	ds_read_b128 v[170:173], v164
	ds_read_b128 v[174:177], v164 offset:1024
	ds_read_b128 v[180:183], v164 offset:2048
	ds_read_b128 v[184:187], v164 offset:3072
	ds_read_b128 v[188:191], v165
	ds_read_b128 v[192:195], v165 offset:1024
	ds_read_b128 v[196:199], v165 offset:2048
	ds_read_b128 v[200:203], v165 offset:3072
	s_add_u32 s30, s2, 0xfffc0080
	s_addc_u32 s31, s3, -1
	s_cmp_eq_u32 s75, 12
	s_cselect_b32 s35, s46, s31
	s_cselect_b32 s34, s47, s30
	s_cselect_b32 s31, s70, s74
	s_cselect_b32 s30, s72, s73
	v_lshl_add_u64 v[238:239], s[2:3], 0, v[140:141]
	s_add_i32 m0, s55, 0xc000
	ds_read_b128 v[204:207], v166
	ds_read_b128 v[208:211], v166 offset:1024
	ds_read_b128 v[212:215], v166 offset:2048
	ds_read_b128 v[216:219], v166 offset:3072
	ds_read_b128 v[222:225], v166 offset:4096
	ds_read_b128 v[226:229], v166 offset:5120
	ds_read_b128 v[230:233], v166 offset:6144
	ds_read_b128 v[234:237], v166 offset:7168
	global_load_lds_dwordx4 v[238:239], off
	v_lshl_add_u64 v[238:239], s[2:3], 0, v[138:139]
	s_add_i32 m0, s55, 0xe000
	s_nop 0
	global_load_lds_dwordx4 v[238:239], off
	s_waitcnt vmcnt(8) lgkmcnt(0)
	s_barrier
	s_setprio 1
	v_mfma_f32_16x16x32_bf16 v[124:127], v[170:173], v[204:207], 0
	v_mfma_f32_16x16x32_bf16 v[116:119], v[180:183], v[204:207], 0
	v_mfma_f32_16x16x32_bf16 v[108:111], v[170:173], v[212:215], 0
	v_mfma_f32_16x16x32_bf16 v[100:103], v[180:183], v[212:215], 0
	v_mfma_f32_16x16x32_bf16 v[92:95], v[170:173], v[222:225], 0
	v_mfma_f32_16x16x32_bf16 v[84:87], v[180:183], v[222:225], 0
	v_mfma_f32_16x16x32_bf16 v[76:79], v[170:173], v[230:233], 0
	v_mfma_f32_16x16x32_bf16 v[68:71], v[180:183], v[230:233], 0
	v_mfma_f32_16x16x32_bf16 v[124:127], v[174:177], v[208:211], v[124:127]
	v_mfma_f32_16x16x32_bf16 v[116:119], v[184:187], v[208:211], v[116:119]
	v_mfma_f32_16x16x32_bf16 v[108:111], v[174:177], v[216:219], v[108:111]
	v_mfma_f32_16x16x32_bf16 v[100:103], v[184:187], v[216:219], v[100:103]
	v_mfma_f32_16x16x32_bf16 v[92:95], v[174:177], v[226:229], v[92:95]
	v_mfma_f32_16x16x32_bf16 v[84:87], v[184:187], v[226:229], v[84:87]
	v_mfma_f32_16x16x32_bf16 v[76:79], v[174:177], v[234:237], v[76:79]
	v_mfma_f32_16x16x32_bf16 v[68:71], v[184:187], v[234:237], v[68:71]
	s_setprio 0
	s_setprio 1
	v_mfma_f32_16x16x32_bf16 v[120:123], v[188:191], v[204:207], 0
	v_mfma_f32_16x16x32_bf16 v[112:115], v[196:199], v[204:207], 0
	v_mfma_f32_16x16x32_bf16 v[104:107], v[188:191], v[212:215], 0
	v_mfma_f32_16x16x32_bf16 v[96:99], v[196:199], v[212:215], 0
	v_mfma_f32_16x16x32_bf16 v[88:91], v[188:191], v[222:225], 0
	v_mfma_f32_16x16x32_bf16 v[80:83], v[196:199], v[222:225], 0
	v_mfma_f32_16x16x32_bf16 v[72:75], v[188:191], v[230:233], 0
	v_mfma_f32_16x16x32_bf16 v[64:67], v[196:199], v[230:233], 0
	v_mfma_f32_16x16x32_bf16 v[120:123], v[192:195], v[208:211], v[120:123]
	v_mfma_f32_16x16x32_bf16 v[112:115], v[200:203], v[208:211], v[112:115]
	v_mfma_f32_16x16x32_bf16 v[104:107], v[192:195], v[216:219], v[104:107]
	v_mfma_f32_16x16x32_bf16 v[96:99], v[200:203], v[216:219], v[96:99]
	v_mfma_f32_16x16x32_bf16 v[88:91], v[192:195], v[226:229], v[88:91]
	v_mfma_f32_16x16x32_bf16 v[80:83], v[200:203], v[226:229], v[80:83]
	v_mfma_f32_16x16x32_bf16 v[72:75], v[192:195], v[234:237], v[72:75]
	v_mfma_f32_16x16x32_bf16 v[64:67], v[200:203], v[234:237], v[64:67]
	s_setprio 0
	s_barrier
	s_add_i32 s68, s54, s51
	v_lshl_add_u64 v[238:239], s[30:31], 0, v[132:133]
	s_mov_b32 m0, s68
	ds_read_b128 v[204:207], v166 offset:16384
	ds_read_b128 v[208:211], v166 offset:17408
	ds_read_b128 v[212:215], v166 offset:18432
	ds_read_b128 v[216:219], v166 offset:19456
	ds_read_b128 v[222:225], v166 offset:20480
	ds_read_b128 v[226:229], v166 offset:21504
	ds_read_b128 v[230:233], v166 offset:22528
	ds_read_b128 v[234:237], v166 offset:23552
	global_load_lds_dwordx4 v[238:239], off
	s_add_i32 m0, s68, 0x2000
	s_add_u32 s76, s30, 0x40000
	v_lshl_add_u64 v[240:241], s[30:31], 0, v[128:129]
	s_addc_u32 s77, s31, 0
	s_add_i32 s68, s62, s51
	global_load_lds_dwordx4 v[240:241], off
	v_lshl_add_u64 v[242:243], s[76:77], 0, v[132:133]
	s_mov_b32 m0, s68
	v_lshl_add_u64 v[244:245], s[34:35], 0, v[130:131]
	global_load_lds_dwordx4 v[242:243], off
	v_lshl_add_u64 v[242:243], s[76:77], 0, v[128:129]
	s_add_i32 m0, s68, 0x2000
	s_nop 0
	global_load_lds_dwordx4 v[242:243], off
	v_lshl_add_u64 v[242:243], s[34:35], 0, v[134:135]
	s_mov_b32 m0, s55
	s_nop 0
	global_load_lds_dwordx4 v[242:243], off
	s_mov_b32 m0, s56
	s_nop 0
	global_load_lds_dwordx4 v[244:245], off
	s_waitcnt vmcnt(8) lgkmcnt(0)
	s_barrier
; #define PG8_STAGE(bufoff, gbase, voff) do { _Pragma("unroll") for (int _i = 0; _i < 2; ++_i) \
;         __builtin_amdgcn_global_load_lds((const unsigned*)((const char*)(gbase) + (voff)[_i]), (PG8_LAS unsigned*)(lds + (bufoff) + ldsw + _i * 8192), 16, 0, 0); } while (0)
; #define PG8_LDA(dst, b, h) do { _Pragma("unroll") for (int m = 0; m < 4; ++m) _Pragma("unroll") for (int k = 0; k < 2; ++k) dst[m][k] = *(const PG8_LAS bf16x8*)(lds + PG8_SA(b, h) + aoff + m * 2048 + k * 1024); } while (0)
; #define PG8_LDB(dst, b, h) do { _Pragma("unroll") for (int n = 0; n < 2; ++n) _Pragma("unroll") for (int k = 0; k < 2; ++k) dst[n][k] = *(const PG8_LAS bf16x8*)(lds + PG8_SB(b, h) + boff + n * 2048 + k * 1024); } while (0)
; #define PG8_MMA(ai, bj, At, Bt) do { __builtin_amdgcn_s_setprio(1); _Pragma("unroll") for (int m = 0; m < 4; ++m) _Pragma("unroll") for (int n = 0; n < 2; ++n) _Pragma("unroll") for (int k = 0; k < 2; ++k) \
;         acc[ai][bj][m][n] = __builtin_amdgcn_mfma_f32_16x16x32_bf16(Bt[n][k], At[m][k], acc[ai][bj][m][n], 0, 0, 0); __builtin_amdgcn_s_setprio(0); } while (0)
; #define PG8_WAIT_V(n) asm volatile("s_waitcnt vmcnt(" #n ")" ::: "memory")
; #define PG8_WAIT_L(n) asm volatile("s_waitcnt lgkmcnt(" #n ")" ::: "memory")
; #define PG8_BAR __builtin_amdgcn_s_barrier()
; #define PG8_SCHED __builtin_amdgcn_sched_barrier(0)
; template <class Epi, class Sched>
; __device__ __forceinline__ void gemm_phase(PG8_LAS unsigned char* lds, PG8_LAS unsigned char* xl, const Gemm g, const Sched& S, const Epi& E) {
;     ...
;             PG8_WAIT_V(8); PG8_WAIT_L(0); PG8_BAR; PG8_MMA(1, 0, At, B0); PG8_MMA(1, 1, At, B1); PG8_BAR; PG8_SCHED;
;             PG8_LDB(B0, 1, 0); PG8_LDB(B1, 1, 1); PG8_SCHED; PG8_LDA(At, 1, 0); PG8_STAGE(PG8_SA(0, 1), a2 + hsA, voffA);
;             PG8_WAIT_V(8); PG8_WAIT_L(0); PG8_BAR; PG8_MMA(0, 0, At, B0); PG8_MMA(0, 1, At, B1); PG8_BAR; PG8_SCHED;
	s_setprio 1
	v_mfma_f32_16x16x32_bf16 v[60:63], v[170:173], v[204:207], 0
	v_mfma_f32_16x16x32_bf16 v[52:55], v[180:183], v[204:207], 0
	v_mfma_f32_16x16x32_bf16 v[44:47], v[170:173], v[212:215], 0
	v_mfma_f32_16x16x32_bf16 v[36:39], v[180:183], v[212:215], 0
	v_mfma_f32_16x16x32_bf16 v[28:31], v[170:173], v[222:225], 0
	v_mfma_f32_16x16x32_bf16 v[20:23], v[180:183], v[222:225], 0
	v_mfma_f32_16x16x32_bf16 v[12:15], v[170:173], v[230:233], 0
	v_mfma_f32_16x16x32_bf16 v[4:7], v[180:183], v[230:233], 0
	v_mfma_f32_16x16x32_bf16 v[60:63], v[174:177], v[208:211], v[60:63]
	v_mfma_f32_16x16x32_bf16 v[52:55], v[184:187], v[208:211], v[52:55]
	v_mfma_f32_16x16x32_bf16 v[44:47], v[174:177], v[216:219], v[44:47]
	v_mfma_f32_16x16x32_bf16 v[36:39], v[184:187], v[216:219], v[36:39]
	v_mfma_f32_16x16x32_bf16 v[28:31], v[174:177], v[226:229], v[28:31]
	v_mfma_f32_16x16x32_bf16 v[20:23], v[184:187], v[226:229], v[20:23]
	v_mfma_f32_16x16x32_bf16 v[12:15], v[174:177], v[234:237], v[12:15]
	v_mfma_f32_16x16x32_bf16 v[4:7], v[184:187], v[234:237], v[4:7]
	s_setprio 0
	s_setprio 1
	v_mfma_f32_16x16x32_bf16 v[56:59], v[188:191], v[204:207], 0
	v_mfma_f32_16x16x32_bf16 v[48:51], v[196:199], v[204:207], 0
	v_mfma_f32_16x16x32_bf16 v[40:43], v[188:191], v[212:215], 0
	v_mfma_f32_16x16x32_bf16 v[32:35], v[196:199], v[212:215], 0
	v_mfma_f32_16x16x32_bf16 v[24:27], v[188:191], v[222:225], 0
	v_mfma_f32_16x16x32_bf16 v[16:19], v[196:199], v[222:225], 0
	v_mfma_f32_16x16x32_bf16 v[8:11], v[188:191], v[230:233], 0
	v_mfma_f32_16x16x32_bf16 v[0:3], v[196:199], v[230:233], 0
	v_mfma_f32_16x16x32_bf16 v[56:59], v[192:195], v[208:211], v[56:59]
	v_mfma_f32_16x16x32_bf16 v[48:51], v[200:203], v[208:211], v[48:51]
	v_mfma_f32_16x16x32_bf16 v[40:43], v[192:195], v[216:219], v[40:43]
	v_mfma_f32_16x16x32_bf16 v[32:35], v[200:203], v[216:219], v[32:35]
	v_mfma_f32_16x16x32_bf16 v[24:27], v[192:195], v[226:229], v[24:27]
	v_mfma_f32_16x16x32_bf16 v[16:19], v[200:203], v[226:229], v[16:19]
	v_mfma_f32_16x16x32_bf16 v[8:11], v[192:195], v[234:237], v[8:11]
	v_mfma_f32_16x16x32_bf16 v[0:3], v[200:203], v[234:237], v[0:3]
	s_setprio 0
	s_barrier
	s_add_i32 s68, 0, 0x18000
	v_add_u32_e32 v169, s68, v147
	s_add_i32 s76, 0, 0x1c000
	ds_read_b128 v[170:173], v169
	ds_read_b128 v[174:177], v169 offset:1024
	ds_read_b128 v[180:183], v169 offset:2048
	ds_read_b128 v[184:187], v169 offset:3072
	v_add_u32_e32 v169, s76, v147
	ds_read_b128 v[188:191], v169
	ds_read_b128 v[192:195], v169 offset:1024
	ds_read_b128 v[196:199], v169 offset:2048
	ds_read_b128 v[200:203], v169 offset:3072
	s_add_u32 s34, s34, 0x40000
	s_addc_u32 s35, s35, 0
	s_mov_b32 m0, s57
	v_lshl_add_u64 v[246:247], s[34:35], 0, v[134:135]
	ds_read_b128 v[204:207], v166 offset:32768
	ds_read_b128 v[208:211], v166 offset:33792
	ds_read_b128 v[212:215], v166 offset:34816
	ds_read_b128 v[216:219], v166 offset:35840
	ds_read_b128 v[222:225], v166 offset:36864
	ds_read_b128 v[226:229], v166 offset:37888
	ds_read_b128 v[230:233], v166 offset:38912
	ds_read_b128 v[234:237], v166 offset:39936
	global_load_lds_dwordx4 v[246:247], off
	v_lshl_add_u64 v[246:247], s[34:35], 0, v[130:131]
	s_mov_b32 m0, s58
	s_nop 0
	global_load_lds_dwordx4 v[246:247], off
	s_waitcnt vmcnt(8) lgkmcnt(0)
	s_barrier
	s_setprio 1
	v_mfma_f32_16x16x32_bf16 v[124:127], v[170:173], v[204:207], v[124:127]
	v_mfma_f32_16x16x32_bf16 v[116:119], v[180:183], v[204:207], v[116:119]
	v_mfma_f32_16x16x32_bf16 v[108:111], v[170:173], v[212:215], v[108:111]
	v_mfma_f32_16x16x32_bf16 v[100:103], v[180:183], v[212:215], v[100:103]
	v_mfma_f32_16x16x32_bf16 v[92:95], v[170:173], v[222:225], v[92:95]
	v_mfma_f32_16x16x32_bf16 v[84:87], v[180:183], v[222:225], v[84:87]
	v_mfma_f32_16x16x32_bf16 v[76:79], v[170:173], v[230:233], v[76:79]
	v_mfma_f32_16x16x32_bf16 v[68:71], v[180:183], v[230:233], v[68:71]
	v_mfma_f32_16x16x32_bf16 v[124:127], v[174:177], v[208:211], v[124:127]
	v_mfma_f32_16x16x32_bf16 v[116:119], v[184:187], v[208:211], v[116:119]
	v_mfma_f32_16x16x32_bf16 v[108:111], v[174:177], v[216:219], v[108:111]
	v_mfma_f32_16x16x32_bf16 v[100:103], v[184:187], v[216:219], v[100:103]
	v_mfma_f32_16x16x32_bf16 v[92:95], v[174:177], v[226:229], v[92:95]
	v_mfma_f32_16x16x32_bf16 v[84:87], v[184:187], v[226:229], v[84:87]
	v_mfma_f32_16x16x32_bf16 v[76:79], v[174:177], v[234:237], v[76:79]
	v_mfma_f32_16x16x32_bf16 v[68:71], v[184:187], v[234:237], v[68:71]
	s_setprio 0
	s_setprio 1
	v_mfma_f32_16x16x32_bf16 v[120:123], v[188:191], v[204:207], v[120:123]
	v_mfma_f32_16x16x32_bf16 v[112:115], v[196:199], v[204:207], v[112:115]
	v_mfma_f32_16x16x32_bf16 v[104:107], v[188:191], v[212:215], v[104:107]
	v_mfma_f32_16x16x32_bf16 v[96:99], v[196:199], v[212:215], v[96:99]
	v_mfma_f32_16x16x32_bf16 v[88:91], v[188:191], v[222:225], v[88:91]
	v_mfma_f32_16x16x32_bf16 v[80:83], v[196:199], v[222:225], v[80:83]
	v_mfma_f32_16x16x32_bf16 v[72:75], v[188:191], v[230:233], v[72:75]
	v_mfma_f32_16x16x32_bf16 v[64:67], v[196:199], v[230:233], v[64:67]
	v_mfma_f32_16x16x32_bf16 v[120:123], v[192:195], v[208:211], v[120:123]
	v_mfma_f32_16x16x32_bf16 v[112:115], v[200:203], v[208:211], v[112:115]
	v_mfma_f32_16x16x32_bf16 v[104:107], v[192:195], v[216:219], v[104:107]
	v_mfma_f32_16x16x32_bf16 v[96:99], v[200:203], v[216:219], v[96:99]
	v_mfma_f32_16x16x32_bf16 v[88:91], v[192:195], v[226:229], v[88:91]
	v_mfma_f32_16x16x32_bf16 v[80:83], v[200:203], v[226:229], v[80:83]
	v_mfma_f32_16x16x32_bf16 v[72:75], v[192:195], v[234:237], v[72:75]
	v_mfma_f32_16x16x32_bf16 v[64:67], v[200:203], v[234:237], v[64:67]
	s_setprio 0
	s_barrier
; #define PG8_STAGE(bufoff, gbase, voff) do { _Pragma("unroll") for (int _i = 0; _i < 2; ++_i) \
;         __builtin_amdgcn_global_load_lds((const unsigned*)((const char*)(gbase) + (voff)[_i]), (PG8_LAS unsigned*)(lds + (bufoff) + ldsw + _i * 8192), 16, 0, 0); } while (0)
; #define PG8_LDA(dst, b, h) do { _Pragma("unroll") for (int m = 0; m < 4; ++m) _Pragma("unroll") for (int k = 0; k < 2; ++k) dst[m][k] = *(const PG8_LAS bf16x8*)(lds + PG8_SA(b, h) + aoff + m * 2048 + k * 1024); } while (0)
; #define PG8_LDB(dst, b, h) do { _Pragma("unroll") for (int n = 0; n < 2; ++n) _Pragma("unroll") for (int k = 0; k < 2; ++k) dst[n][k] = *(const PG8_LAS bf16x8*)(lds + PG8_SB(b, h) + boff + n * 2048 + k * 1024); } while (0)
; #define PG8_MMA(ai, bj, At, Bt) do { __builtin_amdgcn_s_setprio(1); _Pragma("unroll") for (int m = 0; m < 4; ++m) _Pragma("unroll") for (int n = 0; n < 2; ++n) _Pragma("unroll") for (int k = 0; k < 2; ++k) \
;         acc[ai][bj][m][n] = __builtin_amdgcn_mfma_f32_16x16x32_bf16(Bt[n][k], At[m][k], acc[ai][bj][m][n], 0, 0, 0); __builtin_amdgcn_s_setprio(0); } while (0)
; #define PG8_WAIT_V(n) asm volatile("s_waitcnt vmcnt(" #n ")" ::: "memory")
; #define PG8_WAIT_L(n) asm volatile("s_waitcnt lgkmcnt(" #n ")" ::: "memory")
; #define PG8_BAR __builtin_amdgcn_s_barrier()
; #define PG8_SCHED __builtin_amdgcn_sched_barrier(0)
; template <class Epi, class Sched>
; __device__ __forceinline__ void gemm_phase(PG8_LAS unsigned char* lds, PG8_LAS unsigned char* xl, const Gemm g, const Sched& S, const Epi& E) {
;     ...
;             PG8_LDB(B0, 0, 0); PG8_LDB(B1, 0, 1); PG8_SCHED; PG8_LDA(At, 0, 0); PG8_STAGE(PG8_SA(1, 1), a1 + hsA, voffA);
;             PG8_WAIT_V(8); PG8_WAIT_L(0); PG8_BAR; PG8_MMA(0, 0, At, B0); PG8_MMA(0, 1, At, B1); PG8_BAR; PG8_SCHED;
;     ...
;             PG8_LDA(At, 1, 1); PG8_STAGE(PG8_SB(1, 0), b3, voffB); PG8_STAGE(PG8_SB(1, 1), b3 + hsB, voffB); PG8_STAGE(PG8_SA(1, 0), a3, voffA);
;             PG8_WAIT_V(8); PG8_WAIT_L(0); PG8_BAR; PG8_MMA(1, 0, At, B0); PG8_MMA(1, 1, At, B1); PG8_BAR; PG8_SCHED;
	s_add_i32 s34, s68, s51
	v_lshl_add_u64 v[238:239], v[238:239], 0, s[16:17]
	s_mov_b32 m0, s34
	ds_read_b128 v[204:207], v166 offset:49152
	ds_read_b128 v[208:211], v166 offset:50176
	ds_read_b128 v[212:215], v166 offset:51200
	ds_read_b128 v[216:219], v166 offset:52224
	ds_read_b128 v[222:225], v166 offset:53248
	ds_read_b128 v[226:229], v166 offset:54272
	ds_read_b128 v[230:233], v166 offset:55296
	ds_read_b128 v[234:237], v166 offset:56320
	global_load_lds_dwordx4 v[238:239], off
	s_add_i32 m0, s34, 0x2000
	s_add_u32 s30, s30, 0x40080
	v_lshl_add_u64 v[238:239], v[240:241], 0, s[16:17]
	s_addc_u32 s31, s31, 0
	s_add_i32 s34, s76, s51
	global_load_lds_dwordx4 v[238:239], off
	v_lshl_add_u64 v[238:239], s[30:31], 0, v[132:133]
	s_mov_b32 m0, s34
	s_nop 0
	global_load_lds_dwordx4 v[238:239], off
	v_lshl_add_u64 v[238:239], s[30:31], 0, v[128:129]
	s_add_i32 m0, s34, 0x2000
	s_nop 0
	global_load_lds_dwordx4 v[238:239], off
	v_lshl_add_u64 v[238:239], v[242:243], 0, s[16:17]
	s_mov_b32 m0, s59
	s_nop 0
	global_load_lds_dwordx4 v[238:239], off
	v_lshl_add_u64 v[238:239], v[244:245], 0, s[16:17]
	s_mov_b32 m0, s61
	s_nop 0
	global_load_lds_dwordx4 v[238:239], off
	s_waitcnt vmcnt(8) lgkmcnt(0)
	s_barrier
	s_setprio 1
	v_mfma_f32_16x16x32_bf16 v[60:63], v[170:173], v[204:207], v[60:63]
	v_mfma_f32_16x16x32_bf16 v[52:55], v[180:183], v[204:207], v[52:55]
	v_mfma_f32_16x16x32_bf16 v[44:47], v[170:173], v[212:215], v[44:47]
	v_mfma_f32_16x16x32_bf16 v[36:39], v[180:183], v[212:215], v[36:39]
	v_mfma_f32_16x16x32_bf16 v[28:31], v[170:173], v[222:225], v[28:31]
	v_mfma_f32_16x16x32_bf16 v[20:23], v[180:183], v[222:225], v[20:23]
	v_mfma_f32_16x16x32_bf16 v[12:15], v[170:173], v[230:233], v[12:15]
	v_mfma_f32_16x16x32_bf16 v[4:7], v[180:183], v[230:233], v[4:7]
	v_mfma_f32_16x16x32_bf16 v[60:63], v[174:177], v[208:211], v[60:63]
	v_mfma_f32_16x16x32_bf16 v[52:55], v[184:187], v[208:211], v[52:55]
	v_mfma_f32_16x16x32_bf16 v[44:47], v[174:177], v[216:219], v[44:47]
	v_mfma_f32_16x16x32_bf16 v[36:39], v[184:187], v[216:219], v[36:39]
	v_mfma_f32_16x16x32_bf16 v[28:31], v[174:177], v[226:229], v[28:31]
	v_mfma_f32_16x16x32_bf16 v[20:23], v[184:187], v[226:229], v[20:23]
	v_mfma_f32_16x16x32_bf16 v[12:15], v[174:177], v[234:237], v[12:15]
	v_mfma_f32_16x16x32_bf16 v[4:7], v[184:187], v[234:237], v[4:7]
	s_setprio 0
	s_setprio 1
	v_mfma_f32_16x16x32_bf16 v[56:59], v[188:191], v[204:207], v[56:59]
	s_add_i32 s75, s75, 2
	v_mfma_f32_16x16x32_bf16 v[48:51], v[196:199], v[204:207], v[48:51]
	s_add_u32 s73, s73, 0x100
	v_mfma_f32_16x16x32_bf16 v[40:43], v[188:191], v[212:215], v[40:43]
	s_addc_u32 s74, s74, 0
	v_mfma_f32_16x16x32_bf16 v[32:35], v[196:199], v[212:215], v[32:35]
	s_add_u32 s2, s2, 0x100
	v_mfma_f32_16x16x32_bf16 v[24:27], v[188:191], v[222:225], v[24:27]
	s_addc_u32 s3, s3, 0
	v_mfma_f32_16x16x32_bf16 v[16:19], v[196:199], v[222:225], v[16:19]
	s_cmp_gt_u32 s75, 13
	v_mfma_f32_16x16x32_bf16 v[8:11], v[188:191], v[230:233], v[8:11]
	v_mfma_f32_16x16x32_bf16 v[0:3], v[196:199], v[230:233], v[0:3]
	v_mfma_f32_16x16x32_bf16 v[56:59], v[192:195], v[208:211], v[56:59]
	v_mfma_f32_16x16x32_bf16 v[48:51], v[200:203], v[208:211], v[48:51]
	v_mfma_f32_16x16x32_bf16 v[40:43], v[192:195], v[216:219], v[40:43]
	v_mfma_f32_16x16x32_bf16 v[32:35], v[200:203], v[216:219], v[32:35]
	v_mfma_f32_16x16x32_bf16 v[24:27], v[192:195], v[226:229], v[24:27]
	v_mfma_f32_16x16x32_bf16 v[16:19], v[200:203], v[226:229], v[16:19]
	v_mfma_f32_16x16x32_bf16 v[8:11], v[192:195], v[234:237], v[8:11]
	v_mfma_f32_16x16x32_bf16 v[0:3], v[200:203], v[234:237], v[0:3]
	s_setprio 0
	s_barrier
	s_cbranch_scc1 .Lpeel_after_P8
.LBB0_825:
	ds_read_b128 v[170:173], v164
	ds_read_b128 v[174:177], v164 offset:1024
	ds_read_b128 v[180:183], v164 offset:2048
	ds_read_b128 v[184:187], v164 offset:3072
	ds_read_b128 v[188:191], v165
	ds_read_b128 v[192:195], v165 offset:1024
	ds_read_b128 v[196:199], v165 offset:2048
	ds_read_b128 v[200:203], v165 offset:3072
	s_add_u32 s30, s2, 0xfffc0080
	s_addc_u32 s31, s3, -1
	s_cmp_eq_u32 s75, 12
	s_cselect_b32 s35, s46, s31
	s_cselect_b32 s34, s47, s30
	s_cselect_b32 s31, s70, s74
	s_cselect_b32 s30, s72, s73
	v_lshl_add_u64 v[238:239], s[2:3], 0, v[140:141]
	s_add_i32 m0, s55, 0xc000
	ds_read_b128 v[204:207], v166
	ds_read_b128 v[208:211], v166 offset:1024
	ds_read_b128 v[212:215], v166 offset:2048
	ds_read_b128 v[216:219], v166 offset:3072
	ds_read_b128 v[222:225], v166 offset:4096
	ds_read_b128 v[226:229], v166 offset:5120
	ds_read_b128 v[230:233], v166 offset:6144
	ds_read_b128 v[234:237], v166 offset:7168
	global_load_lds_dwordx4 v[238:239], off
	v_lshl_add_u64 v[238:239], s[2:3], 0, v[138:139]
	s_add_i32 m0, s55, 0xe000
	s_nop 0
	global_load_lds_dwordx4 v[238:239], off
	s_waitcnt vmcnt(8) lgkmcnt(0)
	s_barrier
; #define PG8_STAGE(bufoff, gbase, voff) do { _Pragma("unroll") for (int _i = 0; _i < 2; ++_i) \
;         __builtin_amdgcn_global_load_lds((const unsigned*)((const char*)(gbase) + (voff)[_i]), (PG8_LAS unsigned*)(lds + (bufoff) + ldsw + _i * 8192), 16, 0, 0); } while (0)
; #define PG8_LDA(dst, b, h) do { _Pragma("unroll") for (int m = 0; m < 4; ++m) _Pragma("unroll") for (int k = 0; k < 2; ++k) dst[m][k] = *(const PG8_LAS bf16x8*)(lds + PG8_SA(b, h) + aoff + m * 2048 + k * 1024); } while (0)
; #define PG8_LDB(dst, b, h) do { _Pragma("unroll") for (int n = 0; n < 2; ++n) _Pragma("unroll") for (int k = 0; k < 2; ++k) dst[n][k] = *(const PG8_LAS bf16x8*)(lds + PG8_SB(b, h) + boff + n * 2048 + k * 1024); } while (0)
; #define PG8_MMA(ai, bj, At, Bt) do { __builtin_amdgcn_s_setprio(1); _Pragma("unroll") for (int m = 0; m < 4; ++m) _Pragma("unroll") for (int n = 0; n < 2; ++n) _Pragma("unroll") for (int k = 0; k < 2; ++k) \
;         acc[ai][bj][m][n] = __builtin_amdgcn_mfma_f32_16x16x32_bf16(Bt[n][k], At[m][k], acc[ai][bj][m][n], 0, 0, 0); __builtin_amdgcn_s_setprio(0); } while (0)
; #define PG8_WAIT_V(n) asm volatile("s_waitcnt vmcnt(" #n ")" ::: "memory")
; #define PG8_WAIT_L(n) asm volatile("s_waitcnt lgkmcnt(" #n ")" ::: "memory")
; #define PG8_BAR __builtin_amdgcn_s_barrier()
; #define PG8_SCHED __builtin_amdgcn_sched_barrier(0)
; template <class Epi, class Sched>
; __device__ __forceinline__ void gemm_phase(PG8_LAS unsigned char* lds, PG8_LAS unsigned char* xl, const Gemm g, const Sched& S, const Epi& E) {
;     ...
;             PG8_LDB(B0, 0, 0); PG8_LDB(B1, 0, 1); PG8_SCHED; PG8_LDA(At, 0, 0); PG8_STAGE(PG8_SA(1, 1), a1 + hsA, voffA);
;             PG8_WAIT_V(8); PG8_WAIT_L(0); PG8_BAR; PG8_MMA(0, 0, At, B0); PG8_MMA(0, 1, At, B1); PG8_BAR; PG8_SCHED;
;             PG8_LDA(At, 0, 1); PG8_STAGE(PG8_SB(0, 0), b2, voffB); PG8_STAGE(PG8_SB(0, 1), b2 + hsB, voffB); PG8_STAGE(PG8_SA(0, 0), a2, voffA);
;             PG8_WAIT_V(8); PG8_WAIT_L(0); PG8_BAR; PG8_MMA(1, 0, At, B0); PG8_MMA(1, 1, At, B1); PG8_BAR; PG8_SCHED;
	s_setprio 1
	v_mfma_f32_16x16x32_bf16 v[124:127], v[170:173], v[204:207], v[124:127]
	v_mfma_f32_16x16x32_bf16 v[116:119], v[180:183], v[204:207], v[116:119]
	v_mfma_f32_16x16x32_bf16 v[108:111], v[170:173], v[212:215], v[108:111]
	v_mfma_f32_16x16x32_bf16 v[100:103], v[180:183], v[212:215], v[100:103]
	v_mfma_f32_16x16x32_bf16 v[92:95], v[170:173], v[222:225], v[92:95]
	v_mfma_f32_16x16x32_bf16 v[84:87], v[180:183], v[222:225], v[84:87]
	v_mfma_f32_16x16x32_bf16 v[76:79], v[170:173], v[230:233], v[76:79]
	v_mfma_f32_16x16x32_bf16 v[68:71], v[180:183], v[230:233], v[68:71]
	v_mfma_f32_16x16x32_bf16 v[124:127], v[174:177], v[208:211], v[124:127]
	v_mfma_f32_16x16x32_bf16 v[116:119], v[184:187], v[208:211], v[116:119]
	v_mfma_f32_16x16x32_bf16 v[108:111], v[174:177], v[216:219], v[108:111]
	v_mfma_f32_16x16x32_bf16 v[100:103], v[184:187], v[216:219], v[100:103]
	v_mfma_f32_16x16x32_bf16 v[92:95], v[174:177], v[226:229], v[92:95]
	v_mfma_f32_16x16x32_bf16 v[84:87], v[184:187], v[226:229], v[84:87]
	v_mfma_f32_16x16x32_bf16 v[76:79], v[174:177], v[234:237], v[76:79]
	v_mfma_f32_16x16x32_bf16 v[68:71], v[184:187], v[234:237], v[68:71]
	s_setprio 0
	s_setprio 1
	v_mfma_f32_16x16x32_bf16 v[120:123], v[188:191], v[204:207], v[120:123]
	v_mfma_f32_16x16x32_bf16 v[112:115], v[196:199], v[204:207], v[112:115]
	v_mfma_f32_16x16x32_bf16 v[104:107], v[188:191], v[212:215], v[104:107]
	v_mfma_f32_16x16x32_bf16 v[96:99], v[196:199], v[212:215], v[96:99]
	v_mfma_f32_16x16x32_bf16 v[88:91], v[188:191], v[222:225], v[88:91]
	v_mfma_f32_16x16x32_bf16 v[80:83], v[196:199], v[222:225], v[80:83]
	v_mfma_f32_16x16x32_bf16 v[72:75], v[188:191], v[230:233], v[72:75]
	v_mfma_f32_16x16x32_bf16 v[64:67], v[196:199], v[230:233], v[64:67]
	v_mfma_f32_16x16x32_bf16 v[120:123], v[192:195], v[208:211], v[120:123]
	v_mfma_f32_16x16x32_bf16 v[112:115], v[200:203], v[208:211], v[112:115]
	v_mfma_f32_16x16x32_bf16 v[104:107], v[192:195], v[216:219], v[104:107]
	v_mfma_f32_16x16x32_bf16 v[96:99], v[200:203], v[216:219], v[96:99]
	v_mfma_f32_16x16x32_bf16 v[88:91], v[192:195], v[226:229], v[88:91]
	v_mfma_f32_16x16x32_bf16 v[80:83], v[200:203], v[226:229], v[80:83]
	v_mfma_f32_16x16x32_bf16 v[72:75], v[192:195], v[234:237], v[72:75]
	v_mfma_f32_16x16x32_bf16 v[64:67], v[200:203], v[234:237], v[64:67]
	s_setprio 0
	s_barrier
	s_add_i32 s68, s54, s51
	v_lshl_add_u64 v[238:239], s[30:31], 0, v[132:133]
	s_mov_b32 m0, s68
	ds_read_b128 v[204:207], v166 offset:16384
	ds_read_b128 v[208:211], v166 offset:17408
	ds_read_b128 v[212:215], v166 offset:18432
	ds_read_b128 v[216:219], v166 offset:19456
	ds_read_b128 v[222:225], v166 offset:20480
	ds_read_b128 v[226:229], v166 offset:21504
	ds_read_b128 v[230:233], v166 offset:22528
	ds_read_b128 v[234:237], v166 offset:23552
	global_load_lds_dwordx4 v[238:239], off
	s_add_i32 m0, s68, 0x2000
	s_add_u32 s76, s30, 0x40000
	v_lshl_add_u64 v[240:241], s[30:31], 0, v[128:129]
	s_addc_u32 s77, s31, 0
	s_add_i32 s68, s62, s51
	global_load_lds_dwordx4 v[240:241], off
	v_lshl_add_u64 v[242:243], s[76:77], 0, v[132:133]
	s_mov_b32 m0, s68
	v_lshl_add_u64 v[244:245], s[34:35], 0, v[130:131]
	global_load_lds_dwordx4 v[242:243], off
	v_lshl_add_u64 v[242:243], s[76:77], 0, v[128:129]
	s_add_i32 m0, s68, 0x2000
	s_nop 0
	global_load_lds_dwordx4 v[242:243], off
	v_lshl_add_u64 v[242:243], s[34:35], 0, v[134:135]
	s_mov_b32 m0, s55
	s_nop 0
	global_load_lds_dwordx4 v[242:243], off
	s_mov_b32 m0, s56
	s_nop 0
	global_load_lds_dwordx4 v[244:245], off
	s_waitcnt vmcnt(8) lgkmcnt(0)
	s_barrier
	s_setprio 1
	v_mfma_f32_16x16x32_bf16 v[60:63], v[170:173], v[204:207], v[60:63]
	v_mfma_f32_16x16x32_bf16 v[52:55], v[180:183], v[204:207], v[52:55]
	v_mfma_f32_16x16x32_bf16 v[44:47], v[170:173], v[212:215], v[44:47]
	v_mfma_f32_16x16x32_bf16 v[36:39], v[180:183], v[212:215], v[36:39]
	v_mfma_f32_16x16x32_bf16 v[28:31], v[170:173], v[222:225], v[28:31]
	v_mfma_f32_16x16x32_bf16 v[20:23], v[180:183], v[222:225], v[20:23]
	v_mfma_f32_16x16x32_bf16 v[12:15], v[170:173], v[230:233], v[12:15]
	v_mfma_f32_16x16x32_bf16 v[4:7], v[180:183], v[230:233], v[4:7]
	v_mfma_f32_16x16x32_bf16 v[60:63], v[174:177], v[208:211], v[60:63]
	v_mfma_f32_16x16x32_bf16 v[52:55], v[184:187], v[208:211], v[52:55]
	v_mfma_f32_16x16x32_bf16 v[44:47], v[174:177], v[216:219], v[44:47]
	v_mfma_f32_16x16x32_bf16 v[36:39], v[184:187], v[216:219], v[36:39]
	v_mfma_f32_16x16x32_bf16 v[28:31], v[174:177], v[226:229], v[28:31]
	v_mfma_f32_16x16x32_bf16 v[20:23], v[184:187], v[226:229], v[20:23]
	v_mfma_f32_16x16x32_bf16 v[12:15], v[174:177], v[234:237], v[12:15]
	v_mfma_f32_16x16x32_bf16 v[4:7], v[184:187], v[234:237], v[4:7]
	s_setprio 0
	s_setprio 1
	v_mfma_f32_16x16x32_bf16 v[56:59], v[188:191], v[204:207], v[56:59]
	v_mfma_f32_16x16x32_bf16 v[48:51], v[196:199], v[204:207], v[48:51]
	v_mfma_f32_16x16x32_bf16 v[40:43], v[188:191], v[212:215], v[40:43]
	v_mfma_f32_16x16x32_bf16 v[32:35], v[196:199], v[212:215], v[32:35]
	v_mfma_f32_16x16x32_bf16 v[24:27], v[188:191], v[222:225], v[24:27]
	v_mfma_f32_16x16x32_bf16 v[16:19], v[196:199], v[222:225], v[16:19]
	v_mfma_f32_16x16x32_bf16 v[8:11], v[188:191], v[230:233], v[8:11]
	v_mfma_f32_16x16x32_bf16 v[0:3], v[196:199], v[230:233], v[0:3]
	v_mfma_f32_16x16x32_bf16 v[56:59], v[192:195], v[208:211], v[56:59]
	v_mfma_f32_16x16x32_bf16 v[48:51], v[200:203], v[208:211], v[48:51]
	v_mfma_f32_16x16x32_bf16 v[40:43], v[192:195], v[216:219], v[40:43]
	v_mfma_f32_16x16x32_bf16 v[32:35], v[200:203], v[216:219], v[32:35]
	v_mfma_f32_16x16x32_bf16 v[24:27], v[192:195], v[226:229], v[24:27]
	v_mfma_f32_16x16x32_bf16 v[16:19], v[200:203], v[226:229], v[16:19]
	v_mfma_f32_16x16x32_bf16 v[8:11], v[192:195], v[234:237], v[8:11]
	v_mfma_f32_16x16x32_bf16 v[0:3], v[200:203], v[234:237], v[0:3]
	s_setprio 0
	s_barrier
; #define PG8_STAGE(bufoff, gbase, voff) do { _Pragma("unroll") for (int _i = 0; _i < 2; ++_i) \
;         __builtin_amdgcn_global_load_lds((const unsigned*)((const char*)(gbase) + (voff)[_i]), (PG8_LAS unsigned*)(lds + (bufoff) + ldsw + _i * 8192), 16, 0, 0); } while (0)
; #define PG8_LDA(dst, b, h) do { _Pragma("unroll") for (int m = 0; m < 4; ++m) _Pragma("unroll") for (int k = 0; k < 2; ++k) dst[m][k] = *(const PG8_LAS bf16x8*)(lds + PG8_SA(b, h) + aoff + m * 2048 + k * 1024); } while (0)
; #define PG8_LDB(dst, b, h) do { _Pragma("unroll") for (int n = 0; n < 2; ++n) _Pragma("unroll") for (int k = 0; k < 2; ++k) dst[n][k] = *(const PG8_LAS bf16x8*)(lds + PG8_SB(b, h) + boff + n * 2048 + k * 1024); } while (0)
; #define PG8_MMA(ai, bj, At, Bt) do { __builtin_amdgcn_s_setprio(1); _Pragma("unroll") for (int m = 0; m < 4; ++m) _Pragma("unroll") for (int n = 0; n < 2; ++n) _Pragma("unroll") for (int k = 0; k < 2; ++k) \
;         acc[ai][bj][m][n] = __builtin_amdgcn_mfma_f32_16x16x32_bf16(Bt[n][k], At[m][k], acc[ai][bj][m][n], 0, 0, 0); __builtin_amdgcn_s_setprio(0); } while (0)
; #define PG8_WAIT_V(n) asm volatile("s_waitcnt vmcnt(" #n ")" ::: "memory")
; #define PG8_WAIT_L(n) asm volatile("s_waitcnt lgkmcnt(" #n ")" ::: "memory")
; #define PG8_BAR __builtin_amdgcn_s_barrier()
; #define PG8_SCHED __builtin_amdgcn_sched_barrier(0)
; template <class Epi, class Sched>
; __device__ __forceinline__ void gemm_phase(PG8_LAS unsigned char* lds, PG8_LAS unsigned char* xl, const Gemm g, const Sched& S, const Epi& E) {
;     ...
;             PG8_LDB(B0, 1, 0); PG8_LDB(B1, 1, 1); PG8_SCHED; PG8_LDA(At, 1, 0); PG8_STAGE(PG8_SA(0, 1), a2 + hsA, voffA);
;             PG8_WAIT_V(8); PG8_WAIT_L(0); PG8_BAR; PG8_MMA(0, 0, At, B0); PG8_MMA(0, 1, At, B1); PG8_BAR; PG8_SCHED;
	s_add_i32 s68, 0, 0x18000
	v_add_u32_e32 v169, s68, v147
	s_add_i32 s76, 0, 0x1c000
	ds_read_b128 v[170:173], v169
	ds_read_b128 v[174:177], v169 offset:1024
	ds_read_b128 v[180:183], v169 offset:2048
	ds_read_b128 v[184:187], v169 offset:3072
	v_add_u32_e32 v169, s76, v147
	ds_read_b128 v[188:191], v169
	ds_read_b128 v[192:195], v169 offset:1024
	ds_read_b128 v[196:199], v169 offset:2048
	ds_read_b128 v[200:203], v169 offset:3072
	s_add_u32 s34, s34, 0x40000
	s_addc_u32 s35, s35, 0
	s_mov_b32 m0, s57
	v_lshl_add_u64 v[246:247], s[34:35], 0, v[134:135]
	ds_read_b128 v[204:207], v166 offset:32768
	ds_read_b128 v[208:211], v166 offset:33792
	ds_read_b128 v[212:215], v166 offset:34816
	ds_read_b128 v[216:219], v166 offset:35840
	ds_read_b128 v[222:225], v166 offset:36864
	ds_read_b128 v[226:229], v166 offset:37888
	ds_read_b128 v[230:233], v166 offset:38912
	ds_read_b128 v[234:237], v166 offset:39936
	global_load_lds_dwordx4 v[246:247], off
	v_lshl_add_u64 v[246:247], s[34:35], 0, v[130:131]
	s_mov_b32 m0, s58
	s_nop 0
	global_load_lds_dwordx4 v[246:247], off
	s_waitcnt vmcnt(8) lgkmcnt(0)
	s_barrier
	s_setprio 1
	v_mfma_f32_16x16x32_bf16 v[124:127], v[170:173], v[204:207], v[124:127]
	v_mfma_f32_16x16x32_bf16 v[116:119], v[180:183], v[204:207], v[116:119]
	v_mfma_f32_16x16x32_bf16 v[108:111], v[170:173], v[212:215], v[108:111]
	v_mfma_f32_16x16x32_bf16 v[100:103], v[180:183], v[212:215], v[100:103]
	v_mfma_f32_16x16x32_bf16 v[92:95], v[170:173], v[222:225], v[92:95]
	v_mfma_f32_16x16x32_bf16 v[84:87], v[180:183], v[222:225], v[84:87]
	v_mfma_f32_16x16x32_bf16 v[76:79], v[170:173], v[230:233], v[76:79]
	v_mfma_f32_16x16x32_bf16 v[68:71], v[180:183], v[230:233], v[68:71]
	v_mfma_f32_16x16x32_bf16 v[124:127], v[174:177], v[208:211], v[124:127]
	v_mfma_f32_16x16x32_bf16 v[116:119], v[184:187], v[208:211], v[116:119]
	v_mfma_f32_16x16x32_bf16 v[108:111], v[174:177], v[216:219], v[108:111]
	v_mfma_f32_16x16x32_bf16 v[100:103], v[184:187], v[216:219], v[100:103]
	v_mfma_f32_16x16x32_bf16 v[92:95], v[174:177], v[226:229], v[92:95]
	v_mfma_f32_16x16x32_bf16 v[84:87], v[184:187], v[226:229], v[84:87]
	v_mfma_f32_16x16x32_bf16 v[76:79], v[174:177], v[234:237], v[76:79]
	v_mfma_f32_16x16x32_bf16 v[68:71], v[184:187], v[234:237], v[68:71]
	s_setprio 0
	s_setprio 1
	v_mfma_f32_16x16x32_bf16 v[120:123], v[188:191], v[204:207], v[120:123]
	v_mfma_f32_16x16x32_bf16 v[112:115], v[196:199], v[204:207], v[112:115]
	v_mfma_f32_16x16x32_bf16 v[104:107], v[188:191], v[212:215], v[104:107]
	v_mfma_f32_16x16x32_bf16 v[96:99], v[196:199], v[212:215], v[96:99]
	v_mfma_f32_16x16x32_bf16 v[88:91], v[188:191], v[222:225], v[88:91]
	v_mfma_f32_16x16x32_bf16 v[80:83], v[196:199], v[222:225], v[80:83]
	v_mfma_f32_16x16x32_bf16 v[72:75], v[188:191], v[230:233], v[72:75]
	v_mfma_f32_16x16x32_bf16 v[64:67], v[196:199], v[230:233], v[64:67]
	v_mfma_f32_16x16x32_bf16 v[120:123], v[192:195], v[208:211], v[120:123]
	v_mfma_f32_16x16x32_bf16 v[112:115], v[200:203], v[208:211], v[112:115]
	v_mfma_f32_16x16x32_bf16 v[104:107], v[192:195], v[216:219], v[104:107]
	v_mfma_f32_16x16x32_bf16 v[96:99], v[200:203], v[216:219], v[96:99]
	v_mfma_f32_16x16x32_bf16 v[88:91], v[192:195], v[226:229], v[88:91]
	v_mfma_f32_16x16x32_bf16 v[80:83], v[200:203], v[226:229], v[80:83]
	v_mfma_f32_16x16x32_bf16 v[72:75], v[192:195], v[234:237], v[72:75]
	v_mfma_f32_16x16x32_bf16 v[64:67], v[200:203], v[234:237], v[64:67]
	s_setprio 0
	s_barrier
; #define PG8_STAGE(bufoff, gbase, voff) do { _Pragma("unroll") for (int _i = 0; _i < 2; ++_i) \
;         __builtin_amdgcn_global_load_lds((const unsigned*)((const char*)(gbase) + (voff)[_i]), (PG8_LAS unsigned*)(lds + (bufoff) + ldsw + _i * 8192), 16, 0, 0); } while (0)
; #define PG8_LDA(dst, b, h) do { _Pragma("unroll") for (int m = 0; m < 4; ++m) _Pragma("unroll") for (int k = 0; k < 2; ++k) dst[m][k] = *(const PG8_LAS bf16x8*)(lds + PG8_SA(b, h) + aoff + m * 2048 + k * 1024); } while (0)
; #define PG8_MMA(ai, bj, At, Bt) do { __builtin_amdgcn_s_setprio(1); _Pragma("unroll") for (int m = 0; m < 4; ++m) _Pragma("unroll") for (int n = 0; n < 2; ++n) _Pragma("unroll") for (int k = 0; k < 2; ++k) \
;         acc[ai][bj][m][n] = __builtin_amdgcn_mfma_f32_16x16x32_bf16(Bt[n][k], At[m][k], acc[ai][bj][m][n], 0, 0, 0); __builtin_amdgcn_s_setprio(0); } while (0)
; #define PG8_WAIT_V(n) asm volatile("s_waitcnt vmcnt(" #n ")" ::: "memory")
; #define PG8_WAIT_L(n) asm volatile("s_waitcnt lgkmcnt(" #n ")" ::: "memory")
; #define PG8_BAR __builtin_amdgcn_s_barrier()
; #define PG8_SCHED __builtin_amdgcn_sched_barrier(0)
; template <class Epi, class Sched>
; __device__ __forceinline__ void gemm_phase(PG8_LAS unsigned char* lds, PG8_LAS unsigned char* xl, const Gemm g, const Sched& S, const Epi& E) {
;     ...
;         for (int t = 0; t < nt; t += 2) {
;     ...
;             PG8_LDA(At, 1, 1); PG8_STAGE(PG8_SB(1, 0), b3, voffB); PG8_STAGE(PG8_SB(1, 1), b3 + hsB, voffB); PG8_STAGE(PG8_SA(1, 0), a3, voffA);
;             PG8_WAIT_V(8); PG8_WAIT_L(0); PG8_BAR; PG8_MMA(1, 0, At, B0); PG8_MMA(1, 1, At, B1); PG8_BAR; PG8_SCHED;
	s_add_i32 s34, s68, s51
	v_lshl_add_u64 v[238:239], v[238:239], 0, s[16:17]
	s_mov_b32 m0, s34
	ds_read_b128 v[204:207], v166 offset:49152
	ds_read_b128 v[208:211], v166 offset:50176
	ds_read_b128 v[212:215], v166 offset:51200
	ds_read_b128 v[216:219], v166 offset:52224
	ds_read_b128 v[222:225], v166 offset:53248
	ds_read_b128 v[226:229], v166 offset:54272
	ds_read_b128 v[230:233], v166 offset:55296
	ds_read_b128 v[234:237], v166 offset:56320
	global_load_lds_dwordx4 v[238:239], off
	s_add_i32 m0, s34, 0x2000
	s_add_u32 s30, s30, 0x40080
	v_lshl_add_u64 v[238:239], v[240:241], 0, s[16:17]
	s_addc_u32 s31, s31, 0
	s_add_i32 s34, s76, s51
	global_load_lds_dwordx4 v[238:239], off
	v_lshl_add_u64 v[238:239], s[30:31], 0, v[132:133]
	s_mov_b32 m0, s34
	s_nop 0
	global_load_lds_dwordx4 v[238:239], off
	v_lshl_add_u64 v[238:239], s[30:31], 0, v[128:129]
	s_add_i32 m0, s34, 0x2000
	s_nop 0
	global_load_lds_dwordx4 v[238:239], off
	v_lshl_add_u64 v[238:239], v[242:243], 0, s[16:17]
	s_mov_b32 m0, s59
	s_nop 0
	global_load_lds_dwordx4 v[238:239], off
	v_lshl_add_u64 v[238:239], v[244:245], 0, s[16:17]
	s_mov_b32 m0, s61
	s_nop 0
	global_load_lds_dwordx4 v[238:239], off
	s_waitcnt vmcnt(8) lgkmcnt(0)
	s_barrier
	s_setprio 1
	v_mfma_f32_16x16x32_bf16 v[60:63], v[170:173], v[204:207], v[60:63]
	v_mfma_f32_16x16x32_bf16 v[52:55], v[180:183], v[204:207], v[52:55]
	v_mfma_f32_16x16x32_bf16 v[44:47], v[170:173], v[212:215], v[44:47]
	v_mfma_f32_16x16x32_bf16 v[36:39], v[180:183], v[212:215], v[36:39]
	v_mfma_f32_16x16x32_bf16 v[28:31], v[170:173], v[222:225], v[28:31]
	v_mfma_f32_16x16x32_bf16 v[20:23], v[180:183], v[222:225], v[20:23]
	v_mfma_f32_16x16x32_bf16 v[12:15], v[170:173], v[230:233], v[12:15]
	v_mfma_f32_16x16x32_bf16 v[4:7], v[180:183], v[230:233], v[4:7]
	v_mfma_f32_16x16x32_bf16 v[60:63], v[174:177], v[208:211], v[60:63]
	v_mfma_f32_16x16x32_bf16 v[52:55], v[184:187], v[208:211], v[52:55]
	v_mfma_f32_16x16x32_bf16 v[44:47], v[174:177], v[216:219], v[44:47]
	v_mfma_f32_16x16x32_bf16 v[36:39], v[184:187], v[216:219], v[36:39]
	v_mfma_f32_16x16x32_bf16 v[28:31], v[174:177], v[226:229], v[28:31]
	v_mfma_f32_16x16x32_bf16 v[20:23], v[184:187], v[226:229], v[20:23]
	v_mfma_f32_16x16x32_bf16 v[12:15], v[174:177], v[234:237], v[12:15]
	v_mfma_f32_16x16x32_bf16 v[4:7], v[184:187], v[234:237], v[4:7]
	s_setprio 0
	s_setprio 1
	v_mfma_f32_16x16x32_bf16 v[56:59], v[188:191], v[204:207], v[56:59]
	s_add_i32 s75, s75, 2
	v_mfma_f32_16x16x32_bf16 v[48:51], v[196:199], v[204:207], v[48:51]
	s_add_u32 s73, s73, 0x100
	v_mfma_f32_16x16x32_bf16 v[40:43], v[188:191], v[212:215], v[40:43]
	s_addc_u32 s74, s74, 0
	v_mfma_f32_16x16x32_bf16 v[32:35], v[196:199], v[212:215], v[32:35]
	s_add_u32 s2, s2, 0x100
	v_mfma_f32_16x16x32_bf16 v[24:27], v[188:191], v[222:225], v[24:27]
	s_addc_u32 s3, s3, 0
	v_mfma_f32_16x16x32_bf16 v[16:19], v[196:199], v[222:225], v[16:19]
	s_cmp_gt_u32 s75, 13
	v_mfma_f32_16x16x32_bf16 v[8:11], v[188:191], v[230:233], v[8:11]
	v_mfma_f32_16x16x32_bf16 v[0:3], v[196:199], v[230:233], v[0:3]
	v_mfma_f32_16x16x32_bf16 v[56:59], v[192:195], v[208:211], v[56:59]
	v_mfma_f32_16x16x32_bf16 v[48:51], v[200:203], v[208:211], v[48:51]
	v_mfma_f32_16x16x32_bf16 v[40:43], v[192:195], v[216:219], v[40:43]
	v_mfma_f32_16x16x32_bf16 v[32:35], v[200:203], v[216:219], v[32:35]
	v_mfma_f32_16x16x32_bf16 v[24:27], v[192:195], v[226:229], v[24:27]
	v_mfma_f32_16x16x32_bf16 v[16:19], v[200:203], v[226:229], v[16:19]
	v_mfma_f32_16x16x32_bf16 v[8:11], v[192:195], v[234:237], v[8:11]
	v_mfma_f32_16x16x32_bf16 v[0:3], v[200:203], v[234:237], v[0:3]
	s_setprio 0
	s_barrier
	s_cbranch_scc0 .LBB0_825

; #define PG8_STAGE(bufoff, gbase, voff) do { _Pragma("unroll") for (int _i = 0; _i < 2; ++_i) \
;         __builtin_amdgcn_global_load_lds((const unsigned*)((const char*)(gbase) + (voff)[_i]), (PG8_LAS unsigned*)(lds + (bufoff) + ldsw + _i * 8192), 16, 0, 0); } while (0)
; #define PG8_LDA(dst, b, h) do { _Pragma("unroll") for (int m = 0; m < 4; ++m) _Pragma("unroll") for (int k = 0; k < 2; ++k) dst[m][k] = *(const PG8_LAS bf16x8*)(lds + PG8_SA(b, h) + aoff + m * 2048 + k * 1024); } while (0)
; #define PG8_LDB(dst, b, h) do { _Pragma("unroll") for (int n = 0; n < 2; ++n) _Pragma("unroll") for (int k = 0; k < 2; ++k) dst[n][k] = *(const PG8_LAS bf16x8*)(lds + PG8_SB(b, h) + boff + n * 2048 + k * 1024); } while (0)
; #define PG8_MMA(ai, bj, At, Bt) do { __builtin_amdgcn_s_setprio(1); _Pragma("unroll") for (int m = 0; m < 4; ++m) _Pragma("unroll") for (int n = 0; n < 2; ++n) _Pragma("unroll") for (int k = 0; k < 2; ++k) \
;         acc[ai][bj][m][n] = __builtin_amdgcn_mfma_f32_16x16x32_bf16(Bt[n][k], At[m][k], acc[ai][bj][m][n], 0, 0, 0); __builtin_amdgcn_s_setprio(0); } while (0)
; #define PG8_WAIT_V(n) asm volatile("s_waitcnt vmcnt(" #n ")" ::: "memory")
; #define PG8_WAIT_L(n) asm volatile("s_waitcnt lgkmcnt(" #n ")" ::: "memory")
; #define PG8_BAR __builtin_amdgcn_s_barrier()
; #define PG8_SCHED __builtin_amdgcn_sched_barrier(0)
; template <class Epi, class Sched>
; __device__ __forceinline__ void gemm_phase(PG8_LAS unsigned char* lds, PG8_LAS unsigned char* xl, const Gemm g, const Sched& S, const Epi& E) {
;     ...
;             PG8_LDB(B0, 0, 0); PG8_LDB(B1, 0, 1); PG8_SCHED; PG8_LDA(At, 0, 0); PG8_STAGE(PG8_SA(1, 1), a1 + hsA, voffA);
;             PG8_WAIT_V(8); PG8_WAIT_L(0); PG8_BAR; PG8_MMA(0, 0, At, B0); PG8_MMA(0, 1, At, B1); PG8_BAR; PG8_SCHED;
;             PG8_LDA(At, 0, 1); PG8_STAGE(PG8_SB(0, 0), b2, voffB); PG8_STAGE(PG8_SB(0, 1), b2 + hsB, voffB); PG8_STAGE(PG8_SA(0, 0), a2, voffA);
;             PG8_WAIT_V(8); PG8_WAIT_L(0); PG8_BAR; PG8_MMA(1, 0, At, B0); PG8_MMA(1, 1, At, B1); PG8_BAR; PG8_SCHED;
.LBB0_914:
	ds_read_b128 v[144:147], v151
	ds_read_b128 v[154:157], v151 offset:1024
	ds_read_b128 v[158:161], v151 offset:2048
	ds_read_b128 v[162:165], v151 offset:3072
	ds_read_b128 v[166:169], v152
	ds_read_b128 v[170:173], v152 offset:1024
	ds_read_b128 v[174:177], v152 offset:2048
	ds_read_b128 v[180:183], v152 offset:3072
	s_add_u32 s28, s26, 0x100
	s_addc_u32 s29, s27, 0
	s_cmp_eq_u32 s67, 40
	s_cselect_b32 s35, s61, s29
	s_cselect_b32 s34, s62, s28
	s_cselect_b32 s31, s63, s66
	s_cselect_b32 s30, s64, s65
	v_lshl_add_u64 v[216:217], s[26:27], 0, v[138:139]
	s_add_i32 m0, s42, 0xc000
	ds_read_b128 v[184:187], v153
	ds_read_b128 v[188:191], v153 offset:1024
	ds_read_b128 v[192:195], v153 offset:2048
	ds_read_b128 v[196:199], v153 offset:3072
	ds_read_b128 v[200:203], v153 offset:4096
	ds_read_b128 v[204:207], v153 offset:5120
	ds_read_b128 v[208:211], v153 offset:6144
	ds_read_b128 v[212:215], v153 offset:7168
	global_load_lds_dwordx4 v[216:217], off
	v_lshl_add_u64 v[216:217], s[26:27], 0, v[136:137]
	s_add_i32 m0, s42, 0xe000
	s_nop 0
	global_load_lds_dwordx4 v[216:217], off
	s_waitcnt vmcnt(8) lgkmcnt(0)
	s_barrier
	s_setprio 1
	v_mfma_f32_16x16x32_bf16 v[124:127], v[144:147], v[184:187], v[124:127]
	v_mfma_f32_16x16x32_bf16 v[120:123], v[158:161], v[184:187], v[120:123]
	v_mfma_f32_16x16x32_bf16 v[108:111], v[144:147], v[192:195], v[108:111]
	v_mfma_f32_16x16x32_bf16 v[104:107], v[158:161], v[192:195], v[104:107]
	v_mfma_f32_16x16x32_bf16 v[92:95], v[144:147], v[200:203], v[92:95]
	v_mfma_f32_16x16x32_bf16 v[88:91], v[158:161], v[200:203], v[88:91]
	v_mfma_f32_16x16x32_bf16 v[76:79], v[144:147], v[208:211], v[76:79]
	v_mfma_f32_16x16x32_bf16 v[72:75], v[158:161], v[208:211], v[72:75]
	v_mfma_f32_16x16x32_bf16 v[124:127], v[154:157], v[188:191], v[124:127]
	v_mfma_f32_16x16x32_bf16 v[120:123], v[162:165], v[188:191], v[120:123]
	v_mfma_f32_16x16x32_bf16 v[108:111], v[154:157], v[196:199], v[108:111]
	v_mfma_f32_16x16x32_bf16 v[104:107], v[162:165], v[196:199], v[104:107]
	v_mfma_f32_16x16x32_bf16 v[92:95], v[154:157], v[204:207], v[92:95]
	v_mfma_f32_16x16x32_bf16 v[88:91], v[162:165], v[204:207], v[88:91]
	v_mfma_f32_16x16x32_bf16 v[76:79], v[154:157], v[212:215], v[76:79]
	v_mfma_f32_16x16x32_bf16 v[72:75], v[162:165], v[212:215], v[72:75]
	s_setprio 0
	s_setprio 1
	v_mfma_f32_16x16x32_bf16 v[116:119], v[166:169], v[184:187], v[116:119]
	v_mfma_f32_16x16x32_bf16 v[112:115], v[174:177], v[184:187], v[112:115]
	v_mfma_f32_16x16x32_bf16 v[100:103], v[166:169], v[192:195], v[100:103]
	v_mfma_f32_16x16x32_bf16 v[96:99], v[174:177], v[192:195], v[96:99]
	v_mfma_f32_16x16x32_bf16 v[84:87], v[166:169], v[200:203], v[84:87]
	v_mfma_f32_16x16x32_bf16 v[80:83], v[174:177], v[200:203], v[80:83]
	v_mfma_f32_16x16x32_bf16 v[68:71], v[166:169], v[208:211], v[68:71]
	v_mfma_f32_16x16x32_bf16 v[64:67], v[174:177], v[208:211], v[64:67]
	v_mfma_f32_16x16x32_bf16 v[116:119], v[170:173], v[188:191], v[116:119]
	v_mfma_f32_16x16x32_bf16 v[112:115], v[180:183], v[188:191], v[112:115]
	v_mfma_f32_16x16x32_bf16 v[100:103], v[170:173], v[196:199], v[100:103]
	v_mfma_f32_16x16x32_bf16 v[96:99], v[180:183], v[196:199], v[96:99]
	v_mfma_f32_16x16x32_bf16 v[84:87], v[170:173], v[204:207], v[84:87]
	v_mfma_f32_16x16x32_bf16 v[80:83], v[180:183], v[204:207], v[80:83]
	v_mfma_f32_16x16x32_bf16 v[68:71], v[170:173], v[212:215], v[68:71]
	v_mfma_f32_16x16x32_bf16 v[64:67], v[180:183], v[212:215], v[64:67]
	s_setprio 0
	s_barrier
	s_add_i32 s26, s51, s37
	v_lshl_add_u64 v[216:217], s[30:31], 0, v[130:131]
	s_mov_b32 m0, s26
	ds_read_b128 v[184:187], v153 offset:16384
	ds_read_b128 v[188:191], v153 offset:17408
	ds_read_b128 v[192:195], v153 offset:18432
	ds_read_b128 v[196:199], v153 offset:19456
	ds_read_b128 v[200:203], v153 offset:20480
	ds_read_b128 v[204:207], v153 offset:21504
	ds_read_b128 v[208:211], v153 offset:22528
	ds_read_b128 v[212:215], v153 offset:23552
	global_load_lds_dwordx4 v[216:217], off
	s_add_i32 m0, s26, 0x2000
	s_add_u32 s26, s30, 0xb0000
	v_lshl_add_u64 v[218:219], s[30:31], 0, v[134:135]
	s_addc_u32 s27, s31, 0
	s_add_i32 s68, s52, s37
	global_load_lds_dwordx4 v[218:219], off
	v_lshl_add_u64 v[222:223], s[26:27], 0, v[130:131]
	s_mov_b32 m0, s68
	v_lshl_add_u64 v[224:225], s[34:35], 0, v[132:133]
	global_load_lds_dwordx4 v[222:223], off
	v_lshl_add_u64 v[222:223], s[26:27], 0, v[134:135]
	s_add_i32 m0, s68, 0x2000
	s_nop 0
	global_load_lds_dwordx4 v[222:223], off
	v_lshl_add_u64 v[222:223], s[34:35], 0, v[128:129]
	s_mov_b32 m0, s42
	s_nop 0
	global_load_lds_dwordx4 v[222:223], off
	s_mov_b32 m0, s43
	s_nop 0
	global_load_lds_dwordx4 v[224:225], off
	s_waitcnt vmcnt(8) lgkmcnt(0)
	s_barrier
; #define PG8_STAGE(bufoff, gbase, voff) do { _Pragma("unroll") for (int _i = 0; _i < 2; ++_i) \
;         __builtin_amdgcn_global_load_lds((const unsigned*)((const char*)(gbase) + (voff)[_i]), (PG8_LAS unsigned*)(lds + (bufoff) + ldsw + _i * 8192), 16, 0, 0); } while (0)
; #define PG8_LDA(dst, b, h) do { _Pragma("unroll") for (int m = 0; m < 4; ++m) _Pragma("unroll") for (int k = 0; k < 2; ++k) dst[m][k] = *(const PG8_LAS bf16x8*)(lds + PG8_SA(b, h) + aoff + m * 2048 + k * 1024); } while (0)
; #define PG8_LDB(dst, b, h) do { _Pragma("unroll") for (int n = 0; n < 2; ++n) _Pragma("unroll") for (int k = 0; k < 2; ++k) dst[n][k] = *(const PG8_LAS bf16x8*)(lds + PG8_SB(b, h) + boff + n * 2048 + k * 1024); } while (0)
; #define PG8_MMA(ai, bj, At, Bt) do { __builtin_amdgcn_s_setprio(1); _Pragma("unroll") for (int m = 0; m < 4; ++m) _Pragma("unroll") for (int n = 0; n < 2; ++n) _Pragma("unroll") for (int k = 0; k < 2; ++k) \
;         acc[ai][bj][m][n] = __builtin_amdgcn_mfma_f32_16x16x32_bf16(Bt[n][k], At[m][k], acc[ai][bj][m][n], 0, 0, 0); __builtin_amdgcn_s_setprio(0); } while (0)
; #define PG8_WAIT_V(n) asm volatile("s_waitcnt vmcnt(" #n ")" ::: "memory")
; #define PG8_WAIT_L(n) asm volatile("s_waitcnt lgkmcnt(" #n ")" ::: "memory")
; #define PG8_BAR __builtin_amdgcn_s_barrier()
; #define PG8_SCHED __builtin_amdgcn_sched_barrier(0)
; template <class Epi, class Sched>
; __device__ __forceinline__ void gemm_phase(PG8_LAS unsigned char* lds, PG8_LAS unsigned char* xl, const Gemm g, const Sched& S, const Epi& E) {
;     ...
;             PG8_WAIT_V(8); PG8_WAIT_L(0); PG8_BAR; PG8_MMA(1, 0, At, B0); PG8_MMA(1, 1, At, B1); PG8_BAR; PG8_SCHED;
;             PG8_LDB(B0, 1, 0); PG8_LDB(B1, 1, 1); PG8_SCHED; PG8_LDA(At, 1, 0); PG8_STAGE(PG8_SA(0, 1), a2 + hsA, voffA);
;             PG8_WAIT_V(8); PG8_WAIT_L(0); PG8_BAR; PG8_MMA(0, 0, At, B0); PG8_MMA(0, 1, At, B1); PG8_BAR; PG8_SCHED;
	s_setprio 1
	v_mfma_f32_16x16x32_bf16 v[60:63], v[144:147], v[184:187], v[60:63]
	v_mfma_f32_16x16x32_bf16 v[56:59], v[158:161], v[184:187], v[56:59]
	v_mfma_f32_16x16x32_bf16 v[44:47], v[144:147], v[192:195], v[44:47]
	v_mfma_f32_16x16x32_bf16 v[40:43], v[158:161], v[192:195], v[40:43]
	v_mfma_f32_16x16x32_bf16 v[28:31], v[144:147], v[200:203], v[28:31]
	v_mfma_f32_16x16x32_bf16 v[24:27], v[158:161], v[200:203], v[24:27]
	v_mfma_f32_16x16x32_bf16 v[12:15], v[144:147], v[208:211], v[12:15]
	v_mfma_f32_16x16x32_bf16 v[8:11], v[158:161], v[208:211], v[8:11]
	v_mfma_f32_16x16x32_bf16 v[60:63], v[154:157], v[188:191], v[60:63]
	v_mfma_f32_16x16x32_bf16 v[56:59], v[162:165], v[188:191], v[56:59]
	v_mfma_f32_16x16x32_bf16 v[44:47], v[154:157], v[196:199], v[44:47]
	v_mfma_f32_16x16x32_bf16 v[40:43], v[162:165], v[196:199], v[40:43]
	v_mfma_f32_16x16x32_bf16 v[28:31], v[154:157], v[204:207], v[28:31]
	v_mfma_f32_16x16x32_bf16 v[24:27], v[162:165], v[204:207], v[24:27]
	v_mfma_f32_16x16x32_bf16 v[12:15], v[154:157], v[212:215], v[12:15]
	v_mfma_f32_16x16x32_bf16 v[8:11], v[162:165], v[212:215], v[8:11]
	s_setprio 0
	s_setprio 1
	v_mfma_f32_16x16x32_bf16 v[52:55], v[166:169], v[184:187], v[52:55]
	v_mfma_f32_16x16x32_bf16 v[48:51], v[174:177], v[184:187], v[48:51]
	v_mfma_f32_16x16x32_bf16 v[36:39], v[166:169], v[192:195], v[36:39]
	v_mfma_f32_16x16x32_bf16 v[32:35], v[174:177], v[192:195], v[32:35]
	v_mfma_f32_16x16x32_bf16 v[20:23], v[166:169], v[200:203], v[20:23]
	v_mfma_f32_16x16x32_bf16 v[16:19], v[174:177], v[200:203], v[16:19]
	v_mfma_f32_16x16x32_bf16 v[4:7], v[166:169], v[208:211], v[4:7]
	v_mfma_f32_16x16x32_bf16 v[0:3], v[174:177], v[208:211], v[0:3]
	v_mfma_f32_16x16x32_bf16 v[52:55], v[170:173], v[188:191], v[52:55]
	v_mfma_f32_16x16x32_bf16 v[48:51], v[180:183], v[188:191], v[48:51]
	v_mfma_f32_16x16x32_bf16 v[36:39], v[170:173], v[196:199], v[36:39]
	v_mfma_f32_16x16x32_bf16 v[32:35], v[180:183], v[196:199], v[32:35]
	v_mfma_f32_16x16x32_bf16 v[20:23], v[170:173], v[204:207], v[20:23]
	v_mfma_f32_16x16x32_bf16 v[16:19], v[180:183], v[204:207], v[16:19]
	v_mfma_f32_16x16x32_bf16 v[4:7], v[170:173], v[212:215], v[4:7]
	v_mfma_f32_16x16x32_bf16 v[0:3], v[180:183], v[212:215], v[0:3]
	s_setprio 0
	s_barrier
	s_add_i32 s68, 0, 0x18000
	s_add_i32 s70, 0, 0x1c000
	v_add_u32_e32 v162, s68, v149
	v_add_u32_e32 v179, s70, v149
	ds_read_b128 v[144:147], v162
	ds_read_b128 v[154:157], v162 offset:1024
	ds_read_b128 v[158:161], v162 offset:2048
	ds_read_b128 v[162:165], v162 offset:3072
	ds_read_b128 v[166:169], v179
	ds_read_b128 v[170:173], v179 offset:1024
	ds_read_b128 v[174:177], v179 offset:2048
	ds_read_b128 v[180:183], v179 offset:3072
	s_add_u32 s26, s34, 0xb0000
	s_addc_u32 s27, s35, 0
	s_mov_b32 m0, s46
	v_lshl_add_u64 v[226:227], s[26:27], 0, v[128:129]
	ds_read_b128 v[184:187], v153 offset:32768
	ds_read_b128 v[188:191], v153 offset:33792
	ds_read_b128 v[192:195], v153 offset:34816
	ds_read_b128 v[196:199], v153 offset:35840
	ds_read_b128 v[200:203], v153 offset:36864
	ds_read_b128 v[204:207], v153 offset:37888
	ds_read_b128 v[208:211], v153 offset:38912
	ds_read_b128 v[212:215], v153 offset:39936
	global_load_lds_dwordx4 v[226:227], off
	v_lshl_add_u64 v[226:227], s[26:27], 0, v[132:133]
	s_mov_b32 m0, s47
	s_nop 0
	global_load_lds_dwordx4 v[226:227], off
	s_waitcnt vmcnt(8) lgkmcnt(0)
	s_barrier
	s_setprio 1
	v_mfma_f32_16x16x32_bf16 v[124:127], v[144:147], v[184:187], v[124:127]
	v_mfma_f32_16x16x32_bf16 v[120:123], v[158:161], v[184:187], v[120:123]
	v_mfma_f32_16x16x32_bf16 v[108:111], v[144:147], v[192:195], v[108:111]
	v_mfma_f32_16x16x32_bf16 v[104:107], v[158:161], v[192:195], v[104:107]
	v_mfma_f32_16x16x32_bf16 v[92:95], v[144:147], v[200:203], v[92:95]
	v_mfma_f32_16x16x32_bf16 v[88:91], v[158:161], v[200:203], v[88:91]
	v_mfma_f32_16x16x32_bf16 v[76:79], v[144:147], v[208:211], v[76:79]
	v_mfma_f32_16x16x32_bf16 v[72:75], v[158:161], v[208:211], v[72:75]
	v_mfma_f32_16x16x32_bf16 v[124:127], v[154:157], v[188:191], v[124:127]
	v_mfma_f32_16x16x32_bf16 v[120:123], v[162:165], v[188:191], v[120:123]
	v_mfma_f32_16x16x32_bf16 v[108:111], v[154:157], v[196:199], v[108:111]
	v_mfma_f32_16x16x32_bf16 v[104:107], v[162:165], v[196:199], v[104:107]
	v_mfma_f32_16x16x32_bf16 v[92:95], v[154:157], v[204:207], v[92:95]
	v_mfma_f32_16x16x32_bf16 v[88:91], v[162:165], v[204:207], v[88:91]
	v_mfma_f32_16x16x32_bf16 v[76:79], v[154:157], v[212:215], v[76:79]
	v_mfma_f32_16x16x32_bf16 v[72:75], v[162:165], v[212:215], v[72:75]
	s_setprio 0
	s_setprio 1
	v_mfma_f32_16x16x32_bf16 v[116:119], v[166:169], v[184:187], v[116:119]
	v_mfma_f32_16x16x32_bf16 v[112:115], v[174:177], v[184:187], v[112:115]
	v_mfma_f32_16x16x32_bf16 v[100:103], v[166:169], v[192:195], v[100:103]
	v_mfma_f32_16x16x32_bf16 v[96:99], v[174:177], v[192:195], v[96:99]
	v_mfma_f32_16x16x32_bf16 v[84:87], v[166:169], v[200:203], v[84:87]
	v_mfma_f32_16x16x32_bf16 v[80:83], v[174:177], v[200:203], v[80:83]
	v_mfma_f32_16x16x32_bf16 v[68:71], v[166:169], v[208:211], v[68:71]
	v_mfma_f32_16x16x32_bf16 v[64:67], v[174:177], v[208:211], v[64:67]
	v_mfma_f32_16x16x32_bf16 v[116:119], v[170:173], v[188:191], v[116:119]
	v_mfma_f32_16x16x32_bf16 v[112:115], v[180:183], v[188:191], v[112:115]
	v_mfma_f32_16x16x32_bf16 v[100:103], v[170:173], v[196:199], v[100:103]
	v_mfma_f32_16x16x32_bf16 v[96:99], v[180:183], v[196:199], v[96:99]
	v_mfma_f32_16x16x32_bf16 v[84:87], v[170:173], v[204:207], v[84:87]
	v_mfma_f32_16x16x32_bf16 v[80:83], v[180:183], v[204:207], v[80:83]
	v_mfma_f32_16x16x32_bf16 v[68:71], v[170:173], v[212:215], v[68:71]
	v_mfma_f32_16x16x32_bf16 v[64:67], v[180:183], v[212:215], v[64:67]
	s_setprio 0
	s_barrier
; #define PG8_STAGE(bufoff, gbase, voff) do { _Pragma("unroll") for (int _i = 0; _i < 2; ++_i) \
;         __builtin_amdgcn_global_load_lds((const unsigned*)((const char*)(gbase) + (voff)[_i]), (PG8_LAS unsigned*)(lds + (bufoff) + ldsw + _i * 8192), 16, 0, 0); } while (0)
; #define PG8_LDA(dst, b, h) do { _Pragma("unroll") for (int m = 0; m < 4; ++m) _Pragma("unroll") for (int k = 0; k < 2; ++k) dst[m][k] = *(const PG8_LAS bf16x8*)(lds + PG8_SA(b, h) + aoff + m * 2048 + k * 1024); } while (0)
; #define PG8_MMA(ai, bj, At, Bt) do { __builtin_amdgcn_s_setprio(1); _Pragma("unroll") for (int m = 0; m < 4; ++m) _Pragma("unroll") for (int n = 0; n < 2; ++n) _Pragma("unroll") for (int k = 0; k < 2; ++k) \
;         acc[ai][bj][m][n] = __builtin_amdgcn_mfma_f32_16x16x32_bf16(Bt[n][k], At[m][k], acc[ai][bj][m][n], 0, 0, 0); __builtin_amdgcn_s_setprio(0); } while (0)
; #define PG8_WAIT_V(n) asm volatile("s_waitcnt vmcnt(" #n ")" ::: "memory")
; #define PG8_WAIT_L(n) asm volatile("s_waitcnt lgkmcnt(" #n ")" ::: "memory")
; #define PG8_BAR __builtin_amdgcn_s_barrier()
; #define PG8_SCHED __builtin_amdgcn_sched_barrier(0)
; template <class Epi, class Sched>
; __device__ __forceinline__ void gemm_phase(PG8_LAS unsigned char* lds, PG8_LAS unsigned char* xl, const Gemm g, const Sched& S, const Epi& E) {
;     ...
;             PG8_LDA(At, 1, 1); PG8_STAGE(PG8_SB(1, 0), b3, voffB); PG8_STAGE(PG8_SB(1, 1), b3 + hsB, voffB); PG8_STAGE(PG8_SA(1, 0), a3, voffA);
;             PG8_WAIT_V(8); PG8_WAIT_L(0); PG8_BAR; PG8_MMA(1, 0, At, B0); PG8_MMA(1, 1, At, B1); PG8_BAR; PG8_SCHED;
;         }
;         if (wr == 0) PG8_BAR;
	s_add_i32 s26, s68, s37
	v_lshl_add_u64 v[216:217], v[216:217], 0, s[12:13]
	s_mov_b32 m0, s26
	ds_read_b128 v[184:187], v153 offset:49152
	ds_read_b128 v[188:191], v153 offset:50176
	ds_read_b128 v[192:195], v153 offset:51200
	ds_read_b128 v[196:199], v153 offset:52224
	ds_read_b128 v[200:203], v153 offset:53248
	ds_read_b128 v[204:207], v153 offset:54272
	ds_read_b128 v[208:211], v153 offset:55296
	ds_read_b128 v[212:215], v153 offset:56320
	global_load_lds_dwordx4 v[216:217], off
	s_add_i32 m0, s26, 0x2000
	s_add_u32 s26, s30, 0xb0080
	v_lshl_add_u64 v[216:217], v[218:219], 0, s[12:13]
	s_addc_u32 s27, s31, 0
	s_add_i32 s30, s70, s37
	global_load_lds_dwordx4 v[216:217], off
	v_lshl_add_u64 v[216:217], s[26:27], 0, v[130:131]
	s_mov_b32 m0, s30
	s_nop 0
	global_load_lds_dwordx4 v[216:217], off
	v_lshl_add_u64 v[216:217], s[26:27], 0, v[134:135]
	s_add_i32 m0, s30, 0x2000
	s_nop 0
	global_load_lds_dwordx4 v[216:217], off
	v_lshl_add_u64 v[216:217], v[222:223], 0, s[12:13]
	s_mov_b32 m0, s49
	s_nop 0
	global_load_lds_dwordx4 v[216:217], off
	v_lshl_add_u64 v[216:217], v[224:225], 0, s[12:13]
	s_mov_b32 m0, s50
	s_nop 0
	global_load_lds_dwordx4 v[216:217], off
	s_waitcnt vmcnt(8) lgkmcnt(0)
	s_barrier
	s_setprio 1
	v_mfma_f32_16x16x32_bf16 v[60:63], v[144:147], v[184:187], v[60:63]
	v_mfma_f32_16x16x32_bf16 v[56:59], v[158:161], v[184:187], v[56:59]
	v_mfma_f32_16x16x32_bf16 v[44:47], v[144:147], v[192:195], v[44:47]
	v_mfma_f32_16x16x32_bf16 v[40:43], v[158:161], v[192:195], v[40:43]
	v_mfma_f32_16x16x32_bf16 v[28:31], v[144:147], v[200:203], v[28:31]
	v_mfma_f32_16x16x32_bf16 v[24:27], v[158:161], v[200:203], v[24:27]
	v_mfma_f32_16x16x32_bf16 v[12:15], v[144:147], v[208:211], v[12:15]
	v_mfma_f32_16x16x32_bf16 v[8:11], v[158:161], v[208:211], v[8:11]
	v_mfma_f32_16x16x32_bf16 v[60:63], v[154:157], v[188:191], v[60:63]
	v_mfma_f32_16x16x32_bf16 v[56:59], v[162:165], v[188:191], v[56:59]
	v_mfma_f32_16x16x32_bf16 v[44:47], v[154:157], v[196:199], v[44:47]
	v_mfma_f32_16x16x32_bf16 v[40:43], v[162:165], v[196:199], v[40:43]
	v_mfma_f32_16x16x32_bf16 v[28:31], v[154:157], v[204:207], v[28:31]
	v_mfma_f32_16x16x32_bf16 v[24:27], v[162:165], v[204:207], v[24:27]
	v_mfma_f32_16x16x32_bf16 v[12:15], v[154:157], v[212:215], v[12:15]
	v_mfma_f32_16x16x32_bf16 v[8:11], v[162:165], v[212:215], v[8:11]
	s_setprio 0
	s_setprio 1
	v_mfma_f32_16x16x32_bf16 v[52:55], v[166:169], v[184:187], v[52:55]
	s_add_i32 s67, s67, 2
	v_mfma_f32_16x16x32_bf16 v[48:51], v[174:177], v[184:187], v[48:51]
	s_add_u32 s65, s65, 0x100
	v_mfma_f32_16x16x32_bf16 v[36:39], v[166:169], v[192:195], v[36:39]
	s_addc_u32 s66, s66, 0
	v_mfma_f32_16x16x32_bf16 v[32:35], v[174:177], v[192:195], v[32:35]
	s_cmp_gt_u32 s67, 41
	v_mfma_f32_16x16x32_bf16 v[20:23], v[166:169], v[200:203], v[20:23]
	s_mov_b64 s[26:27], s[28:29]
	v_mfma_f32_16x16x32_bf16 v[16:19], v[174:177], v[200:203], v[16:19]
	v_mfma_f32_16x16x32_bf16 v[4:7], v[166:169], v[208:211], v[4:7]
	v_mfma_f32_16x16x32_bf16 v[0:3], v[174:177], v[208:211], v[0:3]
	v_mfma_f32_16x16x32_bf16 v[52:55], v[170:173], v[188:191], v[52:55]
	v_mfma_f32_16x16x32_bf16 v[48:51], v[180:183], v[188:191], v[48:51]
	v_mfma_f32_16x16x32_bf16 v[36:39], v[170:173], v[196:199], v[36:39]
	v_mfma_f32_16x16x32_bf16 v[32:35], v[180:183], v[196:199], v[32:35]
	v_mfma_f32_16x16x32_bf16 v[20:23], v[170:173], v[204:207], v[20:23]
	v_mfma_f32_16x16x32_bf16 v[16:19], v[180:183], v[204:207], v[16:19]
	v_mfma_f32_16x16x32_bf16 v[4:7], v[170:173], v[212:215], v[4:7]
	v_mfma_f32_16x16x32_bf16 v[0:3], v[180:183], v[212:215], v[0:3]
	s_setprio 0
	s_barrier
	s_cbranch_scc0 .LBB0_914
	s_and_b64 vcc, exec, s[14:15]
	s_cbranch_vccz .LBB0_917
	s_barrier

; #define PG8_STAGE(bufoff, gbase, voff) do { _Pragma("unroll") for (int _i = 0; _i < 2; ++_i) \
;         __builtin_amdgcn_global_load_lds((const unsigned*)((const char*)(gbase) + (voff)[_i]), (PG8_LAS unsigned*)(lds + (bufoff) + ldsw + _i * 8192), 16, 0, 0); } while (0)
; #define PG8_LDA(dst, b, h) do { _Pragma("unroll") for (int m = 0; m < 4; ++m) _Pragma("unroll") for (int k = 0; k < 2; ++k) dst[m][k] = *(const PG8_LAS bf16x8*)(lds + PG8_SA(b, h) + aoff + m * 2048 + k * 1024); } while (0)
; #define PG8_LDB(dst, b, h) do { _Pragma("unroll") for (int n = 0; n < 2; ++n) _Pragma("unroll") for (int k = 0; k < 2; ++k) dst[n][k] = *(const PG8_LAS bf16x8*)(lds + PG8_SB(b, h) + boff + n * 2048 + k * 1024); } while (0)
; #define PG8_MMA(ai, bj, At, Bt) do { __builtin_amdgcn_s_setprio(1); _Pragma("unroll") for (int m = 0; m < 4; ++m) _Pragma("unroll") for (int n = 0; n < 2; ++n) _Pragma("unroll") for (int k = 0; k < 2; ++k) \
;         acc[ai][bj][m][n] = __builtin_amdgcn_mfma_f32_16x16x32_bf16(Bt[n][k], At[m][k], acc[ai][bj][m][n], 0, 0, 0); __builtin_amdgcn_s_setprio(0); } while (0)
; #define PG8_BAR __builtin_amdgcn_s_barrier()
; template <class Epi, class Sched>
; __device__ __forceinline__ void gemm_phase(PG8_LAS unsigned char* lds, PG8_LAS unsigned char* xl, const Gemm g, const Sched& S, const Epi& E) {
;     ...
;         const bool has_next = S.next(ui + 1, nxt);
;         const char* nA = has_next ? (const char*)g.A + nxt.aoff : cA; const char* nB = has_next ? (const char*)g.Bt + nxt.boff : cB;
; #pragma unroll 1
;         for (int t = 0; t < nt; t += 2) {
;             const bool last = (t == nt - 2);
;             const char* a1 = cA + (size_t)(t + 1) * kstep;
;             const char* a2 = last ? nA : cA + (size_t)(t + 2) * kstep; const char* b2 = last ? nB : cB + (size_t)(t + 2) * kstep;
;             const char* a3 = a2 + kstep; const char* b3 = b2 + kstep;
;             PG8_LDB(B0, 0, 0); PG8_LDB(B1, 0, 1); PG8_SCHED; PG8_LDA(At, 0, 0); PG8_STAGE(PG8_SA(1, 1), a1 + hsA, voffA);
;             PG8_WAIT_V(8); PG8_WAIT_L(0); PG8_BAR; PG8_MMA(0, 0, At, B0); PG8_MMA(0, 1, At, B1); PG8_BAR; PG8_SCHED;
;             PG8_LDA(At, 0, 1); PG8_STAGE(PG8_SB(0, 0), b2, voffB); PG8_STAGE(PG8_SB(0, 1), b2 + hsB, voffB); PG8_STAGE(PG8_SA(0, 0), a2, voffA);
;             PG8_WAIT_V(8); PG8_WAIT_L(0); PG8_BAR; PG8_MMA(1, 0, At, B0); PG8_MMA(1, 1, At, B1); PG8_BAR; PG8_SCHED;
.LBB0_941:
	s_add_u32 s34, s55, s28
	s_addc_u32 s35, s56, s29
	s_and_b64 s[36:37], s[10:11], exec
	s_cselect_b32 s33, s35, s3
	s_cselect_b32 s46, s34, s2
	s_add_u32 s36, s57, s30
	s_addc_u32 s37, s58, s31
	s_and_b64 s[50:51], s[10:11], exec
	s_cselect_b32 s47, s37, s49
	s_cselect_b32 s77, s36, s48
	s_add_u32 s78, s48, 0x100
	v_mov_b32_e32 v0, 0
	s_addc_u32 s79, s49, 0
	s_mov_b32 s80, -2
	ds_read_b128 v[144:147], v199
	ds_read_b128 v[148:151], v199 offset:1024
	ds_read_b128 v[152:155], v199 offset:2048
	ds_read_b128 v[156:159], v199 offset:3072
	ds_read_b128 v[160:163], v200
	ds_read_b128 v[164:167], v200 offset:1024
	ds_read_b128 v[168:171], v200 offset:2048
	ds_read_b128 v[172:175], v200 offset:3072
	s_add_u32 s48, s2, 0x100
	s_addc_u32 s49, s3, 0
	s_cmp_eq_u32 s80, 40
	s_cselect_b32 s53, s33, s49
	s_cselect_b32 s52, s46, s48
	s_cselect_b32 s51, s47, s79
	s_cselect_b32 s50, s77, s78
	v_lshl_add_u64 v[176:177], s[2:3], 0, v[138:139]
	s_add_i32 m0, s43, 0xc000
	ds_read_b128 v[214:217], v201
	ds_read_b128 v[222:225], v201 offset:1024
	ds_read_b128 v[226:229], v201 offset:2048
	ds_read_b128 v[230:233], v201 offset:3072
	ds_read_b128 v[234:237], v201 offset:4096
	ds_read_b128 v[238:241], v201 offset:5120
	ds_read_b128 v[242:245], v201 offset:6144
	ds_read_b128 v[246:249], v201 offset:7168
	global_load_lds_dwordx4 v[176:177], off
	v_lshl_add_u64 v[176:177], s[2:3], 0, v[136:137]
	s_add_i32 m0, s43, 0xe000
	s_nop 0
	global_load_lds_dwordx4 v[176:177], off
	s_waitcnt vmcnt(8) lgkmcnt(0)
	s_barrier
	s_setprio 1
	v_mfma_f32_16x16x32_bf16 v[124:127], v[144:147], v[214:217], 0
	v_mfma_f32_16x16x32_bf16 v[120:123], v[152:155], v[214:217], 0
	v_mfma_f32_16x16x32_bf16 v[108:111], v[144:147], v[226:229], 0
	v_mfma_f32_16x16x32_bf16 v[104:107], v[152:155], v[226:229], 0
	v_mfma_f32_16x16x32_bf16 v[92:95], v[144:147], v[234:237], 0
	v_mfma_f32_16x16x32_bf16 v[88:91], v[152:155], v[234:237], 0
	v_mfma_f32_16x16x32_bf16 v[76:79], v[144:147], v[242:245], 0
	v_mfma_f32_16x16x32_bf16 v[72:75], v[152:155], v[242:245], 0
	v_mfma_f32_16x16x32_bf16 v[124:127], v[148:151], v[222:225], v[124:127]
	v_mfma_f32_16x16x32_bf16 v[120:123], v[156:159], v[222:225], v[120:123]
	v_mfma_f32_16x16x32_bf16 v[108:111], v[148:151], v[230:233], v[108:111]
	v_mfma_f32_16x16x32_bf16 v[104:107], v[156:159], v[230:233], v[104:107]
	v_mfma_f32_16x16x32_bf16 v[92:95], v[148:151], v[238:241], v[92:95]
	v_mfma_f32_16x16x32_bf16 v[88:91], v[156:159], v[238:241], v[88:91]
	v_mfma_f32_16x16x32_bf16 v[76:79], v[148:151], v[246:249], v[76:79]
	v_mfma_f32_16x16x32_bf16 v[72:75], v[156:159], v[246:249], v[72:75]
	s_setprio 0
	s_setprio 1
	v_mfma_f32_16x16x32_bf16 v[116:119], v[160:163], v[214:217], 0
	v_mfma_f32_16x16x32_bf16 v[112:115], v[168:171], v[214:217], 0
	v_mfma_f32_16x16x32_bf16 v[100:103], v[160:163], v[226:229], 0
	v_mfma_f32_16x16x32_bf16 v[96:99], v[168:171], v[226:229], 0
	v_mfma_f32_16x16x32_bf16 v[84:87], v[160:163], v[234:237], 0
	v_mfma_f32_16x16x32_bf16 v[80:83], v[168:171], v[234:237], 0
	v_mfma_f32_16x16x32_bf16 v[68:71], v[160:163], v[242:245], 0
	v_mfma_f32_16x16x32_bf16 v[64:67], v[168:171], v[242:245], 0
	v_mfma_f32_16x16x32_bf16 v[116:119], v[164:167], v[222:225], v[116:119]
	v_mfma_f32_16x16x32_bf16 v[112:115], v[172:175], v[222:225], v[112:115]
	v_mfma_f32_16x16x32_bf16 v[100:103], v[164:167], v[230:233], v[100:103]
	v_mfma_f32_16x16x32_bf16 v[96:99], v[172:175], v[230:233], v[96:99]
	v_mfma_f32_16x16x32_bf16 v[84:87], v[164:167], v[238:241], v[84:87]
	v_mfma_f32_16x16x32_bf16 v[80:83], v[172:175], v[238:241], v[80:83]
	v_mfma_f32_16x16x32_bf16 v[68:71], v[164:167], v[246:249], v[68:71]
	v_mfma_f32_16x16x32_bf16 v[64:67], v[172:175], v[246:249], v[64:67]
	s_setprio 0
	s_barrier
	s_add_i32 s2, s70, s42
	v_lshl_add_u64 v[176:177], s[50:51], 0, v[130:131]
	s_mov_b32 m0, s2
	ds_read_b128 v[214:217], v201 offset:16384
	ds_read_b128 v[222:225], v201 offset:17408
	ds_read_b128 v[226:229], v201 offset:18432
	ds_read_b128 v[230:233], v201 offset:19456
	ds_read_b128 v[234:237], v201 offset:20480
	ds_read_b128 v[238:241], v201 offset:21504
	ds_read_b128 v[242:245], v201 offset:22528
	ds_read_b128 v[246:249], v201 offset:23552
	global_load_lds_dwordx4 v[176:177], off
	s_add_i32 m0, s2, 0x2000
	s_add_u32 s2, s50, 0xb0000
	v_lshl_add_u64 v[218:219], s[50:51], 0, v[134:135]
	s_addc_u32 s3, s51, 0
	s_add_i32 s68, s71, s42
	global_load_lds_dwordx4 v[218:219], off
	v_lshl_add_u64 v[250:251], s[2:3], 0, v[130:131]
	s_mov_b32 m0, s68
	v_lshl_add_u64 v[252:253], s[52:53], 0, v[132:133]
	global_load_lds_dwordx4 v[250:251], off
	v_lshl_add_u64 v[250:251], s[2:3], 0, v[134:135]
	s_add_i32 m0, s68, 0x2000
	s_nop 0
	global_load_lds_dwordx4 v[250:251], off
	v_lshl_add_u64 v[250:251], s[52:53], 0, v[128:129]
	s_mov_b32 m0, s43
	s_nop 0
	global_load_lds_dwordx4 v[250:251], off
	s_mov_b32 m0, s59
	s_nop 0
	global_load_lds_dwordx4 v[252:253], off
	s_waitcnt vmcnt(8) lgkmcnt(0)
	s_barrier
; #define PG8_STAGE(bufoff, gbase, voff) do { _Pragma("unroll") for (int _i = 0; _i < 2; ++_i) \
;         __builtin_amdgcn_global_load_lds((const unsigned*)((const char*)(gbase) + (voff)[_i]), (PG8_LAS unsigned*)(lds + (bufoff) + ldsw + _i * 8192), 16, 0, 0); } while (0)
; #define PG8_LDA(dst, b, h) do { _Pragma("unroll") for (int m = 0; m < 4; ++m) _Pragma("unroll") for (int k = 0; k < 2; ++k) dst[m][k] = *(const PG8_LAS bf16x8*)(lds + PG8_SA(b, h) + aoff + m * 2048 + k * 1024); } while (0)
; #define PG8_LDB(dst, b, h) do { _Pragma("unroll") for (int n = 0; n < 2; ++n) _Pragma("unroll") for (int k = 0; k < 2; ++k) dst[n][k] = *(const PG8_LAS bf16x8*)(lds + PG8_SB(b, h) + boff + n * 2048 + k * 1024); } while (0)
; #define PG8_MMA(ai, bj, At, Bt) do { __builtin_amdgcn_s_setprio(1); _Pragma("unroll") for (int m = 0; m < 4; ++m) _Pragma("unroll") for (int n = 0; n < 2; ++n) _Pragma("unroll") for (int k = 0; k < 2; ++k) \
;         acc[ai][bj][m][n] = __builtin_amdgcn_mfma_f32_16x16x32_bf16(Bt[n][k], At[m][k], acc[ai][bj][m][n], 0, 0, 0); __builtin_amdgcn_s_setprio(0); } while (0)
; #define PG8_WAIT_V(n) asm volatile("s_waitcnt vmcnt(" #n ")" ::: "memory")
; #define PG8_WAIT_L(n) asm volatile("s_waitcnt lgkmcnt(" #n ")" ::: "memory")
; #define PG8_BAR __builtin_amdgcn_s_barrier()
; #define PG8_SCHED __builtin_amdgcn_sched_barrier(0)
; template <class Epi, class Sched>
; __device__ __forceinline__ void gemm_phase(PG8_LAS unsigned char* lds, PG8_LAS unsigned char* xl, const Gemm g, const Sched& S, const Epi& E) {
;     ...
;             PG8_WAIT_V(8); PG8_WAIT_L(0); PG8_BAR; PG8_MMA(1, 0, At, B0); PG8_MMA(1, 1, At, B1); PG8_BAR; PG8_SCHED;
;             PG8_LDB(B0, 1, 0); PG8_LDB(B1, 1, 1); PG8_SCHED; PG8_LDA(At, 1, 0); PG8_STAGE(PG8_SA(0, 1), a2 + hsA, voffA);
;             PG8_WAIT_V(8); PG8_WAIT_L(0); PG8_BAR; PG8_MMA(0, 0, At, B0); PG8_MMA(0, 1, At, B1); PG8_BAR; PG8_SCHED;
	s_setprio 1
	v_mfma_f32_16x16x32_bf16 v[60:63], v[144:147], v[214:217], 0
	v_mfma_f32_16x16x32_bf16 v[56:59], v[152:155], v[214:217], 0
	v_mfma_f32_16x16x32_bf16 v[44:47], v[144:147], v[226:229], 0
	v_mfma_f32_16x16x32_bf16 v[40:43], v[152:155], v[226:229], 0
	v_mfma_f32_16x16x32_bf16 v[28:31], v[144:147], v[234:237], 0
	v_mfma_f32_16x16x32_bf16 v[24:27], v[152:155], v[234:237], 0
	v_mfma_f32_16x16x32_bf16 v[12:15], v[144:147], v[242:245], 0
	v_mfma_f32_16x16x32_bf16 v[8:11], v[152:155], v[242:245], 0
	v_mfma_f32_16x16x32_bf16 v[60:63], v[148:151], v[222:225], v[60:63]
	v_mfma_f32_16x16x32_bf16 v[56:59], v[156:159], v[222:225], v[56:59]
	v_mfma_f32_16x16x32_bf16 v[44:47], v[148:151], v[230:233], v[44:47]
	v_mfma_f32_16x16x32_bf16 v[40:43], v[156:159], v[230:233], v[40:43]
	v_mfma_f32_16x16x32_bf16 v[28:31], v[148:151], v[238:241], v[28:31]
	v_mfma_f32_16x16x32_bf16 v[24:27], v[156:159], v[238:241], v[24:27]
	v_mfma_f32_16x16x32_bf16 v[12:15], v[148:151], v[246:249], v[12:15]
	v_mfma_f32_16x16x32_bf16 v[8:11], v[156:159], v[246:249], v[8:11]
	s_setprio 0
	s_setprio 1
	v_mfma_f32_16x16x32_bf16 v[52:55], v[160:163], v[214:217], 0
	v_mfma_f32_16x16x32_bf16 v[48:51], v[168:171], v[214:217], 0
	v_mfma_f32_16x16x32_bf16 v[36:39], v[160:163], v[226:229], 0
	v_mfma_f32_16x16x32_bf16 v[32:35], v[168:171], v[226:229], 0
	v_mfma_f32_16x16x32_bf16 v[20:23], v[160:163], v[234:237], 0
	v_mfma_f32_16x16x32_bf16 v[16:19], v[168:171], v[234:237], 0
	v_mfma_f32_16x16x32_bf16 v[4:7], v[160:163], v[242:245], 0
	v_mfma_f32_16x16x32_bf16 v[0:3], v[168:171], v[242:245], 0
	v_mfma_f32_16x16x32_bf16 v[52:55], v[164:167], v[222:225], v[52:55]
	v_mfma_f32_16x16x32_bf16 v[48:51], v[172:175], v[222:225], v[48:51]
	v_mfma_f32_16x16x32_bf16 v[36:39], v[164:167], v[230:233], v[36:39]
	v_mfma_f32_16x16x32_bf16 v[32:35], v[172:175], v[230:233], v[32:35]
	v_mfma_f32_16x16x32_bf16 v[20:23], v[164:167], v[238:241], v[20:23]
	v_mfma_f32_16x16x32_bf16 v[16:19], v[172:175], v[238:241], v[16:19]
	v_mfma_f32_16x16x32_bf16 v[4:7], v[164:167], v[246:249], v[4:7]
	v_mfma_f32_16x16x32_bf16 v[0:3], v[172:175], v[246:249], v[0:3]
	s_setprio 0
	s_barrier
	s_add_i32 s68, 0, 0x18000
	s_add_i32 s81, 0, 0x1c000
	v_add_u32_e32 v156, s68, v181
	v_add_u32_e32 v172, s81, v181
	ds_read_b128 v[144:147], v156
	ds_read_b128 v[148:151], v156 offset:1024
	ds_read_b128 v[152:155], v156 offset:2048
	ds_read_b128 v[156:159], v156 offset:3072
	ds_read_b128 v[160:163], v172
	ds_read_b128 v[164:167], v172 offset:1024
	ds_read_b128 v[168:171], v172 offset:2048
	ds_read_b128 v[172:175], v172 offset:3072
	s_add_u32 s2, s52, 0xb0000
	s_addc_u32 s3, s53, 0
	s_mov_b32 m0, s60
	v_lshl_add_u64 v[212:213], s[2:3], 0, v[128:129]
	ds_read_b128 v[214:217], v201 offset:32768
	ds_read_b128 v[222:225], v201 offset:33792
	ds_read_b128 v[226:229], v201 offset:34816
	ds_read_b128 v[230:233], v201 offset:35840
	ds_read_b128 v[234:237], v201 offset:36864
	ds_read_b128 v[238:241], v201 offset:37888
	ds_read_b128 v[242:245], v201 offset:38912
	ds_read_b128 v[246:249], v201 offset:39936
	global_load_lds_dwordx4 v[212:213], off
	v_lshl_add_u64 v[212:213], s[2:3], 0, v[132:133]
	s_mov_b32 m0, s61
	s_nop 0
	global_load_lds_dwordx4 v[212:213], off
	s_waitcnt vmcnt(8) lgkmcnt(0)
	s_barrier
	s_setprio 1
	v_mfma_f32_16x16x32_bf16 v[124:127], v[144:147], v[214:217], v[124:127]
	v_mfma_f32_16x16x32_bf16 v[120:123], v[152:155], v[214:217], v[120:123]
	v_mfma_f32_16x16x32_bf16 v[108:111], v[144:147], v[226:229], v[108:111]
	v_mfma_f32_16x16x32_bf16 v[104:107], v[152:155], v[226:229], v[104:107]
	v_mfma_f32_16x16x32_bf16 v[92:95], v[144:147], v[234:237], v[92:95]
	v_mfma_f32_16x16x32_bf16 v[88:91], v[152:155], v[234:237], v[88:91]
	v_mfma_f32_16x16x32_bf16 v[76:79], v[144:147], v[242:245], v[76:79]
	v_mfma_f32_16x16x32_bf16 v[72:75], v[152:155], v[242:245], v[72:75]
	v_mfma_f32_16x16x32_bf16 v[124:127], v[148:151], v[222:225], v[124:127]
	v_mfma_f32_16x16x32_bf16 v[120:123], v[156:159], v[222:225], v[120:123]
	v_mfma_f32_16x16x32_bf16 v[108:111], v[148:151], v[230:233], v[108:111]
	v_mfma_f32_16x16x32_bf16 v[104:107], v[156:159], v[230:233], v[104:107]
	v_mfma_f32_16x16x32_bf16 v[92:95], v[148:151], v[238:241], v[92:95]
	v_mfma_f32_16x16x32_bf16 v[88:91], v[156:159], v[238:241], v[88:91]
	v_mfma_f32_16x16x32_bf16 v[76:79], v[148:151], v[246:249], v[76:79]
	v_mfma_f32_16x16x32_bf16 v[72:75], v[156:159], v[246:249], v[72:75]
	s_setprio 0
	s_setprio 1
	v_mfma_f32_16x16x32_bf16 v[116:119], v[160:163], v[214:217], v[116:119]
	v_mfma_f32_16x16x32_bf16 v[112:115], v[168:171], v[214:217], v[112:115]
	v_mfma_f32_16x16x32_bf16 v[100:103], v[160:163], v[226:229], v[100:103]
	v_mfma_f32_16x16x32_bf16 v[96:99], v[168:171], v[226:229], v[96:99]
	v_mfma_f32_16x16x32_bf16 v[84:87], v[160:163], v[234:237], v[84:87]
	v_mfma_f32_16x16x32_bf16 v[80:83], v[168:171], v[234:237], v[80:83]
	v_mfma_f32_16x16x32_bf16 v[68:71], v[160:163], v[242:245], v[68:71]
	v_mfma_f32_16x16x32_bf16 v[64:67], v[168:171], v[242:245], v[64:67]
	v_mfma_f32_16x16x32_bf16 v[116:119], v[164:167], v[222:225], v[116:119]
	v_mfma_f32_16x16x32_bf16 v[112:115], v[172:175], v[222:225], v[112:115]
	v_mfma_f32_16x16x32_bf16 v[100:103], v[164:167], v[230:233], v[100:103]
	v_mfma_f32_16x16x32_bf16 v[96:99], v[172:175], v[230:233], v[96:99]
	v_mfma_f32_16x16x32_bf16 v[84:87], v[164:167], v[238:241], v[84:87]
	v_mfma_f32_16x16x32_bf16 v[80:83], v[172:175], v[238:241], v[80:83]
	v_mfma_f32_16x16x32_bf16 v[68:71], v[164:167], v[246:249], v[68:71]
	v_mfma_f32_16x16x32_bf16 v[64:67], v[172:175], v[246:249], v[64:67]
	s_setprio 0
	s_barrier
; #define PG8_STAGE(bufoff, gbase, voff) do { _Pragma("unroll") for (int _i = 0; _i < 2; ++_i) \
;         __builtin_amdgcn_global_load_lds((const unsigned*)((const char*)(gbase) + (voff)[_i]), (PG8_LAS unsigned*)(lds + (bufoff) + ldsw + _i * 8192), 16, 0, 0); } while (0)
; #define PG8_LDA(dst, b, h) do { _Pragma("unroll") for (int m = 0; m < 4; ++m) _Pragma("unroll") for (int k = 0; k < 2; ++k) dst[m][k] = *(const PG8_LAS bf16x8*)(lds + PG8_SA(b, h) + aoff + m * 2048 + k * 1024); } while (0)
; #define PG8_LDB(dst, b, h) do { _Pragma("unroll") for (int n = 0; n < 2; ++n) _Pragma("unroll") for (int k = 0; k < 2; ++k) dst[n][k] = *(const PG8_LAS bf16x8*)(lds + PG8_SB(b, h) + boff + n * 2048 + k * 1024); } while (0)
; #define PG8_MMA(ai, bj, At, Bt) do { __builtin_amdgcn_s_setprio(1); _Pragma("unroll") for (int m = 0; m < 4; ++m) _Pragma("unroll") for (int n = 0; n < 2; ++n) _Pragma("unroll") for (int k = 0; k < 2; ++k) \
;         acc[ai][bj][m][n] = __builtin_amdgcn_mfma_f32_16x16x32_bf16(Bt[n][k], At[m][k], acc[ai][bj][m][n], 0, 0, 0); __builtin_amdgcn_s_setprio(0); } while (0)
; #define PG8_WAIT_V(n) asm volatile("s_waitcnt vmcnt(" #n ")" ::: "memory")
; #define PG8_WAIT_L(n) asm volatile("s_waitcnt lgkmcnt(" #n ")" ::: "memory")
; #define PG8_BAR __builtin_amdgcn_s_barrier()
; #define PG8_SCHED __builtin_amdgcn_sched_barrier(0)
; template <class Epi, class Sched>
; __device__ __forceinline__ void gemm_phase(PG8_LAS unsigned char* lds, PG8_LAS unsigned char* xl, const Gemm g, const Sched& S, const Epi& E) {
;     ...
;             PG8_LDB(B0, 0, 0); PG8_LDB(B1, 0, 1); PG8_SCHED; PG8_LDA(At, 0, 0); PG8_STAGE(PG8_SA(1, 1), a1 + hsA, voffA);
;             PG8_WAIT_V(8); PG8_WAIT_L(0); PG8_BAR; PG8_MMA(0, 0, At, B0); PG8_MMA(0, 1, At, B1); PG8_BAR; PG8_SCHED;
;     ...
;             PG8_LDA(At, 1, 1); PG8_STAGE(PG8_SB(1, 0), b3, voffB); PG8_STAGE(PG8_SB(1, 1), b3 + hsB, voffB); PG8_STAGE(PG8_SA(1, 0), a3, voffA);
;             PG8_WAIT_V(8); PG8_WAIT_L(0); PG8_BAR; PG8_MMA(1, 0, At, B0); PG8_MMA(1, 1, At, B1); PG8_BAR; PG8_SCHED;
	s_add_i32 s2, s68, s42
	v_lshl_add_u64 v[176:177], v[176:177], 0, s[22:23]
	s_mov_b32 m0, s2
	ds_read_b128 v[214:217], v201 offset:49152
	ds_read_b128 v[222:225], v201 offset:50176
	ds_read_b128 v[226:229], v201 offset:51200
	ds_read_b128 v[230:233], v201 offset:52224
	ds_read_b128 v[234:237], v201 offset:53248
	ds_read_b128 v[238:241], v201 offset:54272
	ds_read_b128 v[242:245], v201 offset:55296
	ds_read_b128 v[246:249], v201 offset:56320
	global_load_lds_dwordx4 v[176:177], off
	s_add_i32 m0, s2, 0x2000
	s_add_u32 s2, s50, 0xb0080
	v_lshl_add_u64 v[176:177], v[218:219], 0, s[22:23]
	s_addc_u32 s3, s51, 0
	s_add_i32 s50, s81, s42
	global_load_lds_dwordx4 v[176:177], off
	v_lshl_add_u64 v[176:177], s[2:3], 0, v[130:131]
	s_mov_b32 m0, s50
	s_nop 0
	global_load_lds_dwordx4 v[176:177], off
	v_lshl_add_u64 v[176:177], s[2:3], 0, v[134:135]
	s_add_i32 m0, s50, 0x2000
	s_nop 0
	global_load_lds_dwordx4 v[176:177], off
	v_lshl_add_u64 v[176:177], v[250:251], 0, s[22:23]
	s_mov_b32 m0, s65
	s_nop 0
	global_load_lds_dwordx4 v[176:177], off
	v_lshl_add_u64 v[176:177], v[252:253], 0, s[22:23]
	s_mov_b32 m0, s66
	s_nop 0
	global_load_lds_dwordx4 v[176:177], off
	s_waitcnt vmcnt(8) lgkmcnt(0)
	s_barrier
	s_setprio 1
	v_mfma_f32_16x16x32_bf16 v[60:63], v[144:147], v[214:217], v[60:63]
	v_mfma_f32_16x16x32_bf16 v[56:59], v[152:155], v[214:217], v[56:59]
	v_mfma_f32_16x16x32_bf16 v[44:47], v[144:147], v[226:229], v[44:47]
	v_mfma_f32_16x16x32_bf16 v[40:43], v[152:155], v[226:229], v[40:43]
	v_mfma_f32_16x16x32_bf16 v[28:31], v[144:147], v[234:237], v[28:31]
	v_mfma_f32_16x16x32_bf16 v[24:27], v[152:155], v[234:237], v[24:27]
	v_mfma_f32_16x16x32_bf16 v[12:15], v[144:147], v[242:245], v[12:15]
	v_mfma_f32_16x16x32_bf16 v[8:11], v[152:155], v[242:245], v[8:11]
	v_mfma_f32_16x16x32_bf16 v[60:63], v[148:151], v[222:225], v[60:63]
	v_mfma_f32_16x16x32_bf16 v[56:59], v[156:159], v[222:225], v[56:59]
	v_mfma_f32_16x16x32_bf16 v[44:47], v[148:151], v[230:233], v[44:47]
	v_mfma_f32_16x16x32_bf16 v[40:43], v[156:159], v[230:233], v[40:43]
	v_mfma_f32_16x16x32_bf16 v[28:31], v[148:151], v[238:241], v[28:31]
	v_mfma_f32_16x16x32_bf16 v[24:27], v[156:159], v[238:241], v[24:27]
	v_mfma_f32_16x16x32_bf16 v[12:15], v[148:151], v[246:249], v[12:15]
	v_mfma_f32_16x16x32_bf16 v[8:11], v[156:159], v[246:249], v[8:11]
	s_setprio 0
	s_setprio 1
	v_mfma_f32_16x16x32_bf16 v[52:55], v[160:163], v[214:217], v[52:55]
	s_add_i32 s80, s80, 2
	v_mfma_f32_16x16x32_bf16 v[48:51], v[168:171], v[214:217], v[48:51]
	s_add_u32 s78, s78, 0x100
	v_mfma_f32_16x16x32_bf16 v[36:39], v[160:163], v[226:229], v[36:39]
	s_addc_u32 s79, s79, 0
	v_mfma_f32_16x16x32_bf16 v[32:35], v[168:171], v[226:229], v[32:35]
	s_cmp_gt_u32 s80, 41
	v_mfma_f32_16x16x32_bf16 v[20:23], v[160:163], v[234:237], v[20:23]
	s_mov_b64 s[2:3], s[48:49]
	v_mfma_f32_16x16x32_bf16 v[16:19], v[168:171], v[234:237], v[16:19]
	v_mfma_f32_16x16x32_bf16 v[4:7], v[160:163], v[242:245], v[4:7]
	v_mfma_f32_16x16x32_bf16 v[0:3], v[168:171], v[242:245], v[0:3]
	v_mfma_f32_16x16x32_bf16 v[52:55], v[164:167], v[222:225], v[52:55]
	v_mfma_f32_16x16x32_bf16 v[48:51], v[172:175], v[222:225], v[48:51]
	v_mfma_f32_16x16x32_bf16 v[36:39], v[164:167], v[230:233], v[36:39]
	v_mfma_f32_16x16x32_bf16 v[32:35], v[172:175], v[230:233], v[32:35]
	v_mfma_f32_16x16x32_bf16 v[20:23], v[164:167], v[238:241], v[20:23]
	v_mfma_f32_16x16x32_bf16 v[16:19], v[172:175], v[238:241], v[16:19]
	v_mfma_f32_16x16x32_bf16 v[4:7], v[164:167], v[246:249], v[4:7]
	v_mfma_f32_16x16x32_bf16 v[0:3], v[172:175], v[246:249], v[0:3]
	s_setprio 0
	s_barrier
	s_cbranch_scc1 .Lpeel_after_P9
.LBB0_942:
	ds_read_b128 v[144:147], v199
	ds_read_b128 v[148:151], v199 offset:1024
	ds_read_b128 v[152:155], v199 offset:2048
	ds_read_b128 v[156:159], v199 offset:3072
	ds_read_b128 v[160:163], v200
	ds_read_b128 v[164:167], v200 offset:1024
	ds_read_b128 v[168:171], v200 offset:2048
	ds_read_b128 v[172:175], v200 offset:3072
	s_add_u32 s48, s2, 0x100
	s_addc_u32 s49, s3, 0
	s_cmp_eq_u32 s80, 40
	s_cselect_b32 s53, s33, s49
	s_cselect_b32 s52, s46, s48
	s_cselect_b32 s51, s47, s79
	s_cselect_b32 s50, s77, s78
	v_lshl_add_u64 v[176:177], s[2:3], 0, v[138:139]
	s_add_i32 m0, s43, 0xc000
	ds_read_b128 v[214:217], v201
	ds_read_b128 v[222:225], v201 offset:1024
	ds_read_b128 v[226:229], v201 offset:2048
	ds_read_b128 v[230:233], v201 offset:3072
	ds_read_b128 v[234:237], v201 offset:4096
	ds_read_b128 v[238:241], v201 offset:5120
	ds_read_b128 v[242:245], v201 offset:6144
	ds_read_b128 v[246:249], v201 offset:7168
	global_load_lds_dwordx4 v[176:177], off
	v_lshl_add_u64 v[176:177], s[2:3], 0, v[136:137]
	s_add_i32 m0, s43, 0xe000
	s_nop 0
	global_load_lds_dwordx4 v[176:177], off
	s_waitcnt vmcnt(8) lgkmcnt(0)
	s_barrier
; #define PG8_STAGE(bufoff, gbase, voff) do { _Pragma("unroll") for (int _i = 0; _i < 2; ++_i) \
;         __builtin_amdgcn_global_load_lds((const unsigned*)((const char*)(gbase) + (voff)[_i]), (PG8_LAS unsigned*)(lds + (bufoff) + ldsw + _i * 8192), 16, 0, 0); } while (0)
; #define PG8_LDA(dst, b, h) do { _Pragma("unroll") for (int m = 0; m < 4; ++m) _Pragma("unroll") for (int k = 0; k < 2; ++k) dst[m][k] = *(const PG8_LAS bf16x8*)(lds + PG8_SA(b, h) + aoff + m * 2048 + k * 1024); } while (0)
; #define PG8_LDB(dst, b, h) do { _Pragma("unroll") for (int n = 0; n < 2; ++n) _Pragma("unroll") for (int k = 0; k < 2; ++k) dst[n][k] = *(const PG8_LAS bf16x8*)(lds + PG8_SB(b, h) + boff + n * 2048 + k * 1024); } while (0)
; #define PG8_MMA(ai, bj, At, Bt) do { __builtin_amdgcn_s_setprio(1); _Pragma("unroll") for (int m = 0; m < 4; ++m) _Pragma("unroll") for (int n = 0; n < 2; ++n) _Pragma("unroll") for (int k = 0; k < 2; ++k) \
;         acc[ai][bj][m][n] = __builtin_amdgcn_mfma_f32_16x16x32_bf16(Bt[n][k], At[m][k], acc[ai][bj][m][n], 0, 0, 0); __builtin_amdgcn_s_setprio(0); } while (0)
; #define PG8_WAIT_V(n) asm volatile("s_waitcnt vmcnt(" #n ")" ::: "memory")
; #define PG8_WAIT_L(n) asm volatile("s_waitcnt lgkmcnt(" #n ")" ::: "memory")
; #define PG8_BAR __builtin_amdgcn_s_barrier()
; #define PG8_SCHED __builtin_amdgcn_sched_barrier(0)
; template <class Epi, class Sched>
; __device__ __forceinline__ void gemm_phase(PG8_LAS unsigned char* lds, PG8_LAS unsigned char* xl, const Gemm g, const Sched& S, const Epi& E) {
;     ...
;             PG8_LDB(B0, 0, 0); PG8_LDB(B1, 0, 1); PG8_SCHED; PG8_LDA(At, 0, 0); PG8_STAGE(PG8_SA(1, 1), a1 + hsA, voffA);
;             PG8_WAIT_V(8); PG8_WAIT_L(0); PG8_BAR; PG8_MMA(0, 0, At, B0); PG8_MMA(0, 1, At, B1); PG8_BAR; PG8_SCHED;
;             PG8_LDA(At, 0, 1); PG8_STAGE(PG8_SB(0, 0), b2, voffB); PG8_STAGE(PG8_SB(0, 1), b2 + hsB, voffB); PG8_STAGE(PG8_SA(0, 0), a2, voffA);
;             PG8_WAIT_V(8); PG8_WAIT_L(0); PG8_BAR; PG8_MMA(1, 0, At, B0); PG8_MMA(1, 1, At, B1); PG8_BAR; PG8_SCHED;
	s_setprio 1
	v_mfma_f32_16x16x32_bf16 v[124:127], v[144:147], v[214:217], v[124:127]
	v_mfma_f32_16x16x32_bf16 v[120:123], v[152:155], v[214:217], v[120:123]
	v_mfma_f32_16x16x32_bf16 v[108:111], v[144:147], v[226:229], v[108:111]
	v_mfma_f32_16x16x32_bf16 v[104:107], v[152:155], v[226:229], v[104:107]
	v_mfma_f32_16x16x32_bf16 v[92:95], v[144:147], v[234:237], v[92:95]
	v_mfma_f32_16x16x32_bf16 v[88:91], v[152:155], v[234:237], v[88:91]
	v_mfma_f32_16x16x32_bf16 v[76:79], v[144:147], v[242:245], v[76:79]
	v_mfma_f32_16x16x32_bf16 v[72:75], v[152:155], v[242:245], v[72:75]
	v_mfma_f32_16x16x32_bf16 v[124:127], v[148:151], v[222:225], v[124:127]
	v_mfma_f32_16x16x32_bf16 v[120:123], v[156:159], v[222:225], v[120:123]
	v_mfma_f32_16x16x32_bf16 v[108:111], v[148:151], v[230:233], v[108:111]
	v_mfma_f32_16x16x32_bf16 v[104:107], v[156:159], v[230:233], v[104:107]
	v_mfma_f32_16x16x32_bf16 v[92:95], v[148:151], v[238:241], v[92:95]
	v_mfma_f32_16x16x32_bf16 v[88:91], v[156:159], v[238:241], v[88:91]
	v_mfma_f32_16x16x32_bf16 v[76:79], v[148:151], v[246:249], v[76:79]
	v_mfma_f32_16x16x32_bf16 v[72:75], v[156:159], v[246:249], v[72:75]
	s_setprio 0
	s_setprio 1
	v_mfma_f32_16x16x32_bf16 v[116:119], v[160:163], v[214:217], v[116:119]
	v_mfma_f32_16x16x32_bf16 v[112:115], v[168:171], v[214:217], v[112:115]
	v_mfma_f32_16x16x32_bf16 v[100:103], v[160:163], v[226:229], v[100:103]
	v_mfma_f32_16x16x32_bf16 v[96:99], v[168:171], v[226:229], v[96:99]
	v_mfma_f32_16x16x32_bf16 v[84:87], v[160:163], v[234:237], v[84:87]
	v_mfma_f32_16x16x32_bf16 v[80:83], v[168:171], v[234:237], v[80:83]
	v_mfma_f32_16x16x32_bf16 v[68:71], v[160:163], v[242:245], v[68:71]
	v_mfma_f32_16x16x32_bf16 v[64:67], v[168:171], v[242:245], v[64:67]
	v_mfma_f32_16x16x32_bf16 v[116:119], v[164:167], v[222:225], v[116:119]
	v_mfma_f32_16x16x32_bf16 v[112:115], v[172:175], v[222:225], v[112:115]
	v_mfma_f32_16x16x32_bf16 v[100:103], v[164:167], v[230:233], v[100:103]
	v_mfma_f32_16x16x32_bf16 v[96:99], v[172:175], v[230:233], v[96:99]
	v_mfma_f32_16x16x32_bf16 v[84:87], v[164:167], v[238:241], v[84:87]
	v_mfma_f32_16x16x32_bf16 v[80:83], v[172:175], v[238:241], v[80:83]
	v_mfma_f32_16x16x32_bf16 v[68:71], v[164:167], v[246:249], v[68:71]
	v_mfma_f32_16x16x32_bf16 v[64:67], v[172:175], v[246:249], v[64:67]
	s_setprio 0
	s_barrier
	s_add_i32 s2, s70, s42
	v_lshl_add_u64 v[176:177], s[50:51], 0, v[130:131]
	s_mov_b32 m0, s2
	ds_read_b128 v[214:217], v201 offset:16384
	ds_read_b128 v[222:225], v201 offset:17408
	ds_read_b128 v[226:229], v201 offset:18432
	ds_read_b128 v[230:233], v201 offset:19456
	ds_read_b128 v[234:237], v201 offset:20480
	ds_read_b128 v[238:241], v201 offset:21504
	ds_read_b128 v[242:245], v201 offset:22528
	ds_read_b128 v[246:249], v201 offset:23552
	global_load_lds_dwordx4 v[176:177], off
	s_add_i32 m0, s2, 0x2000
	s_add_u32 s2, s50, 0xb0000
	v_lshl_add_u64 v[218:219], s[50:51], 0, v[134:135]
	s_addc_u32 s3, s51, 0
	s_add_i32 s68, s71, s42
	global_load_lds_dwordx4 v[218:219], off
	v_lshl_add_u64 v[250:251], s[2:3], 0, v[130:131]
	s_mov_b32 m0, s68
	v_lshl_add_u64 v[252:253], s[52:53], 0, v[132:133]
	global_load_lds_dwordx4 v[250:251], off
	v_lshl_add_u64 v[250:251], s[2:3], 0, v[134:135]
	s_add_i32 m0, s68, 0x2000
	s_nop 0
	global_load_lds_dwordx4 v[250:251], off
	v_lshl_add_u64 v[250:251], s[52:53], 0, v[128:129]
	s_mov_b32 m0, s43
	s_nop 0
	global_load_lds_dwordx4 v[250:251], off
	s_mov_b32 m0, s59
	s_nop 0
	global_load_lds_dwordx4 v[252:253], off
	s_waitcnt vmcnt(8) lgkmcnt(0)
	s_barrier
	s_setprio 1
	v_mfma_f32_16x16x32_bf16 v[60:63], v[144:147], v[214:217], v[60:63]
	v_mfma_f32_16x16x32_bf16 v[56:59], v[152:155], v[214:217], v[56:59]
	v_mfma_f32_16x16x32_bf16 v[44:47], v[144:147], v[226:229], v[44:47]
	v_mfma_f32_16x16x32_bf16 v[40:43], v[152:155], v[226:229], v[40:43]
	v_mfma_f32_16x16x32_bf16 v[28:31], v[144:147], v[234:237], v[28:31]
	v_mfma_f32_16x16x32_bf16 v[24:27], v[152:155], v[234:237], v[24:27]
	v_mfma_f32_16x16x32_bf16 v[12:15], v[144:147], v[242:245], v[12:15]
	v_mfma_f32_16x16x32_bf16 v[8:11], v[152:155], v[242:245], v[8:11]
	v_mfma_f32_16x16x32_bf16 v[60:63], v[148:151], v[222:225], v[60:63]
	v_mfma_f32_16x16x32_bf16 v[56:59], v[156:159], v[222:225], v[56:59]
	v_mfma_f32_16x16x32_bf16 v[44:47], v[148:151], v[230:233], v[44:47]
	v_mfma_f32_16x16x32_bf16 v[40:43], v[156:159], v[230:233], v[40:43]
	v_mfma_f32_16x16x32_bf16 v[28:31], v[148:151], v[238:241], v[28:31]
	v_mfma_f32_16x16x32_bf16 v[24:27], v[156:159], v[238:241], v[24:27]
	v_mfma_f32_16x16x32_bf16 v[12:15], v[148:151], v[246:249], v[12:15]
	v_mfma_f32_16x16x32_bf16 v[8:11], v[156:159], v[246:249], v[8:11]
	s_setprio 0
	s_setprio 1
	v_mfma_f32_16x16x32_bf16 v[52:55], v[160:163], v[214:217], v[52:55]
	v_mfma_f32_16x16x32_bf16 v[48:51], v[168:171], v[214:217], v[48:51]
	v_mfma_f32_16x16x32_bf16 v[36:39], v[160:163], v[226:229], v[36:39]
	v_mfma_f32_16x16x32_bf16 v[32:35], v[168:171], v[226:229], v[32:35]
	v_mfma_f32_16x16x32_bf16 v[20:23], v[160:163], v[234:237], v[20:23]
	v_mfma_f32_16x16x32_bf16 v[16:19], v[168:171], v[234:237], v[16:19]
	v_mfma_f32_16x16x32_bf16 v[4:7], v[160:163], v[242:245], v[4:7]
	v_mfma_f32_16x16x32_bf16 v[0:3], v[168:171], v[242:245], v[0:3]
	v_mfma_f32_16x16x32_bf16 v[52:55], v[164:167], v[222:225], v[52:55]
	v_mfma_f32_16x16x32_bf16 v[48:51], v[172:175], v[222:225], v[48:51]
	v_mfma_f32_16x16x32_bf16 v[36:39], v[164:167], v[230:233], v[36:39]
	v_mfma_f32_16x16x32_bf16 v[32:35], v[172:175], v[230:233], v[32:35]
	v_mfma_f32_16x16x32_bf16 v[20:23], v[164:167], v[238:241], v[20:23]
	v_mfma_f32_16x16x32_bf16 v[16:19], v[172:175], v[238:241], v[16:19]
	v_mfma_f32_16x16x32_bf16 v[4:7], v[164:167], v[246:249], v[4:7]
	v_mfma_f32_16x16x32_bf16 v[0:3], v[172:175], v[246:249], v[0:3]
	s_setprio 0
	s_barrier
; #define PG8_STAGE(bufoff, gbase, voff) do { _Pragma("unroll") for (int _i = 0; _i < 2; ++_i) \
;         __builtin_amdgcn_global_load_lds((const unsigned*)((const char*)(gbase) + (voff)[_i]), (PG8_LAS unsigned*)(lds + (bufoff) + ldsw + _i * 8192), 16, 0, 0); } while (0)
; #define PG8_LDA(dst, b, h) do { _Pragma("unroll") for (int m = 0; m < 4; ++m) _Pragma("unroll") for (int k = 0; k < 2; ++k) dst[m][k] = *(const PG8_LAS bf16x8*)(lds + PG8_SA(b, h) + aoff + m * 2048 + k * 1024); } while (0)
; #define PG8_LDB(dst, b, h) do { _Pragma("unroll") for (int n = 0; n < 2; ++n) _Pragma("unroll") for (int k = 0; k < 2; ++k) dst[n][k] = *(const PG8_LAS bf16x8*)(lds + PG8_SB(b, h) + boff + n * 2048 + k * 1024); } while (0)
; #define PG8_MMA(ai, bj, At, Bt) do { __builtin_amdgcn_s_setprio(1); _Pragma("unroll") for (int m = 0; m < 4; ++m) _Pragma("unroll") for (int n = 0; n < 2; ++n) _Pragma("unroll") for (int k = 0; k < 2; ++k) \
;         acc[ai][bj][m][n] = __builtin_amdgcn_mfma_f32_16x16x32_bf16(Bt[n][k], At[m][k], acc[ai][bj][m][n], 0, 0, 0); __builtin_amdgcn_s_setprio(0); } while (0)
; #define PG8_WAIT_V(n) asm volatile("s_waitcnt vmcnt(" #n ")" ::: "memory")
; #define PG8_WAIT_L(n) asm volatile("s_waitcnt lgkmcnt(" #n ")" ::: "memory")
; #define PG8_BAR __builtin_amdgcn_s_barrier()
; #define PG8_SCHED __builtin_amdgcn_sched_barrier(0)
; template <class Epi, class Sched>
; __device__ __forceinline__ void gemm_phase(PG8_LAS unsigned char* lds, PG8_LAS unsigned char* xl, const Gemm g, const Sched& S, const Epi& E) {
;     ...
;             PG8_LDB(B0, 1, 0); PG8_LDB(B1, 1, 1); PG8_SCHED; PG8_LDA(At, 1, 0); PG8_STAGE(PG8_SA(0, 1), a2 + hsA, voffA);
;             PG8_WAIT_V(8); PG8_WAIT_L(0); PG8_BAR; PG8_MMA(0, 0, At, B0); PG8_MMA(0, 1, At, B1); PG8_BAR; PG8_SCHED;
;             PG8_LDA(At, 1, 1); PG8_STAGE(PG8_SB(1, 0), b3, voffB); PG8_STAGE(PG8_SB(1, 1), b3 + hsB, voffB); PG8_STAGE(PG8_SA(1, 0), a3, voffA);
;             PG8_WAIT_V(8); PG8_WAIT_L(0); PG8_BAR; PG8_MMA(1, 0, At, B0); PG8_MMA(1, 1, At, B1); PG8_BAR; PG8_SCHED;
	s_add_i32 s68, 0, 0x18000
	s_add_i32 s81, 0, 0x1c000
	v_add_u32_e32 v156, s68, v181
	v_add_u32_e32 v172, s81, v181
	ds_read_b128 v[144:147], v156
	ds_read_b128 v[148:151], v156 offset:1024
	ds_read_b128 v[152:155], v156 offset:2048
	ds_read_b128 v[156:159], v156 offset:3072
	ds_read_b128 v[160:163], v172
	ds_read_b128 v[164:167], v172 offset:1024
	ds_read_b128 v[168:171], v172 offset:2048
	ds_read_b128 v[172:175], v172 offset:3072
	s_add_u32 s2, s52, 0xb0000
	s_addc_u32 s3, s53, 0
	s_mov_b32 m0, s60
	v_lshl_add_u64 v[212:213], s[2:3], 0, v[128:129]
	ds_read_b128 v[214:217], v201 offset:32768
	ds_read_b128 v[222:225], v201 offset:33792
	ds_read_b128 v[226:229], v201 offset:34816
	ds_read_b128 v[230:233], v201 offset:35840
	ds_read_b128 v[234:237], v201 offset:36864
	ds_read_b128 v[238:241], v201 offset:37888
	ds_read_b128 v[242:245], v201 offset:38912
	ds_read_b128 v[246:249], v201 offset:39936
	global_load_lds_dwordx4 v[212:213], off
	v_lshl_add_u64 v[212:213], s[2:3], 0, v[132:133]
	s_mov_b32 m0, s61
	s_nop 0
	global_load_lds_dwordx4 v[212:213], off
	s_waitcnt vmcnt(8) lgkmcnt(0)
	s_barrier
	s_setprio 1
	v_mfma_f32_16x16x32_bf16 v[124:127], v[144:147], v[214:217], v[124:127]
	v_mfma_f32_16x16x32_bf16 v[120:123], v[152:155], v[214:217], v[120:123]
	v_mfma_f32_16x16x32_bf16 v[108:111], v[144:147], v[226:229], v[108:111]
	v_mfma_f32_16x16x32_bf16 v[104:107], v[152:155], v[226:229], v[104:107]
	v_mfma_f32_16x16x32_bf16 v[92:95], v[144:147], v[234:237], v[92:95]
	v_mfma_f32_16x16x32_bf16 v[88:91], v[152:155], v[234:237], v[88:91]
	v_mfma_f32_16x16x32_bf16 v[76:79], v[144:147], v[242:245], v[76:79]
	v_mfma_f32_16x16x32_bf16 v[72:75], v[152:155], v[242:245], v[72:75]
	v_mfma_f32_16x16x32_bf16 v[124:127], v[148:151], v[222:225], v[124:127]
	v_mfma_f32_16x16x32_bf16 v[120:123], v[156:159], v[222:225], v[120:123]
	v_mfma_f32_16x16x32_bf16 v[108:111], v[148:151], v[230:233], v[108:111]
	v_mfma_f32_16x16x32_bf16 v[104:107], v[156:159], v[230:233], v[104:107]
	v_mfma_f32_16x16x32_bf16 v[92:95], v[148:151], v[238:241], v[92:95]
	v_mfma_f32_16x16x32_bf16 v[88:91], v[156:159], v[238:241], v[88:91]
	v_mfma_f32_16x16x32_bf16 v[76:79], v[148:151], v[246:249], v[76:79]
	v_mfma_f32_16x16x32_bf16 v[72:75], v[156:159], v[246:249], v[72:75]
	s_setprio 0
	s_setprio 1
	v_mfma_f32_16x16x32_bf16 v[116:119], v[160:163], v[214:217], v[116:119]
	v_mfma_f32_16x16x32_bf16 v[112:115], v[168:171], v[214:217], v[112:115]
	v_mfma_f32_16x16x32_bf16 v[100:103], v[160:163], v[226:229], v[100:103]
	v_mfma_f32_16x16x32_bf16 v[96:99], v[168:171], v[226:229], v[96:99]
	v_mfma_f32_16x16x32_bf16 v[84:87], v[160:163], v[234:237], v[84:87]
	v_mfma_f32_16x16x32_bf16 v[80:83], v[168:171], v[234:237], v[80:83]
	v_mfma_f32_16x16x32_bf16 v[68:71], v[160:163], v[242:245], v[68:71]
	v_mfma_f32_16x16x32_bf16 v[64:67], v[168:171], v[242:245], v[64:67]
	v_mfma_f32_16x16x32_bf16 v[116:119], v[164:167], v[222:225], v[116:119]
	v_mfma_f32_16x16x32_bf16 v[112:115], v[172:175], v[222:225], v[112:115]
	v_mfma_f32_16x16x32_bf16 v[100:103], v[164:167], v[230:233], v[100:103]
	v_mfma_f32_16x16x32_bf16 v[96:99], v[172:175], v[230:233], v[96:99]
	v_mfma_f32_16x16x32_bf16 v[84:87], v[164:167], v[238:241], v[84:87]
	v_mfma_f32_16x16x32_bf16 v[80:83], v[172:175], v[238:241], v[80:83]
	v_mfma_f32_16x16x32_bf16 v[68:71], v[164:167], v[246:249], v[68:71]
	v_mfma_f32_16x16x32_bf16 v[64:67], v[172:175], v[246:249], v[64:67]
	s_setprio 0
	s_barrier
	s_add_i32 s2, s68, s42
	v_lshl_add_u64 v[176:177], v[176:177], 0, s[22:23]
	s_mov_b32 m0, s2
	ds_read_b128 v[214:217], v201 offset:49152
	ds_read_b128 v[222:225], v201 offset:50176
	ds_read_b128 v[226:229], v201 offset:51200
	ds_read_b128 v[230:233], v201 offset:52224
	ds_read_b128 v[234:237], v201 offset:53248
	ds_read_b128 v[238:241], v201 offset:54272
	ds_read_b128 v[242:245], v201 offset:55296
	ds_read_b128 v[246:249], v201 offset:56320
	global_load_lds_dwordx4 v[176:177], off
	s_add_i32 m0, s2, 0x2000
	s_add_u32 s2, s50, 0xb0080
	v_lshl_add_u64 v[176:177], v[218:219], 0, s[22:23]
	s_addc_u32 s3, s51, 0
	s_add_i32 s50, s81, s42
	global_load_lds_dwordx4 v[176:177], off
	v_lshl_add_u64 v[176:177], s[2:3], 0, v[130:131]
	s_mov_b32 m0, s50
	s_nop 0
	global_load_lds_dwordx4 v[176:177], off
	v_lshl_add_u64 v[176:177], s[2:3], 0, v[134:135]
	s_add_i32 m0, s50, 0x2000
	s_nop 0
	global_load_lds_dwordx4 v[176:177], off
	v_lshl_add_u64 v[176:177], v[250:251], 0, s[22:23]
	s_mov_b32 m0, s65
	s_nop 0
	global_load_lds_dwordx4 v[176:177], off
	v_lshl_add_u64 v[176:177], v[252:253], 0, s[22:23]
	s_mov_b32 m0, s66
	s_nop 0
	global_load_lds_dwordx4 v[176:177], off
	s_waitcnt vmcnt(8) lgkmcnt(0)
	s_barrier
	s_setprio 1
	v_mfma_f32_16x16x32_bf16 v[60:63], v[144:147], v[214:217], v[60:63]
	v_mfma_f32_16x16x32_bf16 v[56:59], v[152:155], v[214:217], v[56:59]
	v_mfma_f32_16x16x32_bf16 v[44:47], v[144:147], v[226:229], v[44:47]
	v_mfma_f32_16x16x32_bf16 v[40:43], v[152:155], v[226:229], v[40:43]
	v_mfma_f32_16x16x32_bf16 v[28:31], v[144:147], v[234:237], v[28:31]
	v_mfma_f32_16x16x32_bf16 v[24:27], v[152:155], v[234:237], v[24:27]
	v_mfma_f32_16x16x32_bf16 v[12:15], v[144:147], v[242:245], v[12:15]
	v_mfma_f32_16x16x32_bf16 v[8:11], v[152:155], v[242:245], v[8:11]
	v_mfma_f32_16x16x32_bf16 v[60:63], v[148:151], v[222:225], v[60:63]
	v_mfma_f32_16x16x32_bf16 v[56:59], v[156:159], v[222:225], v[56:59]
	v_mfma_f32_16x16x32_bf16 v[44:47], v[148:151], v[230:233], v[44:47]
	v_mfma_f32_16x16x32_bf16 v[40:43], v[156:159], v[230:233], v[40:43]
	v_mfma_f32_16x16x32_bf16 v[28:31], v[148:151], v[238:241], v[28:31]
	v_mfma_f32_16x16x32_bf16 v[24:27], v[156:159], v[238:241], v[24:27]
	v_mfma_f32_16x16x32_bf16 v[12:15], v[148:151], v[246:249], v[12:15]
	v_mfma_f32_16x16x32_bf16 v[8:11], v[156:159], v[246:249], v[8:11]
	s_setprio 0
	s_setprio 1
	v_mfma_f32_16x16x32_bf16 v[52:55], v[160:163], v[214:217], v[52:55]
	s_add_i32 s80, s80, 2
	v_mfma_f32_16x16x32_bf16 v[48:51], v[168:171], v[214:217], v[48:51]
	s_add_u32 s78, s78, 0x100
	v_mfma_f32_16x16x32_bf16 v[36:39], v[160:163], v[226:229], v[36:39]
	s_addc_u32 s79, s79, 0
	v_mfma_f32_16x16x32_bf16 v[32:35], v[168:171], v[226:229], v[32:35]
	s_cmp_gt_u32 s80, 41
	v_mfma_f32_16x16x32_bf16 v[20:23], v[160:163], v[234:237], v[20:23]
	s_mov_b64 s[2:3], s[48:49]
	v_mfma_f32_16x16x32_bf16 v[16:19], v[168:171], v[234:237], v[16:19]
	v_mfma_f32_16x16x32_bf16 v[4:7], v[160:163], v[242:245], v[4:7]
	v_mfma_f32_16x16x32_bf16 v[0:3], v[168:171], v[242:245], v[0:3]
	v_mfma_f32_16x16x32_bf16 v[52:55], v[164:167], v[222:225], v[52:55]
	v_mfma_f32_16x16x32_bf16 v[48:51], v[172:175], v[222:225], v[48:51]
	v_mfma_f32_16x16x32_bf16 v[36:39], v[164:167], v[230:233], v[36:39]
	v_mfma_f32_16x16x32_bf16 v[32:35], v[172:175], v[230:233], v[32:35]
	v_mfma_f32_16x16x32_bf16 v[20:23], v[164:167], v[238:241], v[20:23]
	v_mfma_f32_16x16x32_bf16 v[16:19], v[172:175], v[238:241], v[16:19]
	v_mfma_f32_16x16x32_bf16 v[4:7], v[164:167], v[246:249], v[4:7]
	v_mfma_f32_16x16x32_bf16 v[0:3], v[172:175], v[246:249], v[0:3]
	s_setprio 0
	s_barrier
	s_cbranch_scc0 .LBB0_942
